# attn one barrier per KV tile + MoE-up epilogue silu in packed f32 (same f32 math, fewer VALU)
# speedup vs baseline: 1.0149x; 1.0149x over previous
.LBB0_285:
	v_mov_b32_e32 v2, v0
	s_barrier
	s_cmpk_gt_i32 s2, 0x65f
	v_readfirstlane_b32 s3, v2
	s_cbranch_scc1 .LBB0_303
	v_bfe_i32 v4, v2, 27, 1
	v_lshlrev_b32_e32 v1, 4, v2
	v_lshrrev_b32_e32 v4, 22, v4
	v_add_u32_e32 v4, v1, v4
	v_and_b32_e32 v4, 0xfffffc00, v4
	v_sub_u32_e32 v1, v1, v4
	v_ashrrev_i32_e32 v3, 31, v2
	v_lshrrev_b32_e32 v4, 4, v1
	v_lshrrev_b32_e32 v3, 26, v3
	v_bitop3_b32 v1, v4, v1, 32 bitop3:0x6c
	s_add_u32 s8, s52, 0xb00000
	v_add_u32_e32 v3, v2, v3
	v_ashrrev_i32_e32 v5, 31, v1
	s_addc_u32 s6, s53, 0
	v_ashrrev_i32_e32 v3, 6, v3
	v_lshrrev_b32_e32 v5, 26, v5
	s_ashr_i32 s20, s2, 31
	v_lshlrev_b32_e32 v4, 3, v3
	v_add_u32_e32 v5, v1, v5
	s_lshr_b32 s7, s20, 29
	v_readlane_b32 s10, v255, 8
	v_and_b32_e32 v4, -16, v4
	v_ashrrev_i32_e32 v6, 6, v5
	s_add_i32 s7, s2, s7
	s_ashr_i32 s4, s3, 6
	v_readlane_b32 s11, v255, 9
	v_add_u32_e32 v4, v6, v4
	v_and_b32_e32 v6, 3, v6
	s_mov_b32 s5, 0x1fffe0
	s_ashr_i32 s12, s7, 3
	s_and_b32 s7, s7, -8
	s_and_b32 s41, s11, 0xffff
	v_and_or_b32 v6, v4, s5, v6
	s_ashr_i32 s5, s3, 8
	s_and_b32 s9, s6, 0xffff
	s_lshl_b32 s6, s4, 10
	s_sub_i32 s7, s2, s7
	s_cmp_lt_i32 s7, 0
	s_movk_i32 s21, 0xcd
	s_cselect_b32 s13, s21, 0xcc
	s_mul_i32 s7, s13, s7
	s_add_i32 s7, s7, s12
	s_mul_hi_i32 s12, s7, 0x2aaaaaab
	s_lshr_b32 s13, s12, 31
	s_ashr_i32 s12, s12, 4
	s_add_i32 s12, s12, s13
	s_lshl_b32 s13, s12, 3
	s_mulk_i32 s12, 0x60
	s_sub_i32 s7, s7, s12
	s_bfe_i32 s12, s7, 0x80000
	s_bfe_u32 s12, s12, 0x3000c
	s_add_i32 s12, s7, s12
	s_bfe_i32 s14, s12, 0x80000
	s_and_b32 s12, s12, 0xf8
	s_sub_i32 s7, s7, s12
	s_sext_i32_i8 s7, s7
	s_add_i32 s78, s13, s7
	s_ashr_i32 s7, s78, 31
	v_and_b32_e32 v5, 0xc0, v5
	s_lshr_b32 s7, s7, 12
	v_sub_u32_e32 v1, v1, v5
	v_mov_b32_e32 v5, 1
	s_add_i32 s7, s78, s7
	v_lshlrev_b32_e32 v3, 5, v3
	v_ashrrev_i16_sdwa v1, v5, sext(v1) dst_sel:DWORD dst_unused:UNUSED_PAD src0_sel:DWORD src1_sel:BYTE_0
	v_lshlrev_b32_e32 v5, 1, v4
	v_lshrrev_b32_e32 v7, 2, v4
	s_sext_i32_i16 s14, s14
	s_ashr_i32 s7, s7, 20
	v_and_b32_e32 v3, 32, v3
	v_bfe_i32 v1, v1, 0, 16
	v_and_b32_e32 v5, 24, v5
	v_and_b32_e32 v7, 4, v7
	s_ashr_i32 s73, s14, 3
	s_mul_i32 s7, s7, 12
	s_add_i32 s22, s6, 0
	s_mov_b32 s43, 0x20000
	s_brev_b32 s42, -2
	v_or3_b32 v5, v6, v7, v5
	v_add_lshl_u32 v3, v3, v1, 1
	s_add_i32 s7, s7, s73
	s_add_i32 s23, s22, 0x10000
	v_lshl_add_u32 v144, v5, 11, v3
	s_mov_b32 s10, s42
	s_mov_b32 s11, s43
	s_lshl_b32 s79, s7, 19
	s_mov_b32 m0, s23
	s_add_i32 s24, s22, 0x12000
	buffer_load_dwordx4 v144, s[8:11], s79 offen lds
	s_or_b32 s6, s79, 0x20000
	s_mov_b32 m0, s24
	v_lshl_add_u32 v1, v4, 11, v3
	buffer_load_dwordx4 v144, s[8:11], s6 offen lds
	s_lshl_b32 s86, s78, 19
	s_mov_b32 m0, s22
	s_add_i32 s25, s22, 0x2000
	buffer_load_dwordx4 v1, s[40:43], s86 offen lds
	s_or_b32 s6, s86, 0x20000
	s_mov_b32 m0, s25
	s_add_i32 s26, s22, 0x14000
	buffer_load_dwordx4 v1, s[40:43], s6 offen lds
	s_or_b32 s6, s79, 0x40000
	s_mov_b32 m0, s26
	s_add_i32 s27, s22, 0x16000
	buffer_load_dwordx4 v144, s[8:11], s6 offen lds
	s_or_b32 s6, s79, 0x60000
	s_mov_b32 m0, s27
	s_add_i32 s28, s22, 0x4000
	buffer_load_dwordx4 v144, s[8:11], s6 offen lds
	s_or_b32 s6, s86, 0x40000
	s_mov_b32 m0, s28
	s_add_i32 s29, s22, 0x6000
	buffer_load_dwordx4 v1, s[40:43], s6 offen lds
	s_or_b32 s6, s86, 0x60000
	s_mov_b32 m0, s29
	s_cmp_lg_u32 s5, 1
	buffer_load_dwordx4 v1, s[40:43], s6 offen lds
	s_mov_b32 s30, 0
	s_cbranch_scc1 .LBB0_288
	s_barrier

.LBB0_295:
	ds_read_b128 v[136:139], v147
	ds_read_b128 v[140:143], v147 offset:1024
	ds_read_b128 v[152:155], v147 offset:2048
	ds_read_b128 v[156:159], v147 offset:3072
	s_add_i32 s10, s7, 0xfffa0080
	s_cmp_eq_u32 s86, 12
	s_cselect_b32 s88, s6, s10
	s_cselect_b32 s87, s59, s79
	s_or_b32 s89, s88, 0x80
	s_add_i32 s10, s7, 0xfffe0000
	s_mov_b32 m0, s39
	ds_read_b128 v[160:163], v148
	ds_read_b128 v[164:167], v148 offset:1024
	ds_read_b128 v[168:171], v148 offset:2048
	ds_read_b128 v[172:175], v148 offset:3072
	ds_read_b128 v[176:179], v148 offset:4096
	ds_read_b128 v[180:183], v148 offset:5120
	ds_read_b128 v[184:187], v148 offset:6144
	ds_read_b128 v[188:191], v148 offset:7168
	buffer_load_dwordx4 v1, s[40:43], s10 offen lds
	s_mov_b32 m0, s45
	s_nop 0
	buffer_load_dwordx4 v1, s[40:43], s7 offen lds
	s_waitcnt lgkmcnt(8)
	s_barrier
	s_waitcnt lgkmcnt(0)
	s_setprio 1
	s_waitcnt lgkmcnt(7)
	v_mfma_f32_16x16x32_bf16 v[126:129], v[136:139], v[160:163], v[126:129]
	v_mfma_f32_16x16x32_bf16 v[122:125], v[152:155], v[160:163], v[122:125]
	s_waitcnt lgkmcnt(5)
	v_mfma_f32_16x16x32_bf16 v[118:121], v[136:139], v[168:171], v[118:121]
	v_mfma_f32_16x16x32_bf16 v[110:113], v[152:155], v[168:171], v[110:113]
	s_waitcnt lgkmcnt(3)
	v_mfma_f32_16x16x32_bf16 v[102:105], v[136:139], v[176:179], v[102:105]
	v_mfma_f32_16x16x32_bf16 v[94:97], v[152:155], v[176:179], v[94:97]
	s_waitcnt lgkmcnt(1)
	v_mfma_f32_16x16x32_bf16 v[86:89], v[136:139], v[184:187], v[86:89]
	v_mfma_f32_16x16x32_bf16 v[78:81], v[152:155], v[184:187], v[78:81]
	v_mfma_f32_16x16x32_bf16 v[126:129], v[140:143], v[164:167], v[126:129]
	v_mfma_f32_16x16x32_bf16 v[122:125], v[156:159], v[164:167], v[122:125]
	v_mfma_f32_16x16x32_bf16 v[118:121], v[140:143], v[172:175], v[118:121]
	v_mfma_f32_16x16x32_bf16 v[110:113], v[156:159], v[172:175], v[110:113]
	v_mfma_f32_16x16x32_bf16 v[102:105], v[140:143], v[180:183], v[102:105]
	v_mfma_f32_16x16x32_bf16 v[94:97], v[156:159], v[180:183], v[94:97]
	s_waitcnt lgkmcnt(0)
	v_mfma_f32_16x16x32_bf16 v[86:89], v[140:143], v[188:191], v[86:89]
	v_mfma_f32_16x16x32_bf16 v[78:81], v[156:159], v[188:191], v[78:81]
	s_setprio 0
	s_barrier
	s_mov_b32 m0, s23
	s_mov_b32 s10, s42
	s_mov_b32 s11, s43
	ds_read_b128 v[192:195], v149
	ds_read_b128 v[196:199], v149 offset:1024
	ds_read_b128 v[200:203], v149 offset:2048
	ds_read_b128 v[204:207], v149 offset:3072
	buffer_load_dwordx4 v144, s[8:11], s87 offen lds
	s_add_i32 s33, s87, 0x20000
	s_mov_b32 m0, s24
	s_nop 0
	buffer_load_dwordx4 v144, s[8:11], s33 offen lds
	s_barrier
	s_waitcnt lgkmcnt(0)
	s_setprio 1
	s_waitcnt lgkmcnt(3)
	v_mfma_f32_16x16x32_bf16 v[114:117], v[192:195], v[160:163], v[114:117]
	s_waitcnt lgkmcnt(1)
	v_mfma_f32_16x16x32_bf16 v[106:109], v[200:203], v[160:163], v[106:109]
	v_mfma_f32_16x16x32_bf16 v[98:101], v[192:195], v[168:171], v[98:101]
	v_mfma_f32_16x16x32_bf16 v[90:93], v[200:203], v[168:171], v[90:93]
	v_mfma_f32_16x16x32_bf16 v[82:85], v[192:195], v[176:179], v[82:85]
	v_mfma_f32_16x16x32_bf16 v[74:77], v[200:203], v[176:179], v[74:77]
	v_mfma_f32_16x16x32_bf16 v[70:73], v[192:195], v[184:187], v[70:73]
	v_mfma_f32_16x16x32_bf16 v[66:69], v[200:203], v[184:187], v[66:69]
	v_mfma_f32_16x16x32_bf16 v[114:117], v[196:199], v[164:167], v[114:117]
	s_waitcnt lgkmcnt(0)
	v_mfma_f32_16x16x32_bf16 v[106:109], v[204:207], v[164:167], v[106:109]
	v_mfma_f32_16x16x32_bf16 v[98:101], v[196:199], v[172:175], v[98:101]
	v_mfma_f32_16x16x32_bf16 v[90:93], v[204:207], v[172:175], v[90:93]
	v_mfma_f32_16x16x32_bf16 v[82:85], v[196:199], v[180:183], v[82:85]
	v_mfma_f32_16x16x32_bf16 v[74:77], v[204:207], v[180:183], v[74:77]
	v_mfma_f32_16x16x32_bf16 v[70:73], v[196:199], v[188:191], v[70:73]
	v_mfma_f32_16x16x32_bf16 v[66:69], v[204:207], v[188:191], v[66:69]
	s_setprio 0
	s_mov_b32 m0, s22
	s_barrier
	ds_read_b128 v[160:163], v148 offset:16384
	ds_read_b128 v[164:167], v148 offset:17408
	ds_read_b128 v[168:171], v148 offset:18432
	ds_read_b128 v[172:175], v148 offset:19456
	ds_read_b128 v[176:179], v148 offset:20480
	ds_read_b128 v[180:183], v148 offset:21504
	ds_read_b128 v[184:187], v148 offset:22528
	ds_read_b128 v[188:191], v148 offset:23552
	buffer_load_dwordx4 v1, s[40:43], s88 offen lds
	s_add_i32 s33, s88, 0x20000
	s_mov_b32 m0, s25
	s_nop 0
	buffer_load_dwordx4 v1, s[40:43], s33 offen lds
	s_barrier
	s_waitcnt lgkmcnt(0)
	s_setprio 1
	s_waitcnt lgkmcnt(7)
	v_mfma_f32_16x16x32_bf16 v[62:65], v[136:139], v[160:163], v[62:65]
	v_mfma_f32_16x16x32_bf16 v[58:61], v[152:155], v[160:163], v[58:61]
	s_waitcnt lgkmcnt(5)
	v_mfma_f32_16x16x32_bf16 v[54:57], v[136:139], v[168:171], v[54:57]
	v_mfma_f32_16x16x32_bf16 v[46:49], v[152:155], v[168:171], v[46:49]
	s_waitcnt lgkmcnt(3)
	v_mfma_f32_16x16x32_bf16 v[38:41], v[136:139], v[176:179], v[38:41]
	v_mfma_f32_16x16x32_bf16 v[30:33], v[152:155], v[176:179], v[30:33]
	s_waitcnt lgkmcnt(1)
	v_mfma_f32_16x16x32_bf16 v[22:25], v[136:139], v[184:187], v[22:25]
	v_mfma_f32_16x16x32_bf16 v[14:17], v[152:155], v[184:187], v[14:17]
	v_mfma_f32_16x16x32_bf16 v[62:65], v[140:143], v[164:167], v[62:65]
	v_mfma_f32_16x16x32_bf16 v[58:61], v[156:159], v[164:167], v[58:61]
	v_mfma_f32_16x16x32_bf16 v[54:57], v[140:143], v[172:175], v[54:57]
	v_mfma_f32_16x16x32_bf16 v[46:49], v[156:159], v[172:175], v[46:49]
	v_mfma_f32_16x16x32_bf16 v[38:41], v[140:143], v[180:183], v[38:41]
	v_mfma_f32_16x16x32_bf16 v[30:33], v[156:159], v[180:183], v[30:33]
	s_waitcnt lgkmcnt(0)
	v_mfma_f32_16x16x32_bf16 v[22:25], v[140:143], v[188:191], v[22:25]
	v_mfma_f32_16x16x32_bf16 v[14:17], v[156:159], v[188:191], v[14:17]
	s_setprio 0
	s_barrier
	s_mov_b32 m0, s26
	s_add_i32 s33, s87, 0x40000
	buffer_load_dwordx4 v144, s[8:11], s33 offen lds
	s_add_i32 s33, s87, 0x60000
	s_mov_b32 m0, s27
	s_nop 0
	buffer_load_dwordx4 v144, s[8:11], s33 offen lds
	s_waitcnt vmcnt(6)
	s_barrier
	s_setprio 1
	v_mfma_f32_16x16x32_bf16 v[50:53], v[192:195], v[160:163], v[50:53]
	v_mfma_f32_16x16x32_bf16 v[42:45], v[200:203], v[160:163], v[42:45]
	v_mfma_f32_16x16x32_bf16 v[34:37], v[192:195], v[168:171], v[34:37]
	v_mfma_f32_16x16x32_bf16 v[26:29], v[200:203], v[168:171], v[26:29]
	v_mfma_f32_16x16x32_bf16 v[18:21], v[192:195], v[176:179], v[18:21]
	v_mfma_f32_16x16x32_bf16 v[10:13], v[200:203], v[176:179], v[10:13]
	v_mfma_f32_16x16x32_bf16 v[6:9], v[192:195], v[184:187], v[6:9]
	v_mfma_f32_16x16x32_bf16 v[2:5], v[200:203], v[184:187], v[2:5]
	v_mfma_f32_16x16x32_bf16 v[50:53], v[196:199], v[164:167], v[50:53]
	v_mfma_f32_16x16x32_bf16 v[42:45], v[204:207], v[164:167], v[42:45]
	v_mfma_f32_16x16x32_bf16 v[34:37], v[196:199], v[172:175], v[34:37]
	v_mfma_f32_16x16x32_bf16 v[26:29], v[204:207], v[172:175], v[26:29]
	v_mfma_f32_16x16x32_bf16 v[18:21], v[196:199], v[180:183], v[18:21]
	v_mfma_f32_16x16x32_bf16 v[10:13], v[204:207], v[180:183], v[10:13]
	v_mfma_f32_16x16x32_bf16 v[6:9], v[196:199], v[188:191], v[6:9]
	v_mfma_f32_16x16x32_bf16 v[2:5], v[204:207], v[188:191], v[2:5]
	s_setprio 0
	s_barrier
	ds_read_b128 v[136:139], v150
	ds_read_b128 v[140:143], v150 offset:1024
	ds_read_b128 v[152:155], v150 offset:2048
	ds_read_b128 v[156:159], v150 offset:3072
	s_mov_b32 m0, s28
	s_add_i32 s33, s88, 0x40000
	ds_read_b128 v[160:163], v148 offset:32768
	ds_read_b128 v[164:167], v148 offset:33792
	ds_read_b128 v[168:171], v148 offset:34816
	ds_read_b128 v[172:175], v148 offset:35840
	ds_read_b128 v[176:179], v148 offset:36864
	ds_read_b128 v[180:183], v148 offset:37888
	ds_read_b128 v[184:187], v148 offset:38912
	ds_read_b128 v[188:191], v148 offset:39936
	buffer_load_dwordx4 v1, s[40:43], s33 offen lds
	s_add_i32 s33, s88, 0x60000
	s_mov_b32 m0, s29
	s_nop 0
	buffer_load_dwordx4 v1, s[40:43], s33 offen lds
	s_waitcnt lgkmcnt(8)
	s_barrier
	s_waitcnt lgkmcnt(0)
	s_setprio 1
	s_waitcnt lgkmcnt(7)
	v_mfma_f32_16x16x32_bf16 v[126:129], v[136:139], v[160:163], v[126:129]
	v_mfma_f32_16x16x32_bf16 v[122:125], v[152:155], v[160:163], v[122:125]
	s_waitcnt lgkmcnt(5)
	v_mfma_f32_16x16x32_bf16 v[118:121], v[136:139], v[168:171], v[118:121]
	v_mfma_f32_16x16x32_bf16 v[110:113], v[152:155], v[168:171], v[110:113]
	s_waitcnt lgkmcnt(3)
	v_mfma_f32_16x16x32_bf16 v[102:105], v[136:139], v[176:179], v[102:105]
	v_mfma_f32_16x16x32_bf16 v[94:97], v[152:155], v[176:179], v[94:97]
	s_waitcnt lgkmcnt(1)
	v_mfma_f32_16x16x32_bf16 v[86:89], v[136:139], v[184:187], v[86:89]
	v_mfma_f32_16x16x32_bf16 v[78:81], v[152:155], v[184:187], v[78:81]
	v_mfma_f32_16x16x32_bf16 v[126:129], v[140:143], v[164:167], v[126:129]
	v_mfma_f32_16x16x32_bf16 v[122:125], v[156:159], v[164:167], v[122:125]
	v_mfma_f32_16x16x32_bf16 v[118:121], v[140:143], v[172:175], v[118:121]
	v_mfma_f32_16x16x32_bf16 v[110:113], v[156:159], v[172:175], v[110:113]
	v_mfma_f32_16x16x32_bf16 v[102:105], v[140:143], v[180:183], v[102:105]
	v_mfma_f32_16x16x32_bf16 v[94:97], v[156:159], v[180:183], v[94:97]
	s_waitcnt lgkmcnt(0)
	v_mfma_f32_16x16x32_bf16 v[86:89], v[140:143], v[188:191], v[86:89]
	v_mfma_f32_16x16x32_bf16 v[78:81], v[156:159], v[188:191], v[78:81]
	s_setprio 0
	s_barrier
	s_mov_b32 m0, s31
	s_or_b32 s33, s87, 0x80
	ds_read_b128 v[192:195], v151
	ds_read_b128 v[196:199], v151 offset:1024
	ds_read_b128 v[200:203], v151 offset:2048
	ds_read_b128 v[204:207], v151 offset:3072
	buffer_load_dwordx4 v144, s[8:11], s33 offen lds
	s_add_i32 s33, s87, 0x20080
	s_mov_b32 m0, s34
	s_nop 0
	buffer_load_dwordx4 v144, s[8:11], s33 offen lds
	s_barrier
	s_waitcnt lgkmcnt(0)
	s_setprio 1
	s_waitcnt lgkmcnt(3)
	v_mfma_f32_16x16x32_bf16 v[114:117], v[192:195], v[160:163], v[114:117]
	s_waitcnt lgkmcnt(1)
	v_mfma_f32_16x16x32_bf16 v[106:109], v[200:203], v[160:163], v[106:109]
	v_mfma_f32_16x16x32_bf16 v[98:101], v[192:195], v[168:171], v[98:101]
	v_mfma_f32_16x16x32_bf16 v[90:93], v[200:203], v[168:171], v[90:93]
	v_mfma_f32_16x16x32_bf16 v[82:85], v[192:195], v[176:179], v[82:85]
	v_mfma_f32_16x16x32_bf16 v[74:77], v[200:203], v[176:179], v[74:77]
	v_mfma_f32_16x16x32_bf16 v[70:73], v[192:195], v[184:187], v[70:73]
	v_mfma_f32_16x16x32_bf16 v[66:69], v[200:203], v[184:187], v[66:69]
	v_mfma_f32_16x16x32_bf16 v[114:117], v[196:199], v[164:167], v[114:117]
	s_waitcnt lgkmcnt(0)
	v_mfma_f32_16x16x32_bf16 v[106:109], v[204:207], v[164:167], v[106:109]
	v_mfma_f32_16x16x32_bf16 v[98:101], v[196:199], v[172:175], v[98:101]
	v_mfma_f32_16x16x32_bf16 v[90:93], v[204:207], v[172:175], v[90:93]
	v_mfma_f32_16x16x32_bf16 v[82:85], v[196:199], v[180:183], v[82:85]
	v_mfma_f32_16x16x32_bf16 v[74:77], v[204:207], v[180:183], v[74:77]
	v_mfma_f32_16x16x32_bf16 v[70:73], v[196:199], v[188:191], v[70:73]
	v_mfma_f32_16x16x32_bf16 v[66:69], v[204:207], v[188:191], v[66:69]
	s_setprio 0
	s_mov_b32 m0, s35
	s_barrier
	ds_read_b128 v[160:163], v148 offset:49152
	ds_read_b128 v[164:167], v148 offset:50176
	ds_read_b128 v[168:171], v148 offset:51200
	ds_read_b128 v[172:175], v148 offset:52224
	ds_read_b128 v[176:179], v148 offset:53248
	ds_read_b128 v[180:183], v148 offset:54272
	ds_read_b128 v[184:187], v148 offset:55296
	ds_read_b128 v[188:191], v148 offset:56320
	buffer_load_dwordx4 v1, s[40:43], s89 offen lds
	s_add_i32 s88, s88, 0x20080
	s_mov_b32 m0, s36
	s_nop 0
	buffer_load_dwordx4 v1, s[40:43], s88 offen lds
	s_barrier
	s_waitcnt lgkmcnt(0)
	s_setprio 1
	s_waitcnt lgkmcnt(7)
	v_mfma_f32_16x16x32_bf16 v[62:65], v[136:139], v[160:163], v[62:65]
	v_mfma_f32_16x16x32_bf16 v[58:61], v[152:155], v[160:163], v[58:61]
	s_waitcnt lgkmcnt(5)
	v_mfma_f32_16x16x32_bf16 v[54:57], v[136:139], v[168:171], v[54:57]
	v_mfma_f32_16x16x32_bf16 v[46:49], v[152:155], v[168:171], v[46:49]
	s_waitcnt lgkmcnt(3)
	v_mfma_f32_16x16x32_bf16 v[38:41], v[136:139], v[176:179], v[38:41]
	v_mfma_f32_16x16x32_bf16 v[30:33], v[152:155], v[176:179], v[30:33]
	s_waitcnt lgkmcnt(1)
	v_mfma_f32_16x16x32_bf16 v[22:25], v[136:139], v[184:187], v[22:25]
	v_mfma_f32_16x16x32_bf16 v[14:17], v[152:155], v[184:187], v[14:17]
	v_mfma_f32_16x16x32_bf16 v[62:65], v[140:143], v[164:167], v[62:65]
	v_mfma_f32_16x16x32_bf16 v[58:61], v[156:159], v[164:167], v[58:61]
	v_mfma_f32_16x16x32_bf16 v[54:57], v[140:143], v[172:175], v[54:57]
	v_mfma_f32_16x16x32_bf16 v[46:49], v[156:159], v[172:175], v[46:49]
	v_mfma_f32_16x16x32_bf16 v[38:41], v[140:143], v[180:183], v[38:41]
	v_mfma_f32_16x16x32_bf16 v[30:33], v[156:159], v[180:183], v[30:33]
	s_waitcnt lgkmcnt(0)
	v_mfma_f32_16x16x32_bf16 v[22:25], v[140:143], v[188:191], v[22:25]
	v_mfma_f32_16x16x32_bf16 v[14:17], v[156:159], v[188:191], v[14:17]
	s_setprio 0
	s_barrier
	s_mov_b32 m0, s37
	s_add_i32 s33, s87, 0x40080
	buffer_load_dwordx4 v144, s[8:11], s33 offen lds
	s_add_i32 s87, s87, 0x60080
	s_mov_b32 m0, s38
	s_nop 0
	buffer_load_dwordx4 v144, s[8:11], s87 offen lds
	s_waitcnt vmcnt(6)
	s_barrier
	s_setprio 1
	v_mfma_f32_16x16x32_bf16 v[50:53], v[192:195], v[160:163], v[50:53]
	v_mfma_f32_16x16x32_bf16 v[42:45], v[200:203], v[160:163], v[42:45]
	v_mfma_f32_16x16x32_bf16 v[34:37], v[192:195], v[168:171], v[34:37]
	v_mfma_f32_16x16x32_bf16 v[26:29], v[200:203], v[168:171], v[26:29]
	v_mfma_f32_16x16x32_bf16 v[18:21], v[192:195], v[176:179], v[18:21]
	v_mfma_f32_16x16x32_bf16 v[10:13], v[200:203], v[176:179], v[10:13]
	v_mfma_f32_16x16x32_bf16 v[6:9], v[192:195], v[184:187], v[6:9]
	v_mfma_f32_16x16x32_bf16 v[2:5], v[200:203], v[184:187], v[2:5]
	v_mfma_f32_16x16x32_bf16 v[50:53], v[196:199], v[164:167], v[50:53]
	v_mfma_f32_16x16x32_bf16 v[42:45], v[204:207], v[164:167], v[42:45]
	v_mfma_f32_16x16x32_bf16 v[34:37], v[196:199], v[172:175], v[34:37]
	v_mfma_f32_16x16x32_bf16 v[26:29], v[204:207], v[172:175], v[26:29]
	v_mfma_f32_16x16x32_bf16 v[18:21], v[196:199], v[180:183], v[18:21]
	v_mfma_f32_16x16x32_bf16 v[10:13], v[204:207], v[180:183], v[10:13]
	v_mfma_f32_16x16x32_bf16 v[6:9], v[196:199], v[188:191], v[6:9]
	v_mfma_f32_16x16x32_bf16 v[2:5], v[204:207], v[188:191], v[2:5]
	s_setprio 0
	s_add_i32 s86, s86, 2
	s_addk_i32 s7, 0x100
	s_addk_i32 s79, 0x100
	s_cmp_gt_u32 s86, 13
	s_barrier
	s_cbranch_scc0 .LBB0_295
	v_lshl_add_u32 v142, s78, 8, v145
	v_or_b32_e32 v140, 16, v142
	v_or_b32_e32 v138, 32, v142
	v_or_b32_e32 v136, 48, v142
	s_mov_b64 s[6:7], -1
	s_cmp_gt_i32 s73, 3
	v_ashrrev_i32_e32 v143, 31, v142
	v_ashrrev_i32_e32 v141, 31, v140
	v_ashrrev_i32_e32 v139, 31, v138
	v_ashrrev_i32_e32 v137, 31, v136
	s_cbranch_scc0 .LBB0_298
	v_pk_mul_f32 v[154:155], v[128:129], v[116:117]
	v_pk_mul_f32 v[152:153], v[126:127], v[114:115]
	v_pk_mul_f32 v[156:157], v[124:125], v[108:109]
	v_pk_mul_f32 v[158:159], v[122:123], v[106:107]
	v_cvt_pk_bf16_f32 v152, v152, v153
	v_cvt_pk_bf16_f32 v153, v154, v155
	v_lshlrev_b32_e32 v134, 1, v146
	v_cvt_pk_bf16_f32 v154, v158, v159
	v_cvt_pk_bf16_f32 v155, v156, v157
	v_lshlrev_b64 v[156:157], 12, v[142:143]
	v_lshl_add_u64 v[156:157], s[82:83], 0, v[156:157]
	v_lshl_or_b32 v134, s73, 8, v134
	v_lshl_add_u64 v[156:157], v[156:157], 0, v[134:135]
	global_store_dwordx4 v[156:157], v[152:155], off offset:1024
	v_pk_mul_f32 v[158:159], v[112:113], v[92:93]
	v_pk_mul_f32 v[160:161], v[110:111], v[90:91]
	v_pk_mul_f32 v[154:155], v[120:121], v[100:101]
	v_pk_mul_f32 v[152:153], v[118:119], v[98:99]
	s_mov_b64 s[6:7], 0
	v_cvt_pk_bf16_f32 v152, v152, v153
	v_cvt_pk_bf16_f32 v153, v154, v155
	v_cvt_pk_bf16_f32 v154, v160, v161
	v_cvt_pk_bf16_f32 v155, v158, v159
	v_lshlrev_b64 v[158:159], 12, v[140:141]
	v_lshl_add_u64 v[158:159], s[82:83], 0, v[158:159]
	v_lshl_add_u64 v[158:159], v[158:159], 0, v[134:135]
	global_store_dwordx4 v[158:159], v[152:155], off offset:1024
	v_pk_mul_f32 v[158:159], v[96:97], v[76:77]
	v_pk_mul_f32 v[160:161], v[94:95], v[74:75]
	v_pk_mul_f32 v[154:155], v[104:105], v[84:85]
	v_pk_mul_f32 v[152:153], v[102:103], v[82:83]
	s_nop 0
	v_cvt_pk_bf16_f32 v152, v152, v153
	v_cvt_pk_bf16_f32 v153, v154, v155
	v_cvt_pk_bf16_f32 v154, v160, v161
	v_cvt_pk_bf16_f32 v155, v158, v159
	v_lshlrev_b64 v[158:159], 12, v[138:139]
	v_lshl_add_u64 v[158:159], s[82:83], 0, v[158:159]
	v_lshl_add_u64 v[158:159], v[158:159], 0, v[134:135]
	global_store_dwordx4 v[158:159], v[152:155], off offset:1024
	v_pk_mul_f32 v[158:159], v[80:81], v[68:69]
	v_pk_mul_f32 v[160:161], v[78:79], v[66:67]
	v_pk_mul_f32 v[154:155], v[88:89], v[72:73]
	v_pk_mul_f32 v[152:153], v[86:87], v[70:71]
	s_nop 0
	v_cvt_pk_bf16_f32 v152, v152, v153
	v_cvt_pk_bf16_f32 v153, v154, v155
	v_cvt_pk_bf16_f32 v154, v160, v161
	v_cvt_pk_bf16_f32 v155, v158, v159
	v_lshlrev_b64 v[158:159], 12, v[136:137]
	v_lshl_add_u64 v[158:159], s[82:83], 0, v[158:159]
	v_lshl_add_u64 v[158:159], v[158:159], 0, v[134:135]
	global_store_dwordx4 v[158:159], v[152:155], off offset:1024
	v_pk_mul_f32 v[158:159], v[60:61], v[44:45]
	v_pk_mul_f32 v[160:161], v[58:59], v[42:43]
	v_pk_mul_f32 v[154:155], v[64:65], v[52:53]
	v_pk_mul_f32 v[152:153], v[62:63], v[50:51]
	s_nop 0
	v_cvt_pk_bf16_f32 v152, v152, v153
	v_cvt_pk_bf16_f32 v153, v154, v155
	v_cvt_pk_bf16_f32 v154, v160, v161
	v_cvt_pk_bf16_f32 v155, v158, v159
	v_add_co_u32_e32 v158, vcc, s47, v156
	v_pk_mul_f32 v[160:161], v[46:47], v[26:27]
	s_nop 0
	v_addc_co_u32_e32 v159, vcc, 0, v157, vcc
	global_store_dwordx4 v[158:159], v[152:155], off offset:1024
	v_pk_mul_f32 v[158:159], v[48:49], v[28:29]
	s_nop 0
	v_pk_mul_f32 v[154:155], v[56:57], v[36:37]
	v_pk_mul_f32 v[152:153], v[54:55], v[34:35]
	s_nop 0
	v_cvt_pk_bf16_f32 v152, v152, v153
	v_cvt_pk_bf16_f32 v153, v154, v155
	v_cvt_pk_bf16_f32 v154, v160, v161
	v_cvt_pk_bf16_f32 v155, v158, v159
	v_add_co_u32_e32 v158, vcc, s49, v156
	v_pk_mul_f32 v[160:161], v[30:31], v[10:11]
	s_nop 0
	v_addc_co_u32_e32 v159, vcc, 0, v157, vcc
	global_store_dwordx4 v[158:159], v[152:155], off offset:1024
	v_pk_mul_f32 v[158:159], v[32:33], v[12:13]
	s_nop 0
	v_pk_mul_f32 v[154:155], v[40:41], v[20:21]
	v_pk_mul_f32 v[152:153], v[38:39], v[18:19]
	s_nop 0
	v_cvt_pk_bf16_f32 v152, v152, v153
	v_cvt_pk_bf16_f32 v153, v154, v155
	v_cvt_pk_bf16_f32 v154, v160, v161
	v_cvt_pk_bf16_f32 v155, v158, v159
	v_add_co_u32_e32 v158, vcc, s50, v156
	v_pk_mul_f32 v[160:161], v[14:15], v[2:3]
	s_nop 0
	v_addc_co_u32_e32 v159, vcc, 0, v157, vcc
	v_add_co_u32_e32 v156, vcc, 0xb0000, v156
	global_store_dwordx4 v[158:159], v[152:155], off offset:1024
	s_nop 0
	v_addc_co_u32_e32 v157, vcc, 0, v157, vcc
	v_pk_mul_f32 v[154:155], v[24:25], v[8:9]
	v_pk_mul_f32 v[152:153], v[22:23], v[6:7]
	v_pk_mul_f32 v[158:159], v[16:17], v[4:5]
	v_cvt_pk_bf16_f32 v152, v152, v153
	v_cvt_pk_bf16_f32 v153, v154, v155
	v_cvt_pk_bf16_f32 v154, v160, v161
	s_nop 0
	v_cvt_pk_bf16_f32 v155, v158, v159
	global_store_dwordx4 v[156:157], v[152:155], off offset:1024
.LBB0_298:
	s_andn2_b64 vcc, exec, s[6:7]
	s_cbranch_vccnz .LBB0_289
	v_lshl_or_b32 v152, s73, 8, v146
	v_ashrrev_i32_e32 v153, 31, v152
	v_lshlrev_b64 v[142:143], 12, v[142:143]
	v_lshl_add_u64 v[142:143], s[82:83], 0, v[142:143]
	v_lshlrev_b64 v[152:153], 1, v[152:153]
	v_lshl_add_u64 v[142:143], v[142:143], 0, v[152:153]
	v_cvt_pk_bf16_f32 v126, v126, v127
	v_cvt_pk_bf16_f32 v127, v128, v129
	v_cvt_pk_bf16_f32 v128, v122, v123
	v_cvt_pk_bf16_f32 v129, v124, v125
	global_store_dwordx4 v[142:143], v[126:129], off
	v_cvt_pk_bf16_f32 v114, v114, v115
	v_cvt_pk_bf16_f32 v115, v116, v117
	v_cvt_pk_bf16_f32 v116, v106, v107
	v_lshlrev_b64 v[106:107], 12, v[140:141]
	v_lshl_add_u64 v[106:107], s[82:83], 0, v[106:107]
	v_cvt_pk_bf16_f32 v117, v108, v109
	global_store_dwordx4 v[142:143], v[114:117], off offset:256
	s_nop 1
	v_lshl_add_u64 v[114:115], v[106:107], 0, v[152:153]
	v_cvt_pk_bf16_f32 v106, v118, v119
	v_cvt_pk_bf16_f32 v107, v120, v121
	v_cvt_pk_bf16_f32 v108, v110, v111
	v_cvt_pk_bf16_f32 v109, v112, v113
	global_store_dwordx4 v[114:115], v[106:109], off
	v_cvt_pk_bf16_f32 v98, v98, v99
	v_cvt_pk_bf16_f32 v99, v100, v101
	v_cvt_pk_bf16_f32 v100, v90, v91
	v_lshlrev_b64 v[90:91], 12, v[138:139]
	v_lshl_add_u64 v[90:91], s[82:83], 0, v[90:91]
	v_cvt_pk_bf16_f32 v101, v92, v93
	global_store_dwordx4 v[114:115], v[98:101], off offset:256
	s_nop 1
	v_lshl_add_u64 v[98:99], v[90:91], 0, v[152:153]
	v_cvt_pk_bf16_f32 v90, v102, v103
	v_cvt_pk_bf16_f32 v91, v104, v105
	v_cvt_pk_bf16_f32 v92, v94, v95
	v_cvt_pk_bf16_f32 v93, v96, v97
	global_store_dwordx4 v[98:99], v[90:93], off
	v_cvt_pk_bf16_f32 v82, v82, v83
	v_cvt_pk_bf16_f32 v83, v84, v85
	v_cvt_pk_bf16_f32 v84, v74, v75
	v_lshlrev_b64 v[74:75], 12, v[136:137]
	v_lshl_add_u64 v[74:75], s[82:83], 0, v[74:75]
	v_cvt_pk_bf16_f32 v85, v76, v77
	global_store_dwordx4 v[98:99], v[82:85], off offset:256
	s_nop 1
	v_lshl_add_u64 v[82:83], v[74:75], 0, v[152:153]
	v_cvt_pk_bf16_f32 v74, v86, v87
	v_cvt_pk_bf16_f32 v75, v88, v89
	v_cvt_pk_bf16_f32 v76, v78, v79
	v_cvt_pk_bf16_f32 v77, v80, v81
	global_store_dwordx4 v[82:83], v[74:77], off
	v_cvt_pk_bf16_f32 v70, v70, v71
	v_cvt_pk_bf16_f32 v71, v72, v73
	v_cvt_pk_bf16_f32 v72, v66, v67
	v_cvt_pk_bf16_f32 v73, v68, v69
	global_store_dwordx4 v[82:83], v[70:73], off offset:256
	v_cvt_pk_bf16_f32 v62, v62, v63
	v_cvt_pk_bf16_f32 v63, v64, v65
	v_cvt_pk_bf16_f32 v64, v58, v59
	v_add_co_u32_e32 v58, vcc, s47, v142
	v_lshl_add_u64 v[66:67], v[142:143], 0, s[12:13]
	s_nop 0
	v_addc_co_u32_e32 v59, vcc, 0, v143, vcc
	v_cvt_pk_bf16_f32 v65, v60, v61
	global_store_dwordx4 v[58:59], v[62:65], off
	v_cvt_pk_bf16_f32 v50, v50, v51
	v_cvt_pk_bf16_f32 v51, v52, v53
	v_cvt_pk_bf16_f32 v52, v42, v43
	v_cvt_pk_bf16_f32 v53, v44, v45
	global_store_dwordx4 v[66:67], v[50:53], off offset:256
	v_cvt_pk_bf16_f32 v42, v54, v55
	v_cvt_pk_bf16_f32 v43, v56, v57
	v_cvt_pk_bf16_f32 v44, v46, v47
	v_add_co_u32_e32 v46, vcc, s49, v142
	s_nop 0
	v_lshl_add_u64 v[50:51], v[142:143], 0, s[14:15]
	v_addc_co_u32_e32 v47, vcc, 0, v143, vcc
	v_cvt_pk_bf16_f32 v45, v48, v49
	global_store_dwordx4 v[46:47], v[42:45], off
	v_cvt_pk_bf16_f32 v34, v34, v35
	v_cvt_pk_bf16_f32 v35, v36, v37
	v_cvt_pk_bf16_f32 v36, v26, v27
	v_cvt_pk_bf16_f32 v37, v28, v29
	global_store_dwordx4 v[50:51], v[34:37], off offset:256
	v_cvt_pk_bf16_f32 v26, v38, v39
	v_cvt_pk_bf16_f32 v27, v40, v41
	v_cvt_pk_bf16_f32 v28, v30, v31
	v_add_co_u32_e32 v30, vcc, s50, v142
	s_nop 0
	v_lshl_add_u64 v[34:35], v[142:143], 0, s[16:17]
	v_addc_co_u32_e32 v31, vcc, 0, v143, vcc
	v_cvt_pk_bf16_f32 v29, v32, v33
	global_store_dwordx4 v[30:31], v[26:29], off
	v_cvt_pk_bf16_f32 v18, v18, v19
	v_cvt_pk_bf16_f32 v19, v20, v21
	v_cvt_pk_bf16_f32 v20, v10, v11
	v_cvt_pk_bf16_f32 v21, v12, v13
	global_store_dwordx4 v[34:35], v[18:21], off offset:256
	v_cvt_pk_bf16_f32 v10, v22, v23
	v_cvt_pk_bf16_f32 v11, v24, v25
	v_cvt_pk_bf16_f32 v12, v14, v15
	v_add_co_u32_e32 v14, vcc, s51, v142
	s_nop 0
	v_lshl_add_u64 v[18:19], v[142:143], 0, s[18:19]
	v_addc_co_u32_e32 v15, vcc, 0, v143, vcc
	v_cvt_pk_bf16_f32 v13, v16, v17
	global_store_dwordx4 v[14:15], v[10:13], off
	v_cvt_pk_bf16_f32 v6, v6, v7
	v_cvt_pk_bf16_f32 v7, v8, v9
	v_cvt_pk_bf16_f32 v8, v2, v3
	v_cvt_pk_bf16_f32 v9, v4, v5
	global_store_dwordx4 v[18:19], v[6:9], off offset:256
	s_branch .LBB0_289

.LBB0_439:
	v_mov_b32_e32 v2, v0
	s_waitcnt vmcnt(0)
	s_barrier
	s_cmpk_gt_i32 s2, 0x21f
	v_readfirstlane_b32 s3, v2
	s_cbranch_scc1 .LBB0_456
	v_bfe_i32 v4, v2, 27, 1
	v_lshlrev_b32_e32 v1, 4, v2
	v_lshrrev_b32_e32 v4, 22, v4
	v_add_u32_e32 v4, v1, v4
	v_and_b32_e32 v4, 0xfffffc00, v4
	v_sub_u32_e32 v1, v1, v4
	v_ashrrev_i32_e32 v3, 31, v2
	v_lshrrev_b32_e32 v4, 4, v1
	v_lshrrev_b32_e32 v3, 26, v3
	v_bitop3_b32 v1, v4, v1, 32 bitop3:0x6c
	s_add_u32 s8, s52, 0x1700000
	v_add_u32_e32 v3, v2, v3
	v_ashrrev_i32_e32 v5, 31, v1
	s_addc_u32 s6, s53, 0
	v_ashrrev_i32_e32 v3, 6, v3
	v_lshrrev_b32_e32 v5, 26, v5
	s_ashr_i32 s18, s2, 31
	v_lshlrev_b32_e32 v4, 3, v3
	v_add_u32_e32 v5, v1, v5
	s_lshr_b32 s7, s18, 29
	v_readlane_b32 s10, v255, 11
	v_and_b32_e32 v4, -16, v4
	v_ashrrev_i32_e32 v6, 6, v5
	s_add_i32 s7, s2, s7
	s_ashr_i32 s4, s3, 6
	v_readlane_b32 s11, v255, 12
	v_add_u32_e32 v4, v6, v4
	v_and_b32_e32 v6, 3, v6
	s_mov_b32 s5, 0x1fffe0
	s_ashr_i32 s12, s7, 3
	s_and_b32 s7, s7, -8
	s_and_b32 s49, s11, 0xffff
	v_and_or_b32 v6, v4, s5, v6
	s_ashr_i32 s5, s3, 8
	s_and_b32 s9, s6, 0xffff
	s_lshl_b32 s6, s4, 10
	s_sub_i32 s7, s2, s7
	s_cmp_lt_i32 s7, 0
	s_movk_i32 s19, 0x45
	s_cselect_b32 s13, s19, 0x44
	s_mul_i32 s7, s13, s7
	s_add_i32 s7, s7, s12
	s_ashr_i32 s12, s7, 31
	s_lshr_b32 s12, s12, 27
	s_add_i32 s12, s7, s12
	s_ashr_i32 s13, s12, 5
	s_andn2_b32 s12, s12, 31
	s_sub_i32 s7, s7, s12
	s_bfe_i32 s12, s7, 0x80000
	s_bfe_u32 s12, s12, 0x3000c
	s_add_i32 s12, s7, s12
	s_bfe_i32 s14, s12, 0x80000
	s_and_b32 s12, s12, 0xf8
	s_sub_i32 s7, s7, s12
	s_lshl_b32 s13, s13, 3
	s_sext_i32_i8 s7, s7
	s_add_i32 s78, s13, s7
	v_and_b32_e32 v5, 0xc0, v5
	s_ashr_i32 s7, s78, 31
	v_sub_u32_e32 v1, v1, v5
	v_mov_b32_e32 v5, 1
	s_lshr_b32 s7, s7, 12
	v_lshlrev_b32_e32 v3, 5, v3
	v_ashrrev_i16_sdwa v1, v5, sext(v1) dst_sel:DWORD dst_unused:UNUSED_PAD src0_sel:DWORD src1_sel:BYTE_0
	v_lshlrev_b32_e32 v5, 1, v4
	v_lshrrev_b32_e32 v7, 2, v4
	s_sext_i32_i16 s14, s14
	s_add_i32 s7, s78, s7
	v_and_b32_e32 v3, 32, v3
	v_bfe_i32 v1, v1, 0, 16
	v_and_b32_e32 v5, 24, v5
	v_and_b32_e32 v7, 4, v7
	s_ashr_i32 s79, s14, 3
	s_lshl_b32 s7, s7, 1
	s_add_i32 s20, s6, 0
	s_mov_b32 s51, 0x20000
	s_brev_b32 s50, -2
	v_or3_b32 v5, v6, v7, v5
	v_add_lshl_u32 v3, v3, v1, 1
	s_and_b32 s7, s7, 0xffe00000
	s_lshl_b32 s12, s79, 19
	s_add_i32 s21, s20, 0x10000
	v_lshl_add_u32 v194, v5, 11, v3
	s_mov_b32 s10, s50
	s_mov_b32 s11, s51
	s_add_i32 s16, s7, s12
	s_mov_b32 m0, s21
	s_add_i32 s22, s20, 0x12000
	buffer_load_dwordx4 v194, s[8:11], s16 offen lds
	s_or_b32 s6, s16, 0x20000
	s_mov_b32 m0, s22
	v_lshl_add_u32 v1, v4, 11, v3
	buffer_load_dwordx4 v194, s[8:11], s6 offen lds
	s_lshl_b32 s17, s78, 19
	s_mov_b32 m0, s20
	s_add_i32 s23, s20, 0x2000
	buffer_load_dwordx4 v1, s[48:51], s17 offen lds
	s_or_b32 s6, s17, 0x20000
	s_mov_b32 m0, s23
	s_add_i32 s24, s20, 0x14000
	buffer_load_dwordx4 v1, s[48:51], s6 offen lds
	s_or_b32 s6, s16, 0x40000
	s_mov_b32 m0, s24
	s_add_i32 s25, s20, 0x16000
	buffer_load_dwordx4 v194, s[8:11], s6 offen lds
	s_or_b32 s6, s16, 0x60000
	s_mov_b32 m0, s25
	s_add_i32 s26, s20, 0x4000
	buffer_load_dwordx4 v194, s[8:11], s6 offen lds
	s_or_b32 s6, s17, 0x40000
	s_mov_b32 m0, s26
	s_add_i32 s27, s20, 0x6000
	buffer_load_dwordx4 v1, s[48:51], s6 offen lds
	s_or_b32 s6, s17, 0x60000
	s_mov_b32 m0, s27
	s_mov_b32 s28, 0
	buffer_load_dwordx4 v1, s[48:51], s6 offen lds
	s_cmp_lg_u32 s5, 1
	s_mov_b32 s29, 0x10000
	s_cbranch_scc1 .LBB0_442
	s_barrier

.LBB0_444:
	v_lshl_add_u32 v118, s78, 8, v195
	v_add_u32_e32 v119, 0xffff8000, v118
	v_cndmask_b32_e64 v150, v118, v119, s[6:7]
	v_ashrrev_i32_e32 v119, 31, v118
	v_lshl_or_b32 v146, s79, 8, v196
	v_lshlrev_b64 v[118:119], 11, v[118:119]
	v_ashrrev_i32_e32 v147, 31, v146
	v_lshl_add_u64 v[152:153], s[66:67], 0, v[118:119]
	v_ashrrev_i32_e32 v151, 31, v150
	s_lshl_b64 s[16:17], s[16:17], 2
	v_lshlrev_b64 v[148:149], 2, v[146:147]
	v_lshl_add_u64 v[190:191], v[146:147], 1, v[152:153]
	v_lshlrev_b64 v[146:147], 12, v[150:151]
	s_add_u32 s16, s30, s16
	s_waitcnt lgkmcnt(0)
	v_lshl_add_u64 v[146:147], s[10:11], 0, v[146:147]
	s_addc_u32 s17, s31, s17
	v_lshl_add_u64 v[192:193], v[146:147], 0, v[148:149]
	v_lshl_add_u64 v[126:127], s[16:17], 0, v[148:149]
	v_add_co_u32_e32 v148, vcc, s29, v192
	global_load_dwordx4 v[130:133], v[126:127], off offset:16
	global_load_dwordx4 v[138:141], v[126:127], off
	global_load_dwordx4 v[118:121], v[126:127], off offset:528
	s_nop 0
	global_load_dwordx4 v[126:129], v[126:127], off offset:512
	s_nop 0
	global_load_dwordx4 v[202:205], v[192:193], off offset:16
	global_load_dwordx4 v[206:209], v[192:193], off
	global_load_dwordx4 v[210:213], v[192:193], off offset:528
	global_load_dwordx4 v[214:217], v[192:193], off offset:512
	s_mov_b64 s[6:7], 0x10000
	v_addc_co_u32_e32 v149, vcc, 0, v193, vcc
	v_lshl_add_u64 v[146:147], v[192:193], 0, s[6:7]
	global_load_dwordx4 v[218:221], v[148:149], off
	global_load_dwordx4 v[222:225], v[146:147], off offset:16
	s_mov_b64 s[6:7], 0x10200
	v_lshl_add_u64 v[146:147], v[192:193], 0, s[6:7]
	global_load_dwordx4 v[182:185], v[148:149], off offset:512
	global_load_dwordx4 v[178:181], v[146:147], off offset:16
	s_mov_b64 s[6:7], 0x20000
	v_add_co_u32_e32 v148, vcc, s51, v192
	v_lshl_add_u64 v[146:147], v[192:193], 0, s[6:7]
	s_nop 0
	v_addc_co_u32_e32 v149, vcc, 0, v193, vcc
	s_mov_b64 s[6:7], 0x20200
	global_load_dwordx4 v[174:177], v[148:149], off
	global_load_dwordx4 v[170:173], v[146:147], off offset:16
	v_lshl_add_u64 v[146:147], v[192:193], 0, s[6:7]
	s_mov_b64 s[6:7], 0x30000
	global_load_dwordx4 v[166:169], v[148:149], off offset:512
	global_load_dwordx4 v[162:165], v[146:147], off offset:16
	v_lshl_add_u64 v[146:147], v[192:193], 0, s[6:7]
	s_mov_b32 s6, 0x30000
	v_add_co_u32_e32 v148, vcc, s6, v192
	s_mov_b64 s[6:7], 0x30200
	s_nop 0
	v_addc_co_u32_e32 v149, vcc, 0, v193, vcc
	global_load_dwordx4 v[158:161], v[148:149], off
	global_load_dwordx4 v[154:157], v[146:147], off offset:16
	v_lshl_add_u64 v[146:147], v[192:193], 0, s[6:7]
	global_load_dwordx4 v[150:153], v[148:149], off offset:512
	s_nop 0
	global_load_dwordx4 v[146:149], v[146:147], off offset:16
	s_mov_b32 s6, 0x8000
	s_mov_b32 s79, s58
	s_mov_b32 s78, s59
	s_mov_b32 s16, s72
	s_mov_b32 s17, s73
	s_waitcnt vmcnt(15)
	v_pk_fma_f32 v[204:205], v[136:137], v[132:133], v[204:205]
	s_waitcnt vmcnt(14)
	v_pk_fma_f32 v[144:145], v[144:145], v[140:141], v[208:209]
	v_pk_fma_f32 v[142:143], v[142:143], v[138:139], v[206:207]
	v_pk_fma_f32 v[136:137], v[134:135], v[130:131], v[202:203]
	v_cvt_pk_bf16_f32 v134, v142, v143
	v_cvt_pk_bf16_f32 v135, v144, v145
	s_waitcnt vmcnt(12)
	v_pk_fma_f32 v[112:113], v[112:113], v[128:129], v[216:217]
	v_cvt_pk_bf16_f32 v136, v136, v137
	v_cvt_pk_bf16_f32 v137, v204, v205
	global_store_dwordx4 v[190:191], v[134:137], off
	v_pk_fma_f32 v[110:111], v[110:111], v[126:127], v[214:215]
	s_waitcnt vmcnt(10)
	v_pk_fma_f32 v[104:105], v[104:105], v[128:129], v[184:185]
	v_pk_fma_f32 v[134:135], v[108:109], v[120:121], v[212:213]
	v_pk_fma_f32 v[108:109], v[106:107], v[118:119], v[210:211]
	v_cvt_pk_bf16_f32 v106, v110, v111
	v_cvt_pk_bf16_f32 v107, v112, v113
	v_pk_fma_f32 v[110:111], v[116:117], v[132:133], v[224:225]
	v_cvt_pk_bf16_f32 v108, v108, v109
	v_cvt_pk_bf16_f32 v109, v134, v135
	global_store_dwordx4 v[190:191], v[106:109], off offset:256
	v_pk_fma_f32 v[112:113], v[114:115], v[130:131], v[222:223]
	v_pk_fma_f32 v[102:103], v[102:103], v[126:127], v[182:183]
	v_pk_fma_f32 v[108:109], v[124:125], v[140:141], v[220:221]
	v_pk_fma_f32 v[106:107], v[122:123], v[138:139], v[218:219]
	s_waitcnt vmcnt(9)
	v_pk_fma_f32 v[94:95], v[94:95], v[138:139], v[174:175]
	v_cvt_pk_bf16_f32 v106, v106, v107
	v_cvt_pk_bf16_f32 v107, v108, v109
	v_cvt_pk_bf16_f32 v108, v112, v113
	v_cvt_pk_bf16_f32 v109, v110, v111
	v_add_co_u32_e32 v110, vcc, s6, v190
	v_pk_fma_f32 v[96:97], v[96:97], v[140:141], v[176:177]
	s_nop 0
	v_addc_co_u32_e32 v111, vcc, 0, v191, vcc
	global_store_dwordx4 v[110:111], v[106:109], off
	s_waitcnt vmcnt(8)
	v_pk_fma_f32 v[88:89], v[88:89], v[128:129], v[168:169]
	v_pk_fma_f32 v[86:87], v[86:87], v[126:127], v[166:167]
	v_pk_fma_f32 v[106:107], v[100:101], v[120:121], v[180:181]
	v_pk_fma_f32 v[100:101], v[98:99], v[118:119], v[178:179]
	v_cvt_pk_bf16_f32 v98, v102, v103
	v_cvt_pk_bf16_f32 v99, v104, v105
	s_mov_b32 s6, 0x18000
	v_cvt_pk_bf16_f32 v100, v100, v101
	v_cvt_pk_bf16_f32 v101, v106, v107
	global_store_dwordx4 v[110:111], v[98:101], off offset:256
	s_waitcnt vmcnt(5)
	v_pk_fma_f32 v[70:71], v[70:71], v[126:127], v[150:151]
	v_pk_fma_f32 v[72:73], v[72:73], v[128:129], v[152:153]
	v_pk_fma_f32 v[98:99], v[92:93], v[132:133], v[172:173]
	v_pk_fma_f32 v[92:93], v[90:91], v[130:131], v[170:171]
	v_cvt_pk_bf16_f32 v90, v94, v95
	v_add_co_u32_e32 v94, vcc, s29, v190
	v_cvt_pk_bf16_f32 v91, v96, v97
	v_cvt_pk_bf16_f32 v92, v92, v93
	v_cvt_pk_bf16_f32 v93, v98, v99
	v_lshl_add_u64 v[122:123], v[192:193], 0, s[12:13]
	s_nop 0
	v_addc_co_u32_e32 v95, vcc, 0, v191, vcc
	global_store_dwordx4 v[94:95], v[90:93], off
	v_lshl_add_u64 v[142:143], v[192:193], 0, s[14:15]
	s_nop 0
	v_pk_fma_f32 v[90:91], v[80:81], v[120:121], v[164:165]
	v_pk_fma_f32 v[80:81], v[78:79], v[118:119], v[162:163]
	v_cvt_pk_bf16_f32 v78, v86, v87
	v_cvt_pk_bf16_f32 v79, v88, v89
	s_nop 0
	v_cvt_pk_bf16_f32 v80, v80, v81
	v_cvt_pk_bf16_f32 v81, v90, v91
	global_store_dwordx4 v[94:95], v[78:81], off offset:256
	s_nop 1
	v_pk_fma_f32 v[78:79], v[84:85], v[140:141], v[160:161]
	v_pk_fma_f32 v[80:81], v[82:83], v[138:139], v[158:159]
	v_pk_fma_f32 v[82:83], v[76:77], v[132:133], v[156:157]
	v_pk_fma_f32 v[76:77], v[74:75], v[130:131], v[154:155]
	v_cvt_pk_bf16_f32 v74, v80, v81
	v_cvt_pk_bf16_f32 v75, v78, v79
	v_add_co_u32_e32 v78, vcc, s6, v190
	s_mov_b64 s[6:7], 0x80000
	s_nop 0
	v_addc_co_u32_e32 v79, vcc, 0, v191, vcc
	v_cvt_pk_bf16_f32 v76, v76, v77
	v_cvt_pk_bf16_f32 v77, v82, v83
	global_store_dwordx4 v[78:79], v[74:77], off
	s_waitcnt vmcnt(7)
	s_nop 0
	v_pk_fma_f32 v[74:75], v[68:69], v[120:121], v[148:149]
	v_pk_fma_f32 v[68:69], v[66:67], v[118:119], v[146:147]
	v_cvt_pk_bf16_f32 v66, v70, v71
	v_lshl_add_u64 v[70:71], v[192:193], 0, s[6:7]
	s_mov_b32 s6, 0x80000
	v_cvt_pk_bf16_f32 v67, v72, v73
	v_cvt_pk_bf16_f32 v68, v68, v69
	v_cvt_pk_bf16_f32 v69, v74, v75
	global_store_dwordx4 v[78:79], v[66:69], off offset:256
	v_add_co_u32_e32 v74, vcc, s6, v192
	s_mov_b64 s[6:7], 0x80200
	s_nop 0
	v_addc_co_u32_e32 v75, vcc, 0, v193, vcc
	global_load_dwordx4 v[66:69], v[74:75], off
	s_nop 0
	global_load_dwordx4 v[70:73], v[70:71], off offset:16
	v_lshl_add_u64 v[78:79], v[192:193], 0, s[6:7]
	s_mov_b64 s[6:7], 0x90000
	v_lshl_add_u64 v[86:87], v[192:193], 0, s[6:7]
	s_mov_b32 s6, 0x90000
	global_load_dwordx4 v[74:77], v[74:75], off offset:512
	s_nop 0
	global_load_dwordx4 v[78:81], v[78:79], off offset:16
	v_add_co_u32_e32 v90, vcc, s6, v192
	s_mov_b64 s[6:7], 0x90200
	s_nop 0
	v_addc_co_u32_e32 v91, vcc, 0, v193, vcc
	global_load_dwordx4 v[82:85], v[90:91], off
	s_nop 0
	global_load_dwordx4 v[86:89], v[86:87], off offset:16
	v_lshl_add_u64 v[94:95], v[192:193], 0, s[6:7]
	s_mov_b64 s[6:7], 0xa0000
	v_lshl_add_u64 v[102:103], v[192:193], 0, s[6:7]
	s_mov_b32 s6, 0xa0000
	global_load_dwordx4 v[90:93], v[90:91], off offset:512
	s_nop 0
	global_load_dwordx4 v[94:97], v[94:95], off offset:16
	v_add_co_u32_e32 v106, vcc, s6, v192
	s_mov_b64 s[6:7], 0xa0200
	s_nop 0
	v_addc_co_u32_e32 v107, vcc, 0, v193, vcc
	global_load_dwordx4 v[98:101], v[106:107], off
	s_nop 0
	global_load_dwordx4 v[102:105], v[102:103], off offset:16
	v_lshl_add_u64 v[110:111], v[192:193], 0, s[6:7]
	global_load_dwordx4 v[106:109], v[106:107], off offset:512
	s_nop 0
	global_load_dwordx4 v[110:113], v[110:111], off offset:16
	v_add_co_u32_e32 v134, vcc, s45, v192
	s_mov_b32 s6, 0x40000
	s_nop 0
	v_addc_co_u32_e32 v135, vcc, 0, v193, vcc
	global_load_dwordx4 v[114:117], v[134:135], off
	s_nop 0
	global_load_dwordx4 v[122:125], v[122:123], off offset:16
	s_nop 0
	global_load_dwordx4 v[134:137], v[134:135], off offset:512
	s_nop 0
	global_load_dwordx4 v[142:145], v[142:143], off offset:16
	s_waitcnt vmcnt(15)
	v_pk_fma_f32 v[62:63], v[62:63], v[138:139], v[66:67]
	s_waitcnt vmcnt(14)
	v_pk_fma_f32 v[66:67], v[60:61], v[132:133], v[72:73]
	v_pk_fma_f32 v[60:61], v[58:59], v[130:131], v[70:71]
	v_cvt_pk_bf16_f32 v58, v62, v63
	v_add_co_u32_e32 v62, vcc, s6, v190
	v_pk_fma_f32 v[64:65], v[64:65], v[140:141], v[68:69]
	s_nop 0
	v_addc_co_u32_e32 v63, vcc, 0, v191, vcc
	v_cvt_pk_bf16_f32 v59, v64, v65
	v_cvt_pk_bf16_f32 v60, v60, v61
	v_cvt_pk_bf16_f32 v61, v66, v67
	global_store_dwordx4 v[62:63], v[58:61], off
	s_waitcnt vmcnt(14)
	v_pk_fma_f32 v[56:57], v[56:57], v[128:129], v[76:77]
	v_pk_fma_f32 v[54:55], v[54:55], v[126:127], v[74:75]
	s_waitcnt vmcnt(13)
	v_pk_fma_f32 v[58:59], v[48:49], v[120:121], v[80:81]
	v_pk_fma_f32 v[48:49], v[46:47], v[118:119], v[78:79]
	v_cvt_pk_bf16_f32 v46, v54, v55
	v_cvt_pk_bf16_f32 v47, v56, v57
	s_waitcnt vmcnt(10)
	v_pk_fma_f32 v[40:41], v[40:41], v[128:129], v[92:93]
	v_cvt_pk_bf16_f32 v48, v48, v49
	v_cvt_pk_bf16_f32 v49, v58, v59
	global_store_dwordx4 v[62:63], v[46:49], off offset:256
	v_pk_fma_f32 v[38:39], v[38:39], v[126:127], v[90:91]
	s_waitcnt vmcnt(7)
	v_pk_fma_f32 v[24:25], v[24:25], v[128:129], v[108:109]
	v_pk_fma_f32 v[46:47], v[52:53], v[140:141], v[84:85]
	v_pk_fma_f32 v[48:49], v[50:51], v[138:139], v[82:83]
	v_pk_fma_f32 v[50:51], v[44:45], v[132:133], v[88:89]
	v_pk_fma_f32 v[44:45], v[42:43], v[130:131], v[86:87]
	v_cvt_pk_bf16_f32 v42, v48, v49
	v_cvt_pk_bf16_f32 v43, v46, v47
	v_add_co_u32_e32 v46, vcc, s46, v190
	v_cvt_pk_bf16_f32 v44, v44, v45
	v_cvt_pk_bf16_f32 v45, v50, v51
	v_pk_fma_f32 v[22:23], v[22:23], v[126:127], v[106:107]
	s_nop 0
	v_addc_co_u32_e32 v47, vcc, 0, v191, vcc
	global_store_dwordx4 v[46:47], v[42:45], off
	s_waitcnt vmcnt(4)
	v_pk_fma_f32 v[8:9], v[8:9], v[128:129], v[136:137]
	v_pk_fma_f32 v[6:7], v[6:7], v[126:127], v[134:135]
	v_pk_fma_f32 v[42:43], v[32:33], v[120:121], v[96:97]
	v_pk_fma_f32 v[32:33], v[30:31], v[118:119], v[94:95]
	v_cvt_pk_bf16_f32 v30, v38, v39
	v_cvt_pk_bf16_f32 v31, v40, v41
	s_nop 0
	v_cvt_pk_bf16_f32 v32, v32, v33
	v_cvt_pk_bf16_f32 v33, v42, v43
	global_store_dwordx4 v[46:47], v[30:33], off offset:256
	s_nop 1
	v_pk_fma_f32 v[30:31], v[36:37], v[140:141], v[100:101]
	v_pk_fma_f32 v[32:33], v[34:35], v[138:139], v[98:99]
	v_pk_fma_f32 v[34:35], v[28:29], v[132:133], v[104:105]
	v_pk_fma_f32 v[28:29], v[26:27], v[130:131], v[102:103]
	v_cvt_pk_bf16_f32 v26, v32, v33
	v_cvt_pk_bf16_f32 v27, v30, v31
	v_add_co_u32_e32 v30, vcc, s47, v190
	v_cvt_pk_bf16_f32 v28, v28, v29
	v_cvt_pk_bf16_f32 v29, v34, v35
	s_nop 1
	v_addc_co_u32_e32 v31, vcc, 0, v191, vcc
	global_store_dwordx4 v[30:31], v[26:29], off
	s_nop 1
	v_pk_fma_f32 v[26:27], v[16:17], v[120:121], v[112:113]
	v_pk_fma_f32 v[16:17], v[14:15], v[118:119], v[110:111]
	v_cvt_pk_bf16_f32 v14, v22, v23
	v_cvt_pk_bf16_f32 v15, v24, v25
	s_nop 0
	v_cvt_pk_bf16_f32 v16, v16, v17
	v_cvt_pk_bf16_f32 v17, v26, v27
	global_store_dwordx4 v[30:31], v[14:17], off offset:256
	s_nop 1
	v_pk_fma_f32 v[14:15], v[20:21], v[140:141], v[116:117]
	v_pk_fma_f32 v[16:17], v[18:19], v[138:139], v[114:115]
	v_pk_fma_f32 v[18:19], v[12:13], v[132:133], v[124:125]
	v_pk_fma_f32 v[12:13], v[10:11], v[130:131], v[122:123]
	v_cvt_pk_bf16_f32 v10, v16, v17
	v_cvt_pk_bf16_f32 v11, v14, v15
	v_add_co_u32_e32 v14, vcc, s57, v190
	v_cvt_pk_bf16_f32 v12, v12, v13
	v_cvt_pk_bf16_f32 v13, v18, v19
	s_nop 1
	v_addc_co_u32_e32 v15, vcc, 0, v191, vcc
	global_store_dwordx4 v[14:15], v[10:13], off
	s_and_b64 vcc, exec, s[4:5]
	s_waitcnt vmcnt(7)
	v_pk_fma_f32 v[10:11], v[4:5], v[120:121], v[144:145]
	v_pk_fma_f32 v[4:5], v[2:3], v[118:119], v[142:143]
	v_cvt_pk_bf16_f32 v2, v6, v7
	v_cvt_pk_bf16_f32 v3, v8, v9
	s_nop 0
	v_cvt_pk_bf16_f32 v4, v4, v5
	v_cvt_pk_bf16_f32 v5, v10, v11
	global_store_dwordx4 v[14:15], v[2:5], off offset:256
	s_cbranch_vccnz .LBB0_453

.LBB0_450:
	ds_read_b128 v[118:121], v197
	ds_read_b128 v[126:129], v197 offset:1024
	ds_read_b128 v[130:133], v197 offset:2048
	ds_read_b128 v[138:141], v197 offset:3072
	s_add_i32 s10, s7, 0xfffa0080
	s_cmp_eq_u32 s17, 12
	s_cselect_b32 s87, s6, s10
	s_cselect_b32 s86, s72, s16
	s_or_b32 s88, s87, 0x80
	s_add_i32 s10, s7, 0xfffe0000
	s_mov_b32 m0, s41
	ds_read_b128 v[146:149], v198
	ds_read_b128 v[150:153], v198 offset:1024
	ds_read_b128 v[154:157], v198 offset:2048
	ds_read_b128 v[158:161], v198 offset:3072
	ds_read_b128 v[162:165], v198 offset:4096
	ds_read_b128 v[166:169], v198 offset:5120
	ds_read_b128 v[170:173], v198 offset:6144
	ds_read_b128 v[174:177], v198 offset:7168
	buffer_load_dwordx4 v1, s[48:51], s10 offen lds
	s_mov_b32 m0, s42
	s_nop 0
	buffer_load_dwordx4 v1, s[48:51], s7 offen lds
	s_waitcnt lgkmcnt(8)
	s_barrier
	s_waitcnt lgkmcnt(0)
	s_setprio 1
	s_waitcnt lgkmcnt(7)
	v_mfma_f32_16x16x32_bf16 v[142:145], v[118:121], v[146:149], v[142:145]
	v_mfma_f32_16x16x32_bf16 v[134:137], v[130:133], v[146:149], v[134:137]
	s_waitcnt lgkmcnt(5)
	v_mfma_f32_16x16x32_bf16 v[122:125], v[118:121], v[154:157], v[122:125]
	v_mfma_f32_16x16x32_bf16 v[114:117], v[130:133], v[154:157], v[114:117]
	s_waitcnt lgkmcnt(3)
	v_mfma_f32_16x16x32_bf16 v[94:97], v[118:121], v[162:165], v[94:97]
	v_mfma_f32_16x16x32_bf16 v[90:93], v[130:133], v[162:165], v[90:93]
	s_waitcnt lgkmcnt(1)
	v_mfma_f32_16x16x32_bf16 v[82:85], v[118:121], v[170:173], v[82:85]
	v_mfma_f32_16x16x32_bf16 v[74:77], v[130:133], v[170:173], v[74:77]
	v_mfma_f32_16x16x32_bf16 v[142:145], v[126:129], v[150:153], v[142:145]
	v_mfma_f32_16x16x32_bf16 v[134:137], v[138:141], v[150:153], v[134:137]
	v_mfma_f32_16x16x32_bf16 v[122:125], v[126:129], v[158:161], v[122:125]
	v_mfma_f32_16x16x32_bf16 v[114:117], v[138:141], v[158:161], v[114:117]
	v_mfma_f32_16x16x32_bf16 v[94:97], v[126:129], v[166:169], v[94:97]
	v_mfma_f32_16x16x32_bf16 v[90:93], v[138:141], v[166:169], v[90:93]
	s_waitcnt lgkmcnt(0)
	v_mfma_f32_16x16x32_bf16 v[82:85], v[126:129], v[174:177], v[82:85]
	v_mfma_f32_16x16x32_bf16 v[74:77], v[138:141], v[174:177], v[74:77]
	s_setprio 0
	s_barrier
	s_mov_b32 m0, s21
	s_mov_b32 s10, s50
	s_mov_b32 s11, s51
	ds_read_b128 v[178:181], v199
	ds_read_b128 v[182:185], v199 offset:1024
	ds_read_b128 v[190:193], v199 offset:2048
	ds_read_b128 v[202:205], v199 offset:3072
	buffer_load_dwordx4 v194, s[8:11], s86 offen lds
	s_add_i32 s33, s86, 0x20000
	s_mov_b32 m0, s22
	s_nop 0
	buffer_load_dwordx4 v194, s[8:11], s33 offen lds
	s_barrier
	s_waitcnt lgkmcnt(0)
	s_setprio 1
	s_waitcnt lgkmcnt(3)
	v_mfma_f32_16x16x32_bf16 v[110:113], v[178:181], v[146:149], v[110:113]
	s_waitcnt lgkmcnt(1)
	v_mfma_f32_16x16x32_bf16 v[106:109], v[190:193], v[146:149], v[106:109]
	v_mfma_f32_16x16x32_bf16 v[102:105], v[178:181], v[154:157], v[102:105]
	v_mfma_f32_16x16x32_bf16 v[98:101], v[190:193], v[154:157], v[98:101]
	v_mfma_f32_16x16x32_bf16 v[86:89], v[178:181], v[162:165], v[86:89]
	v_mfma_f32_16x16x32_bf16 v[78:81], v[190:193], v[162:165], v[78:81]
	v_mfma_f32_16x16x32_bf16 v[70:73], v[178:181], v[170:173], v[70:73]
	v_mfma_f32_16x16x32_bf16 v[66:69], v[190:193], v[170:173], v[66:69]
	v_mfma_f32_16x16x32_bf16 v[110:113], v[182:185], v[150:153], v[110:113]
	s_waitcnt lgkmcnt(0)
	v_mfma_f32_16x16x32_bf16 v[106:109], v[202:205], v[150:153], v[106:109]
	v_mfma_f32_16x16x32_bf16 v[102:105], v[182:185], v[158:161], v[102:105]
	v_mfma_f32_16x16x32_bf16 v[98:101], v[202:205], v[158:161], v[98:101]
	v_mfma_f32_16x16x32_bf16 v[86:89], v[182:185], v[166:169], v[86:89]
	v_mfma_f32_16x16x32_bf16 v[78:81], v[202:205], v[166:169], v[78:81]
	v_mfma_f32_16x16x32_bf16 v[70:73], v[182:185], v[174:177], v[70:73]
	v_mfma_f32_16x16x32_bf16 v[66:69], v[202:205], v[174:177], v[66:69]
	s_setprio 0
	s_mov_b32 m0, s20
	s_barrier
	ds_read_b128 v[146:149], v198 offset:16384
	ds_read_b128 v[150:153], v198 offset:17408
	ds_read_b128 v[154:157], v198 offset:18432
	ds_read_b128 v[158:161], v198 offset:19456
	ds_read_b128 v[162:165], v198 offset:20480
	ds_read_b128 v[166:169], v198 offset:21504
	ds_read_b128 v[170:173], v198 offset:22528
	ds_read_b128 v[174:177], v198 offset:23552
	buffer_load_dwordx4 v1, s[48:51], s87 offen lds
	s_add_i32 s33, s87, 0x20000
	s_mov_b32 m0, s23
	s_nop 0
	buffer_load_dwordx4 v1, s[48:51], s33 offen lds
	s_barrier
	s_waitcnt lgkmcnt(0)
	s_setprio 1
	s_waitcnt lgkmcnt(7)
	v_mfma_f32_16x16x32_bf16 v[62:65], v[118:121], v[146:149], v[62:65]
	v_mfma_f32_16x16x32_bf16 v[58:61], v[130:133], v[146:149], v[58:61]
	s_waitcnt lgkmcnt(5)
	v_mfma_f32_16x16x32_bf16 v[50:53], v[118:121], v[154:157], v[50:53]
	v_mfma_f32_16x16x32_bf16 v[42:45], v[130:133], v[154:157], v[42:45]
	s_waitcnt lgkmcnt(3)
	v_mfma_f32_16x16x32_bf16 v[34:37], v[118:121], v[162:165], v[34:37]
	v_mfma_f32_16x16x32_bf16 v[26:29], v[130:133], v[162:165], v[26:29]
	s_waitcnt lgkmcnt(1)
	v_mfma_f32_16x16x32_bf16 v[18:21], v[118:121], v[170:173], v[18:21]
	v_mfma_f32_16x16x32_bf16 v[10:13], v[130:133], v[170:173], v[10:13]
	v_mfma_f32_16x16x32_bf16 v[62:65], v[126:129], v[150:153], v[62:65]
	v_mfma_f32_16x16x32_bf16 v[58:61], v[138:141], v[150:153], v[58:61]
	v_mfma_f32_16x16x32_bf16 v[50:53], v[126:129], v[158:161], v[50:53]
	v_mfma_f32_16x16x32_bf16 v[42:45], v[138:141], v[158:161], v[42:45]
	v_mfma_f32_16x16x32_bf16 v[34:37], v[126:129], v[166:169], v[34:37]
	v_mfma_f32_16x16x32_bf16 v[26:29], v[138:141], v[166:169], v[26:29]
	s_waitcnt lgkmcnt(0)
	v_mfma_f32_16x16x32_bf16 v[18:21], v[126:129], v[174:177], v[18:21]
	v_mfma_f32_16x16x32_bf16 v[10:13], v[138:141], v[174:177], v[10:13]
	s_setprio 0
	s_barrier
	s_mov_b32 m0, s24
	s_add_i32 s33, s86, 0x40000
	buffer_load_dwordx4 v194, s[8:11], s33 offen lds
	s_add_i32 s33, s86, 0x60000
	s_mov_b32 m0, s25
	s_nop 0
	buffer_load_dwordx4 v194, s[8:11], s33 offen lds
	s_waitcnt vmcnt(6)
	s_barrier
	s_setprio 1
	v_mfma_f32_16x16x32_bf16 v[54:57], v[178:181], v[146:149], v[54:57]
	v_mfma_f32_16x16x32_bf16 v[46:49], v[190:193], v[146:149], v[46:49]
	v_mfma_f32_16x16x32_bf16 v[38:41], v[178:181], v[154:157], v[38:41]
	v_mfma_f32_16x16x32_bf16 v[30:33], v[190:193], v[154:157], v[30:33]
	v_mfma_f32_16x16x32_bf16 v[22:25], v[178:181], v[162:165], v[22:25]
	v_mfma_f32_16x16x32_bf16 v[14:17], v[190:193], v[162:165], v[14:17]
	v_mfma_f32_16x16x32_bf16 v[6:9], v[178:181], v[170:173], v[6:9]
	v_mfma_f32_16x16x32_bf16 v[2:5], v[190:193], v[170:173], v[2:5]
	v_mfma_f32_16x16x32_bf16 v[54:57], v[182:185], v[150:153], v[54:57]
	v_mfma_f32_16x16x32_bf16 v[46:49], v[202:205], v[150:153], v[46:49]
	v_mfma_f32_16x16x32_bf16 v[38:41], v[182:185], v[158:161], v[38:41]
	v_mfma_f32_16x16x32_bf16 v[30:33], v[202:205], v[158:161], v[30:33]
	v_mfma_f32_16x16x32_bf16 v[22:25], v[182:185], v[166:169], v[22:25]
	v_mfma_f32_16x16x32_bf16 v[14:17], v[202:205], v[166:169], v[14:17]
	v_mfma_f32_16x16x32_bf16 v[6:9], v[182:185], v[174:177], v[6:9]
	v_mfma_f32_16x16x32_bf16 v[2:5], v[202:205], v[174:177], v[2:5]
	s_setprio 0
	s_barrier
	ds_read_b128 v[118:121], v200
	ds_read_b128 v[126:129], v200 offset:1024
	ds_read_b128 v[130:133], v200 offset:2048
	ds_read_b128 v[138:141], v200 offset:3072
	s_mov_b32 m0, s26
	s_add_i32 s33, s87, 0x40000
	ds_read_b128 v[146:149], v198 offset:32768
	ds_read_b128 v[150:153], v198 offset:33792
	ds_read_b128 v[154:157], v198 offset:34816
	ds_read_b128 v[158:161], v198 offset:35840
	ds_read_b128 v[162:165], v198 offset:36864
	ds_read_b128 v[166:169], v198 offset:37888
	ds_read_b128 v[170:173], v198 offset:38912
	ds_read_b128 v[174:177], v198 offset:39936
	buffer_load_dwordx4 v1, s[48:51], s33 offen lds
	s_add_i32 s33, s87, 0x60000
	s_mov_b32 m0, s27
	s_nop 0
	buffer_load_dwordx4 v1, s[48:51], s33 offen lds
	s_waitcnt lgkmcnt(8)
	s_barrier
	s_waitcnt lgkmcnt(0)
	s_setprio 1
	s_waitcnt lgkmcnt(7)
	v_mfma_f32_16x16x32_bf16 v[142:145], v[118:121], v[146:149], v[142:145]
	v_mfma_f32_16x16x32_bf16 v[134:137], v[130:133], v[146:149], v[134:137]
	s_waitcnt lgkmcnt(5)
	v_mfma_f32_16x16x32_bf16 v[122:125], v[118:121], v[154:157], v[122:125]
	v_mfma_f32_16x16x32_bf16 v[114:117], v[130:133], v[154:157], v[114:117]
	s_waitcnt lgkmcnt(3)
	v_mfma_f32_16x16x32_bf16 v[94:97], v[118:121], v[162:165], v[94:97]
	v_mfma_f32_16x16x32_bf16 v[90:93], v[130:133], v[162:165], v[90:93]
	s_waitcnt lgkmcnt(1)
	v_mfma_f32_16x16x32_bf16 v[82:85], v[118:121], v[170:173], v[82:85]
	v_mfma_f32_16x16x32_bf16 v[74:77], v[130:133], v[170:173], v[74:77]
	v_mfma_f32_16x16x32_bf16 v[142:145], v[126:129], v[150:153], v[142:145]
	v_mfma_f32_16x16x32_bf16 v[134:137], v[138:141], v[150:153], v[134:137]
	v_mfma_f32_16x16x32_bf16 v[122:125], v[126:129], v[158:161], v[122:125]
	v_mfma_f32_16x16x32_bf16 v[114:117], v[138:141], v[158:161], v[114:117]
	v_mfma_f32_16x16x32_bf16 v[94:97], v[126:129], v[166:169], v[94:97]
	v_mfma_f32_16x16x32_bf16 v[90:93], v[138:141], v[166:169], v[90:93]
	s_waitcnt lgkmcnt(0)
	v_mfma_f32_16x16x32_bf16 v[82:85], v[126:129], v[174:177], v[82:85]
	v_mfma_f32_16x16x32_bf16 v[74:77], v[138:141], v[174:177], v[74:77]
	s_setprio 0
	s_barrier
	s_mov_b32 m0, s34
	s_add_i32 s33, s86, 0x80
	ds_read_b128 v[178:181], v201
	ds_read_b128 v[182:185], v201 offset:1024
	ds_read_b128 v[190:193], v201 offset:2048
	ds_read_b128 v[202:205], v201 offset:3072
	buffer_load_dwordx4 v194, s[8:11], s33 offen lds
	s_add_i32 s33, s86, 0x20080
	s_mov_b32 m0, s35
	s_nop 0
	buffer_load_dwordx4 v194, s[8:11], s33 offen lds
	s_barrier
	s_waitcnt lgkmcnt(0)
	s_setprio 1
	s_waitcnt lgkmcnt(3)
	v_mfma_f32_16x16x32_bf16 v[110:113], v[178:181], v[146:149], v[110:113]
	s_waitcnt lgkmcnt(1)
	v_mfma_f32_16x16x32_bf16 v[106:109], v[190:193], v[146:149], v[106:109]
	v_mfma_f32_16x16x32_bf16 v[102:105], v[178:181], v[154:157], v[102:105]
	v_mfma_f32_16x16x32_bf16 v[98:101], v[190:193], v[154:157], v[98:101]
	v_mfma_f32_16x16x32_bf16 v[86:89], v[178:181], v[162:165], v[86:89]
	v_mfma_f32_16x16x32_bf16 v[78:81], v[190:193], v[162:165], v[78:81]
	v_mfma_f32_16x16x32_bf16 v[70:73], v[178:181], v[170:173], v[70:73]
	v_mfma_f32_16x16x32_bf16 v[66:69], v[190:193], v[170:173], v[66:69]
	v_mfma_f32_16x16x32_bf16 v[110:113], v[182:185], v[150:153], v[110:113]
	s_waitcnt lgkmcnt(0)
	v_mfma_f32_16x16x32_bf16 v[106:109], v[202:205], v[150:153], v[106:109]
	v_mfma_f32_16x16x32_bf16 v[102:105], v[182:185], v[158:161], v[102:105]
	v_mfma_f32_16x16x32_bf16 v[98:101], v[202:205], v[158:161], v[98:101]
	v_mfma_f32_16x16x32_bf16 v[86:89], v[182:185], v[166:169], v[86:89]
	v_mfma_f32_16x16x32_bf16 v[78:81], v[202:205], v[166:169], v[78:81]
	v_mfma_f32_16x16x32_bf16 v[70:73], v[182:185], v[174:177], v[70:73]
	v_mfma_f32_16x16x32_bf16 v[66:69], v[202:205], v[174:177], v[66:69]
	s_setprio 0
	s_mov_b32 m0, s36
	s_barrier
	ds_read_b128 v[146:149], v198 offset:49152
	ds_read_b128 v[150:153], v198 offset:50176
	ds_read_b128 v[154:157], v198 offset:51200
	ds_read_b128 v[158:161], v198 offset:52224
	ds_read_b128 v[162:165], v198 offset:53248
	ds_read_b128 v[166:169], v198 offset:54272
	ds_read_b128 v[170:173], v198 offset:55296
	ds_read_b128 v[174:177], v198 offset:56320
	buffer_load_dwordx4 v1, s[48:51], s88 offen lds
	s_add_i32 s87, s87, 0x20080
	s_mov_b32 m0, s37
	s_nop 0
	buffer_load_dwordx4 v1, s[48:51], s87 offen lds
	s_barrier
	s_waitcnt lgkmcnt(0)
	s_setprio 1
	s_waitcnt lgkmcnt(7)
	v_mfma_f32_16x16x32_bf16 v[62:65], v[118:121], v[146:149], v[62:65]
	v_mfma_f32_16x16x32_bf16 v[58:61], v[130:133], v[146:149], v[58:61]
	s_waitcnt lgkmcnt(5)
	v_mfma_f32_16x16x32_bf16 v[50:53], v[118:121], v[154:157], v[50:53]
	v_mfma_f32_16x16x32_bf16 v[42:45], v[130:133], v[154:157], v[42:45]
	s_waitcnt lgkmcnt(3)
	v_mfma_f32_16x16x32_bf16 v[34:37], v[118:121], v[162:165], v[34:37]
	v_mfma_f32_16x16x32_bf16 v[26:29], v[130:133], v[162:165], v[26:29]
	s_waitcnt lgkmcnt(1)
	v_mfma_f32_16x16x32_bf16 v[18:21], v[118:121], v[170:173], v[18:21]
	v_mfma_f32_16x16x32_bf16 v[10:13], v[130:133], v[170:173], v[10:13]
	v_mfma_f32_16x16x32_bf16 v[62:65], v[126:129], v[150:153], v[62:65]
	v_mfma_f32_16x16x32_bf16 v[58:61], v[138:141], v[150:153], v[58:61]
	v_mfma_f32_16x16x32_bf16 v[50:53], v[126:129], v[158:161], v[50:53]
	v_mfma_f32_16x16x32_bf16 v[42:45], v[138:141], v[158:161], v[42:45]
	v_mfma_f32_16x16x32_bf16 v[34:37], v[126:129], v[166:169], v[34:37]
	v_mfma_f32_16x16x32_bf16 v[26:29], v[138:141], v[166:169], v[26:29]
	s_waitcnt lgkmcnt(0)
	v_mfma_f32_16x16x32_bf16 v[18:21], v[126:129], v[174:177], v[18:21]
	v_mfma_f32_16x16x32_bf16 v[10:13], v[138:141], v[174:177], v[10:13]
	s_setprio 0
	s_barrier
	s_mov_b32 m0, s38
	s_add_i32 s33, s86, 0x40080
	buffer_load_dwordx4 v194, s[8:11], s33 offen lds
	s_add_i32 s86, s86, 0x60080
	s_mov_b32 m0, s39
	s_nop 0
	buffer_load_dwordx4 v194, s[8:11], s86 offen lds
	s_waitcnt vmcnt(6)
	s_barrier
	s_setprio 1
	v_mfma_f32_16x16x32_bf16 v[54:57], v[178:181], v[146:149], v[54:57]
	v_mfma_f32_16x16x32_bf16 v[46:49], v[190:193], v[146:149], v[46:49]
	v_mfma_f32_16x16x32_bf16 v[38:41], v[178:181], v[154:157], v[38:41]
	v_mfma_f32_16x16x32_bf16 v[30:33], v[190:193], v[154:157], v[30:33]
	v_mfma_f32_16x16x32_bf16 v[22:25], v[178:181], v[162:165], v[22:25]
	v_mfma_f32_16x16x32_bf16 v[14:17], v[190:193], v[162:165], v[14:17]
	v_mfma_f32_16x16x32_bf16 v[6:9], v[178:181], v[170:173], v[6:9]
	v_mfma_f32_16x16x32_bf16 v[2:5], v[190:193], v[170:173], v[2:5]
	v_mfma_f32_16x16x32_bf16 v[54:57], v[182:185], v[150:153], v[54:57]
	v_mfma_f32_16x16x32_bf16 v[46:49], v[202:205], v[150:153], v[46:49]
	v_mfma_f32_16x16x32_bf16 v[38:41], v[182:185], v[158:161], v[38:41]
	v_mfma_f32_16x16x32_bf16 v[30:33], v[202:205], v[158:161], v[30:33]
	v_mfma_f32_16x16x32_bf16 v[22:25], v[182:185], v[166:169], v[22:25]
	v_mfma_f32_16x16x32_bf16 v[14:17], v[202:205], v[166:169], v[14:17]
	v_mfma_f32_16x16x32_bf16 v[6:9], v[182:185], v[174:177], v[6:9]
	v_mfma_f32_16x16x32_bf16 v[2:5], v[202:205], v[174:177], v[2:5]
	s_setprio 0
	s_add_i32 s17, s17, 2
	s_addk_i32 s7, 0x100
	s_addk_i32 s16, 0x100
	s_cmp_gt_u32 s17, 13
	s_barrier
	s_cbranch_scc0 .LBB0_450
	s_cmpk_gt_i32 s78, 0x7f
	s_cselect_b64 s[6:7], -1, 0
	s_and_b64 vcc, exec, s[6:7]
	s_cbranch_vccz .LBB0_443
	s_load_dwordx2 s[10:11], s[0:1], 0x10
	s_mov_b64 s[16:17], 0xc000
	s_branch .LBB0_444

.LBB0_761:
	s_cmp_gt_i32 s60, 9
	s_cselect_b64 s[4:5], -1, 0
	s_cmp_lt_i32 s61, 10
	s_cselect_b64 s[6:7], -1, 0
	s_or_b64 s[4:5], s[4:5], s[6:7]
	s_and_b64 vcc, exec, s[4:5]
	s_cbranch_vccnz .LBB0_830
	s_waitcnt vmcnt(0)
	v_mov_b32_e32 v4, v0
	s_cmpk_gt_i32 s2, 0x87f
	v_readfirstlane_b32 s3, v4
	s_cbranch_scc1 .LBB0_780
	s_add_u32 s12, s52, 0x2b00000
	s_addc_u32 s6, s53, 0
	s_ashr_i32 s11, s2, 31
	s_and_b32 s13, s6, 0xffff
	s_lshr_b32 s6, s11, 29
	v_readlane_b32 s8, v255, 8
	s_add_i32 s6, s2, s6
	s_ashr_i32 s4, s3, 6
	v_readlane_b32 s9, v255, 9
	s_ashr_i32 s7, s6, 3
	s_and_b32 s6, s6, -8
	s_and_b32 s41, s9, 0xffff
	s_ashr_i32 s5, s3, 8
	s_lshl_b32 s8, s4, 10
	s_sub_i32 s6, s2, s6
	s_cmp_lt_i32 s6, 0
	s_movk_i32 s16, 0x111
	s_cselect_b32 s9, s16, 0x110
	s_mul_i32 s6, s9, s6
	s_add_i32 s6, s6, s7
	s_ashr_i32 s7, s6, 31
	s_lshr_b32 s7, s7, 26
	s_add_i32 s7, s6, s7
	v_ashrrev_i32_e32 v2, 31, v4
	s_ashr_i32 s9, s7, 6
	s_andn2_b32 s7, s7, 63
	v_lshrrev_b32_e32 v2, 26, v2
	s_sub_i32 s6, s6, s7
	v_add_u32_e32 v2, v4, v2
	s_bfe_i32 s7, s6, 0x80000
	v_ashrrev_i32_e32 v5, 6, v2
	v_bfe_i32 v2, v4, 27, 1
	s_bfe_u32 s7, s7, 0x3000c
	v_lshlrev_b32_e32 v1, 4, v4
	v_lshrrev_b32_e32 v2, 22, v2
	s_add_i32 s7, s6, s7
	v_add_u32_e32 v2, v1, v2
	s_bfe_i32 s10, s7, 0x80000
	s_and_b32 s7, s7, 0xf8
	v_and_b32_e32 v2, 0xfffffc00, v2
	s_sub_i32 s6, s6, s7
	v_sub_u32_e32 v1, v1, v2
	s_lshl_b32 s9, s9, 3
	s_sext_i32_i8 s6, s6
	v_lshrrev_b32_e32 v2, 4, v1
	s_add_i32 s49, s9, s6
	v_bitop3_b32 v1, v2, v1, 32 bitop3:0x6c
	s_mul_hi_i32 s6, s49, 0x78787879
	v_ashrrev_i32_e32 v3, 31, v1
	s_lshr_b32 s7, s6, 31
	s_lshr_b32 s6, s6, 3
	v_lshrrev_b32_e32 v3, 26, v3
	s_sext_i32_i16 s10, s10
	s_add_i32 s9, s6, s7
	s_lshl_b32 s6, s49, 8
	v_lshlrev_b32_e32 v2, 3, v5
	v_add_u32_e32 v8, v1, v3
	s_ashr_i32 s47, s10, 3
	s_ashr_i32 s7, s6, 31
	v_and_b32_e32 v2, -16, v2
	v_ashrrev_i32_e32 v9, 6, v8
	s_lshl_b32 s10, s47, 18
	s_lshl_b64 s[6:7], s[6:7], 2
	v_add_u32_e32 v2, v9, v2
	s_add_u32 s6, s74, s6
	s_addc_u32 s7, s75, s7
	v_ashrrev_i32_e32 v3, 31, v2
	v_lshl_add_u64 v[6:7], v[2:3], 2, s[6:7]
	global_load_dword v10, v[6:7], off
	global_load_dword v11, v[6:7], off offset:512
	global_load_dword v12, v[6:7], off offset:768
	s_nop 0
	global_load_dword v6, v[6:7], off offset:256
	v_and_b32_e32 v8, 0xc0, v8
	v_mov_b32_e32 v7, 1
	v_sub_u32_e32 v1, v1, v8
	s_mov_b32 s6, 0x3fffe0
	v_lshlrev_b32_e32 v5, 5, v5
	v_and_b32_e32 v8, 3, v9
	v_ashrrev_i16_sdwa v1, v7, sext(v1) dst_sel:DWORD dst_unused:UNUSED_PAD src0_sel:DWORD src1_sel:BYTE_0
	v_lshlrev_b32_e32 v7, 1, v2
	v_lshrrev_b32_e32 v9, 2, v2
	v_and_b32_e32 v5, 32, v5
	v_and_or_b32 v8, v2, s6, v8
	v_bfe_i32 v1, v1, 0, 16
	v_and_b32_e32 v7, 24, v7
	v_and_b32_e32 v9, 4, v9
	s_add_i32 s17, s8, 0
	s_mov_b32 s43, 0x20000
	s_brev_b32 s42, -2
	v_or3_b32 v7, v8, v9, v7
	v_add_lshl_u32 v1, v5, v1, 1
	s_lshl_b32 s6, s9, 21
	s_add_i32 s18, s17, 0x10000
	s_mov_b32 s14, s42
	s_mov_b32 s15, s43
	v_lshl_add_u32 v184, v7, 10, v1
	s_add_i32 s50, s6, s10
	s_add_i32 s19, s17, 0x12000
	s_mov_b32 m0, s18
	s_or_b32 s6, s50, 0x10000
	buffer_load_dwordx4 v184, s[12:15], s50 offen lds
	s_mov_b32 m0, s19
	s_add_i32 s20, s17, 0x2000
	buffer_load_dwordx4 v184, s[12:15], s6 offen lds
	s_mov_b32 m0, s17
	s_add_i32 s21, s17, 0x14000
	s_or_b32 s6, s50, 0x20000
	s_add_i32 s22, s17, 0x16000
	s_add_i32 s23, s17, 0x4000
	s_add_i32 s24, s17, 0x6000
	s_mov_b32 s25, 0
	s_waitcnt vmcnt(5)
	v_lshlrev_b32_e32 v5, 10, v10
	v_and_b32_e32 v5, 0x3fffc00, v5
	s_waitcnt vmcnt(4)
	v_lshl_or_b32 v186, v11, 16, v10
	s_waitcnt vmcnt(2)
	v_lshl_or_b32 v185, v12, 16, v6
	v_lshlrev_b32_e32 v6, 10, v6
	v_and_b32_e32 v7, 0x3fffc00, v6
	v_add_u32_e32 v6, v5, v1
	v_add_u32_e32 v5, v7, v1
	buffer_load_dwordx4 v6, s[40:43], 0 offen lds
	s_mov_b32 m0, s20
	v_bfe_u32 v7, v186, 16, 16
	buffer_load_dwordx4 v5, s[40:43], 0 offen lds
	s_mov_b32 m0, s21
	v_lshl_add_u32 v7, v7, 10, v1
	buffer_load_dwordx4 v184, s[12:15], s6 offen lds
	s_or_b32 s6, s50, 0x30000
	s_mov_b32 m0, s22
	s_cmp_lg_u32 s5, 1
	buffer_load_dwordx4 v184, s[12:15], s6 offen lds
	s_mov_b32 m0, s23
	s_nop 0
	buffer_load_dwordx4 v7, s[40:43], 0 offen lds
	v_bfe_u32 v7, v185, 16, 16
	v_lshl_add_u32 v7, v7, 10, v1
	s_mov_b32 m0, s24
	s_nop 0
	buffer_load_dwordx4 v7, s[40:43], 0 offen lds
	s_cbranch_scc1 .LBB0_765
	s_barrier

.LBB0_766:
	v_mov_b32_e32 v218, 0xbd38aa3b
	v_mov_b32_e32 v219, 0xbd38aa3b
	v_mov_b32_e32 v220, 0x44800000
	v_mov_b32_e32 v221, 0x44800000
	v_lshl_add_u32 v222, s49, 8, v187
	v_lshl_or_b32 v224, s47, 7, v188
	s_nop 0
	v_lshl_add_u32 v222, v222, 10, v224
	s_mov_b32 s47, s39
	s_mov_b32 s49, s45
	s_mov_b32 s50, s46
	v_pk_mul_f32 v[226:227], v[174:175], v[218:219]
	v_pk_mul_f32 v[228:229], v[176:177], v[218:219]
	v_pk_mul_f32 v[230:231], v[166:167], v[218:219]
	v_pk_mul_f32 v[232:233], v[168:169], v[218:219]
	v_exp_f32_e32 v226, v226
	v_exp_f32_e32 v227, v227
	v_exp_f32_e32 v228, v228
	v_exp_f32_e32 v229, v229
	v_exp_f32_e32 v230, v230
	v_exp_f32_e32 v231, v231
	v_exp_f32_e32 v232, v232
	v_exp_f32_e32 v233, v233
	v_pk_fma_f32 v[226:227], v[226:227], v[220:221], v[220:221]
	v_pk_fma_f32 v[228:229], v[228:229], v[220:221], v[220:221]
	v_pk_fma_f32 v[230:231], v[230:231], v[220:221], v[220:221]
	v_pk_fma_f32 v[232:233], v[232:233], v[220:221], v[220:221]
	v_rcp_f32_e32 v226, v226
	v_rcp_f32_e32 v227, v227
	v_rcp_f32_e32 v228, v228
	v_rcp_f32_e32 v229, v229
	v_rcp_f32_e32 v230, v230
	v_rcp_f32_e32 v231, v231
	v_rcp_f32_e32 v232, v232
	v_rcp_f32_e32 v233, v233
	v_pk_mul_f32 v[174:175], v[174:175], v[170:171]
	v_pk_mul_f32 v[176:177], v[176:177], v[172:173]
	v_pk_mul_f32 v[166:167], v[166:167], v[162:163]
	v_pk_mul_f32 v[168:169], v[168:169], v[164:165]
	v_pk_mul_f32 v[174:175], v[174:175], v[226:227]
	v_pk_mul_f32 v[176:177], v[176:177], v[228:229]
	v_pk_mul_f32 v[166:167], v[166:167], v[230:231]
	v_pk_mul_f32 v[168:169], v[168:169], v[232:233]
	v_mov_b32_e32 v223, v222
	v_cvt_pk_fp8_f32 v234, v174, v175
	v_cvt_pk_fp8_f32 v235, v166, v167
	v_cvt_pk_fp8_f32 v234, v176, v177 op_sel:[0,0,1]
	v_cvt_pk_fp8_f32 v235, v168, v169 op_sel:[0,0,1]
	s_nop 0
	global_store_dwordx2 v223, v[234:235], s[70:71]
	v_pk_mul_f32 v[226:227], v[158:159], v[218:219]
	v_pk_mul_f32 v[228:229], v[160:161], v[218:219]
	v_pk_mul_f32 v[230:231], v[150:151], v[218:219]
	v_pk_mul_f32 v[232:233], v[152:153], v[218:219]
	v_exp_f32_e32 v226, v226
	v_exp_f32_e32 v227, v227
	v_exp_f32_e32 v228, v228
	v_exp_f32_e32 v229, v229
	v_exp_f32_e32 v230, v230
	v_exp_f32_e32 v231, v231
	v_exp_f32_e32 v232, v232
	v_exp_f32_e32 v233, v233
	v_pk_fma_f32 v[226:227], v[226:227], v[220:221], v[220:221]
	v_pk_fma_f32 v[228:229], v[228:229], v[220:221], v[220:221]
	v_pk_fma_f32 v[230:231], v[230:231], v[220:221], v[220:221]
	v_pk_fma_f32 v[232:233], v[232:233], v[220:221], v[220:221]
	v_rcp_f32_e32 v226, v226
	v_rcp_f32_e32 v227, v227
	v_rcp_f32_e32 v228, v228
	v_rcp_f32_e32 v229, v229
	v_rcp_f32_e32 v230, v230
	v_rcp_f32_e32 v231, v231
	v_rcp_f32_e32 v232, v232
	v_rcp_f32_e32 v233, v233
	v_pk_mul_f32 v[158:159], v[158:159], v[154:155]
	v_pk_mul_f32 v[160:161], v[160:161], v[156:157]
	v_pk_mul_f32 v[150:151], v[150:151], v[146:147]
	v_pk_mul_f32 v[152:153], v[152:153], v[148:149]
	v_pk_mul_f32 v[158:159], v[158:159], v[226:227]
	v_pk_mul_f32 v[160:161], v[160:161], v[228:229]
	v_pk_mul_f32 v[150:151], v[150:151], v[230:231]
	v_pk_mul_f32 v[152:153], v[152:153], v[232:233]
	v_add_u32_e32 v225, 0x4000, v222
	v_cvt_pk_fp8_f32 v236, v158, v159
	v_cvt_pk_fp8_f32 v237, v150, v151
	v_cvt_pk_fp8_f32 v236, v160, v161 op_sel:[0,0,1]
	v_cvt_pk_fp8_f32 v237, v152, v153 op_sel:[0,0,1]
	s_nop 0
	global_store_dwordx2 v225, v[236:237], s[70:71]
	v_pk_mul_f32 v[226:227], v[142:143], v[218:219]
	v_pk_mul_f32 v[228:229], v[144:145], v[218:219]
	v_pk_mul_f32 v[230:231], v[134:135], v[218:219]
	v_pk_mul_f32 v[232:233], v[136:137], v[218:219]
	v_exp_f32_e32 v226, v226
	v_exp_f32_e32 v227, v227
	v_exp_f32_e32 v228, v228
	v_exp_f32_e32 v229, v229
	v_exp_f32_e32 v230, v230
	v_exp_f32_e32 v231, v231
	v_exp_f32_e32 v232, v232
	v_exp_f32_e32 v233, v233
	v_pk_fma_f32 v[226:227], v[226:227], v[220:221], v[220:221]
	v_pk_fma_f32 v[228:229], v[228:229], v[220:221], v[220:221]
	v_pk_fma_f32 v[230:231], v[230:231], v[220:221], v[220:221]
	v_pk_fma_f32 v[232:233], v[232:233], v[220:221], v[220:221]
	v_rcp_f32_e32 v226, v226
	v_rcp_f32_e32 v227, v227
	v_rcp_f32_e32 v228, v228
	v_rcp_f32_e32 v229, v229
	v_rcp_f32_e32 v230, v230
	v_rcp_f32_e32 v231, v231
	v_rcp_f32_e32 v232, v232
	v_rcp_f32_e32 v233, v233
	v_pk_mul_f32 v[142:143], v[142:143], v[138:139]
	v_pk_mul_f32 v[144:145], v[144:145], v[140:141]
	v_pk_mul_f32 v[134:135], v[134:135], v[130:131]
	v_pk_mul_f32 v[136:137], v[136:137], v[132:133]
	v_pk_mul_f32 v[142:143], v[142:143], v[226:227]
	v_pk_mul_f32 v[144:145], v[144:145], v[228:229]
	v_pk_mul_f32 v[134:135], v[134:135], v[230:231]
	v_pk_mul_f32 v[136:137], v[136:137], v[232:233]
	v_add_u32_e32 v223, 0x8000, v222
	v_cvt_pk_fp8_f32 v234, v142, v143
	v_cvt_pk_fp8_f32 v235, v134, v135
	v_cvt_pk_fp8_f32 v234, v144, v145 op_sel:[0,0,1]
	v_cvt_pk_fp8_f32 v235, v136, v137 op_sel:[0,0,1]
	s_nop 0
	global_store_dwordx2 v223, v[234:235], s[70:71]
	v_pk_mul_f32 v[226:227], v[126:127], v[218:219]
	v_pk_mul_f32 v[228:229], v[128:129], v[218:219]
	v_pk_mul_f32 v[230:231], v[118:119], v[218:219]
	v_pk_mul_f32 v[232:233], v[120:121], v[218:219]
	v_exp_f32_e32 v226, v226
	v_exp_f32_e32 v227, v227
	v_exp_f32_e32 v228, v228
	v_exp_f32_e32 v229, v229
	v_exp_f32_e32 v230, v230
	v_exp_f32_e32 v231, v231
	v_exp_f32_e32 v232, v232
	v_exp_f32_e32 v233, v233
	v_pk_fma_f32 v[226:227], v[226:227], v[220:221], v[220:221]
	v_pk_fma_f32 v[228:229], v[228:229], v[220:221], v[220:221]
	v_pk_fma_f32 v[230:231], v[230:231], v[220:221], v[220:221]
	v_pk_fma_f32 v[232:233], v[232:233], v[220:221], v[220:221]
	v_rcp_f32_e32 v226, v226
	v_rcp_f32_e32 v227, v227
	v_rcp_f32_e32 v228, v228
	v_rcp_f32_e32 v229, v229
	v_rcp_f32_e32 v230, v230
	v_rcp_f32_e32 v231, v231
	v_rcp_f32_e32 v232, v232
	v_rcp_f32_e32 v233, v233
	v_pk_mul_f32 v[126:127], v[126:127], v[122:123]
	v_pk_mul_f32 v[128:129], v[128:129], v[124:125]
	v_pk_mul_f32 v[118:119], v[118:119], v[114:115]
	v_pk_mul_f32 v[120:121], v[120:121], v[116:117]
	v_pk_mul_f32 v[126:127], v[126:127], v[226:227]
	v_pk_mul_f32 v[128:129], v[128:129], v[228:229]
	v_pk_mul_f32 v[118:119], v[118:119], v[230:231]
	v_pk_mul_f32 v[120:121], v[120:121], v[232:233]
	v_add_u32_e32 v225, 0xc000, v222
	v_cvt_pk_fp8_f32 v236, v126, v127
	v_cvt_pk_fp8_f32 v237, v118, v119
	v_cvt_pk_fp8_f32 v236, v128, v129 op_sel:[0,0,1]
	v_cvt_pk_fp8_f32 v237, v120, v121 op_sel:[0,0,1]
	s_nop 0
	global_store_dwordx2 v225, v[236:237], s[70:71]
	v_pk_mul_f32 v[226:227], v[110:111], v[218:219]
	v_pk_mul_f32 v[228:229], v[112:113], v[218:219]
	v_pk_mul_f32 v[230:231], v[102:103], v[218:219]
	v_pk_mul_f32 v[232:233], v[104:105], v[218:219]
	v_exp_f32_e32 v226, v226
	v_exp_f32_e32 v227, v227
	v_exp_f32_e32 v228, v228
	v_exp_f32_e32 v229, v229
	v_exp_f32_e32 v230, v230
	v_exp_f32_e32 v231, v231
	v_exp_f32_e32 v232, v232
	v_exp_f32_e32 v233, v233
	v_pk_fma_f32 v[226:227], v[226:227], v[220:221], v[220:221]
	v_pk_fma_f32 v[228:229], v[228:229], v[220:221], v[220:221]
	v_pk_fma_f32 v[230:231], v[230:231], v[220:221], v[220:221]
	v_pk_fma_f32 v[232:233], v[232:233], v[220:221], v[220:221]
	v_rcp_f32_e32 v226, v226
	v_rcp_f32_e32 v227, v227
	v_rcp_f32_e32 v228, v228
	v_rcp_f32_e32 v229, v229
	v_rcp_f32_e32 v230, v230
	v_rcp_f32_e32 v231, v231
	v_rcp_f32_e32 v232, v232
	v_rcp_f32_e32 v233, v233
	v_pk_mul_f32 v[110:111], v[110:111], v[106:107]
	v_pk_mul_f32 v[112:113], v[112:113], v[108:109]
	v_pk_mul_f32 v[102:103], v[102:103], v[98:99]
	v_pk_mul_f32 v[104:105], v[104:105], v[100:101]
	v_pk_mul_f32 v[110:111], v[110:111], v[226:227]
	v_pk_mul_f32 v[112:113], v[112:113], v[228:229]
	v_pk_mul_f32 v[102:103], v[102:103], v[230:231]
	v_pk_mul_f32 v[104:105], v[104:105], v[232:233]
	v_add_u32_e32 v223, 0x20000, v222
	v_cvt_pk_fp8_f32 v234, v110, v111
	v_cvt_pk_fp8_f32 v235, v102, v103
	v_cvt_pk_fp8_f32 v234, v112, v113 op_sel:[0,0,1]
	v_cvt_pk_fp8_f32 v235, v104, v105 op_sel:[0,0,1]
	s_nop 0
	global_store_dwordx2 v223, v[234:235], s[70:71]
	v_pk_mul_f32 v[226:227], v[94:95], v[218:219]
	v_pk_mul_f32 v[228:229], v[96:97], v[218:219]
	v_pk_mul_f32 v[230:231], v[86:87], v[218:219]
	v_pk_mul_f32 v[232:233], v[88:89], v[218:219]
	v_exp_f32_e32 v226, v226
	v_exp_f32_e32 v227, v227
	v_exp_f32_e32 v228, v228
	v_exp_f32_e32 v229, v229
	v_exp_f32_e32 v230, v230
	v_exp_f32_e32 v231, v231
	v_exp_f32_e32 v232, v232
	v_exp_f32_e32 v233, v233
	v_pk_fma_f32 v[226:227], v[226:227], v[220:221], v[220:221]
	v_pk_fma_f32 v[228:229], v[228:229], v[220:221], v[220:221]
	v_pk_fma_f32 v[230:231], v[230:231], v[220:221], v[220:221]
	v_pk_fma_f32 v[232:233], v[232:233], v[220:221], v[220:221]
	v_rcp_f32_e32 v226, v226
	v_rcp_f32_e32 v227, v227
	v_rcp_f32_e32 v228, v228
	v_rcp_f32_e32 v229, v229
	v_rcp_f32_e32 v230, v230
	v_rcp_f32_e32 v231, v231
	v_rcp_f32_e32 v232, v232
	v_rcp_f32_e32 v233, v233
	v_pk_mul_f32 v[94:95], v[94:95], v[90:91]
	v_pk_mul_f32 v[96:97], v[96:97], v[92:93]
	v_pk_mul_f32 v[86:87], v[86:87], v[82:83]
	v_pk_mul_f32 v[88:89], v[88:89], v[84:85]
	v_pk_mul_f32 v[94:95], v[94:95], v[226:227]
	v_pk_mul_f32 v[96:97], v[96:97], v[228:229]
	v_pk_mul_f32 v[86:87], v[86:87], v[230:231]
	v_pk_mul_f32 v[88:89], v[88:89], v[232:233]
	v_add_u32_e32 v225, 0x24000, v222
	v_cvt_pk_fp8_f32 v236, v94, v95
	v_cvt_pk_fp8_f32 v237, v86, v87
	v_cvt_pk_fp8_f32 v236, v96, v97 op_sel:[0,0,1]
	v_cvt_pk_fp8_f32 v237, v88, v89 op_sel:[0,0,1]
	s_nop 0
	global_store_dwordx2 v225, v[236:237], s[70:71]
	v_pk_mul_f32 v[226:227], v[78:79], v[218:219]
	v_pk_mul_f32 v[228:229], v[80:81], v[218:219]
	v_pk_mul_f32 v[230:231], v[70:71], v[218:219]
	v_pk_mul_f32 v[232:233], v[72:73], v[218:219]
	v_exp_f32_e32 v226, v226
	v_exp_f32_e32 v227, v227
	v_exp_f32_e32 v228, v228
	v_exp_f32_e32 v229, v229
	v_exp_f32_e32 v230, v230
	v_exp_f32_e32 v231, v231
	v_exp_f32_e32 v232, v232
	v_exp_f32_e32 v233, v233
	v_pk_fma_f32 v[226:227], v[226:227], v[220:221], v[220:221]
	v_pk_fma_f32 v[228:229], v[228:229], v[220:221], v[220:221]
	v_pk_fma_f32 v[230:231], v[230:231], v[220:221], v[220:221]
	v_pk_fma_f32 v[232:233], v[232:233], v[220:221], v[220:221]
	v_rcp_f32_e32 v226, v226
	v_rcp_f32_e32 v227, v227
	v_rcp_f32_e32 v228, v228
	v_rcp_f32_e32 v229, v229
	v_rcp_f32_e32 v230, v230
	v_rcp_f32_e32 v231, v231
	v_rcp_f32_e32 v232, v232
	v_rcp_f32_e32 v233, v233
	v_pk_mul_f32 v[78:79], v[78:79], v[74:75]
	v_pk_mul_f32 v[80:81], v[80:81], v[76:77]
	v_pk_mul_f32 v[70:71], v[70:71], v[66:67]
	v_pk_mul_f32 v[72:73], v[72:73], v[68:69]
	v_pk_mul_f32 v[78:79], v[78:79], v[226:227]
	v_pk_mul_f32 v[80:81], v[80:81], v[228:229]
	v_pk_mul_f32 v[70:71], v[70:71], v[230:231]
	v_pk_mul_f32 v[72:73], v[72:73], v[232:233]
	v_add_u32_e32 v223, 0x28000, v222
	v_cvt_pk_fp8_f32 v234, v78, v79
	v_cvt_pk_fp8_f32 v235, v70, v71
	v_cvt_pk_fp8_f32 v234, v80, v81 op_sel:[0,0,1]
	v_cvt_pk_fp8_f32 v235, v72, v73 op_sel:[0,0,1]
	s_nop 0
	global_store_dwordx2 v223, v[234:235], s[70:71]
	v_pk_mul_f32 v[226:227], v[62:63], v[218:219]
	v_pk_mul_f32 v[228:229], v[64:65], v[218:219]
	v_pk_mul_f32 v[230:231], v[54:55], v[218:219]
	v_pk_mul_f32 v[232:233], v[56:57], v[218:219]
	v_exp_f32_e32 v226, v226
	v_exp_f32_e32 v227, v227
	v_exp_f32_e32 v228, v228
	v_exp_f32_e32 v229, v229
	v_exp_f32_e32 v230, v230
	v_exp_f32_e32 v231, v231
	v_exp_f32_e32 v232, v232
	v_exp_f32_e32 v233, v233
	v_pk_fma_f32 v[226:227], v[226:227], v[220:221], v[220:221]
	v_pk_fma_f32 v[228:229], v[228:229], v[220:221], v[220:221]
	v_pk_fma_f32 v[230:231], v[230:231], v[220:221], v[220:221]
	v_pk_fma_f32 v[232:233], v[232:233], v[220:221], v[220:221]
	v_rcp_f32_e32 v226, v226
	v_rcp_f32_e32 v227, v227
	v_rcp_f32_e32 v228, v228
	v_rcp_f32_e32 v229, v229
	v_rcp_f32_e32 v230, v230
	v_rcp_f32_e32 v231, v231
	v_rcp_f32_e32 v232, v232
	v_rcp_f32_e32 v233, v233
	v_pk_mul_f32 v[62:63], v[62:63], v[58:59]
	v_pk_mul_f32 v[64:65], v[64:65], v[60:61]
	v_pk_mul_f32 v[54:55], v[54:55], v[50:51]
	v_pk_mul_f32 v[56:57], v[56:57], v[52:53]
	v_pk_mul_f32 v[62:63], v[62:63], v[226:227]
	v_pk_mul_f32 v[64:65], v[64:65], v[228:229]
	v_pk_mul_f32 v[54:55], v[54:55], v[230:231]
	v_pk_mul_f32 v[56:57], v[56:57], v[232:233]
	v_add_u32_e32 v225, 0x2c000, v222
	v_cvt_pk_fp8_f32 v236, v62, v63
	v_cvt_pk_fp8_f32 v237, v54, v55
	v_cvt_pk_fp8_f32 v236, v64, v65 op_sel:[0,0,1]
	v_cvt_pk_fp8_f32 v237, v56, v57 op_sel:[0,0,1]
	s_nop 0
	global_store_dwordx2 v225, v[236:237], s[70:71]
	s_and_b64 vcc, exec, s[4:5]
	s_cbranch_vccnz .LBB0_777

.LBB0_774:
	s_and_b64 s[14:15], s[6:7], exec
	s_cselect_b32 s57, 0, s9
	s_add_i32 s14, s50, s9
	s_or_b32 s51, s57, 0x80
	s_waitcnt lgkmcnt(8)
	s_barrier
	s_waitcnt lgkmcnt(0)
	s_and_b64 s[6:7], s[6:7], exec
	s_cselect_b32 s6, s46, s14
	s_add_i32 s7, s6, 0x80
	s_setprio 1
	s_waitcnt lgkmcnt(6)
	v_mfma_f32_16x16x128_f8f6f4 v[174:177], v[2:9], v[42:49], v[174:177]
	v_mfma_f32_16x16x128_f8f6f4 v[166:169], v[10:17], v[42:49], v[166:169]
	s_waitcnt lgkmcnt(4)
	v_mfma_f32_16x16x128_f8f6f4 v[158:161], v[2:9], v[34:41], v[158:161]
	v_mfma_f32_16x16x128_f8f6f4 v[150:153], v[10:17], v[34:41], v[150:153]
	s_waitcnt lgkmcnt(2)
	v_mfma_f32_16x16x128_f8f6f4 v[142:145], v[2:9], v[26:33], v[142:145]
	v_mfma_f32_16x16x128_f8f6f4 v[134:137], v[10:17], v[26:33], v[134:137]
	s_waitcnt lgkmcnt(0)
	v_mfma_f32_16x16x128_f8f6f4 v[126:129], v[2:9], v[18:25], v[126:129]
	v_mfma_f32_16x16x128_f8f6f4 v[118:121], v[10:17], v[18:25], v[118:121]
	s_setprio 0
	s_barrier
	s_mov_b32 m0, s18
	v_add_u32_e32 v210, 0x14000, v189
	s_mov_b32 s14, s42
	s_mov_b32 s15, s43
	ds_read_b128 v[198:201], v210
	ds_read_b128 v[202:205], v210 offset:1024
	ds_read_b128 v[206:209], v210 offset:2048
	ds_read_b128 v[210:213], v210 offset:3072
	buffer_load_dwordx4 v184, s[12:15], s6 offen lds
	s_add_i32 s33, s6, 0x10000
	s_mov_b32 m0, s19
	s_nop 0
	buffer_load_dwordx4 v184, s[12:15], s33 offen lds
	s_barrier
	s_waitcnt lgkmcnt(0)
	s_setprio 1
	s_waitcnt lgkmcnt(2)
	v_mfma_f32_16x16x128_f8f6f4 v[170:173], v[198:205], v[42:49], v[170:173]
	s_waitcnt lgkmcnt(0)
	v_mfma_f32_16x16x128_f8f6f4 v[162:165], v[206:213], v[42:49], v[162:165]
	v_mfma_f32_16x16x128_f8f6f4 v[154:157], v[198:205], v[34:41], v[154:157]
	v_mfma_f32_16x16x128_f8f6f4 v[146:149], v[206:213], v[34:41], v[146:149]
	v_mfma_f32_16x16x128_f8f6f4 v[138:141], v[198:205], v[26:33], v[138:141]
	v_mfma_f32_16x16x128_f8f6f4 v[130:133], v[206:213], v[26:33], v[130:133]
	v_mfma_f32_16x16x128_f8f6f4 v[122:125], v[198:205], v[18:25], v[122:125]
	v_mfma_f32_16x16x128_f8f6f4 v[114:117], v[206:213], v[18:25], v[114:117]
	s_setprio 0
	v_lshlrev_b32_e32 v214, 10, v186
	v_and_b32_e32 v214, 0x3fffc00, v214
	v_lshlrev_b32_e32 v215, 10, v185
	s_mov_b32 m0, s17
	v_add_u32_e32 v214, v214, v1
	v_and_b32_e32 v215, 0x3fffc00, v215
	s_barrier
	ds_read_b128 v[18:21], v191 offset:16384
	ds_read_b128 v[22:25], v191 offset:17408
	ds_read_b128 v[26:29], v191 offset:18432
	ds_read_b128 v[30:33], v191 offset:19456
	ds_read_b128 v[34:37], v191 offset:20480
	ds_read_b128 v[38:41], v191 offset:21504
	ds_read_b128 v[42:45], v191 offset:22528
	ds_read_b128 v[46:49], v191 offset:23552
	buffer_load_dwordx4 v214, s[40:43], s57 offen lds
	v_add_u32_e32 v215, v215, v1
	s_mov_b32 m0, s20
	s_nop 0
	buffer_load_dwordx4 v215, s[40:43], s57 offen lds
	s_barrier
	s_waitcnt lgkmcnt(0)
	s_setprio 1
	s_waitcnt lgkmcnt(6)
	v_mfma_f32_16x16x128_f8f6f4 v[110:113], v[2:9], v[18:25], v[110:113]
	v_mfma_f32_16x16x128_f8f6f4 v[102:105], v[10:17], v[18:25], v[102:105]
	s_waitcnt lgkmcnt(4)
	v_mfma_f32_16x16x128_f8f6f4 v[94:97], v[2:9], v[26:33], v[94:97]
	v_mfma_f32_16x16x128_f8f6f4 v[86:89], v[10:17], v[26:33], v[86:89]
	s_waitcnt lgkmcnt(2)
	v_mfma_f32_16x16x128_f8f6f4 v[78:81], v[2:9], v[34:41], v[78:81]
	v_mfma_f32_16x16x128_f8f6f4 v[70:73], v[10:17], v[34:41], v[70:73]
	s_waitcnt lgkmcnt(0)
	v_mfma_f32_16x16x128_f8f6f4 v[62:65], v[2:9], v[42:49], v[62:65]
	v_mfma_f32_16x16x128_f8f6f4 v[54:57], v[10:17], v[42:49], v[54:57]
	s_setprio 0
	s_barrier
	s_mov_b32 m0, s21
	s_add_i32 s33, s6, 0x20000
	buffer_load_dwordx4 v184, s[12:15], s33 offen lds
	s_add_i32 s33, s6, 0x30000
	s_mov_b32 m0, s22
	s_nop 0
	buffer_load_dwordx4 v184, s[12:15], s33 offen lds
	s_waitcnt vmcnt(6)
	s_barrier
	s_setprio 1
	v_mfma_f32_16x16x128_f8f6f4 v[106:109], v[198:205], v[18:25], v[106:109]
	v_mfma_f32_16x16x128_f8f6f4 v[98:101], v[206:213], v[18:25], v[98:101]
	v_mfma_f32_16x16x128_f8f6f4 v[90:93], v[198:205], v[26:33], v[90:93]
	v_mfma_f32_16x16x128_f8f6f4 v[82:85], v[206:213], v[26:33], v[82:85]
	v_mfma_f32_16x16x128_f8f6f4 v[74:77], v[198:205], v[34:41], v[74:77]
	v_mfma_f32_16x16x128_f8f6f4 v[66:69], v[206:213], v[34:41], v[66:69]
	v_mfma_f32_16x16x128_f8f6f4 v[58:61], v[198:205], v[42:49], v[58:61]
	v_mfma_f32_16x16x128_f8f6f4 v[50:53], v[206:213], v[42:49], v[50:53]
	s_setprio 0
	v_add_u32_e32 v14, 0x18000, v189
	s_barrier
	ds_read_b128 v[2:5], v14
	ds_read_b128 v[6:9], v14 offset:1024
	ds_read_b128 v[10:13], v14 offset:2048
	ds_read_b128 v[14:17], v14 offset:3072
	s_mov_b32 m0, s23
	ds_read_b128 v[18:21], v191 offset:32768
	ds_read_b128 v[22:25], v191 offset:33792
	ds_read_b128 v[26:29], v191 offset:34816
	ds_read_b128 v[30:33], v191 offset:35840
	ds_read_b128 v[34:37], v191 offset:36864
	ds_read_b128 v[38:41], v191 offset:37888
	ds_read_b128 v[42:45], v191 offset:38912
	ds_read_b128 v[46:49], v191 offset:39936
	buffer_load_dwordx4 v196, s[40:43], s57 offen lds
	s_mov_b32 m0, s24
	s_nop 0
	buffer_load_dwordx4 v197, s[40:43], s57 offen lds
	s_waitcnt lgkmcnt(8)
	s_barrier
	s_waitcnt lgkmcnt(0)
	s_setprio 1
	s_waitcnt lgkmcnt(6)
	v_mfma_f32_16x16x128_f8f6f4 v[174:177], v[2:9], v[18:25], v[174:177]
	v_mfma_f32_16x16x128_f8f6f4 v[166:169], v[10:17], v[18:25], v[166:169]
	s_waitcnt lgkmcnt(4)
	v_mfma_f32_16x16x128_f8f6f4 v[158:161], v[2:9], v[26:33], v[158:161]
	v_mfma_f32_16x16x128_f8f6f4 v[150:153], v[10:17], v[26:33], v[150:153]
	s_waitcnt lgkmcnt(2)
	v_mfma_f32_16x16x128_f8f6f4 v[142:145], v[2:9], v[34:41], v[142:145]
	v_mfma_f32_16x16x128_f8f6f4 v[134:137], v[10:17], v[34:41], v[134:137]
	s_waitcnt lgkmcnt(0)
	v_mfma_f32_16x16x128_f8f6f4 v[126:129], v[2:9], v[42:49], v[126:129]
	v_mfma_f32_16x16x128_f8f6f4 v[118:121], v[10:17], v[42:49], v[118:121]
	s_setprio 0
	s_barrier
	s_mov_b32 m0, s26
	v_add_u32_e32 v208, 0x1c000, v189
	ds_read_b128 v[196:199], v208
	ds_read_b128 v[200:203], v208 offset:1024
	ds_read_b128 v[204:207], v208 offset:2048
	ds_read_b128 v[208:211], v208 offset:3072
	buffer_load_dwordx4 v184, s[12:15], s7 offen lds
	s_add_i32 s7, s6, 0x10080
	s_mov_b32 m0, s27
	s_nop 0
	buffer_load_dwordx4 v184, s[12:15], s7 offen lds
	s_barrier
	s_waitcnt lgkmcnt(0)
	s_setprio 1
	s_waitcnt lgkmcnt(2)
	v_mfma_f32_16x16x128_f8f6f4 v[170:173], v[196:203], v[18:25], v[170:173]
	s_waitcnt lgkmcnt(0)
	v_mfma_f32_16x16x128_f8f6f4 v[162:165], v[204:211], v[18:25], v[162:165]
	v_mfma_f32_16x16x128_f8f6f4 v[154:157], v[196:203], v[26:33], v[154:157]
	v_mfma_f32_16x16x128_f8f6f4 v[146:149], v[204:211], v[26:33], v[146:149]
	v_mfma_f32_16x16x128_f8f6f4 v[138:141], v[196:203], v[34:41], v[138:141]
	v_mfma_f32_16x16x128_f8f6f4 v[130:133], v[204:211], v[34:41], v[130:133]
	v_mfma_f32_16x16x128_f8f6f4 v[122:125], v[196:203], v[42:49], v[122:125]
	v_mfma_f32_16x16x128_f8f6f4 v[114:117], v[204:211], v[42:49], v[114:117]
	s_setprio 0
	s_mov_b32 m0, s28
	s_barrier
	ds_read_b128 v[18:21], v191 offset:49152
	ds_read_b128 v[22:25], v191 offset:50176
	ds_read_b128 v[26:29], v191 offset:51200
	ds_read_b128 v[30:33], v191 offset:52224
	ds_read_b128 v[34:37], v191 offset:53248
	ds_read_b128 v[38:41], v191 offset:54272
	ds_read_b128 v[42:45], v191 offset:55296
	ds_read_b128 v[46:49], v191 offset:56320
	buffer_load_dwordx4 v214, s[40:43], s51 offen lds
	s_mov_b32 m0, s29
	s_nop 0
	buffer_load_dwordx4 v215, s[40:43], s51 offen lds
	s_barrier
	s_waitcnt lgkmcnt(0)
	s_setprio 1
	s_waitcnt lgkmcnt(6)
	v_mfma_f32_16x16x128_f8f6f4 v[110:113], v[2:9], v[18:25], v[110:113]
	v_mfma_f32_16x16x128_f8f6f4 v[102:105], v[10:17], v[18:25], v[102:105]
	s_waitcnt lgkmcnt(4)
	v_mfma_f32_16x16x128_f8f6f4 v[94:97], v[2:9], v[26:33], v[94:97]
	v_mfma_f32_16x16x128_f8f6f4 v[86:89], v[10:17], v[26:33], v[86:89]
	s_waitcnt lgkmcnt(2)
	v_mfma_f32_16x16x128_f8f6f4 v[78:81], v[2:9], v[34:41], v[78:81]
	v_mfma_f32_16x16x128_f8f6f4 v[70:73], v[10:17], v[34:41], v[70:73]
	s_waitcnt lgkmcnt(0)
	v_mfma_f32_16x16x128_f8f6f4 v[62:65], v[2:9], v[42:49], v[62:65]
	v_mfma_f32_16x16x128_f8f6f4 v[54:57], v[10:17], v[42:49], v[54:57]
	s_setprio 0
	s_barrier
	s_mov_b32 m0, s30
	s_add_i32 s7, s6, 0x20080
	buffer_load_dwordx4 v184, s[12:15], s7 offen lds
	s_add_i32 s6, s6, 0x30080
	s_mov_b32 m0, s31
	s_nop 0
	buffer_load_dwordx4 v184, s[12:15], s6 offen lds
	s_waitcnt vmcnt(6)
	s_barrier
	s_setprio 1
	v_mfma_f32_16x16x128_f8f6f4 v[106:109], v[196:203], v[18:25], v[106:109]
	v_mfma_f32_16x16x128_f8f6f4 v[98:101], v[204:211], v[18:25], v[98:101]
	v_mfma_f32_16x16x128_f8f6f4 v[90:93], v[196:203], v[26:33], v[90:93]
	v_mfma_f32_16x16x128_f8f6f4 v[82:85], v[204:211], v[26:33], v[82:85]
	v_mfma_f32_16x16x128_f8f6f4 v[74:77], v[196:203], v[34:41], v[74:77]
	v_mfma_f32_16x16x128_f8f6f4 v[66:69], v[204:211], v[34:41], v[66:69]
	v_mfma_f32_16x16x128_f8f6f4 v[58:61], v[196:203], v[42:49], v[58:61]
	v_mfma_f32_16x16x128_f8f6f4 v[50:53], v[204:211], v[42:49], v[50:53]
	s_setprio 0
	s_add_i32 s8, s8, 2
	s_addk_i32 s9, 0x100
	s_cmp_gt_u32 s8, 5
	s_barrier
	s_cbranch_scc1 .LBB0_766

.LBB0_830:
	s_cmp_gt_i32 s60, 10
	s_cselect_b64 s[4:5], -1, 0
	s_cmp_lt_i32 s61, 11
	s_cselect_b64 s[6:7], -1, 0
	s_or_b64 s[4:5], s[4:5], s[6:7]
	s_and_b64 vcc, exec, s[4:5]
	s_cbranch_vccnz .LBB0_895
	s_waitcnt vmcnt(0)
	v_mov_b32_e32 v2, v0
	s_cmpk_gt_i32 s2, 0x43f
	v_readfirstlane_b32 s3, v2
	s_cbranch_scc1 .LBB0_845
	v_bfe_i32 v4, v2, 27, 1
	v_lshlrev_b32_e32 v1, 4, v2
	v_lshrrev_b32_e32 v4, 22, v4
	v_add_u32_e32 v4, v1, v4
	v_and_b32_e32 v4, 0xfffffc00, v4
	v_sub_u32_e32 v1, v1, v4
	v_ashrrev_i32_e32 v3, 31, v2
	v_lshrrev_b32_e32 v4, 4, v1
	v_lshrrev_b32_e32 v3, 26, v3
	v_bitop3_b32 v1, v4, v1, 32 bitop3:0x6c
	s_add_u32 s8, s52, 0x6b00000
	v_add_u32_e32 v3, v2, v3
	v_ashrrev_i32_e32 v5, 31, v1
	s_addc_u32 s6, s53, 0
	v_ashrrev_i32_e32 v3, 6, v3
	v_lshrrev_b32_e32 v5, 26, v5
	s_ashr_i32 s20, s2, 31
	v_lshlrev_b32_e32 v4, 3, v3
	v_add_u32_e32 v5, v1, v5
	s_lshr_b32 s7, s20, 29
	v_and_b32_e32 v4, -16, v4
	v_ashrrev_i32_e32 v6, 6, v5
	s_add_i32 s7, s2, s7
	s_ashr_i32 s4, s3, 6
	v_add_u32_e32 v4, v6, v4
	v_and_b32_e32 v6, 3, v6
	s_mov_b32 s5, 0x3fffe0
	s_ashr_i32 s12, s7, 3
	s_and_b32 s7, s7, -8
	s_and_b32 s45, s71, 0xffff
	v_and_or_b32 v6, v4, s5, v6
	s_ashr_i32 s5, s3, 8
	s_and_b32 s9, s6, 0xffff
	s_lshl_b32 s6, s4, 10
	s_sub_i32 s7, s2, s7
	s_cmp_lt_i32 s7, 0
	s_movk_i32 s21, 0x89
	s_cselect_b32 s13, s21, 0x88
	s_mul_i32 s7, s13, s7
	s_add_i32 s7, s7, s12
	s_ashr_i32 s12, s7, 31
	s_lshr_b32 s12, s12, 27
	s_add_i32 s12, s7, s12
	s_ashr_i32 s13, s12, 5
	s_andn2_b32 s12, s12, 31
	s_sub_i32 s7, s7, s12
	s_bfe_i32 s12, s7, 0x80000
	s_bfe_u32 s12, s12, 0x3000c
	s_add_i32 s12, s7, s12
	s_bfe_i32 s14, s12, 0x80000
	s_and_b32 s12, s12, 0xf8
	s_sub_i32 s7, s7, s12
	s_lshl_b32 s13, s13, 3
	s_sext_i32_i8 s7, s7
	v_and_b32_e32 v5, 0xc0, v5
	s_add_i32 s73, s13, s7
	v_sub_u32_e32 v1, v1, v5
	v_mov_b32_e32 v5, 1
	s_mul_hi_i32 s7, s73, 0x78787879
	v_lshlrev_b32_e32 v3, 5, v3
	v_ashrrev_i16_sdwa v1, v5, sext(v1) dst_sel:DWORD dst_unused:UNUSED_PAD src0_sel:DWORD src1_sel:BYTE_0
	v_lshlrev_b32_e32 v5, 1, v4
	v_lshrrev_b32_e32 v7, 2, v4
	s_sext_i32_i16 s14, s14
	s_lshr_b32 s12, s7, 31
	s_lshr_b32 s7, s7, 3
	v_and_b32_e32 v3, 32, v3
	v_bfe_i32 v1, v1, 0, 16
	v_and_b32_e32 v5, 24, v5
	v_and_b32_e32 v7, 4, v7
	s_ashr_i32 s72, s14, 3
	s_add_i32 s7, s7, s12
	s_add_i32 s22, s6, 0
	s_mov_b32 s47, 0x20000
	s_brev_b32 s46, -2
	v_or3_b32 v5, v6, v7, v5
	v_add_lshl_u32 v3, v3, v1, 1
	s_lshl_b32 s7, s7, 20
	s_lshl_b32 s12, s72, 18
	s_add_i32 s23, s22, 0x10000
	v_lshl_add_u32 v134, v5, 10, v3
	s_mov_b32 s10, s46
	s_mov_b32 s11, s47
	s_add_i32 s78, s7, s12
	s_mov_b32 m0, s23
	s_add_i32 s24, s22, 0x12000
	buffer_load_dwordx4 v134, s[8:11], s78 offen lds
	s_or_b32 s6, s78, 0x10000
	s_mov_b32 m0, s24
	v_lshl_add_u32 v1, v4, 10, v3
	buffer_load_dwordx4 v134, s[8:11], s6 offen lds
	s_lshl_b32 s79, s73, 18
	s_mov_b32 m0, s22
	s_add_i32 s25, s22, 0x2000
	buffer_load_dwordx4 v1, s[44:47], s79 offen lds
	s_or_b32 s6, s79, 0x10000
	s_mov_b32 m0, s25
	s_add_i32 s26, s22, 0x14000
	buffer_load_dwordx4 v1, s[44:47], s6 offen lds
	s_or_b32 s6, s78, 0x20000
	s_mov_b32 m0, s26
	s_add_i32 s27, s22, 0x16000
	buffer_load_dwordx4 v134, s[8:11], s6 offen lds
	s_or_b32 s6, s78, 0x30000
	s_mov_b32 m0, s27
	s_add_i32 s28, s22, 0x4000
	buffer_load_dwordx4 v134, s[8:11], s6 offen lds
	s_or_b32 s6, s79, 0x20000
	s_mov_b32 m0, s28
	s_add_i32 s29, s22, 0x6000
	buffer_load_dwordx4 v1, s[44:47], s6 offen lds
	s_or_b32 s6, s79, 0x30000
	s_mov_b32 m0, s29
	s_cmp_lg_u32 s5, 1
	buffer_load_dwordx4 v1, s[44:47], s6 offen lds
	s_mov_b32 s30, 0
	s_cbranch_scc1 .LBB0_834
	s_barrier

.LBB0_840:
	ds_read_b128 v[142:145], v137
	ds_read_b128 v[146:149], v137 offset:1024
	ds_read_b128 v[150:153], v137 offset:2048
	ds_read_b128 v[154:157], v137 offset:3072
	s_add_i32 s10, s7, 0xfffd0080
	s_cmp_eq_u32 s79, 4
	s_cselect_b32 s87, s6, s10
	s_cselect_b32 s86, s58, s78
	s_or_b32 s88, s87, 0x80
	s_add_i32 s10, s7, 0xffff0000
	s_mov_b32 m0, s39
	ds_read_b128 v[158:161], v138
	ds_read_b128 v[162:165], v138 offset:1024
	ds_read_b128 v[166:169], v138 offset:2048
	ds_read_b128 v[170:173], v138 offset:3072
	ds_read_b128 v[174:177], v138 offset:4096
	ds_read_b128 v[178:181], v138 offset:5120
	ds_read_b128 v[182:185], v138 offset:6144
	ds_read_b128 v[186:189], v138 offset:7168
	buffer_load_dwordx4 v1, s[44:47], s10 offen lds
	s_mov_b32 m0, s41
	s_nop 0
	buffer_load_dwordx4 v1, s[44:47], s7 offen lds
	s_waitcnt lgkmcnt(8)
	s_barrier
	s_waitcnt lgkmcnt(0)
	s_setprio 1
	s_waitcnt lgkmcnt(4)
	v_mfma_f32_16x16x128_f8f6f4 v[114:117], v[142:149], v[166:173], v[114:117]
	v_mfma_f32_16x16x128_f8f6f4 v[106:109], v[150:157], v[166:173], v[106:109]
	s_waitcnt lgkmcnt(2)
	v_mfma_f32_16x16x128_f8f6f4 v[98:101], v[142:149], v[174:181], v[98:101]
	v_mfma_f32_16x16x128_f8f6f4 v[198:201], v[142:149], v[158:165], v[126:129]
	v_mfma_f32_16x16x128_f8f6f4 v[202:205], v[150:157], v[158:165], v[122:125]
	v_mfma_f32_16x16x128_f8f6f4 v[206:209], v[150:157], v[174:181], v[90:93]
	s_waitcnt lgkmcnt(0)
	v_mfma_f32_16x16x128_f8f6f4 v[210:213], v[142:149], v[182:189], v[82:85]
	v_mfma_f32_16x16x128_f8f6f4 v[214:217], v[150:157], v[182:189], v[74:77]
	s_setprio 0
	s_barrier
	s_mov_b32 m0, s23
	s_mov_b32 s10, s46
	s_mov_b32 s11, s47
	ds_read_b128 v[122:125], v139
	ds_read_b128 v[126:129], v139 offset:1024
	ds_read_b128 v[190:193], v139 offset:2048
	ds_read_b128 v[194:197], v139 offset:3072
	buffer_load_dwordx4 v134, s[8:11], s86 offen lds
	s_add_i32 s33, s86, 0x10000
	s_mov_b32 m0, s24
	s_nop 0
	buffer_load_dwordx4 v134, s[8:11], s33 offen lds
	s_barrier
	s_waitcnt lgkmcnt(0)
	s_setprio 1
	s_waitcnt lgkmcnt(2)
	v_mfma_f32_16x16x128_f8f6f4 v[118:121], v[122:129], v[158:165], v[118:121]
	s_waitcnt lgkmcnt(0)
	v_mfma_f32_16x16x128_f8f6f4 v[110:113], v[190:197], v[158:165], v[110:113]
	v_mfma_f32_16x16x128_f8f6f4 v[102:105], v[122:129], v[166:173], v[102:105]
	v_mfma_f32_16x16x128_f8f6f4 v[158:161], v[190:197], v[166:173], v[94:97]
	v_mfma_f32_16x16x128_f8f6f4 v[162:165], v[122:129], v[174:181], v[86:89]
	v_mfma_f32_16x16x128_f8f6f4 v[166:169], v[190:197], v[174:181], v[78:81]
	v_mfma_f32_16x16x128_f8f6f4 v[170:173], v[122:129], v[182:189], v[70:73]
	v_mfma_f32_16x16x128_f8f6f4 v[174:177], v[190:197], v[182:189], v[18:21]
	s_setprio 0
	s_mov_b32 m0, s22
	s_barrier
	ds_read_b128 v[66:69], v138 offset:16384
	s_nop 1
	ds_read_b128 v[70:73], v138 offset:17408
	ds_read_b128 v[74:77], v138 offset:18432
	ds_read_b128 v[78:81], v138 offset:19456
	ds_read_b128 v[82:85], v138 offset:20480
	ds_read_b128 v[86:89], v138 offset:21504
	ds_read_b128 v[90:93], v138 offset:22528
	ds_read_b128 v[94:97], v138 offset:23552
	buffer_load_dwordx4 v1, s[44:47], s87 offen lds
	s_add_i32 s33, s87, 0x10000
	s_mov_b32 m0, s25
	s_nop 0
	buffer_load_dwordx4 v1, s[44:47], s33 offen lds
	s_barrier
	s_waitcnt lgkmcnt(0)
	s_setprio 1
	s_waitcnt lgkmcnt(6)
	v_mfma_f32_16x16x128_f8f6f4 v[62:65], v[142:149], v[66:73], v[62:65]
	v_mfma_f32_16x16x128_f8f6f4 v[58:61], v[150:157], v[66:73], v[58:61]
	s_waitcnt lgkmcnt(4)
	v_mfma_f32_16x16x128_f8f6f4 v[50:53], v[142:149], v[74:81], v[50:53]
	s_waitcnt lgkmcnt(0)
	v_mfma_f32_16x16x128_f8f6f4 v[230:233], v[142:149], v[90:97], v[230:233]
	v_mfma_f32_16x16x128_f8f6f4 v[218:221], v[150:157], v[74:81], v[42:45]
	v_mfma_f32_16x16x128_f8f6f4 v[222:225], v[142:149], v[82:89], v[34:37]
	v_mfma_f32_16x16x128_f8f6f4 v[226:229], v[150:157], v[82:89], v[26:29]
	v_mfma_f32_16x16x128_f8f6f4 v[234:237], v[150:157], v[90:97], v[10:13]
	s_setprio 0
	s_barrier
	s_mov_b32 m0, s26
	s_add_i32 s33, s86, 0x20000
	buffer_load_dwordx4 v134, s[8:11], s33 offen lds
	s_add_i32 s33, s86, 0x30000
	s_mov_b32 m0, s27
	s_nop 0
	buffer_load_dwordx4 v134, s[8:11], s33 offen lds
	s_waitcnt vmcnt(6)
	s_barrier
	s_setprio 1
	v_mfma_f32_16x16x128_f8f6f4 v[54:57], v[122:129], v[66:73], v[54:57]
	v_mfma_f32_16x16x128_f8f6f4 v[238:241], v[190:197], v[66:73], v[46:49]
	v_mfma_f32_16x16x128_f8f6f4 v[242:245], v[122:129], v[74:81], v[38:41]
	v_mfma_f32_16x16x128_f8f6f4 v[246:249], v[190:197], v[74:81], v[30:33]
	v_mfma_f32_16x16x128_f8f6f4 v[250:253], v[122:129], v[82:89], v[22:25]
	v_mfma_f32_16x16x128_f8f6f4 v[130:133], v[190:197], v[82:89], v[14:17]
	v_mfma_f32_16x16x128_f8f6f4 v[66:69], v[122:129], v[90:97], v[6:9]
	v_mfma_f32_16x16x128_f8f6f4 v[190:193], v[190:197], v[90:97], v[2:5]
	s_setprio 0
	s_barrier
	s_nop 4
	ds_read_b128 v[2:5], v140
	ds_read_b128 v[6:9], v140 offset:1024
	ds_read_b128 v[10:13], v140 offset:2048
	ds_read_b128 v[14:17], v140 offset:3072
	s_mov_b32 m0, s28
	s_add_i32 s33, s87, 0x20000
	ds_read_b128 v[18:21], v138 offset:32768
	ds_read_b128 v[22:25], v138 offset:33792
	ds_read_b128 v[26:29], v138 offset:34816
	ds_read_b128 v[30:33], v138 offset:35840
	ds_read_b128 v[34:37], v138 offset:36864
	ds_read_b128 v[38:41], v138 offset:37888
	ds_read_b128 v[42:45], v138 offset:38912
	ds_read_b128 v[46:49], v138 offset:39936
	buffer_load_dwordx4 v1, s[44:47], s33 offen lds
	s_add_i32 s33, s87, 0x30000
	s_mov_b32 m0, s29
	s_nop 0
	buffer_load_dwordx4 v1, s[44:47], s33 offen lds
	s_waitcnt lgkmcnt(8)
	s_barrier
	s_waitcnt lgkmcnt(0)
	s_setprio 1
	s_waitcnt lgkmcnt(6)
	v_mfma_f32_16x16x128_f8f6f4 v[126:129], v[2:9], v[18:25], v[198:201]
	v_mfma_f32_16x16x128_f8f6f4 v[122:125], v[10:17], v[18:25], v[202:205]
	s_waitcnt lgkmcnt(4)
	v_mfma_f32_16x16x128_f8f6f4 v[114:117], v[2:9], v[26:33], v[114:117]
	v_mfma_f32_16x16x128_f8f6f4 v[106:109], v[10:17], v[26:33], v[106:109]
	s_waitcnt lgkmcnt(2)
	v_mfma_f32_16x16x128_f8f6f4 v[98:101], v[2:9], v[34:41], v[98:101]
	v_mfma_f32_16x16x128_f8f6f4 v[90:93], v[10:17], v[34:41], v[206:209]
	s_waitcnt lgkmcnt(0)
	v_mfma_f32_16x16x128_f8f6f4 v[82:85], v[2:9], v[42:49], v[210:213]
	v_mfma_f32_16x16x128_f8f6f4 v[74:77], v[10:17], v[42:49], v[214:217]
	s_setprio 0
	s_barrier
	s_mov_b32 m0, s31
	s_add_i32 s33, s86, 0x80
	ds_read_b128 v[142:145], v141
	ds_read_b128 v[146:149], v141 offset:1024
	ds_read_b128 v[150:153], v141 offset:2048
	ds_read_b128 v[154:157], v141 offset:3072
	buffer_load_dwordx4 v134, s[8:11], s33 offen lds
	s_add_i32 s33, s86, 0x10080
	s_mov_b32 m0, s34
	s_nop 0
	buffer_load_dwordx4 v134, s[8:11], s33 offen lds
	s_barrier
	s_waitcnt lgkmcnt(0)
	s_setprio 1
	s_waitcnt lgkmcnt(2)
	v_mfma_f32_16x16x128_f8f6f4 v[118:121], v[142:149], v[18:25], v[118:121]
	s_waitcnt lgkmcnt(0)
	v_mfma_f32_16x16x128_f8f6f4 v[110:113], v[150:157], v[18:25], v[110:113]
	v_mfma_f32_16x16x128_f8f6f4 v[102:105], v[142:149], v[26:33], v[102:105]
	v_mfma_f32_16x16x128_f8f6f4 v[94:97], v[150:157], v[26:33], v[158:161]
	v_mfma_f32_16x16x128_f8f6f4 v[86:89], v[142:149], v[34:41], v[162:165]
	v_mfma_f32_16x16x128_f8f6f4 v[78:81], v[150:157], v[34:41], v[166:169]
	v_mfma_f32_16x16x128_f8f6f4 v[70:73], v[142:149], v[42:49], v[170:173]
	v_mfma_f32_16x16x128_f8f6f4 v[18:21], v[150:157], v[42:49], v[174:177]
	s_setprio 0
	s_mov_b32 m0, s35
	s_barrier
	ds_read_b128 v[158:161], v138 offset:49152
	ds_read_b128 v[162:165], v138 offset:50176
	ds_read_b128 v[166:169], v138 offset:51200
	ds_read_b128 v[170:173], v138 offset:52224
	ds_read_b128 v[174:177], v138 offset:53248
	ds_read_b128 v[178:181], v138 offset:54272
	ds_read_b128 v[182:185], v138 offset:55296
	ds_read_b128 v[186:189], v138 offset:56320
	buffer_load_dwordx4 v1, s[44:47], s88 offen lds
	s_add_i32 s87, s87, 0x10080
	s_mov_b32 m0, s36
	s_nop 0
	buffer_load_dwordx4 v1, s[44:47], s87 offen lds
	s_barrier
	s_waitcnt lgkmcnt(0)
	s_setprio 1
	s_waitcnt lgkmcnt(6)
	v_mfma_f32_16x16x128_f8f6f4 v[62:65], v[2:9], v[158:165], v[62:65]
	v_mfma_f32_16x16x128_f8f6f4 v[58:61], v[10:17], v[158:165], v[58:61]
	s_waitcnt lgkmcnt(4)
	v_mfma_f32_16x16x128_f8f6f4 v[50:53], v[2:9], v[166:173], v[50:53]
	v_mfma_f32_16x16x128_f8f6f4 v[42:45], v[10:17], v[166:173], v[218:221]
	s_waitcnt lgkmcnt(2)
	v_mfma_f32_16x16x128_f8f6f4 v[34:37], v[2:9], v[174:181], v[222:225]
	v_mfma_f32_16x16x128_f8f6f4 v[26:29], v[10:17], v[174:181], v[226:229]
	s_waitcnt lgkmcnt(0)
	v_mfma_f32_16x16x128_f8f6f4 v[230:233], v[2:9], v[182:189], v[230:233]
	v_mfma_f32_16x16x128_f8f6f4 v[10:13], v[10:17], v[182:189], v[234:237]
	s_setprio 0
	s_barrier
	s_mov_b32 m0, s37
	s_add_i32 s33, s86, 0x20080
	buffer_load_dwordx4 v134, s[8:11], s33 offen lds
	s_add_i32 s86, s86, 0x30080
	s_mov_b32 m0, s38
	s_nop 0
	buffer_load_dwordx4 v134, s[8:11], s86 offen lds
	s_waitcnt vmcnt(6)
	s_barrier
	s_setprio 1
	v_mfma_f32_16x16x128_f8f6f4 v[54:57], v[142:149], v[158:165], v[54:57]
	v_mfma_f32_16x16x128_f8f6f4 v[46:49], v[150:157], v[158:165], v[238:241]
	v_mfma_f32_16x16x128_f8f6f4 v[38:41], v[142:149], v[166:173], v[242:245]
	v_mfma_f32_16x16x128_f8f6f4 v[30:33], v[150:157], v[166:173], v[246:249]
	v_mfma_f32_16x16x128_f8f6f4 v[22:25], v[142:149], v[174:181], v[250:253]
	v_mfma_f32_16x16x128_f8f6f4 v[14:17], v[150:157], v[174:181], v[130:133]
	v_mfma_f32_16x16x128_f8f6f4 v[6:9], v[142:149], v[182:189], v[66:69]
	v_mfma_f32_16x16x128_f8f6f4 v[2:5], v[150:157], v[182:189], v[190:193]
	s_setprio 0
	s_add_i32 s79, s79, 2
	s_addk_i32 s7, 0x100
	s_addk_i32 s78, 0x100
	s_cmp_gt_u32 s79, 5
	s_barrier
	s_cbranch_scc0 .LBB0_840
	v_pk_mul_f32 v[126:127], v[126:127], 0.5 op_sel_hi:[1,0]
	v_mov_b32_e32 v132, 0
	v_cvt_pk_fp8_f32 v132, v126, v127
	v_pk_mul_f32 v[122:123], v[122:123], 0.5 op_sel_hi:[1,0]
	v_mov_b32_e32 v133, 0
	v_cvt_pk_fp8_f32 v133, v122, v123
	v_pk_mul_f32 v[122:123], v[128:129], 0.5 op_sel_hi:[1,0]
	v_pk_mul_f32 v[118:119], v[118:119], 0.5 op_sel_hi:[1,0]
	v_cvt_pk_fp8_f32 v132, v122, v123 op_sel:[0,0,1]
	v_mov_b32_e32 v122, 0
	v_cvt_pk_fp8_f32 v122, v118, v119
	v_pk_mul_f32 v[114:115], v[114:115], 0.5 op_sel_hi:[1,0]
	v_mov_b32_e32 v118, 0
	v_cvt_pk_fp8_f32 v118, v114, v115
	v_pk_mul_f32 v[106:107], v[106:107], 0.5 op_sel_hi:[1,0]
	v_mov_b32_e32 v119, 0
	v_cvt_pk_fp8_f32 v119, v106, v107
	v_pk_mul_f32 v[106:107], v[116:117], 0.5 op_sel_hi:[1,0]
	v_pk_mul_f32 v[94:95], v[94:95], 0.5 op_sel_hi:[1,0]
	v_cvt_pk_fp8_f32 v118, v106, v107 op_sel:[0,0,1]
	v_mov_b32_e32 v107, 0
	v_cvt_pk_fp8_f32 v107, v94, v95
	v_pk_mul_f32 v[110:111], v[110:111], 0.5 op_sel_hi:[1,0]
	v_mov_b32_e32 v123, 0
	v_cvt_pk_fp8_f32 v123, v110, v111
	v_pk_mul_f32 v[96:97], v[96:97], 0.5 op_sel_hi:[1,0]
	v_pk_mul_f32 v[102:103], v[102:103], 0.5 op_sel_hi:[1,0]
	v_mov_b32_e32 v106, 0
	v_cvt_pk_fp8_f32 v107, v96, v97 op_sel:[0,0,1]
	v_pk_mul_f32 v[96:97], v[98:99], 0.5 op_sel_hi:[1,0]
	v_mov_b32_e32 v98, 0
	v_cvt_pk_fp8_f32 v106, v102, v103
	v_cvt_pk_fp8_f32 v98, v96, v97
	v_lshl_add_u32 v66, s73, 8, v135
	v_pk_mul_f32 v[112:113], v[112:113], 0.5 op_sel_hi:[1,0]
	v_pk_mul_f32 v[124:125], v[124:125], 0.5 op_sel_hi:[1,0]
	v_cvt_pk_fp8_f32 v123, v112, v113 op_sel:[0,0,1]
	v_or_b32_e32 v112, 16, v66
	v_pk_mul_f32 v[108:109], v[108:109], 0.5 op_sel_hi:[1,0]
	v_pk_mul_f32 v[90:91], v[90:91], 0.5 op_sel_hi:[1,0]
	v_mov_b32_e32 v99, 0
	v_ashrrev_i32_e32 v67, 31, v66
	v_cvt_pk_fp8_f32 v133, v124, v125 op_sel:[0,0,1]
	v_pk_mul_f32 v[110:111], v[120:121], 0.5 op_sel_hi:[1,0]
	v_ashrrev_i32_e32 v113, 31, v112
	v_cvt_pk_fp8_f32 v119, v108, v109 op_sel:[0,0,1]
	v_pk_mul_f32 v[94:95], v[104:105], 0.5 op_sel_hi:[1,0]
	v_cvt_pk_fp8_f32 v99, v90, v91
	v_pk_mul_f32 v[90:91], v[100:101], 0.5 op_sel_hi:[1,0]
	v_lshl_or_b32 v68, s72, 8, v136
	v_lshlrev_b64 v[130:131], 10, v[66:67]
	v_cvt_pk_fp8_f32 v122, v110, v111 op_sel:[0,0,1]
	v_lshlrev_b64 v[112:113], 10, v[112:113]
	v_cvt_pk_fp8_f32 v106, v94, v95 op_sel:[0,0,1]
	v_cvt_pk_fp8_f32 v98, v90, v91 op_sel:[0,0,1]
	v_pk_mul_f32 v[86:87], v[86:87], 0.5 op_sel_hi:[1,0]
	v_pk_mul_f32 v[78:79], v[78:79], 0.5 op_sel_hi:[1,0]
	v_mov_b32_e32 v90, 0
	v_mov_b32_e32 v91, 0
	v_ashrrev_i32_e32 v69, 31, v68
	v_lshl_add_u64 v[110:111], s[68:69], 0, v[130:131]
	v_lshl_add_u64 v[94:95], s[68:69], 0, v[112:113]
	v_cvt_pk_fp8_f32 v90, v86, v87
	v_cvt_pk_fp8_f32 v91, v78, v79
	v_lshl_add_u64 v[110:111], v[110:111], 0, v[68:69]
	v_lshl_add_u64 v[94:95], v[94:95], 0, v[68:69]
	global_store_dwordx2 v[110:111], v[132:133], off
	global_store_dwordx2 v[110:111], v[122:123], off offset:128
	global_store_dwordx2 v[94:95], v[118:119], off
	global_store_dwordx2 v[94:95], v[106:107], off offset:128
	v_or_b32_e32 v94, 32, v66
	v_pk_mul_f32 v[92:93], v[92:93], 0.5 op_sel_hi:[1,0]
	v_ashrrev_i32_e32 v95, 31, v94
	v_cvt_pk_fp8_f32 v99, v92, v93 op_sel:[0,0,1]
	v_pk_mul_f32 v[78:79], v[88:89], 0.5 op_sel_hi:[1,0]
	v_pk_mul_f32 v[80:81], v[80:81], 0.5 op_sel_hi:[1,0]
	v_lshlrev_b64 v[94:95], 10, v[94:95]
	v_cvt_pk_fp8_f32 v90, v78, v79 op_sel:[0,0,1]
	v_cvt_pk_fp8_f32 v91, v80, v81 op_sel:[0,0,1]
	v_lshl_add_u64 v[78:79], s[68:69], 0, v[94:95]
	v_lshl_add_u64 v[78:79], v[78:79], 0, v[68:69]
	global_store_dwordx2 v[78:79], v[98:99], off
	global_store_dwordx2 v[78:79], v[90:91], off offset:128
	v_pk_mul_f32 v[78:79], v[82:83], 0.5 op_sel_hi:[1,0]
	v_mov_b32_e32 v80, 0
	v_cvt_pk_fp8_f32 v80, v78, v79
	v_pk_mul_f32 v[74:75], v[74:75], 0.5 op_sel_hi:[1,0]
	v_mov_b32_e32 v81, 0
	v_cvt_pk_fp8_f32 v81, v74, v75
	v_pk_mul_f32 v[74:75], v[84:85], 0.5 op_sel_hi:[1,0]
	v_pk_mul_f32 v[18:19], v[18:19], 0.5 op_sel_hi:[1,0]
	v_cvt_pk_fp8_f32 v80, v74, v75 op_sel:[0,0,1]
	v_mov_b32_e32 v75, 0
	v_cvt_pk_fp8_f32 v75, v18, v19
	v_pk_mul_f32 v[20:21], v[20:21], 0.5 op_sel_hi:[1,0]
	v_pk_mul_f32 v[58:59], v[58:59], 0.5 op_sel_hi:[1,0]
	v_pk_mul_f32 v[70:71], v[70:71], 0.5 op_sel_hi:[1,0]
	v_cvt_pk_fp8_f32 v75, v20, v21 op_sel:[0,0,1]
	v_pk_mul_f32 v[20:21], v[62:63], 0.5 op_sel_hi:[1,0]
	v_mov_b32_e32 v62, 0
	v_cvt_pk_fp8_f32 v62, v20, v21
	v_mov_b32_e32 v63, 0
	v_pk_mul_f32 v[20:21], v[64:65], 0.5 op_sel_hi:[1,0]
	v_mov_b32_e32 v74, 0
	v_cvt_pk_fp8_f32 v63, v58, v59
	v_cvt_pk_fp8_f32 v62, v20, v21 op_sel:[0,0,1]
	v_pk_mul_f32 v[20:21], v[54:55], 0.5 op_sel_hi:[1,0]
	v_pk_mul_f32 v[46:47], v[46:47], 0.5 op_sel_hi:[1,0]
	v_mov_b32_e32 v54, 0
	v_mov_b32_e32 v55, 0
	v_cvt_pk_fp8_f32 v74, v70, v71
	v_cvt_pk_fp8_f32 v54, v20, v21
	v_cvt_pk_fp8_f32 v55, v46, v47
	v_or_b32_e32 v66, 48, v66
	v_pk_mul_f32 v[76:77], v[76:77], 0.5 op_sel_hi:[1,0]
	v_pk_mul_f32 v[58:59], v[60:61], 0.5 op_sel_hi:[1,0]
	v_ashrrev_i32_e32 v67, 31, v66
	v_cvt_pk_fp8_f32 v81, v76, v77 op_sel:[0,0,1]
	v_pk_mul_f32 v[18:19], v[72:73], 0.5 op_sel_hi:[1,0]
	v_cvt_pk_fp8_f32 v63, v58, v59 op_sel:[0,0,1]
	v_pk_mul_f32 v[20:21], v[56:57], 0.5 op_sel_hi:[1,0]
	v_pk_mul_f32 v[46:47], v[48:49], 0.5 op_sel_hi:[1,0]
	v_lshlrev_b64 v[66:67], 10, v[66:67]
	v_cvt_pk_fp8_f32 v74, v18, v19 op_sel:[0,0,1]
	v_cvt_pk_fp8_f32 v54, v20, v21 op_sel:[0,0,1]
	v_cvt_pk_fp8_f32 v55, v46, v47 op_sel:[0,0,1]
	v_lshl_add_u64 v[18:19], s[68:69], 0, v[66:67]
	v_add_co_u32_e32 v20, vcc, s47, v110
	v_lshl_add_u64 v[18:19], v[18:19], 0, v[68:69]
	s_nop 0
	v_addc_co_u32_e32 v21, vcc, 0, v111, vcc
	global_store_dwordx2 v[18:19], v[80:81], off
	global_store_dwordx2 v[18:19], v[74:75], off offset:128
	v_lshl_add_u64 v[18:19], v[110:111], 0, s[12:13]
	global_store_dwordx2 v[20:21], v[62:63], off
	global_store_dwordx2 v[18:19], v[54:55], off offset:128
	v_pk_mul_f32 v[20:21], v[50:51], 0.5 op_sel_hi:[1,0]
	v_mov_b32_e32 v46, 0
	v_cvt_pk_fp8_f32 v46, v20, v21
	v_pk_mul_f32 v[42:43], v[42:43], 0.5 op_sel_hi:[1,0]
	v_mov_b32_e32 v47, 0
	v_pk_mul_f32 v[20:21], v[52:53], 0.5 op_sel_hi:[1,0]
	v_cvt_pk_fp8_f32 v47, v42, v43
	v_cvt_pk_fp8_f32 v46, v20, v21 op_sel:[0,0,1]
	v_pk_mul_f32 v[20:21], v[38:39], 0.5 op_sel_hi:[1,0]
	v_pk_mul_f32 v[30:31], v[30:31], 0.5 op_sel_hi:[1,0]
	v_mov_b32_e32 v38, 0
	v_mov_b32_e32 v39, 0
	v_cvt_pk_fp8_f32 v38, v20, v21
	v_cvt_pk_fp8_f32 v39, v30, v31
	v_pk_mul_f32 v[42:43], v[44:45], 0.5 op_sel_hi:[1,0]
	v_pk_mul_f32 v[20:21], v[40:41], 0.5 op_sel_hi:[1,0]
	v_cvt_pk_fp8_f32 v47, v42, v43 op_sel:[0,0,1]
	v_pk_mul_f32 v[30:31], v[32:33], 0.5 op_sel_hi:[1,0]
	v_cvt_pk_fp8_f32 v38, v20, v21 op_sel:[0,0,1]
	v_cvt_pk_fp8_f32 v39, v30, v31 op_sel:[0,0,1]
	v_add_co_u32_e32 v20, vcc, s43, v110
	v_lshl_add_u64 v[18:19], v[110:111], 0, s[14:15]
	s_nop 0
	v_addc_co_u32_e32 v21, vcc, 0, v111, vcc
	global_store_dwordx2 v[20:21], v[46:47], off
	global_store_dwordx2 v[18:19], v[38:39], off offset:128
	v_pk_mul_f32 v[20:21], v[34:35], 0.5 op_sel_hi:[1,0]
	v_mov_b32_e32 v30, 0
	v_cvt_pk_fp8_f32 v30, v20, v21
	v_pk_mul_f32 v[26:27], v[26:27], 0.5 op_sel_hi:[1,0]
	v_mov_b32_e32 v31, 0
	v_pk_mul_f32 v[20:21], v[36:37], 0.5 op_sel_hi:[1,0]
	v_cvt_pk_fp8_f32 v31, v26, v27
	v_cvt_pk_fp8_f32 v30, v20, v21 op_sel:[0,0,1]
	v_pk_mul_f32 v[20:21], v[22:23], 0.5 op_sel_hi:[1,0]
	v_pk_mul_f32 v[14:15], v[14:15], 0.5 op_sel_hi:[1,0]
	v_mov_b32_e32 v22, 0
	v_mov_b32_e32 v23, 0
	v_cvt_pk_fp8_f32 v22, v20, v21
	v_cvt_pk_fp8_f32 v23, v14, v15
	v_pk_mul_f32 v[26:27], v[28:29], 0.5 op_sel_hi:[1,0]
	v_pk_mul_f32 v[14:15], v[24:25], 0.5 op_sel_hi:[1,0]
	v_cvt_pk_fp8_f32 v31, v26, v27 op_sel:[0,0,1]
	v_pk_mul_f32 v[16:17], v[16:17], 0.5 op_sel_hi:[1,0]
	v_cvt_pk_fp8_f32 v22, v14, v15 op_sel:[0,0,1]
	v_cvt_pk_fp8_f32 v23, v16, v17 op_sel:[0,0,1]
	v_add_co_u32_e32 v14, vcc, s49, v110
	v_lshl_add_u64 v[18:19], v[110:111], 0, s[16:17]
	s_nop 0
	v_addc_co_u32_e32 v15, vcc, 0, v111, vcc
	global_store_dwordx2 v[14:15], v[30:31], off
	global_store_dwordx2 v[18:19], v[22:23], off offset:128
	v_pk_mul_f32 v[16:17], v[230:231], 0.5 op_sel_hi:[1,0]
	v_mov_b32_e32 v18, 0
	v_cvt_pk_fp8_f32 v18, v16, v17
	v_pk_mul_f32 v[10:11], v[10:11], 0.5 op_sel_hi:[1,0]
	v_mov_b32_e32 v19, 0
	v_cvt_pk_fp8_f32 v19, v10, v11
	v_pk_mul_f32 v[10:11], v[232:233], 0.5 op_sel_hi:[1,0]
	v_pk_mul_f32 v[6:7], v[6:7], 0.5 op_sel_hi:[1,0]
	v_cvt_pk_fp8_f32 v18, v10, v11 op_sel:[0,0,1]
	v_pk_mul_f32 v[2:3], v[2:3], 0.5 op_sel_hi:[1,0]
	v_mov_b32_e32 v10, 0
	v_mov_b32_e32 v11, 0
	v_cvt_pk_fp8_f32 v10, v6, v7
	v_cvt_pk_fp8_f32 v11, v2, v3
	v_pk_mul_f32 v[12:13], v[12:13], 0.5 op_sel_hi:[1,0]
	v_pk_mul_f32 v[2:3], v[8:9], 0.5 op_sel_hi:[1,0]
	v_cvt_pk_fp8_f32 v19, v12, v13 op_sel:[0,0,1]
	v_pk_mul_f32 v[4:5], v[4:5], 0.5 op_sel_hi:[1,0]
	v_cvt_pk_fp8_f32 v10, v2, v3 op_sel:[0,0,1]
	v_cvt_pk_fp8_f32 v11, v4, v5 op_sel:[0,0,1]
	v_add_co_u32_e32 v2, vcc, s50, v110
	s_mov_b32 s72, s51
	s_nop 0
	v_addc_co_u32_e32 v3, vcc, 0, v111, vcc
	s_and_b64 vcc, exec, s[4:5]
	s_mov_b32 s73, s57
	s_mov_b32 s78, s58
	s_mov_b32 s79, s59
	v_lshl_add_u64 v[14:15], v[110:111], 0, s[18:19]
	global_store_dwordx2 v[2:3], v[18:19], off
	global_store_dwordx2 v[14:15], v[10:11], off offset:128
	s_cbranch_vccz .LBB0_835
	s_waitcnt vmcnt(0)
	s_cmpk_gt_u32 s3, 0xff
	s_cbranch_scc1 .LBB0_844
	s_barrier

.LBB0_1011:
	s_waitcnt vmcnt(0)
	v_mov_b32_e32 v2, v0
	s_barrier
	s_cmpk_gt_i32 s2, 0x65f
	v_readfirstlane_b32 s3, v2
	s_cbranch_scc1 .LBB0_1025
	v_bfe_i32 v4, v2, 27, 1
	v_lshlrev_b32_e32 v1, 4, v2
	v_lshrrev_b32_e32 v4, 22, v4
	v_add_u32_e32 v4, v1, v4
	v_and_b32_e32 v4, 0xfffffc00, v4
	v_sub_u32_e32 v1, v1, v4
	v_ashrrev_i32_e32 v3, 31, v2
	v_lshrrev_b32_e32 v4, 4, v1
	v_lshrrev_b32_e32 v3, 26, v3
	v_bitop3_b32 v1, v4, v1, 32 bitop3:0x6c
	v_add_u32_e32 v3, v2, v3
	v_ashrrev_i32_e32 v5, 31, v1
	s_add_u32 s8, s52, 0x1b00000
	v_ashrrev_i32_e32 v3, 6, v3
	v_lshrrev_b32_e32 v5, 26, v5
	s_addc_u32 s6, s53, 0
	v_lshlrev_b32_e32 v4, 3, v3
	v_add_u32_e32 v5, v1, v5
	s_ashr_i32 s12, s2, 31
	v_and_b32_e32 v4, -16, v4
	v_ashrrev_i32_e32 v6, 6, v5
	s_lshr_b32 s7, s12, 29
	v_readlane_b32 s10, v255, 8
	v_add_u32_e32 v4, v6, v4
	v_and_b32_e32 v6, 3, v6
	s_mov_b32 s5, 0x1fffe0
	s_add_i32 s7, s2, s7
	v_readlane_b32 s11, v255, 9
	v_and_or_b32 v6, v4, s5, v6
	s_ashr_i32 s5, s3, 6
	s_ashr_i32 s14, s7, 3
	s_and_b32 s7, s7, -8
	s_ashr_i32 s4, s3, 8
	s_and_b32 s41, s11, 0xffff
	s_and_b32 s9, s6, 0xffff
	s_lshl_b32 s6, s5, 10
	s_sub_i32 s7, s2, s7
	s_cmp_lt_i32 s7, 0
	s_movk_i32 s13, 0xcd
	s_cselect_b32 s15, s13, 0xcc
	s_mul_i32 s7, s15, s7
	s_add_i32 s7, s7, s14
	s_mul_hi_i32 s14, s7, 0x2aaaaaab
	s_lshr_b32 s15, s14, 31
	s_ashr_i32 s14, s14, 4
	s_add_i32 s14, s14, s15
	s_lshl_b32 s15, s14, 3
	s_mulk_i32 s14, 0x60
	s_sub_i32 s7, s7, s14
	s_bfe_i32 s14, s7, 0x80000
	s_bfe_u32 s14, s14, 0x3000c
	s_add_i32 s14, s7, s14
	s_bfe_i32 s16, s14, 0x80000
	s_and_b32 s14, s14, 0xf8
	s_sub_i32 s7, s7, s14
	s_sext_i32_i8 s7, s7
	s_add_i32 s45, s15, s7
	s_ashr_i32 s7, s45, 31
	v_and_b32_e32 v5, 0xc0, v5
	s_lshr_b32 s7, s7, 12
	v_sub_u32_e32 v1, v1, v5
	v_mov_b32_e32 v5, 1
	s_add_i32 s7, s45, s7
	v_lshlrev_b32_e32 v3, 5, v3
	v_ashrrev_i16_sdwa v1, v5, sext(v1) dst_sel:DWORD dst_unused:UNUSED_PAD src0_sel:DWORD src1_sel:BYTE_0
	v_lshlrev_b32_e32 v5, 1, v4
	v_lshrrev_b32_e32 v7, 2, v4
	s_sext_i32_i16 s16, s16
	s_ashr_i32 s7, s7, 20
	v_and_b32_e32 v3, 32, v3
	v_bfe_i32 v1, v1, 0, 16
	v_and_b32_e32 v5, 24, v5
	v_and_b32_e32 v7, 4, v7
	s_ashr_i32 s39, s16, 3
	s_mul_i32 s7, s7, 12
	s_add_i32 s14, s6, 0
	s_mov_b32 s43, 0x20000
	s_brev_b32 s42, -2
	v_or3_b32 v5, v6, v7, v5
	v_add_lshl_u32 v3, v3, v1, 1
	s_add_i32 s7, s7, s39
	s_add_i32 s15, s14, 0x10000
	v_lshl_add_u32 v138, v5, 11, v3
	s_mov_b32 s10, s42
	s_mov_b32 s11, s43
	s_lshl_b32 s46, s7, 19
	s_mov_b32 m0, s15
	s_add_i32 s16, s14, 0x12000
	buffer_load_dwordx4 v138, s[8:11], s46 offen lds
	s_or_b32 s6, s46, 0x20000
	s_mov_b32 m0, s16
	v_lshl_add_u32 v1, v4, 11, v3
	buffer_load_dwordx4 v138, s[8:11], s6 offen lds
	s_lshl_b32 s47, s45, 19
	s_mov_b32 m0, s14
	s_add_i32 s17, s14, 0x2000
	buffer_load_dwordx4 v1, s[40:43], s47 offen lds
	s_or_b32 s6, s47, 0x20000
	s_mov_b32 m0, s17
	s_add_i32 s18, s14, 0x14000
	buffer_load_dwordx4 v1, s[40:43], s6 offen lds
	s_or_b32 s6, s46, 0x40000
	s_mov_b32 m0, s18
	s_add_i32 s19, s14, 0x16000
	buffer_load_dwordx4 v138, s[8:11], s6 offen lds
	s_or_b32 s6, s46, 0x60000
	s_mov_b32 m0, s19
	s_add_i32 s20, s14, 0x4000
	buffer_load_dwordx4 v138, s[8:11], s6 offen lds
	s_or_b32 s6, s47, 0x40000
	s_mov_b32 m0, s20
	s_add_i32 s21, s14, 0x6000
	buffer_load_dwordx4 v1, s[40:43], s6 offen lds
	s_or_b32 s6, s47, 0x60000
	s_mov_b32 m0, s21
	s_cmp_lg_u32 s4, 1
	buffer_load_dwordx4 v1, s[40:43], s6 offen lds
	s_mov_b32 s22, 0
	s_cbranch_scc1 .LBB0_1014
	s_barrier

.LBB0_1020:
	ds_read_b128 v[134:137], v141
	ds_read_b128 v[146:149], v141 offset:1024
	ds_read_b128 v[150:153], v141 offset:2048
	ds_read_b128 v[154:157], v141 offset:3072
	s_add_i32 s10, s7, 0xfffa0080
	s_cmp_eq_u32 s47, 12
	s_cselect_b32 s50, s6, s10
	s_cselect_b32 s49, s37, s46
	s_or_b32 s51, s50, 0x80
	s_add_i32 s10, s7, 0xfffe0000
	s_mov_b32 m0, s29
	ds_read_b128 v[158:161], v142
	ds_read_b128 v[162:165], v142 offset:1024
	ds_read_b128 v[166:169], v142 offset:2048
	ds_read_b128 v[170:173], v142 offset:3072
	ds_read_b128 v[174:177], v142 offset:4096
	ds_read_b128 v[178:181], v142 offset:5120
	ds_read_b128 v[182:185], v142 offset:6144
	ds_read_b128 v[186:189], v142 offset:7168
	buffer_load_dwordx4 v1, s[40:43], s10 offen lds
	s_mov_b32 m0, s30
	s_nop 0
	buffer_load_dwordx4 v1, s[40:43], s7 offen lds
	s_waitcnt lgkmcnt(8)
	s_barrier
	s_waitcnt lgkmcnt(0)
	s_setprio 1
	s_waitcnt lgkmcnt(7)
	v_mfma_f32_16x16x32_bf16 v[126:129], v[134:137], v[158:161], v[126:129]
	v_mfma_f32_16x16x32_bf16 v[122:125], v[150:153], v[158:161], v[122:125]
	s_waitcnt lgkmcnt(5)
	v_mfma_f32_16x16x32_bf16 v[118:121], v[134:137], v[166:169], v[118:121]
	v_mfma_f32_16x16x32_bf16 v[110:113], v[150:153], v[166:169], v[110:113]
	s_waitcnt lgkmcnt(3)
	v_mfma_f32_16x16x32_bf16 v[102:105], v[134:137], v[174:177], v[102:105]
	v_mfma_f32_16x16x32_bf16 v[94:97], v[150:153], v[174:177], v[94:97]
	s_waitcnt lgkmcnt(1)
	v_mfma_f32_16x16x32_bf16 v[86:89], v[134:137], v[182:185], v[86:89]
	v_mfma_f32_16x16x32_bf16 v[78:81], v[150:153], v[182:185], v[78:81]
	v_mfma_f32_16x16x32_bf16 v[126:129], v[146:149], v[162:165], v[126:129]
	v_mfma_f32_16x16x32_bf16 v[122:125], v[154:157], v[162:165], v[122:125]
	v_mfma_f32_16x16x32_bf16 v[118:121], v[146:149], v[170:173], v[118:121]
	v_mfma_f32_16x16x32_bf16 v[110:113], v[154:157], v[170:173], v[110:113]
	v_mfma_f32_16x16x32_bf16 v[102:105], v[146:149], v[178:181], v[102:105]
	v_mfma_f32_16x16x32_bf16 v[94:97], v[154:157], v[178:181], v[94:97]
	s_waitcnt lgkmcnt(0)
	v_mfma_f32_16x16x32_bf16 v[86:89], v[146:149], v[186:189], v[86:89]
	v_mfma_f32_16x16x32_bf16 v[78:81], v[154:157], v[186:189], v[78:81]
	s_setprio 0
	s_barrier
	s_mov_b32 m0, s15
	s_mov_b32 s10, s42
	s_mov_b32 s11, s43
	ds_read_b128 v[190:193], v143
	ds_read_b128 v[194:197], v143 offset:1024
	ds_read_b128 v[198:201], v143 offset:2048
	ds_read_b128 v[202:205], v143 offset:3072
	buffer_load_dwordx4 v138, s[8:11], s49 offen lds
	s_add_i32 s33, s49, 0x20000
	s_mov_b32 m0, s16
	s_nop 0
	buffer_load_dwordx4 v138, s[8:11], s33 offen lds
	s_barrier
	s_waitcnt lgkmcnt(0)
	s_setprio 1
	s_waitcnt lgkmcnt(3)
	v_mfma_f32_16x16x32_bf16 v[114:117], v[190:193], v[158:161], v[114:117]
	s_waitcnt lgkmcnt(1)
	v_mfma_f32_16x16x32_bf16 v[106:109], v[198:201], v[158:161], v[106:109]
	v_mfma_f32_16x16x32_bf16 v[98:101], v[190:193], v[166:169], v[98:101]
	v_mfma_f32_16x16x32_bf16 v[90:93], v[198:201], v[166:169], v[90:93]
	v_mfma_f32_16x16x32_bf16 v[82:85], v[190:193], v[174:177], v[82:85]
	v_mfma_f32_16x16x32_bf16 v[74:77], v[198:201], v[174:177], v[74:77]
	v_mfma_f32_16x16x32_bf16 v[70:73], v[190:193], v[182:185], v[70:73]
	v_mfma_f32_16x16x32_bf16 v[66:69], v[198:201], v[182:185], v[66:69]
	v_mfma_f32_16x16x32_bf16 v[114:117], v[194:197], v[162:165], v[114:117]
	s_waitcnt lgkmcnt(0)
	v_mfma_f32_16x16x32_bf16 v[106:109], v[202:205], v[162:165], v[106:109]
	v_mfma_f32_16x16x32_bf16 v[98:101], v[194:197], v[170:173], v[98:101]
	v_mfma_f32_16x16x32_bf16 v[90:93], v[202:205], v[170:173], v[90:93]
	v_mfma_f32_16x16x32_bf16 v[82:85], v[194:197], v[178:181], v[82:85]
	v_mfma_f32_16x16x32_bf16 v[74:77], v[202:205], v[178:181], v[74:77]
	v_mfma_f32_16x16x32_bf16 v[70:73], v[194:197], v[186:189], v[70:73]
	v_mfma_f32_16x16x32_bf16 v[66:69], v[202:205], v[186:189], v[66:69]
	s_setprio 0
	s_mov_b32 m0, s14
	s_barrier
	ds_read_b128 v[158:161], v142 offset:16384
	ds_read_b128 v[162:165], v142 offset:17408
	ds_read_b128 v[166:169], v142 offset:18432
	ds_read_b128 v[170:173], v142 offset:19456
	ds_read_b128 v[174:177], v142 offset:20480
	ds_read_b128 v[178:181], v142 offset:21504
	ds_read_b128 v[182:185], v142 offset:22528
	ds_read_b128 v[186:189], v142 offset:23552
	buffer_load_dwordx4 v1, s[40:43], s50 offen lds
	s_add_i32 s33, s50, 0x20000
	s_mov_b32 m0, s17
	s_nop 0
	buffer_load_dwordx4 v1, s[40:43], s33 offen lds
	s_barrier
	s_waitcnt lgkmcnt(0)
	s_setprio 1
	s_waitcnt lgkmcnt(7)
	v_mfma_f32_16x16x32_bf16 v[62:65], v[134:137], v[158:161], v[62:65]
	v_mfma_f32_16x16x32_bf16 v[58:61], v[150:153], v[158:161], v[58:61]
	s_waitcnt lgkmcnt(5)
	v_mfma_f32_16x16x32_bf16 v[54:57], v[134:137], v[166:169], v[54:57]
	v_mfma_f32_16x16x32_bf16 v[46:49], v[150:153], v[166:169], v[46:49]
	s_waitcnt lgkmcnt(3)
	v_mfma_f32_16x16x32_bf16 v[38:41], v[134:137], v[174:177], v[38:41]
	v_mfma_f32_16x16x32_bf16 v[30:33], v[150:153], v[174:177], v[30:33]
	s_waitcnt lgkmcnt(1)
	v_mfma_f32_16x16x32_bf16 v[22:25], v[134:137], v[182:185], v[22:25]
	v_mfma_f32_16x16x32_bf16 v[14:17], v[150:153], v[182:185], v[14:17]
	v_mfma_f32_16x16x32_bf16 v[62:65], v[146:149], v[162:165], v[62:65]
	v_mfma_f32_16x16x32_bf16 v[58:61], v[154:157], v[162:165], v[58:61]
	v_mfma_f32_16x16x32_bf16 v[54:57], v[146:149], v[170:173], v[54:57]
	v_mfma_f32_16x16x32_bf16 v[46:49], v[154:157], v[170:173], v[46:49]
	v_mfma_f32_16x16x32_bf16 v[38:41], v[146:149], v[178:181], v[38:41]
	v_mfma_f32_16x16x32_bf16 v[30:33], v[154:157], v[178:181], v[30:33]
	s_waitcnt lgkmcnt(0)
	v_mfma_f32_16x16x32_bf16 v[22:25], v[146:149], v[186:189], v[22:25]
	v_mfma_f32_16x16x32_bf16 v[14:17], v[154:157], v[186:189], v[14:17]
	s_setprio 0
	s_barrier
	s_mov_b32 m0, s18
	s_add_i32 s33, s49, 0x40000
	buffer_load_dwordx4 v138, s[8:11], s33 offen lds
	s_add_i32 s33, s49, 0x60000
	s_mov_b32 m0, s19
	s_nop 0
	buffer_load_dwordx4 v138, s[8:11], s33 offen lds
	s_waitcnt vmcnt(6)
	s_barrier
	s_setprio 1
	v_mfma_f32_16x16x32_bf16 v[50:53], v[190:193], v[158:161], v[50:53]
	v_mfma_f32_16x16x32_bf16 v[42:45], v[198:201], v[158:161], v[42:45]
	v_mfma_f32_16x16x32_bf16 v[34:37], v[190:193], v[166:169], v[34:37]
	v_mfma_f32_16x16x32_bf16 v[26:29], v[198:201], v[166:169], v[26:29]
	v_mfma_f32_16x16x32_bf16 v[18:21], v[190:193], v[174:177], v[18:21]
	v_mfma_f32_16x16x32_bf16 v[10:13], v[198:201], v[174:177], v[10:13]
	v_mfma_f32_16x16x32_bf16 v[6:9], v[190:193], v[182:185], v[6:9]
	v_mfma_f32_16x16x32_bf16 v[2:5], v[198:201], v[182:185], v[2:5]
	v_mfma_f32_16x16x32_bf16 v[50:53], v[194:197], v[162:165], v[50:53]
	v_mfma_f32_16x16x32_bf16 v[42:45], v[202:205], v[162:165], v[42:45]
	v_mfma_f32_16x16x32_bf16 v[34:37], v[194:197], v[170:173], v[34:37]
	v_mfma_f32_16x16x32_bf16 v[26:29], v[202:205], v[170:173], v[26:29]
	v_mfma_f32_16x16x32_bf16 v[18:21], v[194:197], v[178:181], v[18:21]
	v_mfma_f32_16x16x32_bf16 v[10:13], v[202:205], v[178:181], v[10:13]
	v_mfma_f32_16x16x32_bf16 v[6:9], v[194:197], v[186:189], v[6:9]
	v_mfma_f32_16x16x32_bf16 v[2:5], v[202:205], v[186:189], v[2:5]
	s_setprio 0
	s_barrier
	ds_read_b128 v[134:137], v144
	ds_read_b128 v[146:149], v144 offset:1024
	ds_read_b128 v[150:153], v144 offset:2048
	ds_read_b128 v[154:157], v144 offset:3072
	s_mov_b32 m0, s20
	s_add_i32 s33, s50, 0x40000
	ds_read_b128 v[158:161], v142 offset:32768
	ds_read_b128 v[162:165], v142 offset:33792
	ds_read_b128 v[166:169], v142 offset:34816
	ds_read_b128 v[170:173], v142 offset:35840
	ds_read_b128 v[174:177], v142 offset:36864
	ds_read_b128 v[178:181], v142 offset:37888
	ds_read_b128 v[182:185], v142 offset:38912
	ds_read_b128 v[186:189], v142 offset:39936
	buffer_load_dwordx4 v1, s[40:43], s33 offen lds
	s_add_i32 s33, s50, 0x60000
	s_mov_b32 m0, s21
	s_nop 0
	buffer_load_dwordx4 v1, s[40:43], s33 offen lds
	s_waitcnt lgkmcnt(8)
	s_barrier
	s_waitcnt lgkmcnt(0)
	s_setprio 1
	s_waitcnt lgkmcnt(7)
	v_mfma_f32_16x16x32_bf16 v[126:129], v[134:137], v[158:161], v[126:129]
	v_mfma_f32_16x16x32_bf16 v[122:125], v[150:153], v[158:161], v[122:125]
	s_waitcnt lgkmcnt(5)
	v_mfma_f32_16x16x32_bf16 v[118:121], v[134:137], v[166:169], v[118:121]
	v_mfma_f32_16x16x32_bf16 v[110:113], v[150:153], v[166:169], v[110:113]
	s_waitcnt lgkmcnt(3)
	v_mfma_f32_16x16x32_bf16 v[102:105], v[134:137], v[174:177], v[102:105]
	v_mfma_f32_16x16x32_bf16 v[94:97], v[150:153], v[174:177], v[94:97]
	s_waitcnt lgkmcnt(1)
	v_mfma_f32_16x16x32_bf16 v[86:89], v[134:137], v[182:185], v[86:89]
	v_mfma_f32_16x16x32_bf16 v[78:81], v[150:153], v[182:185], v[78:81]
	v_mfma_f32_16x16x32_bf16 v[126:129], v[146:149], v[162:165], v[126:129]
	v_mfma_f32_16x16x32_bf16 v[122:125], v[154:157], v[162:165], v[122:125]
	v_mfma_f32_16x16x32_bf16 v[118:121], v[146:149], v[170:173], v[118:121]
	v_mfma_f32_16x16x32_bf16 v[110:113], v[154:157], v[170:173], v[110:113]
	v_mfma_f32_16x16x32_bf16 v[102:105], v[146:149], v[178:181], v[102:105]
	v_mfma_f32_16x16x32_bf16 v[94:97], v[154:157], v[178:181], v[94:97]
	s_waitcnt lgkmcnt(0)
	v_mfma_f32_16x16x32_bf16 v[86:89], v[146:149], v[186:189], v[86:89]
	v_mfma_f32_16x16x32_bf16 v[78:81], v[154:157], v[186:189], v[78:81]
	s_setprio 0
	s_barrier
	s_mov_b32 m0, s23
	s_or_b32 s33, s49, 0x80
	ds_read_b128 v[190:193], v145
	ds_read_b128 v[194:197], v145 offset:1024
	ds_read_b128 v[198:201], v145 offset:2048
	ds_read_b128 v[202:205], v145 offset:3072
	buffer_load_dwordx4 v138, s[8:11], s33 offen lds
	s_add_i32 s33, s49, 0x20080
	s_mov_b32 m0, s24
	s_nop 0
	buffer_load_dwordx4 v138, s[8:11], s33 offen lds
	s_barrier
	s_waitcnt lgkmcnt(0)
	s_setprio 1
	s_waitcnt lgkmcnt(3)
	v_mfma_f32_16x16x32_bf16 v[114:117], v[190:193], v[158:161], v[114:117]
	s_waitcnt lgkmcnt(1)
	v_mfma_f32_16x16x32_bf16 v[106:109], v[198:201], v[158:161], v[106:109]
	v_mfma_f32_16x16x32_bf16 v[98:101], v[190:193], v[166:169], v[98:101]
	v_mfma_f32_16x16x32_bf16 v[90:93], v[198:201], v[166:169], v[90:93]
	v_mfma_f32_16x16x32_bf16 v[82:85], v[190:193], v[174:177], v[82:85]
	v_mfma_f32_16x16x32_bf16 v[74:77], v[198:201], v[174:177], v[74:77]
	v_mfma_f32_16x16x32_bf16 v[70:73], v[190:193], v[182:185], v[70:73]
	v_mfma_f32_16x16x32_bf16 v[66:69], v[198:201], v[182:185], v[66:69]
	v_mfma_f32_16x16x32_bf16 v[114:117], v[194:197], v[162:165], v[114:117]
	s_waitcnt lgkmcnt(0)
	v_mfma_f32_16x16x32_bf16 v[106:109], v[202:205], v[162:165], v[106:109]
	v_mfma_f32_16x16x32_bf16 v[98:101], v[194:197], v[170:173], v[98:101]
	v_mfma_f32_16x16x32_bf16 v[90:93], v[202:205], v[170:173], v[90:93]
	v_mfma_f32_16x16x32_bf16 v[82:85], v[194:197], v[178:181], v[82:85]
	v_mfma_f32_16x16x32_bf16 v[74:77], v[202:205], v[178:181], v[74:77]
	v_mfma_f32_16x16x32_bf16 v[70:73], v[194:197], v[186:189], v[70:73]
	v_mfma_f32_16x16x32_bf16 v[66:69], v[202:205], v[186:189], v[66:69]
	s_setprio 0
	s_mov_b32 m0, s25
	s_barrier
	ds_read_b128 v[158:161], v142 offset:49152
	ds_read_b128 v[162:165], v142 offset:50176
	ds_read_b128 v[166:169], v142 offset:51200
	ds_read_b128 v[170:173], v142 offset:52224
	ds_read_b128 v[174:177], v142 offset:53248
	ds_read_b128 v[178:181], v142 offset:54272
	ds_read_b128 v[182:185], v142 offset:55296
	ds_read_b128 v[186:189], v142 offset:56320
	buffer_load_dwordx4 v1, s[40:43], s51 offen lds
	s_add_i32 s50, s50, 0x20080
	s_mov_b32 m0, s26
	s_nop 0
	buffer_load_dwordx4 v1, s[40:43], s50 offen lds
	s_barrier
	s_waitcnt lgkmcnt(0)
	s_setprio 1
	s_waitcnt lgkmcnt(7)
	v_mfma_f32_16x16x32_bf16 v[62:65], v[134:137], v[158:161], v[62:65]
	v_mfma_f32_16x16x32_bf16 v[58:61], v[150:153], v[158:161], v[58:61]
	s_waitcnt lgkmcnt(5)
	v_mfma_f32_16x16x32_bf16 v[54:57], v[134:137], v[166:169], v[54:57]
	v_mfma_f32_16x16x32_bf16 v[46:49], v[150:153], v[166:169], v[46:49]
	s_waitcnt lgkmcnt(3)
	v_mfma_f32_16x16x32_bf16 v[38:41], v[134:137], v[174:177], v[38:41]
	v_mfma_f32_16x16x32_bf16 v[30:33], v[150:153], v[174:177], v[30:33]
	s_waitcnt lgkmcnt(1)
	v_mfma_f32_16x16x32_bf16 v[22:25], v[134:137], v[182:185], v[22:25]
	v_mfma_f32_16x16x32_bf16 v[14:17], v[150:153], v[182:185], v[14:17]
	v_mfma_f32_16x16x32_bf16 v[62:65], v[146:149], v[162:165], v[62:65]
	v_mfma_f32_16x16x32_bf16 v[58:61], v[154:157], v[162:165], v[58:61]
	v_mfma_f32_16x16x32_bf16 v[54:57], v[146:149], v[170:173], v[54:57]
	v_mfma_f32_16x16x32_bf16 v[46:49], v[154:157], v[170:173], v[46:49]
	v_mfma_f32_16x16x32_bf16 v[38:41], v[146:149], v[178:181], v[38:41]
	v_mfma_f32_16x16x32_bf16 v[30:33], v[154:157], v[178:181], v[30:33]
	s_waitcnt lgkmcnt(0)
	v_mfma_f32_16x16x32_bf16 v[22:25], v[146:149], v[186:189], v[22:25]
	v_mfma_f32_16x16x32_bf16 v[14:17], v[154:157], v[186:189], v[14:17]
	s_setprio 0
	s_barrier
	s_mov_b32 m0, s27
	s_add_i32 s33, s49, 0x40080
	buffer_load_dwordx4 v138, s[8:11], s33 offen lds
	s_add_i32 s49, s49, 0x60080
	s_mov_b32 m0, s28
	s_nop 0
	buffer_load_dwordx4 v138, s[8:11], s49 offen lds
	s_waitcnt vmcnt(6)
	s_barrier
	s_setprio 1
	v_mfma_f32_16x16x32_bf16 v[50:53], v[190:193], v[158:161], v[50:53]
	v_mfma_f32_16x16x32_bf16 v[42:45], v[198:201], v[158:161], v[42:45]
	v_mfma_f32_16x16x32_bf16 v[34:37], v[190:193], v[166:169], v[34:37]
	v_mfma_f32_16x16x32_bf16 v[26:29], v[198:201], v[166:169], v[26:29]
	v_mfma_f32_16x16x32_bf16 v[18:21], v[190:193], v[174:177], v[18:21]
	v_mfma_f32_16x16x32_bf16 v[10:13], v[198:201], v[174:177], v[10:13]
	v_mfma_f32_16x16x32_bf16 v[6:9], v[190:193], v[182:185], v[6:9]
	v_mfma_f32_16x16x32_bf16 v[2:5], v[198:201], v[182:185], v[2:5]
	v_mfma_f32_16x16x32_bf16 v[50:53], v[194:197], v[162:165], v[50:53]
	v_mfma_f32_16x16x32_bf16 v[42:45], v[202:205], v[162:165], v[42:45]
	v_mfma_f32_16x16x32_bf16 v[34:37], v[194:197], v[170:173], v[34:37]
	v_mfma_f32_16x16x32_bf16 v[26:29], v[202:205], v[170:173], v[26:29]
	v_mfma_f32_16x16x32_bf16 v[18:21], v[194:197], v[178:181], v[18:21]
	v_mfma_f32_16x16x32_bf16 v[10:13], v[202:205], v[178:181], v[10:13]
	v_mfma_f32_16x16x32_bf16 v[6:9], v[194:197], v[186:189], v[6:9]
	v_mfma_f32_16x16x32_bf16 v[2:5], v[202:205], v[186:189], v[2:5]
	s_setprio 0
	s_add_i32 s47, s47, 2
	s_addk_i32 s7, 0x100
	s_addk_i32 s46, 0x100
	s_cmp_gt_u32 s47, 13
	s_barrier
	s_cbranch_scc0 .LBB0_1020
	v_lshl_or_b32 v136, s39, 8, v140
	v_lshl_add_u32 v148, s45, 8, v139
	v_ashrrev_i32_e32 v137, 31, v136
	v_mov_b64_e32 v[134:135], s[82:83]
	v_mad_i64_i32 v[146:147], s[6:7], v148, s34, v[134:135]
	v_lshlrev_b64 v[136:137], 1, v[136:137]
	v_lshl_add_u64 v[146:147], v[146:147], 0, v[136:137]
	v_cvt_pk_bf16_f32 v126, v126, v127
	v_cvt_pk_bf16_f32 v127, v128, v129
	v_cvt_pk_bf16_f32 v128, v122, v123
	v_cvt_pk_bf16_f32 v129, v124, v125
	global_store_dwordx4 v[146:147], v[126:129], off
	v_cvt_pk_bf16_f32 v114, v114, v115
	v_cvt_pk_bf16_f32 v115, v116, v117
	v_cvt_pk_bf16_f32 v116, v106, v107
	v_or_b32_e32 v106, 16, v148
	v_mad_i64_i32 v[106:107], s[6:7], v106, s34, v[134:135]
	v_cvt_pk_bf16_f32 v117, v108, v109
	global_store_dwordx4 v[146:147], v[114:117], off offset:256
	s_and_b64 vcc, exec, s[4:5]
	s_mov_b32 s39, s35
	v_lshl_add_u64 v[114:115], v[106:107], 0, v[136:137]
	v_cvt_pk_bf16_f32 v106, v118, v119
	v_cvt_pk_bf16_f32 v107, v120, v121
	v_cvt_pk_bf16_f32 v108, v110, v111
	v_cvt_pk_bf16_f32 v109, v112, v113
	global_store_dwordx4 v[114:115], v[106:109], off
	v_cvt_pk_bf16_f32 v98, v98, v99
	v_cvt_pk_bf16_f32 v99, v100, v101
	v_cvt_pk_bf16_f32 v100, v90, v91
	v_or_b32_e32 v90, 32, v148
	v_mad_i64_i32 v[90:91], s[6:7], v90, s34, v[134:135]
	v_cvt_pk_bf16_f32 v101, v92, v93
	global_store_dwordx4 v[114:115], v[98:101], off offset:256
	s_mov_b32 s45, s36
	s_mov_b32 s46, s37
	v_lshl_add_u64 v[98:99], v[90:91], 0, v[136:137]
	v_cvt_pk_bf16_f32 v90, v102, v103
	v_cvt_pk_bf16_f32 v91, v104, v105
	v_cvt_pk_bf16_f32 v92, v94, v95
	v_cvt_pk_bf16_f32 v93, v96, v97
	global_store_dwordx4 v[98:99], v[90:93], off
	v_cvt_pk_bf16_f32 v82, v82, v83
	v_cvt_pk_bf16_f32 v83, v84, v85
	v_cvt_pk_bf16_f32 v84, v74, v75
	v_or_b32_e32 v74, 48, v148
	v_mad_i64_i32 v[74:75], s[6:7], v74, s34, v[134:135]
	v_cvt_pk_bf16_f32 v85, v76, v77
	global_store_dwordx4 v[98:99], v[82:85], off offset:256
	s_mov_b32 s47, s38
	s_nop 0
	v_lshl_add_u64 v[82:83], v[74:75], 0, v[136:137]
	v_cvt_pk_bf16_f32 v74, v86, v87
	v_cvt_pk_bf16_f32 v75, v88, v89
	v_cvt_pk_bf16_f32 v76, v78, v79
	v_cvt_pk_bf16_f32 v77, v80, v81
	global_store_dwordx4 v[82:83], v[74:77], off
	v_cvt_pk_bf16_f32 v70, v70, v71
	v_cvt_pk_bf16_f32 v71, v72, v73
	v_cvt_pk_bf16_f32 v72, v66, v67
	v_add_u32_e32 v66, 0x80, v148
	v_mad_i64_i32 v[66:67], s[6:7], v66, s34, v[134:135]
	v_lshl_add_u64 v[66:67], v[66:67], 0, v[136:137]
	v_cvt_pk_bf16_f32 v73, v68, v69
	global_store_dwordx4 v[82:83], v[70:73], off offset:256
	v_cvt_pk_bf16_f32 v62, v62, v63
	v_cvt_pk_bf16_f32 v63, v64, v65
	v_cvt_pk_bf16_f32 v64, v58, v59
	v_cvt_pk_bf16_f32 v65, v60, v61
	global_store_dwordx4 v[66:67], v[62:65], off
	v_cvt_pk_bf16_f32 v50, v50, v51
	v_cvt_pk_bf16_f32 v51, v52, v53
	v_cvt_pk_bf16_f32 v52, v42, v43
	v_add_u32_e32 v42, 0x90, v148
	v_mad_i64_i32 v[42:43], s[6:7], v42, s34, v[134:135]
	v_cvt_pk_bf16_f32 v53, v44, v45
	global_store_dwordx4 v[66:67], v[50:53], off offset:256
	s_nop 1
	v_lshl_add_u64 v[50:51], v[42:43], 0, v[136:137]
	v_cvt_pk_bf16_f32 v42, v54, v55
	v_cvt_pk_bf16_f32 v43, v56, v57
	v_cvt_pk_bf16_f32 v44, v46, v47
	v_cvt_pk_bf16_f32 v45, v48, v49
	global_store_dwordx4 v[50:51], v[42:45], off
	v_cvt_pk_bf16_f32 v34, v34, v35
	v_cvt_pk_bf16_f32 v35, v36, v37
	v_cvt_pk_bf16_f32 v36, v26, v27
	v_add_u32_e32 v26, 0xa0, v148
	v_mad_i64_i32 v[26:27], s[6:7], v26, s34, v[134:135]
	v_cvt_pk_bf16_f32 v37, v28, v29
	global_store_dwordx4 v[50:51], v[34:37], off offset:256
	s_nop 1
	v_lshl_add_u64 v[34:35], v[26:27], 0, v[136:137]
	v_cvt_pk_bf16_f32 v26, v38, v39
	v_cvt_pk_bf16_f32 v27, v40, v41
	v_cvt_pk_bf16_f32 v28, v30, v31
	v_cvt_pk_bf16_f32 v29, v32, v33
	global_store_dwordx4 v[34:35], v[26:29], off
	v_cvt_pk_bf16_f32 v18, v18, v19
	v_cvt_pk_bf16_f32 v19, v20, v21
	v_cvt_pk_bf16_f32 v20, v10, v11
	v_add_u32_e32 v10, 0xb0, v148
	v_mad_i64_i32 v[10:11], s[6:7], v10, s34, v[134:135]
	v_cvt_pk_bf16_f32 v21, v12, v13
	global_store_dwordx4 v[34:35], v[18:21], off offset:256
	s_nop 1
	v_lshl_add_u64 v[18:19], v[10:11], 0, v[136:137]
	v_cvt_pk_bf16_f32 v10, v22, v23
	v_cvt_pk_bf16_f32 v11, v24, v25
	v_cvt_pk_bf16_f32 v12, v14, v15
	v_cvt_pk_bf16_f32 v13, v16, v17
	global_store_dwordx4 v[18:19], v[10:13], off
	v_cvt_pk_bf16_f32 v6, v6, v7
	v_cvt_pk_bf16_f32 v7, v8, v9
	v_cvt_pk_bf16_f32 v8, v2, v3
	v_cvt_pk_bf16_f32 v9, v4, v5
	global_store_dwordx4 v[18:19], v[6:9], off offset:256
	s_cbranch_vccz .LBB0_1015
	s_waitcnt vmcnt(0)
	s_cmpk_gt_u32 s3, 0xff
	s_cbranch_scc1 .LBB0_1024
	s_barrier

.LBB0_1323:
	s_waitcnt vmcnt(0)
	v_mov_b32_e32 v2, v0
	s_barrier
	s_cmpk_gt_i32 s2, 0x21f
	v_readfirstlane_b32 s3, v2
	s_cbranch_scc1 .LBB0_1340
	v_bfe_i32 v4, v2, 27, 1
	v_lshlrev_b32_e32 v1, 4, v2
	v_lshrrev_b32_e32 v4, 22, v4
	v_add_u32_e32 v4, v1, v4
	v_and_b32_e32 v4, 0xfffffc00, v4
	v_sub_u32_e32 v1, v1, v4
	v_ashrrev_i32_e32 v3, 31, v2
	v_lshrrev_b32_e32 v4, 4, v1
	v_lshrrev_b32_e32 v3, 26, v3
	v_bitop3_b32 v1, v4, v1, 32 bitop3:0x6c
	s_add_u32 s8, s52, 0x2100000
	v_add_u32_e32 v3, v2, v3
	v_ashrrev_i32_e32 v5, 31, v1
	s_addc_u32 s6, s53, 0
	v_ashrrev_i32_e32 v3, 6, v3
	v_lshrrev_b32_e32 v5, 26, v5
	s_ashr_i32 s14, s2, 31
	v_lshlrev_b32_e32 v4, 3, v3
	v_add_u32_e32 v5, v1, v5
	s_lshr_b32 s7, s14, 29
	v_readlane_b32 s10, v255, 11
	v_and_b32_e32 v4, -16, v4
	v_ashrrev_i32_e32 v6, 6, v5
	s_add_i32 s7, s2, s7
	s_ashr_i32 s4, s3, 6
	v_readlane_b32 s11, v255, 12
	v_add_u32_e32 v4, v6, v4
	v_and_b32_e32 v6, 3, v6
	s_mov_b32 s5, 0x1fffe0
	s_ashr_i32 s12, s7, 3
	s_and_b32 s7, s7, -8
	s_and_b32 s49, s11, 0xffff
	v_and_or_b32 v6, v4, s5, v6
	s_ashr_i32 s5, s3, 8
	s_and_b32 s9, s6, 0xffff
	s_lshl_b32 s6, s4, 10
	s_sub_i32 s7, s2, s7
	s_cmp_lt_i32 s7, 0
	s_movk_i32 s15, 0x45
	s_cselect_b32 s13, s15, 0x44
	s_mul_i32 s7, s13, s7
	s_add_i32 s7, s7, s12
	s_ashr_i32 s12, s7, 31
	s_lshr_b32 s12, s12, 27
	s_add_i32 s12, s7, s12
	s_ashr_i32 s13, s12, 5
	s_andn2_b32 s12, s12, 31
	s_sub_i32 s7, s7, s12
	s_bfe_i32 s12, s7, 0x80000
	s_bfe_u32 s12, s12, 0x3000c
	s_add_i32 s12, s7, s12
	s_bfe_i32 s16, s12, 0x80000
	s_and_b32 s12, s12, 0xf8
	s_sub_i32 s7, s7, s12
	s_lshl_b32 s13, s13, 3
	s_sext_i32_i8 s7, s7
	s_add_i32 s72, s13, s7
	v_and_b32_e32 v5, 0xc0, v5
	s_ashr_i32 s7, s72, 31
	v_sub_u32_e32 v1, v1, v5
	v_mov_b32_e32 v5, 1
	s_lshr_b32 s7, s7, 12
	v_lshlrev_b32_e32 v3, 5, v3
	v_ashrrev_i16_sdwa v1, v5, sext(v1) dst_sel:DWORD dst_unused:UNUSED_PAD src0_sel:DWORD src1_sel:BYTE_0
	v_lshlrev_b32_e32 v5, 1, v4
	v_lshrrev_b32_e32 v7, 2, v4
	s_sext_i32_i16 s16, s16
	s_add_i32 s7, s72, s7
	v_and_b32_e32 v3, 32, v3
	v_bfe_i32 v1, v1, 0, 16
	v_and_b32_e32 v5, 24, v5
	v_and_b32_e32 v7, 4, v7
	s_ashr_i32 s73, s16, 3
	s_lshl_b32 s7, s7, 1
	s_add_i32 s16, s6, 0
	s_mov_b32 s51, 0x20000
	s_brev_b32 s50, -2
	v_or3_b32 v5, v6, v7, v5
	v_add_lshl_u32 v3, v3, v1, 1
	s_and_b32 s7, s7, 0xffe00000
	s_lshl_b32 s12, s73, 19
	s_add_i32 s17, s16, 0x10000
	v_lshl_add_u32 v192, v5, 11, v3
	s_mov_b32 s10, s50
	s_mov_b32 s11, s51
	s_add_i32 s12, s7, s12
	s_mov_b32 m0, s17
	s_add_i32 s18, s16, 0x12000
	buffer_load_dwordx4 v192, s[8:11], s12 offen lds
	s_or_b32 s6, s12, 0x20000
	s_mov_b32 m0, s18
	v_lshl_add_u32 v1, v4, 11, v3
	buffer_load_dwordx4 v192, s[8:11], s6 offen lds
	s_lshl_b32 s13, s72, 19
	s_mov_b32 m0, s16
	s_add_i32 s19, s16, 0x2000
	buffer_load_dwordx4 v1, s[48:51], s13 offen lds
	s_or_b32 s6, s13, 0x20000
	s_mov_b32 m0, s19
	s_add_i32 s20, s16, 0x14000
	buffer_load_dwordx4 v1, s[48:51], s6 offen lds
	s_or_b32 s6, s12, 0x40000
	s_mov_b32 m0, s20
	s_add_i32 s21, s16, 0x16000
	buffer_load_dwordx4 v192, s[8:11], s6 offen lds
	s_or_b32 s6, s12, 0x60000
	s_mov_b32 m0, s21
	s_add_i32 s22, s16, 0x4000
	buffer_load_dwordx4 v192, s[8:11], s6 offen lds
	s_or_b32 s6, s13, 0x40000
	s_mov_b32 m0, s22
	s_add_i32 s23, s16, 0x6000
	buffer_load_dwordx4 v1, s[48:51], s6 offen lds
	s_or_b32 s6, s13, 0x60000
	s_mov_b32 m0, s23
	s_mov_b32 s24, 0
	buffer_load_dwordx4 v1, s[48:51], s6 offen lds
	s_mov_b32 s25, 0x10000
	s_cmp_lg_u32 s5, 1
	s_mov_b32 s26, 0x40000
	s_cbranch_scc1 .LBB0_1326
	s_barrier

.LBB0_1328:
	v_lshl_add_u32 v146, s72, 8, v193
	v_add_u32_e32 v132, 0xffff8000, v146
	v_cndmask_b32_e64 v132, v146, v132, s[6:7]
	s_add_u32 s12, s52, s12
	v_lshl_or_b32 v130, s73, 8, v194
	v_ashrrev_i32_e32 v133, 31, v132
	s_addc_u32 s13, s53, s13
	v_ashrrev_i32_e32 v131, 31, v130
	v_lshlrev_b64 v[132:133], 11, v[132:133]
	v_lshl_add_u64 v[132:133], s[12:13], 0, v[132:133]
	v_lshlrev_b64 v[148:149], 1, v[130:131]
	s_lshl_b64 s[6:7], s[10:11], 2
	v_lshl_add_u64 v[150:151], v[132:133], 0, v[148:149]
	s_add_u32 s6, s27, s6
	global_load_dwordx4 v[200:203], v[150:151], off
	global_load_dwordx4 v[204:207], v[150:151], off offset:256
	s_addc_u32 s7, s28, s7
	v_lshl_add_u64 v[130:131], v[130:131], 2, s[6:7]
	v_add_co_u32_e32 v152, vcc, s38, v150
	global_load_dwordx4 v[142:145], v[130:131], off
	global_load_dwordx4 v[138:141], v[130:131], off offset:16
	global_load_dwordx4 v[134:137], v[130:131], off offset:512
	s_nop 0
	global_load_dwordx4 v[130:133], v[130:131], off offset:528
	v_addc_co_u32_e32 v153, vcc, 0, v151, vcc
	global_load_dwordx4 v[208:211], v[152:153], off
	global_load_dwordx4 v[212:215], v[152:153], off offset:256
	v_ashrrev_i32_e32 v147, 31, v146
	v_lshlrev_b64 v[146:147], 11, v[146:147]
	v_lshl_add_u64 v[146:147], s[66:67], 0, v[146:147]
	v_lshl_add_u64 v[190:191], v[146:147], 0, v[148:149]
	v_add_co_u32_e32 v146, vcc, s25, v150
	s_mov_b32 s73, s47
	s_nop 0
	v_addc_co_u32_e32 v147, vcc, 0, v151, vcc
	v_add_co_u32_e32 v148, vcc, s37, v150
	s_mov_b32 s72, s57
	s_nop 0
	v_addc_co_u32_e32 v149, vcc, 0, v151, vcc
	v_add_co_u32_e32 v154, vcc, s26, v150
	s_mov_b32 s12, s58
	s_nop 0
	v_addc_co_u32_e32 v155, vcc, 0, v151, vcc
	v_add_co_u32_e32 v152, vcc, s43, v150
	s_mov_b32 s13, s59
	s_nop 0
	v_addc_co_u32_e32 v153, vcc, 0, v151, vcc
	v_add_co_u32_e32 v156, vcc, s45, v150
	s_waitcnt vmcnt(7)
	v_lshlrev_b32_e32 v226, 16, v202
	v_addc_co_u32_e32 v157, vcc, 0, v151, vcc
	v_add_co_u32_e32 v224, vcc, s46, v150
	v_and_b32_e32 v227, 0xffff0000, v202
	s_nop 0
	v_addc_co_u32_e32 v225, vcc, 0, v151, vcc
	global_load_dwordx4 v[216:219], v[146:147], off
	global_load_dwordx4 v[220:223], v[146:147], off offset:256
	global_load_dwordx4 v[182:185], v[148:149], off
	global_load_dwordx4 v[178:181], v[148:149], off offset:256
	global_load_dwordx4 v[174:177], v[154:155], off
	global_load_dwordx4 v[170:173], v[154:155], off offset:256
	global_load_dwordx4 v[166:169], v[152:153], off
	global_load_dwordx4 v[162:165], v[152:153], off offset:256
	global_load_dwordx4 v[158:161], v[156:157], off
	s_nop 0
	global_load_dwordx4 v[154:157], v[156:157], off offset:256
	s_nop 0
	global_load_dwordx4 v[150:153], v[224:225], off
	global_load_dwordx4 v[146:149], v[224:225], off offset:256
	v_lshlrev_b32_e32 v224, 16, v200
	v_and_b32_e32 v225, 0xffff0000, v200
	v_lshlrev_b32_e32 v200, 16, v201
	v_and_b32_e32 v201, 0xffff0000, v201
	v_lshlrev_b32_e32 v202, 16, v203
	v_and_b32_e32 v203, 0xffff0000, v203
	s_waitcnt vmcnt(17)
	v_pk_fma_f32 v[128:129], v[128:129], v[144:145], v[200:201]
	v_pk_fma_f32 v[126:127], v[126:127], v[142:143], v[224:225]
	s_waitcnt vmcnt(16)
	v_pk_fma_f32 v[200:201], v[124:125], v[140:141], v[202:203]
	v_pk_fma_f32 v[124:125], v[122:123], v[138:139], v[226:227]
	v_cvt_pk_bf16_f32 v122, v126, v127
	v_cvt_pk_bf16_f32 v123, v128, v129
	v_lshlrev_b32_e32 v228, 16, v204
	v_and_b32_e32 v229, 0xffff0000, v204
	v_lshlrev_b32_e32 v204, 16, v205
	v_and_b32_e32 v205, 0xffff0000, v205
	v_lshlrev_b32_e32 v230, 16, v206
	v_and_b32_e32 v231, 0xffff0000, v206
	v_cvt_pk_bf16_f32 v124, v124, v125
	v_cvt_pk_bf16_f32 v125, v200, v201
	global_store_dwordx4 v[190:191], v[122:125], off
	s_waitcnt vmcnt(16)
	v_pk_fma_f32 v[120:121], v[120:121], v[136:137], v[204:205]
	v_pk_fma_f32 v[118:119], v[118:119], v[134:135], v[228:229]
	v_lshlrev_b32_e32 v122, 16, v207
	v_and_b32_e32 v123, 0xffff0000, v207
	s_waitcnt vmcnt(15)
	v_pk_fma_f32 v[122:123], v[116:117], v[132:133], v[122:123]
	v_pk_fma_f32 v[116:117], v[114:115], v[130:131], v[230:231]
	v_cvt_pk_bf16_f32 v114, v118, v119
	v_cvt_pk_bf16_f32 v115, v120, v121
	s_waitcnt vmcnt(14)
	v_lshlrev_b32_e32 v118, 16, v210
	v_cvt_pk_bf16_f32 v116, v116, v117
	v_cvt_pk_bf16_f32 v117, v122, v123
	global_store_dwordx4 v[190:191], v[114:117], off offset:256
	v_and_b32_e32 v119, 0xffff0000, v210
	v_lshlrev_b32_e32 v120, 16, v211
	v_lshlrev_b32_e32 v114, 16, v208
	v_and_b32_e32 v115, 0xffff0000, v208
	v_and_b32_e32 v121, 0xffff0000, v211
	v_pk_fma_f32 v[110:111], v[110:111], v[142:143], v[114:115]
	v_lshlrev_b32_e32 v116, 16, v209
	v_and_b32_e32 v117, 0xffff0000, v209
	v_pk_fma_f32 v[114:115], v[108:109], v[140:141], v[120:121]
	v_pk_fma_f32 v[108:109], v[106:107], v[138:139], v[118:119]
	v_cvt_pk_bf16_f32 v106, v110, v111
	v_add_co_u32_e32 v110, vcc, s38, v190
	v_pk_fma_f32 v[112:113], v[112:113], v[144:145], v[116:117]
	s_nop 0
	v_addc_co_u32_e32 v111, vcc, 0, v191, vcc
	v_cvt_pk_bf16_f32 v107, v112, v113
	v_cvt_pk_bf16_f32 v108, v108, v109
	v_cvt_pk_bf16_f32 v109, v114, v115
	global_store_dwordx4 v[110:111], v[106:109], off
	s_waitcnt vmcnt(15)
	v_lshlrev_b32_e32 v112, 16, v214
	v_and_b32_e32 v113, 0xffff0000, v214
	v_lshlrev_b32_e32 v106, 16, v212
	v_and_b32_e32 v107, 0xffff0000, v212
	v_lshlrev_b32_e32 v108, 16, v213
	v_and_b32_e32 v109, 0xffff0000, v213
	v_lshlrev_b32_e32 v114, 16, v215
	v_and_b32_e32 v115, 0xffff0000, v215
	v_pk_fma_f32 v[104:105], v[104:105], v[136:137], v[108:109]
	v_pk_fma_f32 v[102:103], v[102:103], v[134:135], v[106:107]
	v_pk_fma_f32 v[106:107], v[100:101], v[132:133], v[114:115]
	v_pk_fma_f32 v[100:101], v[98:99], v[130:131], v[112:113]
	v_cvt_pk_bf16_f32 v98, v102, v103
	v_cvt_pk_bf16_f32 v99, v104, v105
	s_waitcnt vmcnt(14)
	v_lshlrev_b32_e32 v102, 16, v218
	v_cvt_pk_bf16_f32 v100, v100, v101
	v_cvt_pk_bf16_f32 v101, v106, v107
	global_store_dwordx4 v[110:111], v[98:101], off offset:256
	v_and_b32_e32 v103, 0xffff0000, v218
	v_lshlrev_b32_e32 v104, 16, v219
	v_lshlrev_b32_e32 v98, 16, v216
	v_and_b32_e32 v99, 0xffff0000, v216
	v_and_b32_e32 v105, 0xffff0000, v219
	v_pk_fma_f32 v[94:95], v[94:95], v[142:143], v[98:99]
	v_lshlrev_b32_e32 v100, 16, v217
	v_and_b32_e32 v101, 0xffff0000, v217
	v_pk_fma_f32 v[98:99], v[92:93], v[140:141], v[104:105]
	v_pk_fma_f32 v[92:93], v[90:91], v[138:139], v[102:103]
	v_cvt_pk_bf16_f32 v90, v94, v95
	v_add_co_u32_e32 v94, vcc, s25, v190
	v_pk_fma_f32 v[96:97], v[96:97], v[144:145], v[100:101]
	s_nop 0
	v_addc_co_u32_e32 v95, vcc, 0, v191, vcc
	v_cvt_pk_bf16_f32 v91, v96, v97
	v_cvt_pk_bf16_f32 v92, v92, v93
	v_cvt_pk_bf16_f32 v93, v98, v99
	global_store_dwordx4 v[94:95], v[90:93], off
	s_waitcnt vmcnt(15)
	v_lshlrev_b32_e32 v96, 16, v222
	v_and_b32_e32 v97, 0xffff0000, v222
	v_lshlrev_b32_e32 v90, 16, v220
	v_and_b32_e32 v91, 0xffff0000, v220
	v_lshlrev_b32_e32 v92, 16, v221
	v_and_b32_e32 v93, 0xffff0000, v221
	v_lshlrev_b32_e32 v98, 16, v223
	v_and_b32_e32 v99, 0xffff0000, v223
	v_pk_fma_f32 v[88:89], v[88:89], v[136:137], v[92:93]
	v_pk_fma_f32 v[86:87], v[86:87], v[134:135], v[90:91]
	v_pk_fma_f32 v[90:91], v[84:85], v[132:133], v[98:99]
	v_pk_fma_f32 v[84:85], v[82:83], v[130:131], v[96:97]
	v_cvt_pk_bf16_f32 v82, v86, v87
	v_cvt_pk_bf16_f32 v83, v88, v89
	s_waitcnt vmcnt(14)
	v_lshlrev_b32_e32 v86, 16, v184
	v_cvt_pk_bf16_f32 v84, v84, v85
	v_cvt_pk_bf16_f32 v85, v90, v91
	global_store_dwordx4 v[94:95], v[82:85], off offset:256
	v_and_b32_e32 v87, 0xffff0000, v184
	v_lshlrev_b32_e32 v88, 16, v185
	v_lshlrev_b32_e32 v82, 16, v182
	v_and_b32_e32 v83, 0xffff0000, v182
	v_and_b32_e32 v89, 0xffff0000, v185
	v_pk_fma_f32 v[78:79], v[78:79], v[142:143], v[82:83]
	v_lshlrev_b32_e32 v84, 16, v183
	v_and_b32_e32 v85, 0xffff0000, v183
	v_pk_fma_f32 v[82:83], v[76:77], v[140:141], v[88:89]
	v_pk_fma_f32 v[76:77], v[74:75], v[138:139], v[86:87]
	v_cvt_pk_bf16_f32 v74, v78, v79
	v_add_co_u32_e32 v78, vcc, s37, v190
	v_pk_fma_f32 v[80:81], v[80:81], v[144:145], v[84:85]
	s_nop 0
	v_addc_co_u32_e32 v79, vcc, 0, v191, vcc
	v_cvt_pk_bf16_f32 v75, v80, v81
	v_cvt_pk_bf16_f32 v76, v76, v77
	v_cvt_pk_bf16_f32 v77, v82, v83
	global_store_dwordx4 v[78:79], v[74:77], off
	s_waitcnt vmcnt(15)
	v_lshlrev_b32_e32 v80, 16, v180
	v_and_b32_e32 v81, 0xffff0000, v180
	v_lshlrev_b32_e32 v74, 16, v178
	v_and_b32_e32 v75, 0xffff0000, v178
	v_lshlrev_b32_e32 v76, 16, v179
	v_and_b32_e32 v77, 0xffff0000, v179
	v_lshlrev_b32_e32 v82, 16, v181
	v_and_b32_e32 v83, 0xffff0000, v181
	v_pk_fma_f32 v[72:73], v[72:73], v[136:137], v[76:77]
	v_pk_fma_f32 v[70:71], v[70:71], v[134:135], v[74:75]
	v_pk_fma_f32 v[74:75], v[68:69], v[132:133], v[82:83]
	v_pk_fma_f32 v[68:69], v[66:67], v[130:131], v[80:81]
	v_cvt_pk_bf16_f32 v66, v70, v71
	v_cvt_pk_bf16_f32 v67, v72, v73
	s_waitcnt vmcnt(14)
	v_lshlrev_b32_e32 v70, 16, v176
	v_cvt_pk_bf16_f32 v68, v68, v69
	v_cvt_pk_bf16_f32 v69, v74, v75
	global_store_dwordx4 v[78:79], v[66:69], off offset:256
	v_and_b32_e32 v71, 0xffff0000, v176
	v_lshlrev_b32_e32 v72, 16, v177
	v_lshlrev_b32_e32 v66, 16, v174
	v_and_b32_e32 v67, 0xffff0000, v174
	v_and_b32_e32 v73, 0xffff0000, v177
	v_pk_fma_f32 v[62:63], v[62:63], v[142:143], v[66:67]
	v_lshlrev_b32_e32 v68, 16, v175
	v_and_b32_e32 v69, 0xffff0000, v175
	v_pk_fma_f32 v[66:67], v[60:61], v[140:141], v[72:73]
	v_pk_fma_f32 v[60:61], v[58:59], v[138:139], v[70:71]
	v_cvt_pk_bf16_f32 v58, v62, v63
	v_add_co_u32_e32 v62, vcc, s26, v190
	v_pk_fma_f32 v[64:65], v[64:65], v[144:145], v[68:69]
	s_nop 0
	v_addc_co_u32_e32 v63, vcc, 0, v191, vcc
	v_cvt_pk_bf16_f32 v59, v64, v65
	v_cvt_pk_bf16_f32 v60, v60, v61
	v_cvt_pk_bf16_f32 v61, v66, v67
	global_store_dwordx4 v[62:63], v[58:61], off
	s_waitcnt vmcnt(15)
	v_lshlrev_b32_e32 v64, 16, v172
	v_and_b32_e32 v65, 0xffff0000, v172
	v_lshlrev_b32_e32 v58, 16, v170
	v_and_b32_e32 v59, 0xffff0000, v170
	v_lshlrev_b32_e32 v60, 16, v171
	v_and_b32_e32 v61, 0xffff0000, v171
	v_lshlrev_b32_e32 v66, 16, v173
	v_and_b32_e32 v67, 0xffff0000, v173
	v_pk_fma_f32 v[56:57], v[56:57], v[136:137], v[60:61]
	v_pk_fma_f32 v[54:55], v[54:55], v[134:135], v[58:59]
	v_pk_fma_f32 v[58:59], v[52:53], v[132:133], v[66:67]
	v_pk_fma_f32 v[52:53], v[50:51], v[130:131], v[64:65]
	v_cvt_pk_bf16_f32 v50, v54, v55
	v_cvt_pk_bf16_f32 v51, v56, v57
	s_waitcnt vmcnt(14)
	v_lshlrev_b32_e32 v54, 16, v168
	v_cvt_pk_bf16_f32 v52, v52, v53
	v_cvt_pk_bf16_f32 v53, v58, v59
	global_store_dwordx4 v[62:63], v[50:53], off offset:256
	v_and_b32_e32 v55, 0xffff0000, v168
	v_lshlrev_b32_e32 v56, 16, v169
	v_lshlrev_b32_e32 v50, 16, v166
	v_and_b32_e32 v51, 0xffff0000, v166
	v_and_b32_e32 v57, 0xffff0000, v169
	v_pk_fma_f32 v[46:47], v[46:47], v[142:143], v[50:51]
	v_lshlrev_b32_e32 v52, 16, v167
	v_and_b32_e32 v53, 0xffff0000, v167
	v_pk_fma_f32 v[50:51], v[44:45], v[140:141], v[56:57]
	v_pk_fma_f32 v[44:45], v[42:43], v[138:139], v[54:55]
	v_cvt_pk_bf16_f32 v42, v46, v47
	v_add_co_u32_e32 v46, vcc, s43, v190
	v_pk_fma_f32 v[48:49], v[48:49], v[144:145], v[52:53]
	s_nop 0
	v_addc_co_u32_e32 v47, vcc, 0, v191, vcc
	v_cvt_pk_bf16_f32 v43, v48, v49
	v_cvt_pk_bf16_f32 v44, v44, v45
	v_cvt_pk_bf16_f32 v45, v50, v51
	global_store_dwordx4 v[46:47], v[42:45], off
	s_waitcnt vmcnt(15)
	v_lshlrev_b32_e32 v48, 16, v164
	v_and_b32_e32 v49, 0xffff0000, v164
	v_lshlrev_b32_e32 v42, 16, v162
	v_and_b32_e32 v43, 0xffff0000, v162
	v_lshlrev_b32_e32 v44, 16, v163
	v_and_b32_e32 v45, 0xffff0000, v163
	v_lshlrev_b32_e32 v50, 16, v165
	v_and_b32_e32 v51, 0xffff0000, v165
	v_pk_fma_f32 v[40:41], v[40:41], v[136:137], v[44:45]
	v_pk_fma_f32 v[38:39], v[38:39], v[134:135], v[42:43]
	v_pk_fma_f32 v[42:43], v[36:37], v[132:133], v[50:51]
	v_pk_fma_f32 v[36:37], v[34:35], v[130:131], v[48:49]
	v_cvt_pk_bf16_f32 v34, v38, v39
	v_cvt_pk_bf16_f32 v35, v40, v41
	s_waitcnt vmcnt(14)
	v_lshlrev_b32_e32 v38, 16, v160
	v_cvt_pk_bf16_f32 v36, v36, v37
	v_cvt_pk_bf16_f32 v37, v42, v43
	global_store_dwordx4 v[46:47], v[34:37], off offset:256
	v_and_b32_e32 v39, 0xffff0000, v160
	v_lshlrev_b32_e32 v40, 16, v161
	v_lshlrev_b32_e32 v34, 16, v158
	v_and_b32_e32 v35, 0xffff0000, v158
	v_and_b32_e32 v41, 0xffff0000, v161
	v_pk_fma_f32 v[30:31], v[30:31], v[142:143], v[34:35]
	v_lshlrev_b32_e32 v36, 16, v159
	v_and_b32_e32 v37, 0xffff0000, v159
	v_pk_fma_f32 v[34:35], v[28:29], v[140:141], v[40:41]
	v_pk_fma_f32 v[28:29], v[26:27], v[138:139], v[38:39]
	v_cvt_pk_bf16_f32 v26, v30, v31
	v_add_co_u32_e32 v30, vcc, s45, v190
	v_pk_fma_f32 v[32:33], v[32:33], v[144:145], v[36:37]
	s_nop 0
	v_addc_co_u32_e32 v31, vcc, 0, v191, vcc
	v_cvt_pk_bf16_f32 v27, v32, v33
	v_cvt_pk_bf16_f32 v28, v28, v29
	v_cvt_pk_bf16_f32 v29, v34, v35
	global_store_dwordx4 v[30:31], v[26:29], off
	s_waitcnt vmcnt(15)
	v_lshlrev_b32_e32 v32, 16, v156
	v_and_b32_e32 v33, 0xffff0000, v156
	v_lshlrev_b32_e32 v26, 16, v154
	v_and_b32_e32 v27, 0xffff0000, v154
	v_lshlrev_b32_e32 v28, 16, v155
	v_and_b32_e32 v29, 0xffff0000, v155
	v_lshlrev_b32_e32 v34, 16, v157
	v_and_b32_e32 v35, 0xffff0000, v157
	v_pk_fma_f32 v[24:25], v[24:25], v[136:137], v[28:29]
	v_pk_fma_f32 v[22:23], v[22:23], v[134:135], v[26:27]
	v_pk_fma_f32 v[26:27], v[20:21], v[132:133], v[34:35]
	v_pk_fma_f32 v[20:21], v[18:19], v[130:131], v[32:33]
	v_cvt_pk_bf16_f32 v18, v22, v23
	v_cvt_pk_bf16_f32 v19, v24, v25
	s_waitcnt vmcnt(14)
	v_lshlrev_b32_e32 v22, 16, v152
	v_cvt_pk_bf16_f32 v20, v20, v21
	v_cvt_pk_bf16_f32 v21, v26, v27
	global_store_dwordx4 v[30:31], v[18:21], off offset:256
	v_and_b32_e32 v23, 0xffff0000, v152
	v_lshlrev_b32_e32 v24, 16, v153
	v_lshlrev_b32_e32 v18, 16, v150
	v_and_b32_e32 v19, 0xffff0000, v150
	v_and_b32_e32 v25, 0xffff0000, v153
	v_pk_fma_f32 v[14:15], v[14:15], v[142:143], v[18:19]
	v_lshlrev_b32_e32 v20, 16, v151
	v_and_b32_e32 v21, 0xffff0000, v151
	v_pk_fma_f32 v[18:19], v[12:13], v[140:141], v[24:25]
	v_pk_fma_f32 v[12:13], v[10:11], v[138:139], v[22:23]
	v_cvt_pk_bf16_f32 v10, v14, v15
	v_add_co_u32_e32 v14, vcc, s46, v190
	v_pk_fma_f32 v[16:17], v[16:17], v[144:145], v[20:21]
	s_nop 0
	v_addc_co_u32_e32 v15, vcc, 0, v191, vcc
	v_cvt_pk_bf16_f32 v11, v16, v17
	v_cvt_pk_bf16_f32 v12, v12, v13
	v_cvt_pk_bf16_f32 v13, v18, v19
	global_store_dwordx4 v[14:15], v[10:13], off
	s_waitcnt vmcnt(15)
	v_lshlrev_b32_e32 v16, 16, v148
	v_and_b32_e32 v17, 0xffff0000, v148
	v_lshlrev_b32_e32 v10, 16, v146
	v_and_b32_e32 v11, 0xffff0000, v146
	v_lshlrev_b32_e32 v18, 16, v149
	v_and_b32_e32 v19, 0xffff0000, v149
	v_lshlrev_b32_e32 v12, 16, v147
	v_and_b32_e32 v13, 0xffff0000, v147
	v_pk_fma_f32 v[6:7], v[6:7], v[134:135], v[10:11]
	v_pk_fma_f32 v[10:11], v[4:5], v[132:133], v[18:19]
	v_pk_fma_f32 v[4:5], v[2:3], v[130:131], v[16:17]
	s_and_b64 vcc, exec, s[4:5]
	v_pk_fma_f32 v[8:9], v[8:9], v[136:137], v[12:13]
	v_cvt_pk_bf16_f32 v2, v6, v7
	s_nop 0
	v_cvt_pk_bf16_f32 v3, v8, v9
	v_cvt_pk_bf16_f32 v4, v4, v5
	v_cvt_pk_bf16_f32 v5, v10, v11
	global_store_dwordx4 v[14:15], v[2:5], off offset:256
	s_cbranch_vccnz .LBB0_1337

.LBB0_1334:
	ds_read_b128 v[130:133], v195
	ds_read_b128 v[134:137], v195 offset:1024
	ds_read_b128 v[138:141], v195 offset:2048
	ds_read_b128 v[142:145], v195 offset:3072
	s_add_i32 s10, s7, 0xfffa0080
	s_cmp_eq_u32 s13, 12
	s_cselect_b32 s79, s6, s10
	s_cselect_b32 s78, s58, s12
	s_or_b32 s84, s79, 0x80
	s_add_i32 s10, s7, 0xfffe0000
	s_mov_b32 m0, s39
	ds_read_b128 v[146:149], v196
	ds_read_b128 v[150:153], v196 offset:1024
	ds_read_b128 v[154:157], v196 offset:2048
	ds_read_b128 v[158:161], v196 offset:3072
	ds_read_b128 v[162:165], v196 offset:4096
	ds_read_b128 v[166:169], v196 offset:5120
	ds_read_b128 v[170:173], v196 offset:6144
	ds_read_b128 v[174:177], v196 offset:7168
	buffer_load_dwordx4 v1, s[48:51], s10 offen lds
	s_mov_b32 m0, s41
	s_nop 0
	buffer_load_dwordx4 v1, s[48:51], s7 offen lds
	s_waitcnt lgkmcnt(8)
	s_barrier
	s_waitcnt lgkmcnt(0)
	s_setprio 1
	s_waitcnt lgkmcnt(7)
	v_mfma_f32_16x16x32_bf16 v[126:129], v[130:133], v[146:149], v[126:129]
	v_mfma_f32_16x16x32_bf16 v[122:125], v[138:141], v[146:149], v[122:125]
	s_waitcnt lgkmcnt(5)
	v_mfma_f32_16x16x32_bf16 v[110:113], v[130:133], v[154:157], v[110:113]
	v_mfma_f32_16x16x32_bf16 v[106:109], v[138:141], v[154:157], v[106:109]
	s_waitcnt lgkmcnt(3)
	v_mfma_f32_16x16x32_bf16 v[94:97], v[130:133], v[162:165], v[94:97]
	v_mfma_f32_16x16x32_bf16 v[90:93], v[138:141], v[162:165], v[90:93]
	s_waitcnt lgkmcnt(1)
	v_mfma_f32_16x16x32_bf16 v[78:81], v[130:133], v[170:173], v[78:81]
	v_mfma_f32_16x16x32_bf16 v[74:77], v[138:141], v[170:173], v[74:77]
	v_mfma_f32_16x16x32_bf16 v[126:129], v[134:137], v[150:153], v[126:129]
	v_mfma_f32_16x16x32_bf16 v[122:125], v[142:145], v[150:153], v[122:125]
	v_mfma_f32_16x16x32_bf16 v[110:113], v[134:137], v[158:161], v[110:113]
	v_mfma_f32_16x16x32_bf16 v[106:109], v[142:145], v[158:161], v[106:109]
	v_mfma_f32_16x16x32_bf16 v[94:97], v[134:137], v[166:169], v[94:97]
	v_mfma_f32_16x16x32_bf16 v[90:93], v[142:145], v[166:169], v[90:93]
	s_waitcnt lgkmcnt(0)
	v_mfma_f32_16x16x32_bf16 v[78:81], v[134:137], v[174:177], v[78:81]
	v_mfma_f32_16x16x32_bf16 v[74:77], v[142:145], v[174:177], v[74:77]
	s_setprio 0
	s_barrier
	s_mov_b32 m0, s17
	s_mov_b32 s10, s50
	s_mov_b32 s11, s51
	ds_read_b128 v[178:181], v197
	ds_read_b128 v[182:185], v197 offset:1024
	ds_read_b128 v[200:203], v197 offset:2048
	ds_read_b128 v[204:207], v197 offset:3072
	buffer_load_dwordx4 v192, s[8:11], s78 offen lds
	s_add_i32 s33, s78, 0x20000
	s_mov_b32 m0, s18
	s_nop 0
	buffer_load_dwordx4 v192, s[8:11], s33 offen lds
	s_barrier
	s_waitcnt lgkmcnt(0)
	s_setprio 1
	s_waitcnt lgkmcnt(3)
	v_mfma_f32_16x16x32_bf16 v[118:121], v[178:181], v[146:149], v[118:121]
	s_waitcnt lgkmcnt(1)
	v_mfma_f32_16x16x32_bf16 v[114:117], v[200:203], v[146:149], v[114:117]
	v_mfma_f32_16x16x32_bf16 v[102:105], v[178:181], v[154:157], v[102:105]
	v_mfma_f32_16x16x32_bf16 v[98:101], v[200:203], v[154:157], v[98:101]
	v_mfma_f32_16x16x32_bf16 v[86:89], v[178:181], v[162:165], v[86:89]
	v_mfma_f32_16x16x32_bf16 v[82:85], v[200:203], v[162:165], v[82:85]
	v_mfma_f32_16x16x32_bf16 v[70:73], v[178:181], v[170:173], v[70:73]
	v_mfma_f32_16x16x32_bf16 v[66:69], v[200:203], v[170:173], v[66:69]
	v_mfma_f32_16x16x32_bf16 v[118:121], v[182:185], v[150:153], v[118:121]
	s_waitcnt lgkmcnt(0)
	v_mfma_f32_16x16x32_bf16 v[114:117], v[204:207], v[150:153], v[114:117]
	v_mfma_f32_16x16x32_bf16 v[102:105], v[182:185], v[158:161], v[102:105]
	v_mfma_f32_16x16x32_bf16 v[98:101], v[204:207], v[158:161], v[98:101]
	v_mfma_f32_16x16x32_bf16 v[86:89], v[182:185], v[166:169], v[86:89]
	v_mfma_f32_16x16x32_bf16 v[82:85], v[204:207], v[166:169], v[82:85]
	v_mfma_f32_16x16x32_bf16 v[70:73], v[182:185], v[174:177], v[70:73]
	v_mfma_f32_16x16x32_bf16 v[66:69], v[204:207], v[174:177], v[66:69]
	s_setprio 0
	s_mov_b32 m0, s16
	s_barrier
	ds_read_b128 v[146:149], v196 offset:16384
	ds_read_b128 v[150:153], v196 offset:17408
	ds_read_b128 v[154:157], v196 offset:18432
	ds_read_b128 v[158:161], v196 offset:19456
	ds_read_b128 v[162:165], v196 offset:20480
	ds_read_b128 v[166:169], v196 offset:21504
	ds_read_b128 v[170:173], v196 offset:22528
	ds_read_b128 v[174:177], v196 offset:23552
	buffer_load_dwordx4 v1, s[48:51], s79 offen lds
	s_add_i32 s33, s79, 0x20000
	s_mov_b32 m0, s19
	s_nop 0
	buffer_load_dwordx4 v1, s[48:51], s33 offen lds
	s_barrier
	s_waitcnt lgkmcnt(0)
	s_setprio 1
	s_waitcnt lgkmcnt(7)
	v_mfma_f32_16x16x32_bf16 v[62:65], v[130:133], v[146:149], v[62:65]
	v_mfma_f32_16x16x32_bf16 v[58:61], v[138:141], v[146:149], v[58:61]
	s_waitcnt lgkmcnt(5)
	v_mfma_f32_16x16x32_bf16 v[46:49], v[130:133], v[154:157], v[46:49]
	v_mfma_f32_16x16x32_bf16 v[42:45], v[138:141], v[154:157], v[42:45]
	s_waitcnt lgkmcnt(3)
	v_mfma_f32_16x16x32_bf16 v[30:33], v[130:133], v[162:165], v[30:33]
	v_mfma_f32_16x16x32_bf16 v[26:29], v[138:141], v[162:165], v[26:29]
	s_waitcnt lgkmcnt(1)
	v_mfma_f32_16x16x32_bf16 v[14:17], v[130:133], v[170:173], v[14:17]
	v_mfma_f32_16x16x32_bf16 v[10:13], v[138:141], v[170:173], v[10:13]
	v_mfma_f32_16x16x32_bf16 v[62:65], v[134:137], v[150:153], v[62:65]
	v_mfma_f32_16x16x32_bf16 v[58:61], v[142:145], v[150:153], v[58:61]
	v_mfma_f32_16x16x32_bf16 v[46:49], v[134:137], v[158:161], v[46:49]
	v_mfma_f32_16x16x32_bf16 v[42:45], v[142:145], v[158:161], v[42:45]
	v_mfma_f32_16x16x32_bf16 v[30:33], v[134:137], v[166:169], v[30:33]
	v_mfma_f32_16x16x32_bf16 v[26:29], v[142:145], v[166:169], v[26:29]
	s_waitcnt lgkmcnt(0)
	v_mfma_f32_16x16x32_bf16 v[14:17], v[134:137], v[174:177], v[14:17]
	v_mfma_f32_16x16x32_bf16 v[10:13], v[142:145], v[174:177], v[10:13]
	s_setprio 0
	s_barrier
	s_mov_b32 m0, s20
	s_add_i32 s33, s78, 0x40000
	buffer_load_dwordx4 v192, s[8:11], s33 offen lds
	s_add_i32 s33, s78, 0x60000
	s_mov_b32 m0, s21
	s_nop 0
	buffer_load_dwordx4 v192, s[8:11], s33 offen lds
	s_waitcnt vmcnt(6)
	s_barrier
	s_setprio 1
	v_mfma_f32_16x16x32_bf16 v[54:57], v[178:181], v[146:149], v[54:57]
	v_mfma_f32_16x16x32_bf16 v[50:53], v[200:203], v[146:149], v[50:53]
	v_mfma_f32_16x16x32_bf16 v[38:41], v[178:181], v[154:157], v[38:41]
	v_mfma_f32_16x16x32_bf16 v[34:37], v[200:203], v[154:157], v[34:37]
	v_mfma_f32_16x16x32_bf16 v[22:25], v[178:181], v[162:165], v[22:25]
	v_mfma_f32_16x16x32_bf16 v[18:21], v[200:203], v[162:165], v[18:21]
	v_mfma_f32_16x16x32_bf16 v[6:9], v[178:181], v[170:173], v[6:9]
	v_mfma_f32_16x16x32_bf16 v[2:5], v[200:203], v[170:173], v[2:5]
	v_mfma_f32_16x16x32_bf16 v[54:57], v[182:185], v[150:153], v[54:57]
	v_mfma_f32_16x16x32_bf16 v[50:53], v[204:207], v[150:153], v[50:53]
	v_mfma_f32_16x16x32_bf16 v[38:41], v[182:185], v[158:161], v[38:41]
	v_mfma_f32_16x16x32_bf16 v[34:37], v[204:207], v[158:161], v[34:37]
	v_mfma_f32_16x16x32_bf16 v[22:25], v[182:185], v[166:169], v[22:25]
	v_mfma_f32_16x16x32_bf16 v[18:21], v[204:207], v[166:169], v[18:21]
	v_mfma_f32_16x16x32_bf16 v[6:9], v[182:185], v[174:177], v[6:9]
	v_mfma_f32_16x16x32_bf16 v[2:5], v[204:207], v[174:177], v[2:5]
	s_setprio 0
	s_barrier
	ds_read_b128 v[130:133], v198
	ds_read_b128 v[134:137], v198 offset:1024
	ds_read_b128 v[138:141], v198 offset:2048
	ds_read_b128 v[142:145], v198 offset:3072
	s_mov_b32 m0, s22
	s_add_i32 s33, s79, 0x40000
	ds_read_b128 v[146:149], v196 offset:32768
	ds_read_b128 v[150:153], v196 offset:33792
	ds_read_b128 v[154:157], v196 offset:34816
	ds_read_b128 v[158:161], v196 offset:35840
	ds_read_b128 v[162:165], v196 offset:36864
	ds_read_b128 v[166:169], v196 offset:37888
	ds_read_b128 v[170:173], v196 offset:38912
	ds_read_b128 v[174:177], v196 offset:39936
	buffer_load_dwordx4 v1, s[48:51], s33 offen lds
	s_add_i32 s33, s79, 0x60000
	s_mov_b32 m0, s23
	s_nop 0
	buffer_load_dwordx4 v1, s[48:51], s33 offen lds
	s_waitcnt lgkmcnt(8)
	s_barrier
	s_waitcnt lgkmcnt(0)
	s_setprio 1
	s_waitcnt lgkmcnt(7)
	v_mfma_f32_16x16x32_bf16 v[126:129], v[130:133], v[146:149], v[126:129]
	v_mfma_f32_16x16x32_bf16 v[122:125], v[138:141], v[146:149], v[122:125]
	s_waitcnt lgkmcnt(5)
	v_mfma_f32_16x16x32_bf16 v[110:113], v[130:133], v[154:157], v[110:113]
	v_mfma_f32_16x16x32_bf16 v[106:109], v[138:141], v[154:157], v[106:109]
	s_waitcnt lgkmcnt(3)
	v_mfma_f32_16x16x32_bf16 v[94:97], v[130:133], v[162:165], v[94:97]
	v_mfma_f32_16x16x32_bf16 v[90:93], v[138:141], v[162:165], v[90:93]
	s_waitcnt lgkmcnt(1)
	v_mfma_f32_16x16x32_bf16 v[78:81], v[130:133], v[170:173], v[78:81]
	v_mfma_f32_16x16x32_bf16 v[74:77], v[138:141], v[170:173], v[74:77]
	v_mfma_f32_16x16x32_bf16 v[126:129], v[134:137], v[150:153], v[126:129]
	v_mfma_f32_16x16x32_bf16 v[122:125], v[142:145], v[150:153], v[122:125]
	v_mfma_f32_16x16x32_bf16 v[110:113], v[134:137], v[158:161], v[110:113]
	v_mfma_f32_16x16x32_bf16 v[106:109], v[142:145], v[158:161], v[106:109]
	v_mfma_f32_16x16x32_bf16 v[94:97], v[134:137], v[166:169], v[94:97]
	v_mfma_f32_16x16x32_bf16 v[90:93], v[142:145], v[166:169], v[90:93]
	s_waitcnt lgkmcnt(0)
	v_mfma_f32_16x16x32_bf16 v[78:81], v[134:137], v[174:177], v[78:81]
	v_mfma_f32_16x16x32_bf16 v[74:77], v[142:145], v[174:177], v[74:77]
	s_setprio 0
	s_barrier
	s_mov_b32 m0, s29
	s_add_i32 s33, s78, 0x80
	ds_read_b128 v[178:181], v199
	ds_read_b128 v[182:185], v199 offset:1024
	ds_read_b128 v[200:203], v199 offset:2048
	ds_read_b128 v[204:207], v199 offset:3072
	buffer_load_dwordx4 v192, s[8:11], s33 offen lds
	s_add_i32 s33, s78, 0x20080
	s_mov_b32 m0, s30
	s_nop 0
	buffer_load_dwordx4 v192, s[8:11], s33 offen lds
	s_barrier
	s_waitcnt lgkmcnt(0)
	s_setprio 1
	s_waitcnt lgkmcnt(3)
	v_mfma_f32_16x16x32_bf16 v[118:121], v[178:181], v[146:149], v[118:121]
	s_waitcnt lgkmcnt(1)
	v_mfma_f32_16x16x32_bf16 v[114:117], v[200:203], v[146:149], v[114:117]
	v_mfma_f32_16x16x32_bf16 v[102:105], v[178:181], v[154:157], v[102:105]
	v_mfma_f32_16x16x32_bf16 v[98:101], v[200:203], v[154:157], v[98:101]
	v_mfma_f32_16x16x32_bf16 v[86:89], v[178:181], v[162:165], v[86:89]
	v_mfma_f32_16x16x32_bf16 v[82:85], v[200:203], v[162:165], v[82:85]
	v_mfma_f32_16x16x32_bf16 v[70:73], v[178:181], v[170:173], v[70:73]
	v_mfma_f32_16x16x32_bf16 v[66:69], v[200:203], v[170:173], v[66:69]
	v_mfma_f32_16x16x32_bf16 v[118:121], v[182:185], v[150:153], v[118:121]
	s_waitcnt lgkmcnt(0)
	v_mfma_f32_16x16x32_bf16 v[114:117], v[204:207], v[150:153], v[114:117]
	v_mfma_f32_16x16x32_bf16 v[102:105], v[182:185], v[158:161], v[102:105]
	v_mfma_f32_16x16x32_bf16 v[98:101], v[204:207], v[158:161], v[98:101]
	v_mfma_f32_16x16x32_bf16 v[86:89], v[182:185], v[166:169], v[86:89]
	v_mfma_f32_16x16x32_bf16 v[82:85], v[204:207], v[166:169], v[82:85]
	v_mfma_f32_16x16x32_bf16 v[70:73], v[182:185], v[174:177], v[70:73]
	v_mfma_f32_16x16x32_bf16 v[66:69], v[204:207], v[174:177], v[66:69]
	s_setprio 0
	s_mov_b32 m0, s31
	s_barrier
	ds_read_b128 v[146:149], v196 offset:49152
	ds_read_b128 v[150:153], v196 offset:50176
	ds_read_b128 v[154:157], v196 offset:51200
	ds_read_b128 v[158:161], v196 offset:52224
	ds_read_b128 v[162:165], v196 offset:53248
	ds_read_b128 v[166:169], v196 offset:54272
	ds_read_b128 v[170:173], v196 offset:55296
	ds_read_b128 v[174:177], v196 offset:56320
	buffer_load_dwordx4 v1, s[48:51], s84 offen lds
	s_add_i32 s79, s79, 0x20080
	s_mov_b32 m0, s34
	s_nop 0
	buffer_load_dwordx4 v1, s[48:51], s79 offen lds
	s_barrier
	s_waitcnt lgkmcnt(0)
	s_setprio 1
	s_waitcnt lgkmcnt(7)
	v_mfma_f32_16x16x32_bf16 v[62:65], v[130:133], v[146:149], v[62:65]
	v_mfma_f32_16x16x32_bf16 v[58:61], v[138:141], v[146:149], v[58:61]
	s_waitcnt lgkmcnt(5)
	v_mfma_f32_16x16x32_bf16 v[46:49], v[130:133], v[154:157], v[46:49]
	v_mfma_f32_16x16x32_bf16 v[42:45], v[138:141], v[154:157], v[42:45]
	s_waitcnt lgkmcnt(3)
	v_mfma_f32_16x16x32_bf16 v[30:33], v[130:133], v[162:165], v[30:33]
	v_mfma_f32_16x16x32_bf16 v[26:29], v[138:141], v[162:165], v[26:29]
	s_waitcnt lgkmcnt(1)
	v_mfma_f32_16x16x32_bf16 v[14:17], v[130:133], v[170:173], v[14:17]
	v_mfma_f32_16x16x32_bf16 v[10:13], v[138:141], v[170:173], v[10:13]
	v_mfma_f32_16x16x32_bf16 v[62:65], v[134:137], v[150:153], v[62:65]
	v_mfma_f32_16x16x32_bf16 v[58:61], v[142:145], v[150:153], v[58:61]
	v_mfma_f32_16x16x32_bf16 v[46:49], v[134:137], v[158:161], v[46:49]
	v_mfma_f32_16x16x32_bf16 v[42:45], v[142:145], v[158:161], v[42:45]
	v_mfma_f32_16x16x32_bf16 v[30:33], v[134:137], v[166:169], v[30:33]
	v_mfma_f32_16x16x32_bf16 v[26:29], v[142:145], v[166:169], v[26:29]
	s_waitcnt lgkmcnt(0)
	v_mfma_f32_16x16x32_bf16 v[14:17], v[134:137], v[174:177], v[14:17]
	v_mfma_f32_16x16x32_bf16 v[10:13], v[142:145], v[174:177], v[10:13]
	s_setprio 0
	s_barrier
	s_mov_b32 m0, s35
	s_add_i32 s33, s78, 0x40080
	buffer_load_dwordx4 v192, s[8:11], s33 offen lds
	s_add_i32 s78, s78, 0x60080
	s_mov_b32 m0, s36
	s_nop 0
	buffer_load_dwordx4 v192, s[8:11], s78 offen lds
	s_waitcnt vmcnt(6)
	s_barrier
	s_setprio 1
	v_mfma_f32_16x16x32_bf16 v[54:57], v[178:181], v[146:149], v[54:57]
	v_mfma_f32_16x16x32_bf16 v[50:53], v[200:203], v[146:149], v[50:53]
	v_mfma_f32_16x16x32_bf16 v[38:41], v[178:181], v[154:157], v[38:41]
	v_mfma_f32_16x16x32_bf16 v[34:37], v[200:203], v[154:157], v[34:37]
	v_mfma_f32_16x16x32_bf16 v[22:25], v[178:181], v[162:165], v[22:25]
	v_mfma_f32_16x16x32_bf16 v[18:21], v[200:203], v[162:165], v[18:21]
	v_mfma_f32_16x16x32_bf16 v[6:9], v[178:181], v[170:173], v[6:9]
	v_mfma_f32_16x16x32_bf16 v[2:5], v[200:203], v[170:173], v[2:5]
	v_mfma_f32_16x16x32_bf16 v[54:57], v[182:185], v[150:153], v[54:57]
	v_mfma_f32_16x16x32_bf16 v[50:53], v[204:207], v[150:153], v[50:53]
	v_mfma_f32_16x16x32_bf16 v[38:41], v[182:185], v[158:161], v[38:41]
	v_mfma_f32_16x16x32_bf16 v[34:37], v[204:207], v[158:161], v[34:37]
	v_mfma_f32_16x16x32_bf16 v[22:25], v[182:185], v[166:169], v[22:25]
	v_mfma_f32_16x16x32_bf16 v[18:21], v[204:207], v[166:169], v[18:21]
	v_mfma_f32_16x16x32_bf16 v[6:9], v[182:185], v[174:177], v[6:9]
	v_mfma_f32_16x16x32_bf16 v[2:5], v[204:207], v[174:177], v[2:5]
	s_setprio 0
	s_add_i32 s13, s13, 2
	s_addk_i32 s7, 0x100
	s_addk_i32 s12, 0x100
	s_cmp_gt_u32 s13, 13
	s_barrier
	s_cbranch_scc0 .LBB0_1334
	s_cmpk_gt_i32 s72, 0x7f
	s_cselect_b64 s[6:7], -1, 0
	s_and_b64 vcc, exec, s[6:7]
	s_cbranch_vccz .LBB0_1327
	s_mov_b64 s[10:11], 0xc000
	s_mov_b64 s[12:13], 0xcb00000
	s_branch .LBB0_1328

.LBB0_1645:
	s_cmp_gt_i32 s60, 21
	s_cselect_b64 s[4:5], -1, 0
	s_cmp_lt_i32 s61, 22
	s_cselect_b64 s[6:7], -1, 0
	s_or_b64 s[4:5], s[4:5], s[6:7]
	s_and_b64 vcc, exec, s[4:5]
	s_cbranch_vccnz .LBB0_1714
	s_waitcnt vmcnt(0)
	v_mov_b32_e32 v4, v0
	s_cmpk_gt_i32 s2, 0x87f
	v_readfirstlane_b32 s3, v4
	s_cbranch_scc1 .LBB0_1664
	s_add_u32 s12, s52, 0x4b00000
	s_addc_u32 s6, s53, 0
	s_ashr_i32 s11, s2, 31
	s_and_b32 s13, s6, 0xffff
	s_lshr_b32 s6, s11, 29
	v_readlane_b32 s8, v255, 8
	s_add_i32 s6, s2, s6
	s_ashr_i32 s4, s3, 6
	v_readlane_b32 s9, v255, 9
	s_ashr_i32 s7, s6, 3
	s_and_b32 s6, s6, -8
	s_and_b32 s41, s9, 0xffff
	s_ashr_i32 s5, s3, 8
	s_lshl_b32 s8, s4, 10
	s_sub_i32 s6, s2, s6
	s_cmp_lt_i32 s6, 0
	s_movk_i32 s16, 0x111
	s_cselect_b32 s9, s16, 0x110
	s_mul_i32 s6, s9, s6
	s_add_i32 s6, s6, s7
	s_ashr_i32 s7, s6, 31
	s_lshr_b32 s7, s7, 26
	s_add_i32 s7, s6, s7
	v_ashrrev_i32_e32 v2, 31, v4
	s_ashr_i32 s9, s7, 6
	s_andn2_b32 s7, s7, 63
	v_lshrrev_b32_e32 v2, 26, v2
	s_sub_i32 s6, s6, s7
	v_add_u32_e32 v2, v4, v2
	s_bfe_i32 s7, s6, 0x80000
	v_ashrrev_i32_e32 v5, 6, v2
	v_bfe_i32 v2, v4, 27, 1
	s_bfe_u32 s7, s7, 0x3000c
	v_lshlrev_b32_e32 v1, 4, v4
	v_lshrrev_b32_e32 v2, 22, v2
	s_add_i32 s7, s6, s7
	v_add_u32_e32 v2, v1, v2
	s_bfe_i32 s10, s7, 0x80000
	s_and_b32 s7, s7, 0xf8
	v_and_b32_e32 v2, 0xfffffc00, v2
	s_sub_i32 s6, s6, s7
	v_sub_u32_e32 v1, v1, v2
	s_lshl_b32 s9, s9, 3
	s_sext_i32_i8 s6, s6
	v_lshrrev_b32_e32 v2, 4, v1
	s_add_i32 s49, s9, s6
	v_bitop3_b32 v1, v2, v1, 32 bitop3:0x6c
	s_mul_hi_i32 s6, s49, 0x78787879
	v_ashrrev_i32_e32 v3, 31, v1
	s_lshr_b32 s7, s6, 31
	s_lshr_b32 s6, s6, 3
	v_lshrrev_b32_e32 v3, 26, v3
	s_sext_i32_i16 s10, s10
	s_add_i32 s9, s6, s7
	s_lshl_b32 s6, s49, 8
	v_lshlrev_b32_e32 v2, 3, v5
	v_add_u32_e32 v8, v1, v3
	s_ashr_i32 s47, s10, 3
	s_ashr_i32 s7, s6, 31
	v_and_b32_e32 v2, -16, v2
	v_ashrrev_i32_e32 v9, 6, v8
	s_lshl_b32 s10, s47, 18
	s_lshl_b64 s[6:7], s[6:7], 2
	v_add_u32_e32 v2, v9, v2
	s_add_u32 s6, s74, s6
	s_addc_u32 s7, s75, s7
	v_ashrrev_i32_e32 v3, 31, v2
	v_lshl_add_u64 v[6:7], v[2:3], 2, s[6:7]
	global_load_dword v10, v[6:7], off
	global_load_dword v11, v[6:7], off offset:512
	global_load_dword v12, v[6:7], off offset:768
	s_nop 0
	global_load_dword v6, v[6:7], off offset:256
	v_and_b32_e32 v8, 0xc0, v8
	v_mov_b32_e32 v7, 1
	v_sub_u32_e32 v1, v1, v8
	s_mov_b32 s6, 0x3fffe0
	v_lshlrev_b32_e32 v5, 5, v5
	v_and_b32_e32 v8, 3, v9
	v_ashrrev_i16_sdwa v1, v7, sext(v1) dst_sel:DWORD dst_unused:UNUSED_PAD src0_sel:DWORD src1_sel:BYTE_0
	v_lshlrev_b32_e32 v7, 1, v2
	v_lshrrev_b32_e32 v9, 2, v2
	v_and_b32_e32 v5, 32, v5
	v_and_or_b32 v8, v2, s6, v8
	v_bfe_i32 v1, v1, 0, 16
	v_and_b32_e32 v7, 24, v7
	v_and_b32_e32 v9, 4, v9
	s_add_i32 s17, s8, 0
	s_mov_b32 s43, 0x20000
	s_brev_b32 s42, -2
	v_or3_b32 v7, v8, v9, v7
	v_add_lshl_u32 v1, v5, v1, 1
	s_lshl_b32 s6, s9, 21
	s_add_i32 s18, s17, 0x10000
	s_mov_b32 s14, s42
	s_mov_b32 s15, s43
	v_lshl_add_u32 v184, v7, 10, v1
	s_add_i32 s57, s6, s10
	s_add_i32 s19, s17, 0x12000
	s_mov_b32 m0, s18
	s_or_b32 s6, s57, 0x10000
	buffer_load_dwordx4 v184, s[12:15], s57 offen lds
	s_mov_b32 m0, s19
	s_add_i32 s20, s17, 0x2000
	buffer_load_dwordx4 v184, s[12:15], s6 offen lds
	s_mov_b32 m0, s17
	s_add_i32 s21, s17, 0x14000
	s_or_b32 s6, s57, 0x20000
	s_add_i32 s22, s17, 0x16000
	s_add_i32 s23, s17, 0x4000
	s_add_i32 s24, s17, 0x6000
	s_mov_b32 s25, 0
	s_waitcnt vmcnt(5)
	v_lshlrev_b32_e32 v5, 10, v10
	v_and_b32_e32 v5, 0x3fffc00, v5
	s_waitcnt vmcnt(4)
	v_lshl_or_b32 v186, v11, 16, v10
	s_waitcnt vmcnt(2)
	v_lshl_or_b32 v185, v12, 16, v6
	v_lshlrev_b32_e32 v6, 10, v6
	v_and_b32_e32 v7, 0x3fffc00, v6
	v_add_u32_e32 v6, v5, v1
	v_add_u32_e32 v5, v7, v1
	buffer_load_dwordx4 v6, s[40:43], 0 offen lds
	s_mov_b32 m0, s20
	v_bfe_u32 v7, v186, 16, 16
	buffer_load_dwordx4 v5, s[40:43], 0 offen lds
	s_mov_b32 m0, s21
	v_lshl_add_u32 v7, v7, 10, v1
	buffer_load_dwordx4 v184, s[12:15], s6 offen lds
	s_or_b32 s6, s57, 0x30000
	s_mov_b32 m0, s22
	s_cmp_lg_u32 s5, 1
	buffer_load_dwordx4 v184, s[12:15], s6 offen lds
	s_mov_b32 m0, s23
	s_nop 0
	buffer_load_dwordx4 v7, s[40:43], 0 offen lds
	v_bfe_u32 v7, v185, 16, 16
	v_lshl_add_u32 v7, v7, 10, v1
	s_mov_b32 m0, s24
	s_nop 0
	buffer_load_dwordx4 v7, s[40:43], 0 offen lds
	s_cbranch_scc1 .LBB0_1649
	s_barrier

.LBB0_1650:
	v_mov_b32_e32 v218, 0xbd38aa3b
	v_mov_b32_e32 v219, 0xbd38aa3b
	v_mov_b32_e32 v220, 0x44800000
	v_mov_b32_e32 v221, 0x44800000
	v_lshl_add_u32 v222, s49, 8, v187
	v_lshl_or_b32 v224, s47, 7, v188
	s_nop 0
	v_lshl_add_u32 v222, v222, 10, v224
	s_mov_b32 s47, s39
	s_mov_b32 s49, s45
	s_mov_b32 s57, s46
	v_pk_mul_f32 v[226:227], v[174:175], v[218:219]
	v_pk_mul_f32 v[228:229], v[176:177], v[218:219]
	v_pk_mul_f32 v[230:231], v[166:167], v[218:219]
	v_pk_mul_f32 v[232:233], v[168:169], v[218:219]
	v_exp_f32_e32 v226, v226
	v_exp_f32_e32 v227, v227
	v_exp_f32_e32 v228, v228
	v_exp_f32_e32 v229, v229
	v_exp_f32_e32 v230, v230
	v_exp_f32_e32 v231, v231
	v_exp_f32_e32 v232, v232
	v_exp_f32_e32 v233, v233
	v_pk_fma_f32 v[226:227], v[226:227], v[220:221], v[220:221]
	v_pk_fma_f32 v[228:229], v[228:229], v[220:221], v[220:221]
	v_pk_fma_f32 v[230:231], v[230:231], v[220:221], v[220:221]
	v_pk_fma_f32 v[232:233], v[232:233], v[220:221], v[220:221]
	v_rcp_f32_e32 v226, v226
	v_rcp_f32_e32 v227, v227
	v_rcp_f32_e32 v228, v228
	v_rcp_f32_e32 v229, v229
	v_rcp_f32_e32 v230, v230
	v_rcp_f32_e32 v231, v231
	v_rcp_f32_e32 v232, v232
	v_rcp_f32_e32 v233, v233
	v_pk_mul_f32 v[174:175], v[174:175], v[170:171]
	v_pk_mul_f32 v[176:177], v[176:177], v[172:173]
	v_pk_mul_f32 v[166:167], v[166:167], v[162:163]
	v_pk_mul_f32 v[168:169], v[168:169], v[164:165]
	v_pk_mul_f32 v[174:175], v[174:175], v[226:227]
	v_pk_mul_f32 v[176:177], v[176:177], v[228:229]
	v_pk_mul_f32 v[166:167], v[166:167], v[230:231]
	v_pk_mul_f32 v[168:169], v[168:169], v[232:233]
	v_mov_b32_e32 v223, v222
	v_cvt_pk_fp8_f32 v234, v174, v175
	v_cvt_pk_fp8_f32 v235, v166, v167
	v_cvt_pk_fp8_f32 v234, v176, v177 op_sel:[0,0,1]
	v_cvt_pk_fp8_f32 v235, v168, v169 op_sel:[0,0,1]
	s_nop 0
	global_store_dwordx2 v223, v[234:235], s[70:71]
	v_pk_mul_f32 v[226:227], v[158:159], v[218:219]
	v_pk_mul_f32 v[228:229], v[160:161], v[218:219]
	v_pk_mul_f32 v[230:231], v[150:151], v[218:219]
	v_pk_mul_f32 v[232:233], v[152:153], v[218:219]
	v_exp_f32_e32 v226, v226
	v_exp_f32_e32 v227, v227
	v_exp_f32_e32 v228, v228
	v_exp_f32_e32 v229, v229
	v_exp_f32_e32 v230, v230
	v_exp_f32_e32 v231, v231
	v_exp_f32_e32 v232, v232
	v_exp_f32_e32 v233, v233
	v_pk_fma_f32 v[226:227], v[226:227], v[220:221], v[220:221]
	v_pk_fma_f32 v[228:229], v[228:229], v[220:221], v[220:221]
	v_pk_fma_f32 v[230:231], v[230:231], v[220:221], v[220:221]
	v_pk_fma_f32 v[232:233], v[232:233], v[220:221], v[220:221]
	v_rcp_f32_e32 v226, v226
	v_rcp_f32_e32 v227, v227
	v_rcp_f32_e32 v228, v228
	v_rcp_f32_e32 v229, v229
	v_rcp_f32_e32 v230, v230
	v_rcp_f32_e32 v231, v231
	v_rcp_f32_e32 v232, v232
	v_rcp_f32_e32 v233, v233
	v_pk_mul_f32 v[158:159], v[158:159], v[154:155]
	v_pk_mul_f32 v[160:161], v[160:161], v[156:157]
	v_pk_mul_f32 v[150:151], v[150:151], v[146:147]
	v_pk_mul_f32 v[152:153], v[152:153], v[148:149]
	v_pk_mul_f32 v[158:159], v[158:159], v[226:227]
	v_pk_mul_f32 v[160:161], v[160:161], v[228:229]
	v_pk_mul_f32 v[150:151], v[150:151], v[230:231]
	v_pk_mul_f32 v[152:153], v[152:153], v[232:233]
	v_add_u32_e32 v225, 0x4000, v222
	v_cvt_pk_fp8_f32 v236, v158, v159
	v_cvt_pk_fp8_f32 v237, v150, v151
	v_cvt_pk_fp8_f32 v236, v160, v161 op_sel:[0,0,1]
	v_cvt_pk_fp8_f32 v237, v152, v153 op_sel:[0,0,1]
	s_nop 0
	global_store_dwordx2 v225, v[236:237], s[70:71]
	v_pk_mul_f32 v[226:227], v[142:143], v[218:219]
	v_pk_mul_f32 v[228:229], v[144:145], v[218:219]
	v_pk_mul_f32 v[230:231], v[134:135], v[218:219]
	v_pk_mul_f32 v[232:233], v[136:137], v[218:219]
	v_exp_f32_e32 v226, v226
	v_exp_f32_e32 v227, v227
	v_exp_f32_e32 v228, v228
	v_exp_f32_e32 v229, v229
	v_exp_f32_e32 v230, v230
	v_exp_f32_e32 v231, v231
	v_exp_f32_e32 v232, v232
	v_exp_f32_e32 v233, v233
	v_pk_fma_f32 v[226:227], v[226:227], v[220:221], v[220:221]
	v_pk_fma_f32 v[228:229], v[228:229], v[220:221], v[220:221]
	v_pk_fma_f32 v[230:231], v[230:231], v[220:221], v[220:221]
	v_pk_fma_f32 v[232:233], v[232:233], v[220:221], v[220:221]
	v_rcp_f32_e32 v226, v226
	v_rcp_f32_e32 v227, v227
	v_rcp_f32_e32 v228, v228
	v_rcp_f32_e32 v229, v229
	v_rcp_f32_e32 v230, v230
	v_rcp_f32_e32 v231, v231
	v_rcp_f32_e32 v232, v232
	v_rcp_f32_e32 v233, v233
	v_pk_mul_f32 v[142:143], v[142:143], v[138:139]
	v_pk_mul_f32 v[144:145], v[144:145], v[140:141]
	v_pk_mul_f32 v[134:135], v[134:135], v[130:131]
	v_pk_mul_f32 v[136:137], v[136:137], v[132:133]
	v_pk_mul_f32 v[142:143], v[142:143], v[226:227]
	v_pk_mul_f32 v[144:145], v[144:145], v[228:229]
	v_pk_mul_f32 v[134:135], v[134:135], v[230:231]
	v_pk_mul_f32 v[136:137], v[136:137], v[232:233]
	v_add_u32_e32 v223, 0x8000, v222
	v_cvt_pk_fp8_f32 v234, v142, v143
	v_cvt_pk_fp8_f32 v235, v134, v135
	v_cvt_pk_fp8_f32 v234, v144, v145 op_sel:[0,0,1]
	v_cvt_pk_fp8_f32 v235, v136, v137 op_sel:[0,0,1]
	s_nop 0
	global_store_dwordx2 v223, v[234:235], s[70:71]
	v_pk_mul_f32 v[226:227], v[126:127], v[218:219]
	v_pk_mul_f32 v[228:229], v[128:129], v[218:219]
	v_pk_mul_f32 v[230:231], v[118:119], v[218:219]
	v_pk_mul_f32 v[232:233], v[120:121], v[218:219]
	v_exp_f32_e32 v226, v226
	v_exp_f32_e32 v227, v227
	v_exp_f32_e32 v228, v228
	v_exp_f32_e32 v229, v229
	v_exp_f32_e32 v230, v230
	v_exp_f32_e32 v231, v231
	v_exp_f32_e32 v232, v232
	v_exp_f32_e32 v233, v233
	v_pk_fma_f32 v[226:227], v[226:227], v[220:221], v[220:221]
	v_pk_fma_f32 v[228:229], v[228:229], v[220:221], v[220:221]
	v_pk_fma_f32 v[230:231], v[230:231], v[220:221], v[220:221]
	v_pk_fma_f32 v[232:233], v[232:233], v[220:221], v[220:221]
	v_rcp_f32_e32 v226, v226
	v_rcp_f32_e32 v227, v227
	v_rcp_f32_e32 v228, v228
	v_rcp_f32_e32 v229, v229
	v_rcp_f32_e32 v230, v230
	v_rcp_f32_e32 v231, v231
	v_rcp_f32_e32 v232, v232
	v_rcp_f32_e32 v233, v233
	v_pk_mul_f32 v[126:127], v[126:127], v[122:123]
	v_pk_mul_f32 v[128:129], v[128:129], v[124:125]
	v_pk_mul_f32 v[118:119], v[118:119], v[114:115]
	v_pk_mul_f32 v[120:121], v[120:121], v[116:117]
	v_pk_mul_f32 v[126:127], v[126:127], v[226:227]
	v_pk_mul_f32 v[128:129], v[128:129], v[228:229]
	v_pk_mul_f32 v[118:119], v[118:119], v[230:231]
	v_pk_mul_f32 v[120:121], v[120:121], v[232:233]
	v_add_u32_e32 v225, 0xc000, v222
	v_cvt_pk_fp8_f32 v236, v126, v127
	v_cvt_pk_fp8_f32 v237, v118, v119
	v_cvt_pk_fp8_f32 v236, v128, v129 op_sel:[0,0,1]
	v_cvt_pk_fp8_f32 v237, v120, v121 op_sel:[0,0,1]
	s_nop 0
	global_store_dwordx2 v225, v[236:237], s[70:71]
	v_pk_mul_f32 v[226:227], v[110:111], v[218:219]
	v_pk_mul_f32 v[228:229], v[112:113], v[218:219]
	v_pk_mul_f32 v[230:231], v[102:103], v[218:219]
	v_pk_mul_f32 v[232:233], v[104:105], v[218:219]
	v_exp_f32_e32 v226, v226
	v_exp_f32_e32 v227, v227
	v_exp_f32_e32 v228, v228
	v_exp_f32_e32 v229, v229
	v_exp_f32_e32 v230, v230
	v_exp_f32_e32 v231, v231
	v_exp_f32_e32 v232, v232
	v_exp_f32_e32 v233, v233
	v_pk_fma_f32 v[226:227], v[226:227], v[220:221], v[220:221]
	v_pk_fma_f32 v[228:229], v[228:229], v[220:221], v[220:221]
	v_pk_fma_f32 v[230:231], v[230:231], v[220:221], v[220:221]
	v_pk_fma_f32 v[232:233], v[232:233], v[220:221], v[220:221]
	v_rcp_f32_e32 v226, v226
	v_rcp_f32_e32 v227, v227
	v_rcp_f32_e32 v228, v228
	v_rcp_f32_e32 v229, v229
	v_rcp_f32_e32 v230, v230
	v_rcp_f32_e32 v231, v231
	v_rcp_f32_e32 v232, v232
	v_rcp_f32_e32 v233, v233
	v_pk_mul_f32 v[110:111], v[110:111], v[106:107]
	v_pk_mul_f32 v[112:113], v[112:113], v[108:109]
	v_pk_mul_f32 v[102:103], v[102:103], v[98:99]
	v_pk_mul_f32 v[104:105], v[104:105], v[100:101]
	v_pk_mul_f32 v[110:111], v[110:111], v[226:227]
	v_pk_mul_f32 v[112:113], v[112:113], v[228:229]
	v_pk_mul_f32 v[102:103], v[102:103], v[230:231]
	v_pk_mul_f32 v[104:105], v[104:105], v[232:233]
	v_add_u32_e32 v223, 0x20000, v222
	v_cvt_pk_fp8_f32 v234, v110, v111
	v_cvt_pk_fp8_f32 v235, v102, v103
	v_cvt_pk_fp8_f32 v234, v112, v113 op_sel:[0,0,1]
	v_cvt_pk_fp8_f32 v235, v104, v105 op_sel:[0,0,1]
	s_nop 0
	global_store_dwordx2 v223, v[234:235], s[70:71]
	v_pk_mul_f32 v[226:227], v[94:95], v[218:219]
	v_pk_mul_f32 v[228:229], v[96:97], v[218:219]
	v_pk_mul_f32 v[230:231], v[86:87], v[218:219]
	v_pk_mul_f32 v[232:233], v[88:89], v[218:219]
	v_exp_f32_e32 v226, v226
	v_exp_f32_e32 v227, v227
	v_exp_f32_e32 v228, v228
	v_exp_f32_e32 v229, v229
	v_exp_f32_e32 v230, v230
	v_exp_f32_e32 v231, v231
	v_exp_f32_e32 v232, v232
	v_exp_f32_e32 v233, v233
	v_pk_fma_f32 v[226:227], v[226:227], v[220:221], v[220:221]
	v_pk_fma_f32 v[228:229], v[228:229], v[220:221], v[220:221]
	v_pk_fma_f32 v[230:231], v[230:231], v[220:221], v[220:221]
	v_pk_fma_f32 v[232:233], v[232:233], v[220:221], v[220:221]
	v_rcp_f32_e32 v226, v226
	v_rcp_f32_e32 v227, v227
	v_rcp_f32_e32 v228, v228
	v_rcp_f32_e32 v229, v229
	v_rcp_f32_e32 v230, v230
	v_rcp_f32_e32 v231, v231
	v_rcp_f32_e32 v232, v232
	v_rcp_f32_e32 v233, v233
	v_pk_mul_f32 v[94:95], v[94:95], v[90:91]
	v_pk_mul_f32 v[96:97], v[96:97], v[92:93]
	v_pk_mul_f32 v[86:87], v[86:87], v[82:83]
	v_pk_mul_f32 v[88:89], v[88:89], v[84:85]
	v_pk_mul_f32 v[94:95], v[94:95], v[226:227]
	v_pk_mul_f32 v[96:97], v[96:97], v[228:229]
	v_pk_mul_f32 v[86:87], v[86:87], v[230:231]
	v_pk_mul_f32 v[88:89], v[88:89], v[232:233]
	v_add_u32_e32 v225, 0x24000, v222
	v_cvt_pk_fp8_f32 v236, v94, v95
	v_cvt_pk_fp8_f32 v237, v86, v87
	v_cvt_pk_fp8_f32 v236, v96, v97 op_sel:[0,0,1]
	v_cvt_pk_fp8_f32 v237, v88, v89 op_sel:[0,0,1]
	s_nop 0
	global_store_dwordx2 v225, v[236:237], s[70:71]
	v_pk_mul_f32 v[226:227], v[78:79], v[218:219]
	v_pk_mul_f32 v[228:229], v[80:81], v[218:219]
	v_pk_mul_f32 v[230:231], v[70:71], v[218:219]
	v_pk_mul_f32 v[232:233], v[72:73], v[218:219]
	v_exp_f32_e32 v226, v226
	v_exp_f32_e32 v227, v227
	v_exp_f32_e32 v228, v228
	v_exp_f32_e32 v229, v229
	v_exp_f32_e32 v230, v230
	v_exp_f32_e32 v231, v231
	v_exp_f32_e32 v232, v232
	v_exp_f32_e32 v233, v233
	v_pk_fma_f32 v[226:227], v[226:227], v[220:221], v[220:221]
	v_pk_fma_f32 v[228:229], v[228:229], v[220:221], v[220:221]
	v_pk_fma_f32 v[230:231], v[230:231], v[220:221], v[220:221]
	v_pk_fma_f32 v[232:233], v[232:233], v[220:221], v[220:221]
	v_rcp_f32_e32 v226, v226
	v_rcp_f32_e32 v227, v227
	v_rcp_f32_e32 v228, v228
	v_rcp_f32_e32 v229, v229
	v_rcp_f32_e32 v230, v230
	v_rcp_f32_e32 v231, v231
	v_rcp_f32_e32 v232, v232
	v_rcp_f32_e32 v233, v233
	v_pk_mul_f32 v[78:79], v[78:79], v[74:75]
	v_pk_mul_f32 v[80:81], v[80:81], v[76:77]
	v_pk_mul_f32 v[70:71], v[70:71], v[66:67]
	v_pk_mul_f32 v[72:73], v[72:73], v[68:69]
	v_pk_mul_f32 v[78:79], v[78:79], v[226:227]
	v_pk_mul_f32 v[80:81], v[80:81], v[228:229]
	v_pk_mul_f32 v[70:71], v[70:71], v[230:231]
	v_pk_mul_f32 v[72:73], v[72:73], v[232:233]
	v_add_u32_e32 v223, 0x28000, v222
	v_cvt_pk_fp8_f32 v234, v78, v79
	v_cvt_pk_fp8_f32 v235, v70, v71
	v_cvt_pk_fp8_f32 v234, v80, v81 op_sel:[0,0,1]
	v_cvt_pk_fp8_f32 v235, v72, v73 op_sel:[0,0,1]
	s_nop 0
	global_store_dwordx2 v223, v[234:235], s[70:71]
	v_pk_mul_f32 v[226:227], v[62:63], v[218:219]
	v_pk_mul_f32 v[228:229], v[64:65], v[218:219]
	v_pk_mul_f32 v[230:231], v[54:55], v[218:219]
	v_pk_mul_f32 v[232:233], v[56:57], v[218:219]
	v_exp_f32_e32 v226, v226
	v_exp_f32_e32 v227, v227
	v_exp_f32_e32 v228, v228
	v_exp_f32_e32 v229, v229
	v_exp_f32_e32 v230, v230
	v_exp_f32_e32 v231, v231
	v_exp_f32_e32 v232, v232
	v_exp_f32_e32 v233, v233
	v_pk_fma_f32 v[226:227], v[226:227], v[220:221], v[220:221]
	v_pk_fma_f32 v[228:229], v[228:229], v[220:221], v[220:221]
	v_pk_fma_f32 v[230:231], v[230:231], v[220:221], v[220:221]
	v_pk_fma_f32 v[232:233], v[232:233], v[220:221], v[220:221]
	v_rcp_f32_e32 v226, v226
	v_rcp_f32_e32 v227, v227
	v_rcp_f32_e32 v228, v228
	v_rcp_f32_e32 v229, v229
	v_rcp_f32_e32 v230, v230
	v_rcp_f32_e32 v231, v231
	v_rcp_f32_e32 v232, v232
	v_rcp_f32_e32 v233, v233
	v_pk_mul_f32 v[62:63], v[62:63], v[58:59]
	v_pk_mul_f32 v[64:65], v[64:65], v[60:61]
	v_pk_mul_f32 v[54:55], v[54:55], v[50:51]
	v_pk_mul_f32 v[56:57], v[56:57], v[52:53]
	v_pk_mul_f32 v[62:63], v[62:63], v[226:227]
	v_pk_mul_f32 v[64:65], v[64:65], v[228:229]
	v_pk_mul_f32 v[54:55], v[54:55], v[230:231]
	v_pk_mul_f32 v[56:57], v[56:57], v[232:233]
	v_add_u32_e32 v225, 0x2c000, v222
	v_cvt_pk_fp8_f32 v236, v62, v63
	v_cvt_pk_fp8_f32 v237, v54, v55
	v_cvt_pk_fp8_f32 v236, v64, v65 op_sel:[0,0,1]
	v_cvt_pk_fp8_f32 v237, v56, v57 op_sel:[0,0,1]
	s_nop 0
	global_store_dwordx2 v225, v[236:237], s[70:71]
	s_and_b64 vcc, exec, s[4:5]
	s_cbranch_vccnz .LBB0_1661

.LBB0_1658:
	s_and_b64 s[14:15], s[6:7], exec
	s_cselect_b32 s59, 0, s9
	s_add_i32 s14, s57, s9
	s_or_b32 s58, s59, 0x80
	s_waitcnt lgkmcnt(8)
	s_barrier
	s_waitcnt lgkmcnt(0)
	s_and_b64 s[6:7], s[6:7], exec
	s_cselect_b32 s6, s46, s14
	s_add_i32 s7, s6, 0x80
	s_setprio 1
	s_waitcnt lgkmcnt(6)
	v_mfma_f32_16x16x128_f8f6f4 v[174:177], v[2:9], v[42:49], v[174:177]
	v_mfma_f32_16x16x128_f8f6f4 v[166:169], v[10:17], v[42:49], v[166:169]
	s_waitcnt lgkmcnt(4)
	v_mfma_f32_16x16x128_f8f6f4 v[158:161], v[2:9], v[34:41], v[158:161]
	v_mfma_f32_16x16x128_f8f6f4 v[150:153], v[10:17], v[34:41], v[150:153]
	s_waitcnt lgkmcnt(2)
	v_mfma_f32_16x16x128_f8f6f4 v[142:145], v[2:9], v[26:33], v[142:145]
	v_mfma_f32_16x16x128_f8f6f4 v[134:137], v[10:17], v[26:33], v[134:137]
	s_waitcnt lgkmcnt(0)
	v_mfma_f32_16x16x128_f8f6f4 v[126:129], v[2:9], v[18:25], v[126:129]
	v_mfma_f32_16x16x128_f8f6f4 v[118:121], v[10:17], v[18:25], v[118:121]
	s_setprio 0
	s_barrier
	s_mov_b32 m0, s18
	v_add_u32_e32 v210, 0x14000, v189
	s_mov_b32 s14, s42
	s_mov_b32 s15, s43
	ds_read_b128 v[198:201], v210
	ds_read_b128 v[202:205], v210 offset:1024
	ds_read_b128 v[206:209], v210 offset:2048
	ds_read_b128 v[210:213], v210 offset:3072
	buffer_load_dwordx4 v184, s[12:15], s6 offen lds
	s_add_i32 s33, s6, 0x10000
	s_mov_b32 m0, s19
	s_nop 0
	buffer_load_dwordx4 v184, s[12:15], s33 offen lds
	s_barrier
	s_waitcnt lgkmcnt(0)
	s_setprio 1
	s_waitcnt lgkmcnt(2)
	v_mfma_f32_16x16x128_f8f6f4 v[170:173], v[198:205], v[42:49], v[170:173]
	s_waitcnt lgkmcnt(0)
	v_mfma_f32_16x16x128_f8f6f4 v[162:165], v[206:213], v[42:49], v[162:165]
	v_mfma_f32_16x16x128_f8f6f4 v[154:157], v[198:205], v[34:41], v[154:157]
	v_mfma_f32_16x16x128_f8f6f4 v[146:149], v[206:213], v[34:41], v[146:149]
	v_mfma_f32_16x16x128_f8f6f4 v[138:141], v[198:205], v[26:33], v[138:141]
	v_mfma_f32_16x16x128_f8f6f4 v[130:133], v[206:213], v[26:33], v[130:133]
	v_mfma_f32_16x16x128_f8f6f4 v[122:125], v[198:205], v[18:25], v[122:125]
	v_mfma_f32_16x16x128_f8f6f4 v[114:117], v[206:213], v[18:25], v[114:117]
	s_setprio 0
	v_lshlrev_b32_e32 v214, 10, v186
	v_and_b32_e32 v214, 0x3fffc00, v214
	v_lshlrev_b32_e32 v215, 10, v185
	s_mov_b32 m0, s17
	v_add_u32_e32 v214, v214, v1
	v_and_b32_e32 v215, 0x3fffc00, v215
	s_barrier
	ds_read_b128 v[18:21], v191 offset:16384
	ds_read_b128 v[22:25], v191 offset:17408
	ds_read_b128 v[26:29], v191 offset:18432
	ds_read_b128 v[30:33], v191 offset:19456
	ds_read_b128 v[34:37], v191 offset:20480
	ds_read_b128 v[38:41], v191 offset:21504
	ds_read_b128 v[42:45], v191 offset:22528
	ds_read_b128 v[46:49], v191 offset:23552
	buffer_load_dwordx4 v214, s[40:43], s59 offen lds
	v_add_u32_e32 v215, v215, v1
	s_mov_b32 m0, s20
	s_nop 0
	buffer_load_dwordx4 v215, s[40:43], s59 offen lds
	s_barrier
	s_waitcnt lgkmcnt(0)
	s_setprio 1
	s_waitcnt lgkmcnt(6)
	v_mfma_f32_16x16x128_f8f6f4 v[110:113], v[2:9], v[18:25], v[110:113]
	v_mfma_f32_16x16x128_f8f6f4 v[102:105], v[10:17], v[18:25], v[102:105]
	s_waitcnt lgkmcnt(4)
	v_mfma_f32_16x16x128_f8f6f4 v[94:97], v[2:9], v[26:33], v[94:97]
	v_mfma_f32_16x16x128_f8f6f4 v[86:89], v[10:17], v[26:33], v[86:89]
	s_waitcnt lgkmcnt(2)
	v_mfma_f32_16x16x128_f8f6f4 v[78:81], v[2:9], v[34:41], v[78:81]
	v_mfma_f32_16x16x128_f8f6f4 v[70:73], v[10:17], v[34:41], v[70:73]
	s_waitcnt lgkmcnt(0)
	v_mfma_f32_16x16x128_f8f6f4 v[62:65], v[2:9], v[42:49], v[62:65]
	v_mfma_f32_16x16x128_f8f6f4 v[54:57], v[10:17], v[42:49], v[54:57]
	s_setprio 0
	s_barrier
	s_mov_b32 m0, s21
	s_add_i32 s33, s6, 0x20000
	buffer_load_dwordx4 v184, s[12:15], s33 offen lds
	s_add_i32 s33, s6, 0x30000
	s_mov_b32 m0, s22
	s_nop 0
	buffer_load_dwordx4 v184, s[12:15], s33 offen lds
	s_waitcnt vmcnt(6)
	s_barrier
	s_setprio 1
	v_mfma_f32_16x16x128_f8f6f4 v[106:109], v[198:205], v[18:25], v[106:109]
	v_mfma_f32_16x16x128_f8f6f4 v[98:101], v[206:213], v[18:25], v[98:101]
	v_mfma_f32_16x16x128_f8f6f4 v[90:93], v[198:205], v[26:33], v[90:93]
	v_mfma_f32_16x16x128_f8f6f4 v[82:85], v[206:213], v[26:33], v[82:85]
	v_mfma_f32_16x16x128_f8f6f4 v[74:77], v[198:205], v[34:41], v[74:77]
	v_mfma_f32_16x16x128_f8f6f4 v[66:69], v[206:213], v[34:41], v[66:69]
	v_mfma_f32_16x16x128_f8f6f4 v[58:61], v[198:205], v[42:49], v[58:61]
	v_mfma_f32_16x16x128_f8f6f4 v[50:53], v[206:213], v[42:49], v[50:53]
	s_setprio 0
	v_add_u32_e32 v14, 0x18000, v189
	s_barrier
	ds_read_b128 v[2:5], v14
	ds_read_b128 v[6:9], v14 offset:1024
	ds_read_b128 v[10:13], v14 offset:2048
	ds_read_b128 v[14:17], v14 offset:3072
	s_mov_b32 m0, s23
	ds_read_b128 v[18:21], v191 offset:32768
	ds_read_b128 v[22:25], v191 offset:33792
	ds_read_b128 v[26:29], v191 offset:34816
	ds_read_b128 v[30:33], v191 offset:35840
	ds_read_b128 v[34:37], v191 offset:36864
	ds_read_b128 v[38:41], v191 offset:37888
	ds_read_b128 v[42:45], v191 offset:38912
	ds_read_b128 v[46:49], v191 offset:39936
	buffer_load_dwordx4 v196, s[40:43], s59 offen lds
	s_mov_b32 m0, s24
	s_nop 0
	buffer_load_dwordx4 v197, s[40:43], s59 offen lds
	s_waitcnt lgkmcnt(8)
	s_barrier
	s_waitcnt lgkmcnt(0)
	s_setprio 1
	s_waitcnt lgkmcnt(6)
	v_mfma_f32_16x16x128_f8f6f4 v[174:177], v[2:9], v[18:25], v[174:177]
	v_mfma_f32_16x16x128_f8f6f4 v[166:169], v[10:17], v[18:25], v[166:169]
	s_waitcnt lgkmcnt(4)
	v_mfma_f32_16x16x128_f8f6f4 v[158:161], v[2:9], v[26:33], v[158:161]
	v_mfma_f32_16x16x128_f8f6f4 v[150:153], v[10:17], v[26:33], v[150:153]
	s_waitcnt lgkmcnt(2)
	v_mfma_f32_16x16x128_f8f6f4 v[142:145], v[2:9], v[34:41], v[142:145]
	v_mfma_f32_16x16x128_f8f6f4 v[134:137], v[10:17], v[34:41], v[134:137]
	s_waitcnt lgkmcnt(0)
	v_mfma_f32_16x16x128_f8f6f4 v[126:129], v[2:9], v[42:49], v[126:129]
	v_mfma_f32_16x16x128_f8f6f4 v[118:121], v[10:17], v[42:49], v[118:121]
	s_setprio 0
	s_barrier
	s_mov_b32 m0, s26
	v_add_u32_e32 v208, 0x1c000, v189
	ds_read_b128 v[196:199], v208
	ds_read_b128 v[200:203], v208 offset:1024
	ds_read_b128 v[204:207], v208 offset:2048
	ds_read_b128 v[208:211], v208 offset:3072
	buffer_load_dwordx4 v184, s[12:15], s7 offen lds
	s_add_i32 s7, s6, 0x10080
	s_mov_b32 m0, s27
	s_nop 0
	buffer_load_dwordx4 v184, s[12:15], s7 offen lds
	s_barrier
	s_waitcnt lgkmcnt(0)
	s_setprio 1
	s_waitcnt lgkmcnt(2)
	v_mfma_f32_16x16x128_f8f6f4 v[170:173], v[196:203], v[18:25], v[170:173]
	s_waitcnt lgkmcnt(0)
	v_mfma_f32_16x16x128_f8f6f4 v[162:165], v[204:211], v[18:25], v[162:165]
	v_mfma_f32_16x16x128_f8f6f4 v[154:157], v[196:203], v[26:33], v[154:157]
	v_mfma_f32_16x16x128_f8f6f4 v[146:149], v[204:211], v[26:33], v[146:149]
	v_mfma_f32_16x16x128_f8f6f4 v[138:141], v[196:203], v[34:41], v[138:141]
	v_mfma_f32_16x16x128_f8f6f4 v[130:133], v[204:211], v[34:41], v[130:133]
	v_mfma_f32_16x16x128_f8f6f4 v[122:125], v[196:203], v[42:49], v[122:125]
	v_mfma_f32_16x16x128_f8f6f4 v[114:117], v[204:211], v[42:49], v[114:117]
	s_setprio 0
	s_mov_b32 m0, s28
	s_barrier
	ds_read_b128 v[18:21], v191 offset:49152
	ds_read_b128 v[22:25], v191 offset:50176
	ds_read_b128 v[26:29], v191 offset:51200
	ds_read_b128 v[30:33], v191 offset:52224
	ds_read_b128 v[34:37], v191 offset:53248
	ds_read_b128 v[38:41], v191 offset:54272
	ds_read_b128 v[42:45], v191 offset:55296
	ds_read_b128 v[46:49], v191 offset:56320
	buffer_load_dwordx4 v214, s[40:43], s58 offen lds
	s_mov_b32 m0, s29
	s_nop 0
	buffer_load_dwordx4 v215, s[40:43], s58 offen lds
	s_barrier
	s_waitcnt lgkmcnt(0)
	s_setprio 1
	s_waitcnt lgkmcnt(6)
	v_mfma_f32_16x16x128_f8f6f4 v[110:113], v[2:9], v[18:25], v[110:113]
	v_mfma_f32_16x16x128_f8f6f4 v[102:105], v[10:17], v[18:25], v[102:105]
	s_waitcnt lgkmcnt(4)
	v_mfma_f32_16x16x128_f8f6f4 v[94:97], v[2:9], v[26:33], v[94:97]
	v_mfma_f32_16x16x128_f8f6f4 v[86:89], v[10:17], v[26:33], v[86:89]
	s_waitcnt lgkmcnt(2)
	v_mfma_f32_16x16x128_f8f6f4 v[78:81], v[2:9], v[34:41], v[78:81]
	v_mfma_f32_16x16x128_f8f6f4 v[70:73], v[10:17], v[34:41], v[70:73]
	s_waitcnt lgkmcnt(0)
	v_mfma_f32_16x16x128_f8f6f4 v[62:65], v[2:9], v[42:49], v[62:65]
	v_mfma_f32_16x16x128_f8f6f4 v[54:57], v[10:17], v[42:49], v[54:57]
	s_setprio 0
	s_barrier
	s_mov_b32 m0, s30
	s_add_i32 s7, s6, 0x20080
	buffer_load_dwordx4 v184, s[12:15], s7 offen lds
	s_add_i32 s6, s6, 0x30080
	s_mov_b32 m0, s31
	s_nop 0
	buffer_load_dwordx4 v184, s[12:15], s6 offen lds
	s_waitcnt vmcnt(6)
	s_barrier
	s_setprio 1
	v_mfma_f32_16x16x128_f8f6f4 v[106:109], v[196:203], v[18:25], v[106:109]
	v_mfma_f32_16x16x128_f8f6f4 v[98:101], v[204:211], v[18:25], v[98:101]
	v_mfma_f32_16x16x128_f8f6f4 v[90:93], v[196:203], v[26:33], v[90:93]
	v_mfma_f32_16x16x128_f8f6f4 v[82:85], v[204:211], v[26:33], v[82:85]
	v_mfma_f32_16x16x128_f8f6f4 v[74:77], v[196:203], v[34:41], v[74:77]
	v_mfma_f32_16x16x128_f8f6f4 v[66:69], v[204:211], v[34:41], v[66:69]
	v_mfma_f32_16x16x128_f8f6f4 v[58:61], v[196:203], v[42:49], v[58:61]
	v_mfma_f32_16x16x128_f8f6f4 v[50:53], v[204:211], v[42:49], v[50:53]
	s_setprio 0
	s_add_i32 s8, s8, 2
	s_addk_i32 s9, 0x100
	s_cmp_gt_u32 s8, 5
	s_barrier
	s_cbranch_scc1 .LBB0_1650

.LBB0_1714:
	s_cmp_gt_i32 s60, 22
	s_cselect_b64 s[4:5], -1, 0
	s_cmp_lt_i32 s61, 23
	s_cselect_b64 s[6:7], -1, 0
	s_or_b64 s[4:5], s[4:5], s[6:7]
	s_and_b64 vcc, exec, s[4:5]
	s_cbranch_vccnz .LBB0_1779
	s_waitcnt vmcnt(0)
	v_mov_b32_e32 v2, v0
	s_cmpk_gt_i32 s2, 0x43f
	v_readfirstlane_b32 s3, v2
	s_cbranch_scc1 .LBB0_1729
	v_bfe_i32 v4, v2, 27, 1
	v_lshlrev_b32_e32 v1, 4, v2
	v_lshrrev_b32_e32 v4, 22, v4
	v_add_u32_e32 v4, v1, v4
	v_and_b32_e32 v4, 0xfffffc00, v4
	v_sub_u32_e32 v1, v1, v4
	v_ashrrev_i32_e32 v3, 31, v2
	v_lshrrev_b32_e32 v4, 4, v1
	v_lshrrev_b32_e32 v3, 26, v3
	v_bitop3_b32 v1, v4, v1, 32 bitop3:0x6c
	s_add_u32 s8, s52, 0x7b00000
	v_add_u32_e32 v3, v2, v3
	v_ashrrev_i32_e32 v5, 31, v1
	s_addc_u32 s6, s53, 0
	v_ashrrev_i32_e32 v3, 6, v3
	v_lshrrev_b32_e32 v5, 26, v5
	s_ashr_i32 s20, s2, 31
	v_lshlrev_b32_e32 v4, 3, v3
	v_add_u32_e32 v5, v1, v5
	s_lshr_b32 s7, s20, 29
	v_and_b32_e32 v4, -16, v4
	v_ashrrev_i32_e32 v6, 6, v5
	s_add_i32 s7, s2, s7
	s_ashr_i32 s4, s3, 6
	v_add_u32_e32 v4, v6, v4
	v_and_b32_e32 v6, 3, v6
	s_mov_b32 s5, 0x3fffe0
	s_ashr_i32 s12, s7, 3
	s_and_b32 s7, s7, -8
	s_and_b32 s45, s71, 0xffff
	v_and_or_b32 v6, v4, s5, v6
	s_ashr_i32 s5, s3, 8
	s_and_b32 s9, s6, 0xffff
	s_lshl_b32 s6, s4, 10
	s_sub_i32 s7, s2, s7
	s_cmp_lt_i32 s7, 0
	s_movk_i32 s21, 0x89
	s_cselect_b32 s13, s21, 0x88
	s_mul_i32 s7, s13, s7
	s_add_i32 s7, s7, s12
	s_ashr_i32 s12, s7, 31
	s_lshr_b32 s12, s12, 27
	s_add_i32 s12, s7, s12
	s_ashr_i32 s13, s12, 5
	s_andn2_b32 s12, s12, 31
	s_sub_i32 s7, s7, s12
	s_bfe_i32 s12, s7, 0x80000
	s_bfe_u32 s12, s12, 0x3000c
	s_add_i32 s12, s7, s12
	s_bfe_i32 s14, s12, 0x80000
	s_and_b32 s12, s12, 0xf8
	s_sub_i32 s7, s7, s12
	s_lshl_b32 s13, s13, 3
	s_sext_i32_i8 s7, s7
	v_and_b32_e32 v5, 0xc0, v5
	s_add_i32 s79, s13, s7
	v_sub_u32_e32 v1, v1, v5
	v_mov_b32_e32 v5, 1
	s_mul_hi_i32 s7, s79, 0x78787879
	v_lshlrev_b32_e32 v3, 5, v3
	v_ashrrev_i16_sdwa v1, v5, sext(v1) dst_sel:DWORD dst_unused:UNUSED_PAD src0_sel:DWORD src1_sel:BYTE_0
	v_lshlrev_b32_e32 v5, 1, v4
	v_lshrrev_b32_e32 v7, 2, v4
	s_sext_i32_i16 s14, s14
	s_lshr_b32 s12, s7, 31
	s_lshr_b32 s7, s7, 3
	v_and_b32_e32 v3, 32, v3
	v_bfe_i32 v1, v1, 0, 16
	v_and_b32_e32 v5, 24, v5
	v_and_b32_e32 v7, 4, v7
	s_ashr_i32 s78, s14, 3
	s_add_i32 s7, s7, s12
	s_add_i32 s22, s6, 0
	s_mov_b32 s47, 0x20000
	s_brev_b32 s46, -2
	v_or3_b32 v5, v6, v7, v5
	v_add_lshl_u32 v3, v3, v1, 1
	s_lshl_b32 s7, s7, 20
	s_lshl_b32 s12, s78, 18
	s_add_i32 s23, s22, 0x10000
	v_lshl_add_u32 v134, v5, 10, v3
	s_mov_b32 s10, s46
	s_mov_b32 s11, s47
	s_add_i32 s84, s7, s12
	s_mov_b32 m0, s23
	s_add_i32 s24, s22, 0x12000
	buffer_load_dwordx4 v134, s[8:11], s84 offen lds
	s_or_b32 s6, s84, 0x10000
	s_mov_b32 m0, s24
	v_lshl_add_u32 v1, v4, 10, v3
	buffer_load_dwordx4 v134, s[8:11], s6 offen lds
	s_lshl_b32 s85, s79, 18
	s_mov_b32 m0, s22
	s_add_i32 s25, s22, 0x2000
	buffer_load_dwordx4 v1, s[44:47], s85 offen lds
	s_or_b32 s6, s85, 0x10000
	s_mov_b32 m0, s25
	s_add_i32 s26, s22, 0x14000
	buffer_load_dwordx4 v1, s[44:47], s6 offen lds
	s_or_b32 s6, s84, 0x20000
	s_mov_b32 m0, s26
	s_add_i32 s27, s22, 0x16000
	buffer_load_dwordx4 v134, s[8:11], s6 offen lds
	s_or_b32 s6, s84, 0x30000
	s_mov_b32 m0, s27
	s_add_i32 s28, s22, 0x4000
	buffer_load_dwordx4 v134, s[8:11], s6 offen lds
	s_or_b32 s6, s85, 0x20000
	s_mov_b32 m0, s28
	s_add_i32 s29, s22, 0x6000
	buffer_load_dwordx4 v1, s[44:47], s6 offen lds
	s_or_b32 s6, s85, 0x30000
	s_mov_b32 m0, s29
	s_cmp_lg_u32 s5, 1
	buffer_load_dwordx4 v1, s[44:47], s6 offen lds
	s_mov_b32 s30, 0
	s_cbranch_scc1 .LBB0_1718
	s_barrier

.LBB0_1724:
	ds_read_b128 v[142:145], v137
	ds_read_b128 v[146:149], v137 offset:1024
	ds_read_b128 v[150:153], v137 offset:2048
	ds_read_b128 v[154:157], v137 offset:3072
	s_add_i32 s10, s7, 0xfffd0080
	s_cmp_eq_u32 s85, 4
	s_cselect_b32 s87, s6, s10
	s_cselect_b32 s86, s72, s84
	s_or_b32 s88, s87, 0x80
	s_add_i32 s10, s7, 0xffff0000
	s_mov_b32 m0, s39
	ds_read_b128 v[158:161], v138
	ds_read_b128 v[162:165], v138 offset:1024
	ds_read_b128 v[166:169], v138 offset:2048
	ds_read_b128 v[170:173], v138 offset:3072
	ds_read_b128 v[174:177], v138 offset:4096
	ds_read_b128 v[178:181], v138 offset:5120
	ds_read_b128 v[182:185], v138 offset:6144
	ds_read_b128 v[186:189], v138 offset:7168
	buffer_load_dwordx4 v1, s[44:47], s10 offen lds
	s_mov_b32 m0, s41
	s_nop 0
	buffer_load_dwordx4 v1, s[44:47], s7 offen lds
	s_waitcnt lgkmcnt(8)
	s_barrier
	s_waitcnt lgkmcnt(0)
	s_setprio 1
	s_waitcnt lgkmcnt(4)
	v_mfma_f32_16x16x128_f8f6f4 v[114:117], v[142:149], v[166:173], v[114:117]
	v_mfma_f32_16x16x128_f8f6f4 v[106:109], v[150:157], v[166:173], v[106:109]
	s_waitcnt lgkmcnt(2)
	v_mfma_f32_16x16x128_f8f6f4 v[98:101], v[142:149], v[174:181], v[98:101]
	v_mfma_f32_16x16x128_f8f6f4 v[198:201], v[142:149], v[158:165], v[126:129]
	v_mfma_f32_16x16x128_f8f6f4 v[202:205], v[150:157], v[158:165], v[122:125]
	v_mfma_f32_16x16x128_f8f6f4 v[206:209], v[150:157], v[174:181], v[90:93]
	s_waitcnt lgkmcnt(0)
	v_mfma_f32_16x16x128_f8f6f4 v[210:213], v[142:149], v[182:189], v[82:85]
	v_mfma_f32_16x16x128_f8f6f4 v[214:217], v[150:157], v[182:189], v[74:77]
	s_setprio 0
	s_barrier
	s_mov_b32 m0, s23
	s_mov_b32 s10, s46
	s_mov_b32 s11, s47
	ds_read_b128 v[122:125], v139
	ds_read_b128 v[126:129], v139 offset:1024
	ds_read_b128 v[190:193], v139 offset:2048
	ds_read_b128 v[194:197], v139 offset:3072
	buffer_load_dwordx4 v134, s[8:11], s86 offen lds
	s_add_i32 s33, s86, 0x10000
	s_mov_b32 m0, s24
	s_nop 0
	buffer_load_dwordx4 v134, s[8:11], s33 offen lds
	s_barrier
	s_waitcnt lgkmcnt(0)
	s_setprio 1
	s_waitcnt lgkmcnt(2)
	v_mfma_f32_16x16x128_f8f6f4 v[118:121], v[122:129], v[158:165], v[118:121]
	s_waitcnt lgkmcnt(0)
	v_mfma_f32_16x16x128_f8f6f4 v[110:113], v[190:197], v[158:165], v[110:113]
	v_mfma_f32_16x16x128_f8f6f4 v[102:105], v[122:129], v[166:173], v[102:105]
	v_mfma_f32_16x16x128_f8f6f4 v[158:161], v[190:197], v[166:173], v[94:97]
	v_mfma_f32_16x16x128_f8f6f4 v[162:165], v[122:129], v[174:181], v[86:89]
	v_mfma_f32_16x16x128_f8f6f4 v[166:169], v[190:197], v[174:181], v[78:81]
	v_mfma_f32_16x16x128_f8f6f4 v[170:173], v[122:129], v[182:189], v[70:73]
	v_mfma_f32_16x16x128_f8f6f4 v[174:177], v[190:197], v[182:189], v[18:21]
	s_setprio 0
	s_mov_b32 m0, s22
	s_barrier
	ds_read_b128 v[66:69], v138 offset:16384
	s_nop 1
	ds_read_b128 v[70:73], v138 offset:17408
	ds_read_b128 v[74:77], v138 offset:18432
	ds_read_b128 v[78:81], v138 offset:19456
	ds_read_b128 v[82:85], v138 offset:20480
	ds_read_b128 v[86:89], v138 offset:21504
	ds_read_b128 v[90:93], v138 offset:22528
	ds_read_b128 v[94:97], v138 offset:23552
	buffer_load_dwordx4 v1, s[44:47], s87 offen lds
	s_add_i32 s33, s87, 0x10000
	s_mov_b32 m0, s25
	s_nop 0
	buffer_load_dwordx4 v1, s[44:47], s33 offen lds
	s_barrier
	s_waitcnt lgkmcnt(0)
	s_setprio 1
	s_waitcnt lgkmcnt(6)
	v_mfma_f32_16x16x128_f8f6f4 v[62:65], v[142:149], v[66:73], v[62:65]
	v_mfma_f32_16x16x128_f8f6f4 v[58:61], v[150:157], v[66:73], v[58:61]
	s_waitcnt lgkmcnt(4)
	v_mfma_f32_16x16x128_f8f6f4 v[50:53], v[142:149], v[74:81], v[50:53]
	s_waitcnt lgkmcnt(0)
	v_mfma_f32_16x16x128_f8f6f4 v[230:233], v[142:149], v[90:97], v[230:233]
	v_mfma_f32_16x16x128_f8f6f4 v[218:221], v[150:157], v[74:81], v[42:45]
	v_mfma_f32_16x16x128_f8f6f4 v[222:225], v[142:149], v[82:89], v[34:37]
	v_mfma_f32_16x16x128_f8f6f4 v[226:229], v[150:157], v[82:89], v[26:29]
	v_mfma_f32_16x16x128_f8f6f4 v[234:237], v[150:157], v[90:97], v[10:13]
	s_setprio 0
	s_barrier
	s_mov_b32 m0, s26
	s_add_i32 s33, s86, 0x20000
	buffer_load_dwordx4 v134, s[8:11], s33 offen lds
	s_add_i32 s33, s86, 0x30000
	s_mov_b32 m0, s27
	s_nop 0
	buffer_load_dwordx4 v134, s[8:11], s33 offen lds
	s_waitcnt vmcnt(6)
	s_barrier
	s_setprio 1
	v_mfma_f32_16x16x128_f8f6f4 v[54:57], v[122:129], v[66:73], v[54:57]
	v_mfma_f32_16x16x128_f8f6f4 v[238:241], v[190:197], v[66:73], v[46:49]
	v_mfma_f32_16x16x128_f8f6f4 v[242:245], v[122:129], v[74:81], v[38:41]
	v_mfma_f32_16x16x128_f8f6f4 v[246:249], v[190:197], v[74:81], v[30:33]
	v_mfma_f32_16x16x128_f8f6f4 v[250:253], v[122:129], v[82:89], v[22:25]
	v_mfma_f32_16x16x128_f8f6f4 v[130:133], v[190:197], v[82:89], v[14:17]
	v_mfma_f32_16x16x128_f8f6f4 v[66:69], v[122:129], v[90:97], v[6:9]
	v_mfma_f32_16x16x128_f8f6f4 v[190:193], v[190:197], v[90:97], v[2:5]
	s_setprio 0
	s_barrier
	s_nop 4
	ds_read_b128 v[2:5], v140
	ds_read_b128 v[6:9], v140 offset:1024
	ds_read_b128 v[10:13], v140 offset:2048
	ds_read_b128 v[14:17], v140 offset:3072
	s_mov_b32 m0, s28
	s_add_i32 s33, s87, 0x20000
	ds_read_b128 v[18:21], v138 offset:32768
	ds_read_b128 v[22:25], v138 offset:33792
	ds_read_b128 v[26:29], v138 offset:34816
	ds_read_b128 v[30:33], v138 offset:35840
	ds_read_b128 v[34:37], v138 offset:36864
	ds_read_b128 v[38:41], v138 offset:37888
	ds_read_b128 v[42:45], v138 offset:38912
	ds_read_b128 v[46:49], v138 offset:39936
	buffer_load_dwordx4 v1, s[44:47], s33 offen lds
	s_add_i32 s33, s87, 0x30000
	s_mov_b32 m0, s29
	s_nop 0
	buffer_load_dwordx4 v1, s[44:47], s33 offen lds
	s_waitcnt lgkmcnt(8)
	s_barrier
	s_waitcnt lgkmcnt(0)
	s_setprio 1
	s_waitcnt lgkmcnt(6)
	v_mfma_f32_16x16x128_f8f6f4 v[126:129], v[2:9], v[18:25], v[198:201]
	v_mfma_f32_16x16x128_f8f6f4 v[122:125], v[10:17], v[18:25], v[202:205]
	s_waitcnt lgkmcnt(4)
	v_mfma_f32_16x16x128_f8f6f4 v[114:117], v[2:9], v[26:33], v[114:117]
	v_mfma_f32_16x16x128_f8f6f4 v[106:109], v[10:17], v[26:33], v[106:109]
	s_waitcnt lgkmcnt(2)
	v_mfma_f32_16x16x128_f8f6f4 v[98:101], v[2:9], v[34:41], v[98:101]
	v_mfma_f32_16x16x128_f8f6f4 v[90:93], v[10:17], v[34:41], v[206:209]
	s_waitcnt lgkmcnt(0)
	v_mfma_f32_16x16x128_f8f6f4 v[82:85], v[2:9], v[42:49], v[210:213]
	v_mfma_f32_16x16x128_f8f6f4 v[74:77], v[10:17], v[42:49], v[214:217]
	s_setprio 0
	s_barrier
	s_mov_b32 m0, s31
	s_add_i32 s33, s86, 0x80
	ds_read_b128 v[142:145], v141
	ds_read_b128 v[146:149], v141 offset:1024
	ds_read_b128 v[150:153], v141 offset:2048
	ds_read_b128 v[154:157], v141 offset:3072
	buffer_load_dwordx4 v134, s[8:11], s33 offen lds
	s_add_i32 s33, s86, 0x10080
	s_mov_b32 m0, s34
	s_nop 0
	buffer_load_dwordx4 v134, s[8:11], s33 offen lds
	s_barrier
	s_waitcnt lgkmcnt(0)
	s_setprio 1
	s_waitcnt lgkmcnt(2)
	v_mfma_f32_16x16x128_f8f6f4 v[118:121], v[142:149], v[18:25], v[118:121]
	s_waitcnt lgkmcnt(0)
	v_mfma_f32_16x16x128_f8f6f4 v[110:113], v[150:157], v[18:25], v[110:113]
	v_mfma_f32_16x16x128_f8f6f4 v[102:105], v[142:149], v[26:33], v[102:105]
	v_mfma_f32_16x16x128_f8f6f4 v[94:97], v[150:157], v[26:33], v[158:161]
	v_mfma_f32_16x16x128_f8f6f4 v[86:89], v[142:149], v[34:41], v[162:165]
	v_mfma_f32_16x16x128_f8f6f4 v[78:81], v[150:157], v[34:41], v[166:169]
	v_mfma_f32_16x16x128_f8f6f4 v[70:73], v[142:149], v[42:49], v[170:173]
	v_mfma_f32_16x16x128_f8f6f4 v[18:21], v[150:157], v[42:49], v[174:177]
	s_setprio 0
	s_mov_b32 m0, s35
	s_barrier
	ds_read_b128 v[158:161], v138 offset:49152
	ds_read_b128 v[162:165], v138 offset:50176
	ds_read_b128 v[166:169], v138 offset:51200
	ds_read_b128 v[170:173], v138 offset:52224
	ds_read_b128 v[174:177], v138 offset:53248
	ds_read_b128 v[178:181], v138 offset:54272
	ds_read_b128 v[182:185], v138 offset:55296
	ds_read_b128 v[186:189], v138 offset:56320
	buffer_load_dwordx4 v1, s[44:47], s88 offen lds
	s_add_i32 s87, s87, 0x10080
	s_mov_b32 m0, s36
	s_nop 0
	buffer_load_dwordx4 v1, s[44:47], s87 offen lds
	s_barrier
	s_waitcnt lgkmcnt(0)
	s_setprio 1
	s_waitcnt lgkmcnt(6)
	v_mfma_f32_16x16x128_f8f6f4 v[62:65], v[2:9], v[158:165], v[62:65]
	v_mfma_f32_16x16x128_f8f6f4 v[58:61], v[10:17], v[158:165], v[58:61]
	s_waitcnt lgkmcnt(4)
	v_mfma_f32_16x16x128_f8f6f4 v[50:53], v[2:9], v[166:173], v[50:53]
	v_mfma_f32_16x16x128_f8f6f4 v[42:45], v[10:17], v[166:173], v[218:221]
	s_waitcnt lgkmcnt(2)
	v_mfma_f32_16x16x128_f8f6f4 v[34:37], v[2:9], v[174:181], v[222:225]
	v_mfma_f32_16x16x128_f8f6f4 v[26:29], v[10:17], v[174:181], v[226:229]
	s_waitcnt lgkmcnt(0)
	v_mfma_f32_16x16x128_f8f6f4 v[230:233], v[2:9], v[182:189], v[230:233]
	v_mfma_f32_16x16x128_f8f6f4 v[10:13], v[10:17], v[182:189], v[234:237]
	s_setprio 0
	s_barrier
	s_mov_b32 m0, s37
	s_add_i32 s33, s86, 0x20080
	buffer_load_dwordx4 v134, s[8:11], s33 offen lds
	s_add_i32 s86, s86, 0x30080
	s_mov_b32 m0, s38
	s_nop 0
	buffer_load_dwordx4 v134, s[8:11], s86 offen lds
	s_waitcnt vmcnt(6)
	s_barrier
	s_setprio 1
	v_mfma_f32_16x16x128_f8f6f4 v[54:57], v[142:149], v[158:165], v[54:57]
	v_mfma_f32_16x16x128_f8f6f4 v[46:49], v[150:157], v[158:165], v[238:241]
	v_mfma_f32_16x16x128_f8f6f4 v[38:41], v[142:149], v[166:173], v[242:245]
	v_mfma_f32_16x16x128_f8f6f4 v[30:33], v[150:157], v[166:173], v[246:249]
	v_mfma_f32_16x16x128_f8f6f4 v[22:25], v[142:149], v[174:181], v[250:253]
	v_mfma_f32_16x16x128_f8f6f4 v[14:17], v[150:157], v[174:181], v[130:133]
	v_mfma_f32_16x16x128_f8f6f4 v[6:9], v[142:149], v[182:189], v[66:69]
	v_mfma_f32_16x16x128_f8f6f4 v[2:5], v[150:157], v[182:189], v[190:193]
	s_setprio 0
	s_add_i32 s85, s85, 2
	s_addk_i32 s7, 0x100
	s_addk_i32 s84, 0x100
	s_cmp_gt_u32 s85, 5
	s_barrier
	s_cbranch_scc0 .LBB0_1724
	v_pk_mul_f32 v[126:127], v[126:127], 0.5 op_sel_hi:[1,0]
	v_mov_b32_e32 v132, 0
	v_cvt_pk_fp8_f32 v132, v126, v127
	v_pk_mul_f32 v[122:123], v[122:123], 0.5 op_sel_hi:[1,0]
	v_mov_b32_e32 v133, 0
	v_cvt_pk_fp8_f32 v133, v122, v123
	v_pk_mul_f32 v[122:123], v[128:129], 0.5 op_sel_hi:[1,0]
	v_pk_mul_f32 v[118:119], v[118:119], 0.5 op_sel_hi:[1,0]
	v_cvt_pk_fp8_f32 v132, v122, v123 op_sel:[0,0,1]
	v_mov_b32_e32 v122, 0
	v_cvt_pk_fp8_f32 v122, v118, v119
	v_pk_mul_f32 v[114:115], v[114:115], 0.5 op_sel_hi:[1,0]
	v_mov_b32_e32 v118, 0
	v_cvt_pk_fp8_f32 v118, v114, v115
	v_pk_mul_f32 v[106:107], v[106:107], 0.5 op_sel_hi:[1,0]
	v_mov_b32_e32 v119, 0
	v_cvt_pk_fp8_f32 v119, v106, v107
	v_pk_mul_f32 v[106:107], v[116:117], 0.5 op_sel_hi:[1,0]
	v_pk_mul_f32 v[94:95], v[94:95], 0.5 op_sel_hi:[1,0]
	v_cvt_pk_fp8_f32 v118, v106, v107 op_sel:[0,0,1]
	v_mov_b32_e32 v107, 0
	v_cvt_pk_fp8_f32 v107, v94, v95
	v_pk_mul_f32 v[110:111], v[110:111], 0.5 op_sel_hi:[1,0]
	v_mov_b32_e32 v123, 0
	v_cvt_pk_fp8_f32 v123, v110, v111
	v_pk_mul_f32 v[96:97], v[96:97], 0.5 op_sel_hi:[1,0]
	v_pk_mul_f32 v[102:103], v[102:103], 0.5 op_sel_hi:[1,0]
	v_mov_b32_e32 v106, 0
	v_cvt_pk_fp8_f32 v107, v96, v97 op_sel:[0,0,1]
	v_pk_mul_f32 v[96:97], v[98:99], 0.5 op_sel_hi:[1,0]
	v_mov_b32_e32 v98, 0
	v_cvt_pk_fp8_f32 v106, v102, v103
	v_cvt_pk_fp8_f32 v98, v96, v97
	v_lshl_add_u32 v66, s79, 8, v135
	v_pk_mul_f32 v[112:113], v[112:113], 0.5 op_sel_hi:[1,0]
	v_pk_mul_f32 v[124:125], v[124:125], 0.5 op_sel_hi:[1,0]
	v_cvt_pk_fp8_f32 v123, v112, v113 op_sel:[0,0,1]
	v_or_b32_e32 v112, 16, v66
	v_pk_mul_f32 v[108:109], v[108:109], 0.5 op_sel_hi:[1,0]
	v_pk_mul_f32 v[90:91], v[90:91], 0.5 op_sel_hi:[1,0]
	v_mov_b32_e32 v99, 0
	v_ashrrev_i32_e32 v67, 31, v66
	v_cvt_pk_fp8_f32 v133, v124, v125 op_sel:[0,0,1]
	v_pk_mul_f32 v[110:111], v[120:121], 0.5 op_sel_hi:[1,0]
	v_ashrrev_i32_e32 v113, 31, v112
	v_cvt_pk_fp8_f32 v119, v108, v109 op_sel:[0,0,1]
	v_pk_mul_f32 v[94:95], v[104:105], 0.5 op_sel_hi:[1,0]
	v_cvt_pk_fp8_f32 v99, v90, v91
	v_pk_mul_f32 v[90:91], v[100:101], 0.5 op_sel_hi:[1,0]
	v_lshl_or_b32 v68, s78, 8, v136
	v_lshlrev_b64 v[130:131], 10, v[66:67]
	v_cvt_pk_fp8_f32 v122, v110, v111 op_sel:[0,0,1]
	v_lshlrev_b64 v[112:113], 10, v[112:113]
	v_cvt_pk_fp8_f32 v106, v94, v95 op_sel:[0,0,1]
	v_cvt_pk_fp8_f32 v98, v90, v91 op_sel:[0,0,1]
	v_pk_mul_f32 v[86:87], v[86:87], 0.5 op_sel_hi:[1,0]
	v_pk_mul_f32 v[78:79], v[78:79], 0.5 op_sel_hi:[1,0]
	v_mov_b32_e32 v90, 0
	v_mov_b32_e32 v91, 0
	v_ashrrev_i32_e32 v69, 31, v68
	v_lshl_add_u64 v[110:111], s[68:69], 0, v[130:131]
	v_lshl_add_u64 v[94:95], s[68:69], 0, v[112:113]
	v_cvt_pk_fp8_f32 v90, v86, v87
	v_cvt_pk_fp8_f32 v91, v78, v79
	v_lshl_add_u64 v[110:111], v[110:111], 0, v[68:69]
	v_lshl_add_u64 v[94:95], v[94:95], 0, v[68:69]
	global_store_dwordx2 v[110:111], v[132:133], off
	global_store_dwordx2 v[110:111], v[122:123], off offset:128
	global_store_dwordx2 v[94:95], v[118:119], off
	global_store_dwordx2 v[94:95], v[106:107], off offset:128
	v_or_b32_e32 v94, 32, v66
	v_pk_mul_f32 v[92:93], v[92:93], 0.5 op_sel_hi:[1,0]
	v_ashrrev_i32_e32 v95, 31, v94
	v_cvt_pk_fp8_f32 v99, v92, v93 op_sel:[0,0,1]
	v_pk_mul_f32 v[78:79], v[88:89], 0.5 op_sel_hi:[1,0]
	v_pk_mul_f32 v[80:81], v[80:81], 0.5 op_sel_hi:[1,0]
	v_lshlrev_b64 v[94:95], 10, v[94:95]
	v_cvt_pk_fp8_f32 v90, v78, v79 op_sel:[0,0,1]
	v_cvt_pk_fp8_f32 v91, v80, v81 op_sel:[0,0,1]
	v_lshl_add_u64 v[78:79], s[68:69], 0, v[94:95]
	v_lshl_add_u64 v[78:79], v[78:79], 0, v[68:69]
	global_store_dwordx2 v[78:79], v[98:99], off
	global_store_dwordx2 v[78:79], v[90:91], off offset:128
	v_pk_mul_f32 v[78:79], v[82:83], 0.5 op_sel_hi:[1,0]
	v_mov_b32_e32 v80, 0
	v_cvt_pk_fp8_f32 v80, v78, v79
	v_pk_mul_f32 v[74:75], v[74:75], 0.5 op_sel_hi:[1,0]
	v_mov_b32_e32 v81, 0
	v_cvt_pk_fp8_f32 v81, v74, v75
	v_pk_mul_f32 v[74:75], v[84:85], 0.5 op_sel_hi:[1,0]
	v_pk_mul_f32 v[18:19], v[18:19], 0.5 op_sel_hi:[1,0]
	v_cvt_pk_fp8_f32 v80, v74, v75 op_sel:[0,0,1]
	v_mov_b32_e32 v75, 0
	v_cvt_pk_fp8_f32 v75, v18, v19
	v_pk_mul_f32 v[20:21], v[20:21], 0.5 op_sel_hi:[1,0]
	v_pk_mul_f32 v[58:59], v[58:59], 0.5 op_sel_hi:[1,0]
	v_pk_mul_f32 v[70:71], v[70:71], 0.5 op_sel_hi:[1,0]
	v_cvt_pk_fp8_f32 v75, v20, v21 op_sel:[0,0,1]
	v_pk_mul_f32 v[20:21], v[62:63], 0.5 op_sel_hi:[1,0]
	v_mov_b32_e32 v62, 0
	v_cvt_pk_fp8_f32 v62, v20, v21
	v_mov_b32_e32 v63, 0
	v_pk_mul_f32 v[20:21], v[64:65], 0.5 op_sel_hi:[1,0]
	v_mov_b32_e32 v74, 0
	v_cvt_pk_fp8_f32 v63, v58, v59
	v_cvt_pk_fp8_f32 v62, v20, v21 op_sel:[0,0,1]
	v_pk_mul_f32 v[20:21], v[54:55], 0.5 op_sel_hi:[1,0]
	v_pk_mul_f32 v[46:47], v[46:47], 0.5 op_sel_hi:[1,0]
	v_mov_b32_e32 v54, 0
	v_mov_b32_e32 v55, 0
	v_cvt_pk_fp8_f32 v74, v70, v71
	v_cvt_pk_fp8_f32 v54, v20, v21
	v_cvt_pk_fp8_f32 v55, v46, v47
	v_or_b32_e32 v66, 48, v66
	v_pk_mul_f32 v[76:77], v[76:77], 0.5 op_sel_hi:[1,0]
	v_pk_mul_f32 v[58:59], v[60:61], 0.5 op_sel_hi:[1,0]
	v_ashrrev_i32_e32 v67, 31, v66
	v_cvt_pk_fp8_f32 v81, v76, v77 op_sel:[0,0,1]
	v_pk_mul_f32 v[18:19], v[72:73], 0.5 op_sel_hi:[1,0]
	v_cvt_pk_fp8_f32 v63, v58, v59 op_sel:[0,0,1]
	v_pk_mul_f32 v[20:21], v[56:57], 0.5 op_sel_hi:[1,0]
	v_pk_mul_f32 v[46:47], v[48:49], 0.5 op_sel_hi:[1,0]
	v_lshlrev_b64 v[66:67], 10, v[66:67]
	v_cvt_pk_fp8_f32 v74, v18, v19 op_sel:[0,0,1]
	v_cvt_pk_fp8_f32 v54, v20, v21 op_sel:[0,0,1]
	v_cvt_pk_fp8_f32 v55, v46, v47 op_sel:[0,0,1]
	v_lshl_add_u64 v[18:19], s[68:69], 0, v[66:67]
	v_add_co_u32_e32 v20, vcc, s47, v110
	v_lshl_add_u64 v[18:19], v[18:19], 0, v[68:69]
	s_nop 0
	v_addc_co_u32_e32 v21, vcc, 0, v111, vcc
	global_store_dwordx2 v[18:19], v[80:81], off
	global_store_dwordx2 v[18:19], v[74:75], off offset:128
	v_lshl_add_u64 v[18:19], v[110:111], 0, s[12:13]
	global_store_dwordx2 v[20:21], v[62:63], off
	global_store_dwordx2 v[18:19], v[54:55], off offset:128
	v_pk_mul_f32 v[20:21], v[50:51], 0.5 op_sel_hi:[1,0]
	v_mov_b32_e32 v46, 0
	v_cvt_pk_fp8_f32 v46, v20, v21
	v_pk_mul_f32 v[42:43], v[42:43], 0.5 op_sel_hi:[1,0]
	v_mov_b32_e32 v47, 0
	v_pk_mul_f32 v[20:21], v[52:53], 0.5 op_sel_hi:[1,0]
	v_cvt_pk_fp8_f32 v47, v42, v43
	v_cvt_pk_fp8_f32 v46, v20, v21 op_sel:[0,0,1]
	v_pk_mul_f32 v[20:21], v[38:39], 0.5 op_sel_hi:[1,0]
	v_pk_mul_f32 v[30:31], v[30:31], 0.5 op_sel_hi:[1,0]
	v_mov_b32_e32 v38, 0
	v_mov_b32_e32 v39, 0
	v_cvt_pk_fp8_f32 v38, v20, v21
	v_cvt_pk_fp8_f32 v39, v30, v31
	v_pk_mul_f32 v[42:43], v[44:45], 0.5 op_sel_hi:[1,0]
	v_pk_mul_f32 v[20:21], v[40:41], 0.5 op_sel_hi:[1,0]
	v_cvt_pk_fp8_f32 v47, v42, v43 op_sel:[0,0,1]
	v_pk_mul_f32 v[30:31], v[32:33], 0.5 op_sel_hi:[1,0]
	v_cvt_pk_fp8_f32 v38, v20, v21 op_sel:[0,0,1]
	v_cvt_pk_fp8_f32 v39, v30, v31 op_sel:[0,0,1]
	v_add_co_u32_e32 v20, vcc, s43, v110
	v_lshl_add_u64 v[18:19], v[110:111], 0, s[14:15]
	s_nop 0
	v_addc_co_u32_e32 v21, vcc, 0, v111, vcc
	global_store_dwordx2 v[20:21], v[46:47], off
	global_store_dwordx2 v[18:19], v[38:39], off offset:128
	v_pk_mul_f32 v[20:21], v[34:35], 0.5 op_sel_hi:[1,0]
	v_mov_b32_e32 v30, 0
	v_cvt_pk_fp8_f32 v30, v20, v21
	v_pk_mul_f32 v[26:27], v[26:27], 0.5 op_sel_hi:[1,0]
	v_mov_b32_e32 v31, 0
	v_pk_mul_f32 v[20:21], v[36:37], 0.5 op_sel_hi:[1,0]
	v_cvt_pk_fp8_f32 v31, v26, v27
	v_cvt_pk_fp8_f32 v30, v20, v21 op_sel:[0,0,1]
	v_pk_mul_f32 v[20:21], v[22:23], 0.5 op_sel_hi:[1,0]
	v_pk_mul_f32 v[14:15], v[14:15], 0.5 op_sel_hi:[1,0]
	v_mov_b32_e32 v22, 0
	v_mov_b32_e32 v23, 0
	v_cvt_pk_fp8_f32 v22, v20, v21
	v_cvt_pk_fp8_f32 v23, v14, v15
	v_pk_mul_f32 v[26:27], v[28:29], 0.5 op_sel_hi:[1,0]
	v_pk_mul_f32 v[14:15], v[24:25], 0.5 op_sel_hi:[1,0]
	v_cvt_pk_fp8_f32 v31, v26, v27 op_sel:[0,0,1]
	v_pk_mul_f32 v[16:17], v[16:17], 0.5 op_sel_hi:[1,0]
	v_cvt_pk_fp8_f32 v22, v14, v15 op_sel:[0,0,1]
	v_cvt_pk_fp8_f32 v23, v16, v17 op_sel:[0,0,1]
	v_add_co_u32_e32 v14, vcc, s49, v110
	v_lshl_add_u64 v[18:19], v[110:111], 0, s[16:17]
	s_nop 0
	v_addc_co_u32_e32 v15, vcc, 0, v111, vcc
	global_store_dwordx2 v[14:15], v[30:31], off
	global_store_dwordx2 v[18:19], v[22:23], off offset:128
	v_pk_mul_f32 v[16:17], v[230:231], 0.5 op_sel_hi:[1,0]
	v_mov_b32_e32 v18, 0
	v_cvt_pk_fp8_f32 v18, v16, v17
	v_pk_mul_f32 v[10:11], v[10:11], 0.5 op_sel_hi:[1,0]
	v_mov_b32_e32 v19, 0
	v_cvt_pk_fp8_f32 v19, v10, v11
	v_pk_mul_f32 v[10:11], v[232:233], 0.5 op_sel_hi:[1,0]
	v_pk_mul_f32 v[6:7], v[6:7], 0.5 op_sel_hi:[1,0]
	v_cvt_pk_fp8_f32 v18, v10, v11 op_sel:[0,0,1]
	v_pk_mul_f32 v[2:3], v[2:3], 0.5 op_sel_hi:[1,0]
	v_mov_b32_e32 v10, 0
	v_mov_b32_e32 v11, 0
	v_cvt_pk_fp8_f32 v10, v6, v7
	v_cvt_pk_fp8_f32 v11, v2, v3
	v_pk_mul_f32 v[12:13], v[12:13], 0.5 op_sel_hi:[1,0]
	v_pk_mul_f32 v[2:3], v[8:9], 0.5 op_sel_hi:[1,0]
	v_cvt_pk_fp8_f32 v19, v12, v13 op_sel:[0,0,1]
	v_pk_mul_f32 v[4:5], v[4:5], 0.5 op_sel_hi:[1,0]
	v_cvt_pk_fp8_f32 v10, v2, v3 op_sel:[0,0,1]
	v_cvt_pk_fp8_f32 v11, v4, v5 op_sel:[0,0,1]
	v_add_co_u32_e32 v2, vcc, s57, v110
	s_mov_b32 s78, s58
	s_nop 0
	v_addc_co_u32_e32 v3, vcc, 0, v111, vcc
	s_and_b64 vcc, exec, s[4:5]
	s_mov_b32 s79, s59
	s_mov_b32 s84, s72
	s_mov_b32 s85, s73
	v_lshl_add_u64 v[14:15], v[110:111], 0, s[18:19]
	global_store_dwordx2 v[2:3], v[18:19], off
	global_store_dwordx2 v[14:15], v[10:11], off offset:128
	s_cbranch_vccz .LBB0_1719
	s_waitcnt vmcnt(0)
	s_cmpk_gt_u32 s3, 0xff
	s_cbranch_scc1 .LBB0_1728
	s_barrier

.LBB0_1895:
	s_waitcnt vmcnt(0)
	v_mov_b32_e32 v2, v0
	s_barrier
	s_cmpk_gt_i32 s2, 0x32f
	v_readfirstlane_b32 s3, v2
	s_cbranch_scc1 .LBB0_1909
	v_bfe_i32 v4, v2, 27, 1
	v_lshlrev_b32_e32 v1, 4, v2
	v_lshrrev_b32_e32 v4, 22, v4
	v_add_u32_e32 v4, v1, v4
	v_and_b32_e32 v4, 0xfffffc00, v4
	v_sub_u32_e32 v1, v1, v4
	v_ashrrev_i32_e32 v3, 31, v2
	v_lshrrev_b32_e32 v4, 4, v1
	v_lshrrev_b32_e32 v3, 26, v3
	v_bitop3_b32 v1, v4, v1, 32 bitop3:0x6c
	v_add_u32_e32 v3, v2, v3
	v_ashrrev_i32_e32 v5, 31, v1
	s_add_u32 s8, s52, 0x2300000
	v_ashrrev_i32_e32 v3, 6, v3
	v_lshrrev_b32_e32 v5, 26, v5
	s_addc_u32 s6, s53, 0
	v_lshlrev_b32_e32 v4, 3, v3
	v_add_u32_e32 v5, v1, v5
	s_ashr_i32 s12, s2, 31
	v_and_b32_e32 v4, -16, v4
	v_ashrrev_i32_e32 v6, 6, v5
	s_lshr_b32 s7, s12, 29
	v_readlane_b32 s10, v255, 8
	v_add_u32_e32 v4, v6, v4
	v_and_b32_e32 v6, 3, v6
	s_mov_b32 s5, 0x1fffe0
	s_add_i32 s7, s2, s7
	v_readlane_b32 s11, v255, 9
	v_and_or_b32 v6, v4, s5, v6
	s_ashr_i32 s5, s3, 6
	s_ashr_i32 s14, s7, 3
	s_and_b32 s7, s7, -8
	s_ashr_i32 s4, s3, 8
	s_and_b32 s41, s11, 0xffff
	s_and_b32 s9, s6, 0xffff
	s_lshl_b32 s6, s5, 10
	s_sub_i32 s7, s2, s7
	s_cmp_lt_i32 s7, 0
	s_movk_i32 s13, 0x67
	s_cselect_b32 s15, s13, 0x66
	s_mul_i32 s7, s15, s7
	s_add_i32 s7, s7, s14
	s_mul_hi_i32 s14, s7, 0x2aaaaaab
	s_lshr_b32 s15, s14, 31
	s_ashr_i32 s14, s14, 3
	s_add_i32 s14, s14, s15
	s_lshl_b32 s15, s14, 3
	s_mul_i32 s14, s14, 48
	s_sub_i32 s7, s7, s14
	s_bfe_i32 s14, s7, 0x80000
	s_bfe_u32 s14, s14, 0x3000c
	s_add_i32 s14, s7, s14
	s_bfe_i32 s16, s14, 0x80000
	s_and_b32 s14, s14, 0xf8
	s_sub_i32 s7, s7, s14
	s_sext_i32_i8 s7, s7
	s_add_i32 s45, s15, s7
	s_ashr_i32 s7, s45, 31
	v_and_b32_e32 v5, 0xc0, v5
	s_lshr_b32 s7, s7, 12
	v_sub_u32_e32 v1, v1, v5
	v_mov_b32_e32 v5, 1
	s_add_i32 s7, s45, s7
	v_lshlrev_b32_e32 v3, 5, v3
	v_ashrrev_i16_sdwa v1, v5, sext(v1) dst_sel:DWORD dst_unused:UNUSED_PAD src0_sel:DWORD src1_sel:BYTE_0
	v_lshlrev_b32_e32 v5, 1, v4
	v_lshrrev_b32_e32 v7, 2, v4
	s_sext_i32_i16 s16, s16
	s_ashr_i32 s7, s7, 20
	v_and_b32_e32 v3, 32, v3
	v_bfe_i32 v1, v1, 0, 16
	v_and_b32_e32 v5, 24, v5
	v_and_b32_e32 v7, 4, v7
	s_ashr_i32 s39, s16, 3
	s_mul_i32 s7, s7, 6
	s_add_i32 s14, s6, 0
	s_mov_b32 s43, 0x20000
	s_brev_b32 s42, -2
	v_or3_b32 v5, v6, v7, v5
	v_add_lshl_u32 v3, v3, v1, 1
	s_add_i32 s7, s7, s39
	s_add_i32 s15, s14, 0x10000
	v_lshl_add_u32 v138, v5, 11, v3
	s_mov_b32 s10, s42
	s_mov_b32 s11, s43
	s_lshl_b32 s46, s7, 19
	s_mov_b32 m0, s15
	s_add_i32 s16, s14, 0x12000
	buffer_load_dwordx4 v138, s[8:11], s46 offen lds
	s_or_b32 s6, s46, 0x20000
	s_mov_b32 m0, s16
	v_lshl_add_u32 v1, v4, 11, v3
	buffer_load_dwordx4 v138, s[8:11], s6 offen lds
	s_lshl_b32 s47, s45, 19
	s_mov_b32 m0, s14
	s_add_i32 s17, s14, 0x2000
	buffer_load_dwordx4 v1, s[40:43], s47 offen lds
	s_or_b32 s6, s47, 0x20000
	s_mov_b32 m0, s17
	s_add_i32 s18, s14, 0x14000
	buffer_load_dwordx4 v1, s[40:43], s6 offen lds
	s_or_b32 s6, s46, 0x40000
	s_mov_b32 m0, s18
	s_add_i32 s19, s14, 0x16000
	buffer_load_dwordx4 v138, s[8:11], s6 offen lds
	s_or_b32 s6, s46, 0x60000
	s_mov_b32 m0, s19
	s_add_i32 s20, s14, 0x4000
	buffer_load_dwordx4 v138, s[8:11], s6 offen lds
	s_or_b32 s6, s47, 0x40000
	s_mov_b32 m0, s20
	s_add_i32 s21, s14, 0x6000
	buffer_load_dwordx4 v1, s[40:43], s6 offen lds
	s_or_b32 s6, s47, 0x60000
	s_mov_b32 m0, s21
	s_cmp_lg_u32 s4, 1
	buffer_load_dwordx4 v1, s[40:43], s6 offen lds
	s_mov_b32 s22, 0
	s_cbranch_scc1 .LBB0_1898
	s_barrier

.LBB0_2137:
	s_ashr_i32 s5, s7, 3
	s_add_u32 s8, s52, 0x2600000
	s_addc_u32 s7, s53, 0
	s_add_i32 s5, s6, s5
	s_ashr_i32 s6, s5, 31
	s_lshr_b32 s6, s6, 27
	v_bfe_i32 v4, v2, 27, 1
	s_add_i32 s6, s5, s6
	v_lshlrev_b32_e32 v1, 4, v2
	v_lshrrev_b32_e32 v4, 22, v4
	s_ashr_i32 s12, s6, 5
	s_andn2_b32 s6, s6, 31
	v_add_u32_e32 v4, v1, v4
	s_sub_i32 s5, s5, s6
	v_and_b32_e32 v4, 0xfffffc00, v4
	s_bfe_i32 s6, s5, 0x80000
	v_sub_u32_e32 v1, v1, v4
	s_bfe_u32 s6, s6, 0x3000c
	v_ashrrev_i32_e32 v3, 31, v2
	v_lshrrev_b32_e32 v4, 4, v1
	s_add_i32 s6, s5, s6
	v_lshrrev_b32_e32 v3, 26, v3
	v_bitop3_b32 v1, v4, v1, 32 bitop3:0x6c
	s_bfe_i32 s13, s6, 0x80000
	s_and_b32 s6, s6, 0xf8
	v_add_u32_e32 v3, v2, v3
	v_ashrrev_i32_e32 v5, 31, v1
	s_sub_i32 s5, s5, s6
	v_ashrrev_i32_e32 v3, 6, v3
	v_lshrrev_b32_e32 v5, 26, v5
	s_lshl_b32 s12, s12, 3
	s_sext_i32_i8 s5, s5
	v_lshlrev_b32_e32 v4, 3, v3
	v_add_u32_e32 v5, v1, v5
	s_add_i32 s59, s12, s5
	v_and_b32_e32 v4, -16, v4
	v_ashrrev_i32_e32 v6, 6, v5
	v_and_b32_e32 v5, 0xc0, v5
	s_ashr_i32 s5, s59, 31
	s_ashr_i32 s4, s3, 6
	v_add_u32_e32 v4, v6, v4
	v_sub_u32_e32 v1, v1, v5
	v_mov_b32_e32 v5, 1
	v_and_b32_e32 v6, 3, v6
	s_mov_b32 s9, 0x1fffe0
	s_lshr_b32 s5, s5, 12
	v_lshlrev_b32_e32 v3, 5, v3
	v_ashrrev_i16_sdwa v1, v5, sext(v1) dst_sel:DWORD dst_unused:UNUSED_PAD src0_sel:DWORD src1_sel:BYTE_0
	v_lshlrev_b32_e32 v5, 1, v4
	v_lshrrev_b32_e32 v7, 2, v4
	v_and_or_b32 v6, v4, s9, v6
	s_and_b32 s9, s7, 0xffff
	s_lshl_b32 s7, s4, 10
	s_sext_i32_i16 s13, s13
	s_add_i32 s5, s59, s5
	v_readlane_b32 s10, v255, 11
	v_and_b32_e32 v3, 32, v3
	v_bfe_i32 v1, v1, 0, 16
	v_and_b32_e32 v5, 24, v5
	v_and_b32_e32 v7, 4, v7
	s_ashr_i32 s72, s13, 3
	s_lshl_b32 s5, s5, 1
	s_add_i32 s15, s7, 0
	v_readlane_b32 s11, v255, 12
	s_mov_b32 s51, 0x20000
	s_brev_b32 s50, -2
	v_or3_b32 v5, v6, v7, v5
	v_add_lshl_u32 v3, v3, v1, 1
	s_and_b32 s5, s5, 0xffe00000
	s_lshl_b32 s6, s72, 19
	s_add_i32 s16, s15, 0x10000
	s_and_b32 s49, s11, 0xffff
	v_lshl_add_u32 v192, v5, 11, v3
	s_mov_b32 s10, s50
	s_mov_b32 s11, s51
	s_add_i32 s12, s5, s6
	s_mov_b32 m0, s16
	s_add_i32 s17, s15, 0x12000
	buffer_load_dwordx4 v192, s[8:11], s12 offen lds
	s_or_b32 s5, s12, 0x20000
	s_mov_b32 m0, s17
	v_lshl_add_u32 v1, v4, 11, v3
	buffer_load_dwordx4 v192, s[8:11], s5 offen lds
	s_lshl_b32 s13, s59, 19
	s_mov_b32 m0, s15
	s_add_i32 s18, s15, 0x2000
	buffer_load_dwordx4 v1, s[48:51], s13 offen lds
	s_or_b32 s5, s13, 0x20000
	s_mov_b32 m0, s18
	s_add_i32 s19, s15, 0x14000
	buffer_load_dwordx4 v1, s[48:51], s5 offen lds
	s_or_b32 s5, s12, 0x40000
	s_mov_b32 m0, s19
	s_add_i32 s20, s15, 0x16000
	buffer_load_dwordx4 v192, s[8:11], s5 offen lds
	s_or_b32 s5, s12, 0x60000
	s_mov_b32 m0, s20
	s_add_i32 s21, s15, 0x4000
	buffer_load_dwordx4 v192, s[8:11], s5 offen lds
	s_or_b32 s5, s13, 0x40000
	s_mov_b32 m0, s21
	s_add_i32 s22, s15, 0x6000
	buffer_load_dwordx4 v1, s[48:51], s5 offen lds
	s_or_b32 s5, s13, 0x60000
	s_mov_b32 m0, s22
	s_mov_b32 s23, 0
	buffer_load_dwordx4 v1, s[48:51], s5 offen lds
	s_ashr_i32 s5, s3, 8
	s_mov_b32 s24, 0x10000
	s_cmp_lg_u32 s5, 1
	s_mov_b32 s25, 0x40000
	s_cbranch_scc1 .LBB0_2139
	s_barrier

.LBB0_2141:
	v_lshl_add_u32 v146, s59, 8, v193
	v_add_u32_e32 v132, 0xffff8000, v146
	v_cndmask_b32_e64 v132, v146, v132, s[6:7]
	s_add_u32 s12, s52, s12
	v_lshl_or_b32 v130, s72, 8, v194
	v_ashrrev_i32_e32 v133, 31, v132
	s_addc_u32 s13, s53, s13
	v_ashrrev_i32_e32 v131, 31, v130
	v_lshlrev_b64 v[132:133], 11, v[132:133]
	v_lshl_add_u64 v[132:133], s[12:13], 0, v[132:133]
	v_lshlrev_b64 v[148:149], 1, v[130:131]
	s_lshl_b64 s[6:7], s[10:11], 2
	v_lshl_add_u64 v[150:151], v[132:133], 0, v[148:149]
	s_add_u32 s6, s26, s6
	global_load_dwordx4 v[200:203], v[150:151], off
	global_load_dwordx4 v[204:207], v[150:151], off offset:256
	s_addc_u32 s7, s27, s7
	v_lshl_add_u64 v[130:131], v[130:131], 2, s[6:7]
	v_add_co_u32_e32 v152, vcc, s37, v150
	global_load_dwordx4 v[142:145], v[130:131], off
	global_load_dwordx4 v[138:141], v[130:131], off offset:16
	global_load_dwordx4 v[134:137], v[130:131], off offset:512
	s_nop 0
	global_load_dwordx4 v[130:133], v[130:131], off offset:528
	v_addc_co_u32_e32 v153, vcc, 0, v151, vcc
	global_load_dwordx4 v[208:211], v[152:153], off
	global_load_dwordx4 v[212:215], v[152:153], off offset:256
	v_ashrrev_i32_e32 v147, 31, v146
	v_lshlrev_b64 v[146:147], 11, v[146:147]
	v_lshl_add_u64 v[146:147], s[66:67], 0, v[146:147]
	v_lshl_add_u64 v[190:191], v[146:147], 0, v[148:149]
	v_add_co_u32_e32 v146, vcc, s24, v150
	s_mov_b32 s72, s46
	s_nop 0
	v_addc_co_u32_e32 v147, vcc, 0, v151, vcc
	v_add_co_u32_e32 v148, vcc, s36, v150
	s_mov_b32 s59, s47
	s_nop 0
	v_addc_co_u32_e32 v149, vcc, 0, v151, vcc
	v_add_co_u32_e32 v154, vcc, s25, v150
	s_mov_b32 s12, s57
	s_nop 0
	v_addc_co_u32_e32 v155, vcc, 0, v151, vcc
	v_add_co_u32_e32 v152, vcc, s42, v150
	s_mov_b32 s13, s58
	s_nop 0
	v_addc_co_u32_e32 v153, vcc, 0, v151, vcc
	v_add_co_u32_e32 v156, vcc, s43, v150
	s_waitcnt vmcnt(7)
	v_lshlrev_b32_e32 v226, 16, v202
	v_addc_co_u32_e32 v157, vcc, 0, v151, vcc
	v_add_co_u32_e32 v224, vcc, s45, v150
	v_and_b32_e32 v227, 0xffff0000, v202
	s_nop 0
	v_addc_co_u32_e32 v225, vcc, 0, v151, vcc
	global_load_dwordx4 v[216:219], v[146:147], off
	global_load_dwordx4 v[220:223], v[146:147], off offset:256
	global_load_dwordx4 v[182:185], v[148:149], off
	global_load_dwordx4 v[178:181], v[148:149], off offset:256
	global_load_dwordx4 v[174:177], v[154:155], off
	global_load_dwordx4 v[170:173], v[154:155], off offset:256
	global_load_dwordx4 v[166:169], v[152:153], off
	global_load_dwordx4 v[162:165], v[152:153], off offset:256
	global_load_dwordx4 v[158:161], v[156:157], off
	s_nop 0
	global_load_dwordx4 v[154:157], v[156:157], off offset:256
	s_nop 0
	global_load_dwordx4 v[150:153], v[224:225], off
	global_load_dwordx4 v[146:149], v[224:225], off offset:256
	v_lshlrev_b32_e32 v224, 16, v200
	v_and_b32_e32 v225, 0xffff0000, v200
	v_lshlrev_b32_e32 v200, 16, v201
	v_and_b32_e32 v201, 0xffff0000, v201
	v_lshlrev_b32_e32 v202, 16, v203
	v_and_b32_e32 v203, 0xffff0000, v203
	s_waitcnt vmcnt(17)
	v_pk_fma_f32 v[128:129], v[128:129], v[144:145], v[200:201]
	v_pk_fma_f32 v[126:127], v[126:127], v[142:143], v[224:225]
	s_waitcnt vmcnt(16)
	v_pk_fma_f32 v[200:201], v[124:125], v[140:141], v[202:203]
	v_pk_fma_f32 v[124:125], v[122:123], v[138:139], v[226:227]
	v_cvt_pk_bf16_f32 v122, v126, v127
	v_cvt_pk_bf16_f32 v123, v128, v129
	v_lshlrev_b32_e32 v228, 16, v204
	v_and_b32_e32 v229, 0xffff0000, v204
	v_lshlrev_b32_e32 v204, 16, v205
	v_and_b32_e32 v205, 0xffff0000, v205
	v_lshlrev_b32_e32 v230, 16, v206
	v_and_b32_e32 v231, 0xffff0000, v206
	v_cvt_pk_bf16_f32 v124, v124, v125
	v_cvt_pk_bf16_f32 v125, v200, v201
	global_store_dwordx4 v[190:191], v[122:125], off
	s_waitcnt vmcnt(16)
	v_pk_fma_f32 v[120:121], v[120:121], v[136:137], v[204:205]
	v_pk_fma_f32 v[118:119], v[118:119], v[134:135], v[228:229]
	v_lshlrev_b32_e32 v122, 16, v207
	v_and_b32_e32 v123, 0xffff0000, v207
	s_waitcnt vmcnt(15)
	v_pk_fma_f32 v[122:123], v[116:117], v[132:133], v[122:123]
	v_pk_fma_f32 v[116:117], v[114:115], v[130:131], v[230:231]
	v_cvt_pk_bf16_f32 v114, v118, v119
	v_cvt_pk_bf16_f32 v115, v120, v121
	s_waitcnt vmcnt(14)
	v_lshlrev_b32_e32 v118, 16, v210
	v_cvt_pk_bf16_f32 v116, v116, v117
	v_cvt_pk_bf16_f32 v117, v122, v123
	global_store_dwordx4 v[190:191], v[114:117], off offset:256
	v_and_b32_e32 v119, 0xffff0000, v210
	v_lshlrev_b32_e32 v120, 16, v211
	v_lshlrev_b32_e32 v114, 16, v208
	v_and_b32_e32 v115, 0xffff0000, v208
	v_and_b32_e32 v121, 0xffff0000, v211
	v_pk_fma_f32 v[110:111], v[110:111], v[142:143], v[114:115]
	v_lshlrev_b32_e32 v116, 16, v209
	v_and_b32_e32 v117, 0xffff0000, v209
	v_pk_fma_f32 v[114:115], v[108:109], v[140:141], v[120:121]
	v_pk_fma_f32 v[108:109], v[106:107], v[138:139], v[118:119]
	v_cvt_pk_bf16_f32 v106, v110, v111
	v_add_co_u32_e32 v110, vcc, s37, v190
	v_pk_fma_f32 v[112:113], v[112:113], v[144:145], v[116:117]
	s_nop 0
	v_addc_co_u32_e32 v111, vcc, 0, v191, vcc
	v_cvt_pk_bf16_f32 v107, v112, v113
	v_cvt_pk_bf16_f32 v108, v108, v109
	v_cvt_pk_bf16_f32 v109, v114, v115
	global_store_dwordx4 v[110:111], v[106:109], off
	s_waitcnt vmcnt(15)
	v_lshlrev_b32_e32 v112, 16, v214
	v_and_b32_e32 v113, 0xffff0000, v214
	v_lshlrev_b32_e32 v106, 16, v212
	v_and_b32_e32 v107, 0xffff0000, v212
	v_lshlrev_b32_e32 v108, 16, v213
	v_and_b32_e32 v109, 0xffff0000, v213
	v_lshlrev_b32_e32 v114, 16, v215
	v_and_b32_e32 v115, 0xffff0000, v215
	v_pk_fma_f32 v[104:105], v[104:105], v[136:137], v[108:109]
	v_pk_fma_f32 v[102:103], v[102:103], v[134:135], v[106:107]
	v_pk_fma_f32 v[106:107], v[100:101], v[132:133], v[114:115]
	v_pk_fma_f32 v[100:101], v[98:99], v[130:131], v[112:113]
	v_cvt_pk_bf16_f32 v98, v102, v103
	v_cvt_pk_bf16_f32 v99, v104, v105
	s_waitcnt vmcnt(14)
	v_lshlrev_b32_e32 v102, 16, v218
	v_cvt_pk_bf16_f32 v100, v100, v101
	v_cvt_pk_bf16_f32 v101, v106, v107
	global_store_dwordx4 v[110:111], v[98:101], off offset:256
	v_and_b32_e32 v103, 0xffff0000, v218
	v_lshlrev_b32_e32 v104, 16, v219
	v_lshlrev_b32_e32 v98, 16, v216
	v_and_b32_e32 v99, 0xffff0000, v216
	v_and_b32_e32 v105, 0xffff0000, v219
	v_pk_fma_f32 v[94:95], v[94:95], v[142:143], v[98:99]
	v_lshlrev_b32_e32 v100, 16, v217
	v_and_b32_e32 v101, 0xffff0000, v217
	v_pk_fma_f32 v[98:99], v[92:93], v[140:141], v[104:105]
	v_pk_fma_f32 v[92:93], v[90:91], v[138:139], v[102:103]
	v_cvt_pk_bf16_f32 v90, v94, v95
	v_add_co_u32_e32 v94, vcc, s24, v190
	v_pk_fma_f32 v[96:97], v[96:97], v[144:145], v[100:101]
	s_nop 0
	v_addc_co_u32_e32 v95, vcc, 0, v191, vcc
	v_cvt_pk_bf16_f32 v91, v96, v97
	v_cvt_pk_bf16_f32 v92, v92, v93
	v_cvt_pk_bf16_f32 v93, v98, v99
	global_store_dwordx4 v[94:95], v[90:93], off
	s_waitcnt vmcnt(15)
	v_lshlrev_b32_e32 v96, 16, v222
	v_and_b32_e32 v97, 0xffff0000, v222
	v_lshlrev_b32_e32 v90, 16, v220
	v_and_b32_e32 v91, 0xffff0000, v220
	v_lshlrev_b32_e32 v92, 16, v221
	v_and_b32_e32 v93, 0xffff0000, v221
	v_lshlrev_b32_e32 v98, 16, v223
	v_and_b32_e32 v99, 0xffff0000, v223
	v_pk_fma_f32 v[88:89], v[88:89], v[136:137], v[92:93]
	v_pk_fma_f32 v[86:87], v[86:87], v[134:135], v[90:91]
	v_pk_fma_f32 v[90:91], v[84:85], v[132:133], v[98:99]
	v_pk_fma_f32 v[84:85], v[82:83], v[130:131], v[96:97]
	v_cvt_pk_bf16_f32 v82, v86, v87
	v_cvt_pk_bf16_f32 v83, v88, v89
	s_waitcnt vmcnt(14)
	v_lshlrev_b32_e32 v86, 16, v184
	v_cvt_pk_bf16_f32 v84, v84, v85
	v_cvt_pk_bf16_f32 v85, v90, v91
	global_store_dwordx4 v[94:95], v[82:85], off offset:256
	v_and_b32_e32 v87, 0xffff0000, v184
	v_lshlrev_b32_e32 v88, 16, v185
	v_lshlrev_b32_e32 v82, 16, v182
	v_and_b32_e32 v83, 0xffff0000, v182
	v_and_b32_e32 v89, 0xffff0000, v185
	v_pk_fma_f32 v[78:79], v[78:79], v[142:143], v[82:83]
	v_lshlrev_b32_e32 v84, 16, v183
	v_and_b32_e32 v85, 0xffff0000, v183
	v_pk_fma_f32 v[82:83], v[76:77], v[140:141], v[88:89]
	v_pk_fma_f32 v[76:77], v[74:75], v[138:139], v[86:87]
	v_cvt_pk_bf16_f32 v74, v78, v79
	v_add_co_u32_e32 v78, vcc, s36, v190
	v_pk_fma_f32 v[80:81], v[80:81], v[144:145], v[84:85]
	s_nop 0
	v_addc_co_u32_e32 v79, vcc, 0, v191, vcc
	v_cvt_pk_bf16_f32 v75, v80, v81
	v_cvt_pk_bf16_f32 v76, v76, v77
	v_cvt_pk_bf16_f32 v77, v82, v83
	global_store_dwordx4 v[78:79], v[74:77], off
	s_waitcnt vmcnt(15)
	v_lshlrev_b32_e32 v80, 16, v180
	v_and_b32_e32 v81, 0xffff0000, v180
	v_lshlrev_b32_e32 v74, 16, v178
	v_and_b32_e32 v75, 0xffff0000, v178
	v_lshlrev_b32_e32 v76, 16, v179
	v_and_b32_e32 v77, 0xffff0000, v179
	v_lshlrev_b32_e32 v82, 16, v181
	v_and_b32_e32 v83, 0xffff0000, v181
	v_pk_fma_f32 v[72:73], v[72:73], v[136:137], v[76:77]
	v_pk_fma_f32 v[70:71], v[70:71], v[134:135], v[74:75]
	v_pk_fma_f32 v[74:75], v[68:69], v[132:133], v[82:83]
	v_pk_fma_f32 v[68:69], v[66:67], v[130:131], v[80:81]
	v_cvt_pk_bf16_f32 v66, v70, v71
	v_cvt_pk_bf16_f32 v67, v72, v73
	s_waitcnt vmcnt(14)
	v_lshlrev_b32_e32 v70, 16, v176
	v_cvt_pk_bf16_f32 v68, v68, v69
	v_cvt_pk_bf16_f32 v69, v74, v75
	global_store_dwordx4 v[78:79], v[66:69], off offset:256
	v_and_b32_e32 v71, 0xffff0000, v176
	v_lshlrev_b32_e32 v72, 16, v177
	v_lshlrev_b32_e32 v66, 16, v174
	v_and_b32_e32 v67, 0xffff0000, v174
	v_and_b32_e32 v73, 0xffff0000, v177
	v_pk_fma_f32 v[62:63], v[62:63], v[142:143], v[66:67]
	v_lshlrev_b32_e32 v68, 16, v175
	v_and_b32_e32 v69, 0xffff0000, v175
	v_pk_fma_f32 v[66:67], v[60:61], v[140:141], v[72:73]
	v_pk_fma_f32 v[60:61], v[58:59], v[138:139], v[70:71]
	v_cvt_pk_bf16_f32 v58, v62, v63
	v_add_co_u32_e32 v62, vcc, s25, v190
	v_pk_fma_f32 v[64:65], v[64:65], v[144:145], v[68:69]
	s_nop 0
	v_addc_co_u32_e32 v63, vcc, 0, v191, vcc
	v_cvt_pk_bf16_f32 v59, v64, v65
	v_cvt_pk_bf16_f32 v60, v60, v61
	v_cvt_pk_bf16_f32 v61, v66, v67
	global_store_dwordx4 v[62:63], v[58:61], off
	s_waitcnt vmcnt(15)
	v_lshlrev_b32_e32 v64, 16, v172
	v_and_b32_e32 v65, 0xffff0000, v172
	v_lshlrev_b32_e32 v58, 16, v170
	v_and_b32_e32 v59, 0xffff0000, v170
	v_lshlrev_b32_e32 v60, 16, v171
	v_and_b32_e32 v61, 0xffff0000, v171
	v_lshlrev_b32_e32 v66, 16, v173
	v_and_b32_e32 v67, 0xffff0000, v173
	v_pk_fma_f32 v[56:57], v[56:57], v[136:137], v[60:61]
	v_pk_fma_f32 v[54:55], v[54:55], v[134:135], v[58:59]
	v_pk_fma_f32 v[58:59], v[52:53], v[132:133], v[66:67]
	v_pk_fma_f32 v[52:53], v[50:51], v[130:131], v[64:65]
	v_cvt_pk_bf16_f32 v50, v54, v55
	v_cvt_pk_bf16_f32 v51, v56, v57
	s_waitcnt vmcnt(14)
	v_lshlrev_b32_e32 v54, 16, v168
	v_cvt_pk_bf16_f32 v52, v52, v53
	v_cvt_pk_bf16_f32 v53, v58, v59
	global_store_dwordx4 v[62:63], v[50:53], off offset:256
	v_and_b32_e32 v55, 0xffff0000, v168
	v_lshlrev_b32_e32 v56, 16, v169
	v_lshlrev_b32_e32 v50, 16, v166
	v_and_b32_e32 v51, 0xffff0000, v166
	v_and_b32_e32 v57, 0xffff0000, v169
	v_pk_fma_f32 v[46:47], v[46:47], v[142:143], v[50:51]
	v_lshlrev_b32_e32 v52, 16, v167
	v_and_b32_e32 v53, 0xffff0000, v167
	v_pk_fma_f32 v[50:51], v[44:45], v[140:141], v[56:57]
	v_pk_fma_f32 v[44:45], v[42:43], v[138:139], v[54:55]
	v_cvt_pk_bf16_f32 v42, v46, v47
	v_add_co_u32_e32 v46, vcc, s42, v190
	v_pk_fma_f32 v[48:49], v[48:49], v[144:145], v[52:53]
	s_nop 0
	v_addc_co_u32_e32 v47, vcc, 0, v191, vcc
	v_cvt_pk_bf16_f32 v43, v48, v49
	v_cvt_pk_bf16_f32 v44, v44, v45
	v_cvt_pk_bf16_f32 v45, v50, v51
	global_store_dwordx4 v[46:47], v[42:45], off
	s_waitcnt vmcnt(15)
	v_lshlrev_b32_e32 v48, 16, v164
	v_and_b32_e32 v49, 0xffff0000, v164
	v_lshlrev_b32_e32 v42, 16, v162
	v_and_b32_e32 v43, 0xffff0000, v162
	v_lshlrev_b32_e32 v44, 16, v163
	v_and_b32_e32 v45, 0xffff0000, v163
	v_lshlrev_b32_e32 v50, 16, v165
	v_and_b32_e32 v51, 0xffff0000, v165
	v_pk_fma_f32 v[40:41], v[40:41], v[136:137], v[44:45]
	v_pk_fma_f32 v[38:39], v[38:39], v[134:135], v[42:43]
	v_pk_fma_f32 v[42:43], v[36:37], v[132:133], v[50:51]
	v_pk_fma_f32 v[36:37], v[34:35], v[130:131], v[48:49]
	v_cvt_pk_bf16_f32 v34, v38, v39
	v_cvt_pk_bf16_f32 v35, v40, v41
	s_waitcnt vmcnt(14)
	v_lshlrev_b32_e32 v38, 16, v160
	v_cvt_pk_bf16_f32 v36, v36, v37
	v_cvt_pk_bf16_f32 v37, v42, v43
	global_store_dwordx4 v[46:47], v[34:37], off offset:256
	v_and_b32_e32 v39, 0xffff0000, v160
	v_lshlrev_b32_e32 v40, 16, v161
	v_lshlrev_b32_e32 v34, 16, v158
	v_and_b32_e32 v35, 0xffff0000, v158
	v_and_b32_e32 v41, 0xffff0000, v161
	v_pk_fma_f32 v[30:31], v[30:31], v[142:143], v[34:35]
	v_lshlrev_b32_e32 v36, 16, v159
	v_and_b32_e32 v37, 0xffff0000, v159
	v_pk_fma_f32 v[34:35], v[28:29], v[140:141], v[40:41]
	v_pk_fma_f32 v[28:29], v[26:27], v[138:139], v[38:39]
	v_cvt_pk_bf16_f32 v26, v30, v31
	v_add_co_u32_e32 v30, vcc, s43, v190
	v_pk_fma_f32 v[32:33], v[32:33], v[144:145], v[36:37]
	s_nop 0
	v_addc_co_u32_e32 v31, vcc, 0, v191, vcc
	v_cvt_pk_bf16_f32 v27, v32, v33
	v_cvt_pk_bf16_f32 v28, v28, v29
	v_cvt_pk_bf16_f32 v29, v34, v35
	global_store_dwordx4 v[30:31], v[26:29], off
	s_waitcnt vmcnt(15)
	v_lshlrev_b32_e32 v32, 16, v156
	v_and_b32_e32 v33, 0xffff0000, v156
	v_lshlrev_b32_e32 v26, 16, v154
	v_and_b32_e32 v27, 0xffff0000, v154
	v_lshlrev_b32_e32 v28, 16, v155
	v_and_b32_e32 v29, 0xffff0000, v155
	v_lshlrev_b32_e32 v34, 16, v157
	v_and_b32_e32 v35, 0xffff0000, v157
	v_pk_fma_f32 v[24:25], v[24:25], v[136:137], v[28:29]
	v_pk_fma_f32 v[22:23], v[22:23], v[134:135], v[26:27]
	v_pk_fma_f32 v[26:27], v[20:21], v[132:133], v[34:35]
	v_pk_fma_f32 v[20:21], v[18:19], v[130:131], v[32:33]
	v_cvt_pk_bf16_f32 v18, v22, v23
	v_cvt_pk_bf16_f32 v19, v24, v25
	s_waitcnt vmcnt(14)
	v_lshlrev_b32_e32 v22, 16, v152
	v_cvt_pk_bf16_f32 v20, v20, v21
	v_cvt_pk_bf16_f32 v21, v26, v27
	global_store_dwordx4 v[30:31], v[18:21], off offset:256
	v_and_b32_e32 v23, 0xffff0000, v152
	v_lshlrev_b32_e32 v24, 16, v153
	v_lshlrev_b32_e32 v18, 16, v150
	v_and_b32_e32 v19, 0xffff0000, v150
	v_and_b32_e32 v25, 0xffff0000, v153
	v_pk_fma_f32 v[14:15], v[14:15], v[142:143], v[18:19]
	v_lshlrev_b32_e32 v20, 16, v151
	v_and_b32_e32 v21, 0xffff0000, v151
	v_pk_fma_f32 v[18:19], v[12:13], v[140:141], v[24:25]
	v_pk_fma_f32 v[12:13], v[10:11], v[138:139], v[22:23]
	v_cvt_pk_bf16_f32 v10, v14, v15
	v_add_co_u32_e32 v14, vcc, s45, v190
	v_pk_fma_f32 v[16:17], v[16:17], v[144:145], v[20:21]
	s_nop 0
	v_addc_co_u32_e32 v15, vcc, 0, v191, vcc
	v_cvt_pk_bf16_f32 v11, v16, v17
	v_cvt_pk_bf16_f32 v12, v12, v13
	v_cvt_pk_bf16_f32 v13, v18, v19
	global_store_dwordx4 v[14:15], v[10:13], off
	s_waitcnt vmcnt(15)
	v_lshlrev_b32_e32 v16, 16, v148
	v_and_b32_e32 v17, 0xffff0000, v148
	v_lshlrev_b32_e32 v10, 16, v146
	v_and_b32_e32 v11, 0xffff0000, v146
	v_lshlrev_b32_e32 v18, 16, v149
	v_and_b32_e32 v19, 0xffff0000, v149
	v_lshlrev_b32_e32 v12, 16, v147
	v_and_b32_e32 v13, 0xffff0000, v147
	v_pk_fma_f32 v[6:7], v[6:7], v[134:135], v[10:11]
	v_pk_fma_f32 v[10:11], v[4:5], v[132:133], v[18:19]
	v_pk_fma_f32 v[4:5], v[2:3], v[130:131], v[16:17]
	s_and_b64 vcc, exec, s[4:5]
	v_pk_fma_f32 v[8:9], v[8:9], v[136:137], v[12:13]
	v_cvt_pk_bf16_f32 v2, v6, v7
	s_nop 0
	v_cvt_pk_bf16_f32 v3, v8, v9
	v_cvt_pk_bf16_f32 v4, v4, v5
	v_cvt_pk_bf16_f32 v5, v10, v11
	global_store_dwordx4 v[14:15], v[2:5], off offset:256
	s_cbranch_vccnz .LBB0_2154

.LBB0_2151:
	ds_read_b128 v[130:133], v195
	ds_read_b128 v[134:137], v195 offset:1024
	ds_read_b128 v[138:141], v195 offset:2048
	ds_read_b128 v[142:145], v195 offset:3072
	s_add_i32 s10, s7, 0xfffa0080
	s_cmp_eq_u32 s13, 12
	s_cselect_b32 s78, s6, s10
	s_cselect_b32 s73, s57, s12
	s_or_b32 s79, s78, 0x80
	s_add_i32 s10, s7, 0xfffe0000
	s_mov_b32 m0, s38
	ds_read_b128 v[146:149], v196
	ds_read_b128 v[150:153], v196 offset:1024
	ds_read_b128 v[154:157], v196 offset:2048
	ds_read_b128 v[158:161], v196 offset:3072
	ds_read_b128 v[162:165], v196 offset:4096
	ds_read_b128 v[166:169], v196 offset:5120
	ds_read_b128 v[170:173], v196 offset:6144
	ds_read_b128 v[174:177], v196 offset:7168
	buffer_load_dwordx4 v1, s[48:51], s10 offen lds
	s_mov_b32 m0, s39
	s_nop 0
	buffer_load_dwordx4 v1, s[48:51], s7 offen lds
	s_waitcnt lgkmcnt(8)
	s_barrier
	s_waitcnt lgkmcnt(0)
	s_setprio 1
	s_waitcnt lgkmcnt(7)
	v_mfma_f32_16x16x32_bf16 v[126:129], v[130:133], v[146:149], v[126:129]
	v_mfma_f32_16x16x32_bf16 v[122:125], v[138:141], v[146:149], v[122:125]
	s_waitcnt lgkmcnt(5)
	v_mfma_f32_16x16x32_bf16 v[110:113], v[130:133], v[154:157], v[110:113]
	v_mfma_f32_16x16x32_bf16 v[106:109], v[138:141], v[154:157], v[106:109]
	s_waitcnt lgkmcnt(3)
	v_mfma_f32_16x16x32_bf16 v[94:97], v[130:133], v[162:165], v[94:97]
	v_mfma_f32_16x16x32_bf16 v[90:93], v[138:141], v[162:165], v[90:93]
	s_waitcnt lgkmcnt(1)
	v_mfma_f32_16x16x32_bf16 v[78:81], v[130:133], v[170:173], v[78:81]
	v_mfma_f32_16x16x32_bf16 v[74:77], v[138:141], v[170:173], v[74:77]
	v_mfma_f32_16x16x32_bf16 v[126:129], v[134:137], v[150:153], v[126:129]
	v_mfma_f32_16x16x32_bf16 v[122:125], v[142:145], v[150:153], v[122:125]
	v_mfma_f32_16x16x32_bf16 v[110:113], v[134:137], v[158:161], v[110:113]
	v_mfma_f32_16x16x32_bf16 v[106:109], v[142:145], v[158:161], v[106:109]
	v_mfma_f32_16x16x32_bf16 v[94:97], v[134:137], v[166:169], v[94:97]
	v_mfma_f32_16x16x32_bf16 v[90:93], v[142:145], v[166:169], v[90:93]
	s_waitcnt lgkmcnt(0)
	v_mfma_f32_16x16x32_bf16 v[78:81], v[134:137], v[174:177], v[78:81]
	v_mfma_f32_16x16x32_bf16 v[74:77], v[142:145], v[174:177], v[74:77]
	s_setprio 0
	s_barrier
	s_mov_b32 m0, s16
	s_mov_b32 s10, s50
	s_mov_b32 s11, s51
	ds_read_b128 v[178:181], v197
	ds_read_b128 v[182:185], v197 offset:1024
	ds_read_b128 v[200:203], v197 offset:2048
	ds_read_b128 v[204:207], v197 offset:3072
	buffer_load_dwordx4 v192, s[8:11], s73 offen lds
	s_add_i32 s33, s73, 0x20000
	s_mov_b32 m0, s17
	s_nop 0
	buffer_load_dwordx4 v192, s[8:11], s33 offen lds
	s_barrier
	s_waitcnt lgkmcnt(0)
	s_setprio 1
	s_waitcnt lgkmcnt(3)
	v_mfma_f32_16x16x32_bf16 v[118:121], v[178:181], v[146:149], v[118:121]
	s_waitcnt lgkmcnt(1)
	v_mfma_f32_16x16x32_bf16 v[114:117], v[200:203], v[146:149], v[114:117]
	v_mfma_f32_16x16x32_bf16 v[102:105], v[178:181], v[154:157], v[102:105]
	v_mfma_f32_16x16x32_bf16 v[98:101], v[200:203], v[154:157], v[98:101]
	v_mfma_f32_16x16x32_bf16 v[86:89], v[178:181], v[162:165], v[86:89]
	v_mfma_f32_16x16x32_bf16 v[82:85], v[200:203], v[162:165], v[82:85]
	v_mfma_f32_16x16x32_bf16 v[70:73], v[178:181], v[170:173], v[70:73]
	v_mfma_f32_16x16x32_bf16 v[66:69], v[200:203], v[170:173], v[66:69]
	v_mfma_f32_16x16x32_bf16 v[118:121], v[182:185], v[150:153], v[118:121]
	s_waitcnt lgkmcnt(0)
	v_mfma_f32_16x16x32_bf16 v[114:117], v[204:207], v[150:153], v[114:117]
	v_mfma_f32_16x16x32_bf16 v[102:105], v[182:185], v[158:161], v[102:105]
	v_mfma_f32_16x16x32_bf16 v[98:101], v[204:207], v[158:161], v[98:101]
	v_mfma_f32_16x16x32_bf16 v[86:89], v[182:185], v[166:169], v[86:89]
	v_mfma_f32_16x16x32_bf16 v[82:85], v[204:207], v[166:169], v[82:85]
	v_mfma_f32_16x16x32_bf16 v[70:73], v[182:185], v[174:177], v[70:73]
	v_mfma_f32_16x16x32_bf16 v[66:69], v[204:207], v[174:177], v[66:69]
	s_setprio 0
	s_mov_b32 m0, s15
	s_barrier
	ds_read_b128 v[146:149], v196 offset:16384
	ds_read_b128 v[150:153], v196 offset:17408
	ds_read_b128 v[154:157], v196 offset:18432
	ds_read_b128 v[158:161], v196 offset:19456
	ds_read_b128 v[162:165], v196 offset:20480
	ds_read_b128 v[166:169], v196 offset:21504
	ds_read_b128 v[170:173], v196 offset:22528
	ds_read_b128 v[174:177], v196 offset:23552
	buffer_load_dwordx4 v1, s[48:51], s78 offen lds
	s_add_i32 s33, s78, 0x20000
	s_mov_b32 m0, s18
	s_nop 0
	buffer_load_dwordx4 v1, s[48:51], s33 offen lds
	s_barrier
	s_waitcnt lgkmcnt(0)
	s_setprio 1
	s_waitcnt lgkmcnt(7)
	v_mfma_f32_16x16x32_bf16 v[62:65], v[130:133], v[146:149], v[62:65]
	v_mfma_f32_16x16x32_bf16 v[58:61], v[138:141], v[146:149], v[58:61]
	s_waitcnt lgkmcnt(5)
	v_mfma_f32_16x16x32_bf16 v[46:49], v[130:133], v[154:157], v[46:49]
	v_mfma_f32_16x16x32_bf16 v[42:45], v[138:141], v[154:157], v[42:45]
	s_waitcnt lgkmcnt(3)
	v_mfma_f32_16x16x32_bf16 v[30:33], v[130:133], v[162:165], v[30:33]
	v_mfma_f32_16x16x32_bf16 v[26:29], v[138:141], v[162:165], v[26:29]
	s_waitcnt lgkmcnt(1)
	v_mfma_f32_16x16x32_bf16 v[14:17], v[130:133], v[170:173], v[14:17]
	v_mfma_f32_16x16x32_bf16 v[10:13], v[138:141], v[170:173], v[10:13]
	v_mfma_f32_16x16x32_bf16 v[62:65], v[134:137], v[150:153], v[62:65]
	v_mfma_f32_16x16x32_bf16 v[58:61], v[142:145], v[150:153], v[58:61]
	v_mfma_f32_16x16x32_bf16 v[46:49], v[134:137], v[158:161], v[46:49]
	v_mfma_f32_16x16x32_bf16 v[42:45], v[142:145], v[158:161], v[42:45]
	v_mfma_f32_16x16x32_bf16 v[30:33], v[134:137], v[166:169], v[30:33]
	v_mfma_f32_16x16x32_bf16 v[26:29], v[142:145], v[166:169], v[26:29]
	s_waitcnt lgkmcnt(0)
	v_mfma_f32_16x16x32_bf16 v[14:17], v[134:137], v[174:177], v[14:17]
	v_mfma_f32_16x16x32_bf16 v[10:13], v[142:145], v[174:177], v[10:13]
	s_setprio 0
	s_barrier
	s_mov_b32 m0, s19
	s_add_i32 s33, s73, 0x40000
	buffer_load_dwordx4 v192, s[8:11], s33 offen lds
	s_add_i32 s33, s73, 0x60000
	s_mov_b32 m0, s20
	s_nop 0
	buffer_load_dwordx4 v192, s[8:11], s33 offen lds
	s_waitcnt vmcnt(6)
	s_barrier
	s_setprio 1
	v_mfma_f32_16x16x32_bf16 v[54:57], v[178:181], v[146:149], v[54:57]
	v_mfma_f32_16x16x32_bf16 v[50:53], v[200:203], v[146:149], v[50:53]
	v_mfma_f32_16x16x32_bf16 v[38:41], v[178:181], v[154:157], v[38:41]
	v_mfma_f32_16x16x32_bf16 v[34:37], v[200:203], v[154:157], v[34:37]
	v_mfma_f32_16x16x32_bf16 v[22:25], v[178:181], v[162:165], v[22:25]
	v_mfma_f32_16x16x32_bf16 v[18:21], v[200:203], v[162:165], v[18:21]
	v_mfma_f32_16x16x32_bf16 v[6:9], v[178:181], v[170:173], v[6:9]
	v_mfma_f32_16x16x32_bf16 v[2:5], v[200:203], v[170:173], v[2:5]
	v_mfma_f32_16x16x32_bf16 v[54:57], v[182:185], v[150:153], v[54:57]
	v_mfma_f32_16x16x32_bf16 v[50:53], v[204:207], v[150:153], v[50:53]
	v_mfma_f32_16x16x32_bf16 v[38:41], v[182:185], v[158:161], v[38:41]
	v_mfma_f32_16x16x32_bf16 v[34:37], v[204:207], v[158:161], v[34:37]
	v_mfma_f32_16x16x32_bf16 v[22:25], v[182:185], v[166:169], v[22:25]
	v_mfma_f32_16x16x32_bf16 v[18:21], v[204:207], v[166:169], v[18:21]
	v_mfma_f32_16x16x32_bf16 v[6:9], v[182:185], v[174:177], v[6:9]
	v_mfma_f32_16x16x32_bf16 v[2:5], v[204:207], v[174:177], v[2:5]
	s_setprio 0
	s_barrier
	ds_read_b128 v[130:133], v198
	ds_read_b128 v[134:137], v198 offset:1024
	ds_read_b128 v[138:141], v198 offset:2048
	ds_read_b128 v[142:145], v198 offset:3072
	s_mov_b32 m0, s21
	s_add_i32 s33, s78, 0x40000
	ds_read_b128 v[146:149], v196 offset:32768
	ds_read_b128 v[150:153], v196 offset:33792
	ds_read_b128 v[154:157], v196 offset:34816
	ds_read_b128 v[158:161], v196 offset:35840
	ds_read_b128 v[162:165], v196 offset:36864
	ds_read_b128 v[166:169], v196 offset:37888
	ds_read_b128 v[170:173], v196 offset:38912
	ds_read_b128 v[174:177], v196 offset:39936
	buffer_load_dwordx4 v1, s[48:51], s33 offen lds
	s_add_i32 s33, s78, 0x60000
	s_mov_b32 m0, s22
	s_nop 0
	buffer_load_dwordx4 v1, s[48:51], s33 offen lds
	s_waitcnt lgkmcnt(8)
	s_barrier
	s_waitcnt lgkmcnt(0)
	s_setprio 1
	s_waitcnt lgkmcnt(7)
	v_mfma_f32_16x16x32_bf16 v[126:129], v[130:133], v[146:149], v[126:129]
	v_mfma_f32_16x16x32_bf16 v[122:125], v[138:141], v[146:149], v[122:125]
	s_waitcnt lgkmcnt(5)
	v_mfma_f32_16x16x32_bf16 v[110:113], v[130:133], v[154:157], v[110:113]
	v_mfma_f32_16x16x32_bf16 v[106:109], v[138:141], v[154:157], v[106:109]
	s_waitcnt lgkmcnt(3)
	v_mfma_f32_16x16x32_bf16 v[94:97], v[130:133], v[162:165], v[94:97]
	v_mfma_f32_16x16x32_bf16 v[90:93], v[138:141], v[162:165], v[90:93]
	s_waitcnt lgkmcnt(1)
	v_mfma_f32_16x16x32_bf16 v[78:81], v[130:133], v[170:173], v[78:81]
	v_mfma_f32_16x16x32_bf16 v[74:77], v[138:141], v[170:173], v[74:77]
	v_mfma_f32_16x16x32_bf16 v[126:129], v[134:137], v[150:153], v[126:129]
	v_mfma_f32_16x16x32_bf16 v[122:125], v[142:145], v[150:153], v[122:125]
	v_mfma_f32_16x16x32_bf16 v[110:113], v[134:137], v[158:161], v[110:113]
	v_mfma_f32_16x16x32_bf16 v[106:109], v[142:145], v[158:161], v[106:109]
	v_mfma_f32_16x16x32_bf16 v[94:97], v[134:137], v[166:169], v[94:97]
	v_mfma_f32_16x16x32_bf16 v[90:93], v[142:145], v[166:169], v[90:93]
	s_waitcnt lgkmcnt(0)
	v_mfma_f32_16x16x32_bf16 v[78:81], v[134:137], v[174:177], v[78:81]
	v_mfma_f32_16x16x32_bf16 v[74:77], v[142:145], v[174:177], v[74:77]
	s_setprio 0
	s_barrier
	s_mov_b32 m0, s28
	s_add_i32 s33, s73, 0x80
	ds_read_b128 v[178:181], v199
	ds_read_b128 v[182:185], v199 offset:1024
	ds_read_b128 v[200:203], v199 offset:2048
	ds_read_b128 v[204:207], v199 offset:3072
	buffer_load_dwordx4 v192, s[8:11], s33 offen lds
	s_add_i32 s33, s73, 0x20080
	s_mov_b32 m0, s29
	s_nop 0
	buffer_load_dwordx4 v192, s[8:11], s33 offen lds
	s_barrier
	s_waitcnt lgkmcnt(0)
	s_setprio 1
	s_waitcnt lgkmcnt(3)
	v_mfma_f32_16x16x32_bf16 v[118:121], v[178:181], v[146:149], v[118:121]
	s_waitcnt lgkmcnt(1)
	v_mfma_f32_16x16x32_bf16 v[114:117], v[200:203], v[146:149], v[114:117]
	v_mfma_f32_16x16x32_bf16 v[102:105], v[178:181], v[154:157], v[102:105]
	v_mfma_f32_16x16x32_bf16 v[98:101], v[200:203], v[154:157], v[98:101]
	v_mfma_f32_16x16x32_bf16 v[86:89], v[178:181], v[162:165], v[86:89]
	v_mfma_f32_16x16x32_bf16 v[82:85], v[200:203], v[162:165], v[82:85]
	v_mfma_f32_16x16x32_bf16 v[70:73], v[178:181], v[170:173], v[70:73]
	v_mfma_f32_16x16x32_bf16 v[66:69], v[200:203], v[170:173], v[66:69]
	v_mfma_f32_16x16x32_bf16 v[118:121], v[182:185], v[150:153], v[118:121]
	s_waitcnt lgkmcnt(0)
	v_mfma_f32_16x16x32_bf16 v[114:117], v[204:207], v[150:153], v[114:117]
	v_mfma_f32_16x16x32_bf16 v[102:105], v[182:185], v[158:161], v[102:105]
	v_mfma_f32_16x16x32_bf16 v[98:101], v[204:207], v[158:161], v[98:101]
	v_mfma_f32_16x16x32_bf16 v[86:89], v[182:185], v[166:169], v[86:89]
	v_mfma_f32_16x16x32_bf16 v[82:85], v[204:207], v[166:169], v[82:85]
	v_mfma_f32_16x16x32_bf16 v[70:73], v[182:185], v[174:177], v[70:73]
	v_mfma_f32_16x16x32_bf16 v[66:69], v[204:207], v[174:177], v[66:69]
	s_setprio 0
	s_mov_b32 m0, s30
	s_barrier
	ds_read_b128 v[146:149], v196 offset:49152
	ds_read_b128 v[150:153], v196 offset:50176
	ds_read_b128 v[154:157], v196 offset:51200
	ds_read_b128 v[158:161], v196 offset:52224
	ds_read_b128 v[162:165], v196 offset:53248
	ds_read_b128 v[166:169], v196 offset:54272
	ds_read_b128 v[170:173], v196 offset:55296
	ds_read_b128 v[174:177], v196 offset:56320
	buffer_load_dwordx4 v1, s[48:51], s79 offen lds
	s_add_i32 s78, s78, 0x20080
	s_mov_b32 m0, s31
	s_nop 0
	buffer_load_dwordx4 v1, s[48:51], s78 offen lds
	s_barrier
	s_waitcnt lgkmcnt(0)
	s_setprio 1
	s_waitcnt lgkmcnt(7)
	v_mfma_f32_16x16x32_bf16 v[62:65], v[130:133], v[146:149], v[62:65]
	v_mfma_f32_16x16x32_bf16 v[58:61], v[138:141], v[146:149], v[58:61]
	s_waitcnt lgkmcnt(5)
	v_mfma_f32_16x16x32_bf16 v[46:49], v[130:133], v[154:157], v[46:49]
	v_mfma_f32_16x16x32_bf16 v[42:45], v[138:141], v[154:157], v[42:45]
	s_waitcnt lgkmcnt(3)
	v_mfma_f32_16x16x32_bf16 v[30:33], v[130:133], v[162:165], v[30:33]
	v_mfma_f32_16x16x32_bf16 v[26:29], v[138:141], v[162:165], v[26:29]
	s_waitcnt lgkmcnt(1)
	v_mfma_f32_16x16x32_bf16 v[14:17], v[130:133], v[170:173], v[14:17]
	v_mfma_f32_16x16x32_bf16 v[10:13], v[138:141], v[170:173], v[10:13]
	v_mfma_f32_16x16x32_bf16 v[62:65], v[134:137], v[150:153], v[62:65]
	v_mfma_f32_16x16x32_bf16 v[58:61], v[142:145], v[150:153], v[58:61]
	v_mfma_f32_16x16x32_bf16 v[46:49], v[134:137], v[158:161], v[46:49]
	v_mfma_f32_16x16x32_bf16 v[42:45], v[142:145], v[158:161], v[42:45]
	v_mfma_f32_16x16x32_bf16 v[30:33], v[134:137], v[166:169], v[30:33]
	v_mfma_f32_16x16x32_bf16 v[26:29], v[142:145], v[166:169], v[26:29]
	s_waitcnt lgkmcnt(0)
	v_mfma_f32_16x16x32_bf16 v[14:17], v[134:137], v[174:177], v[14:17]
	v_mfma_f32_16x16x32_bf16 v[10:13], v[142:145], v[174:177], v[10:13]
	s_setprio 0
	s_barrier
	s_mov_b32 m0, s34
	s_add_i32 s33, s73, 0x40080
	buffer_load_dwordx4 v192, s[8:11], s33 offen lds
	s_add_i32 s73, s73, 0x60080
	s_mov_b32 m0, s35
	s_nop 0
	buffer_load_dwordx4 v192, s[8:11], s73 offen lds
	s_waitcnt vmcnt(6)
	s_barrier
	s_setprio 1
	v_mfma_f32_16x16x32_bf16 v[54:57], v[178:181], v[146:149], v[54:57]
	v_mfma_f32_16x16x32_bf16 v[50:53], v[200:203], v[146:149], v[50:53]
	v_mfma_f32_16x16x32_bf16 v[38:41], v[178:181], v[154:157], v[38:41]
	v_mfma_f32_16x16x32_bf16 v[34:37], v[200:203], v[154:157], v[34:37]
	v_mfma_f32_16x16x32_bf16 v[22:25], v[178:181], v[162:165], v[22:25]
	v_mfma_f32_16x16x32_bf16 v[18:21], v[200:203], v[162:165], v[18:21]
	v_mfma_f32_16x16x32_bf16 v[6:9], v[178:181], v[170:173], v[6:9]
	v_mfma_f32_16x16x32_bf16 v[2:5], v[200:203], v[170:173], v[2:5]
	v_mfma_f32_16x16x32_bf16 v[54:57], v[182:185], v[150:153], v[54:57]
	v_mfma_f32_16x16x32_bf16 v[50:53], v[204:207], v[150:153], v[50:53]
	v_mfma_f32_16x16x32_bf16 v[38:41], v[182:185], v[158:161], v[38:41]
	v_mfma_f32_16x16x32_bf16 v[34:37], v[204:207], v[158:161], v[34:37]
	v_mfma_f32_16x16x32_bf16 v[22:25], v[182:185], v[166:169], v[22:25]
	v_mfma_f32_16x16x32_bf16 v[18:21], v[204:207], v[166:169], v[18:21]
	v_mfma_f32_16x16x32_bf16 v[6:9], v[182:185], v[174:177], v[6:9]
	v_mfma_f32_16x16x32_bf16 v[2:5], v[204:207], v[174:177], v[2:5]
	s_setprio 0
	s_add_i32 s13, s13, 2
	s_addk_i32 s7, 0x100
	s_addk_i32 s12, 0x100
	s_cmp_gt_u32 s13, 13
	s_barrier
	s_cbranch_scc0 .LBB0_2151
	s_cmpk_gt_i32 s59, 0x7f
	s_cselect_b64 s[6:7], -1, 0
	s_and_b64 vcc, exec, s[6:7]
	s_cbranch_vccz .LBB0_2140
	s_mov_b64 s[10:11], 0xc000
	s_mov_b64 s[12:13], 0xcb00000
	s_branch .LBB0_2141

.LBB0_2420:
	s_ashr_i32 s7, s7, 3
	s_add_u32 s12, s52, 0x3bb00000
	s_addc_u32 s8, s53, 0
	s_add_i32 s6, s6, s7
	s_ashr_i32 s7, s6, 31
	s_lshr_b32 s7, s7, 26
	s_add_i32 s7, s6, s7
	v_ashrrev_i32_e32 v2, 31, v4
	s_ashr_i32 s9, s7, 6
	s_andn2_b32 s7, s7, 63
	v_lshrrev_b32_e32 v2, 26, v2
	s_sub_i32 s6, s6, s7
	v_add_u32_e32 v2, v4, v2
	s_bfe_i32 s7, s6, 0x80000
	v_ashrrev_i32_e32 v5, 6, v2
	v_bfe_i32 v2, v4, 27, 1
	s_bfe_u32 s7, s7, 0x3000c
	v_lshlrev_b32_e32 v1, 4, v4
	v_lshrrev_b32_e32 v2, 22, v2
	s_add_i32 s7, s6, s7
	v_add_u32_e32 v2, v1, v2
	s_bfe_i32 s10, s7, 0x80000
	s_and_b32 s7, s7, 0xf8
	v_and_b32_e32 v2, 0xfffffc00, v2
	s_sub_i32 s6, s6, s7
	v_sub_u32_e32 v1, v1, v2
	s_lshl_b32 s9, s9, 3
	s_sext_i32_i8 s6, s6
	v_lshrrev_b32_e32 v2, 4, v1
	s_add_i32 s47, s9, s6
	v_bitop3_b32 v1, v2, v1, 32 bitop3:0x6c
	s_ashr_i32 s6, s47, 31
	v_ashrrev_i32_e32 v3, 31, v1
	s_lshr_b32 s6, s6, 28
	v_readlane_b32 s14, v255, 8
	v_lshrrev_b32_e32 v3, 26, v3
	s_sext_i32_i16 s10, s10
	s_add_i32 s9, s47, s6
	s_lshl_b32 s6, s47, 8
	s_ashr_i32 s4, s3, 6
	v_readlane_b32 s15, v255, 9
	v_lshlrev_b32_e32 v2, 3, v5
	v_add_u32_e32 v8, v1, v3
	s_ashr_i32 s46, s10, 3
	s_ashr_i32 s7, s6, 31
	s_and_b32 s41, s15, 0xffff
	v_and_b32_e32 v2, -16, v2
	v_ashrrev_i32_e32 v9, 6, v8
	s_ashr_i32 s5, s3, 8
	s_and_b32 s13, s8, 0xffff
	s_lshl_b32 s8, s4, 10
	s_lshl_b32 s10, s46, 18
	s_lshl_b64 s[6:7], s[6:7], 2
	v_add_u32_e32 v2, v9, v2
	s_add_u32 s6, s74, s6
	s_addc_u32 s7, s75, s7
	v_ashrrev_i32_e32 v3, 31, v2
	v_lshl_add_u64 v[6:7], v[2:3], 2, s[6:7]
	global_load_dword v10, v[6:7], off
	global_load_dword v11, v[6:7], off offset:512
	global_load_dword v12, v[6:7], off offset:768
	s_nop 0
	global_load_dword v6, v[6:7], off offset:256
	v_and_b32_e32 v8, 0xc0, v8
	v_mov_b32_e32 v7, 1
	v_sub_u32_e32 v1, v1, v8
	s_mov_b32 s6, 0x3fffe0
	v_lshlrev_b32_e32 v5, 5, v5
	v_and_b32_e32 v8, 3, v9
	v_ashrrev_i16_sdwa v1, v7, sext(v1) dst_sel:DWORD dst_unused:UNUSED_PAD src0_sel:DWORD src1_sel:BYTE_0
	v_lshlrev_b32_e32 v7, 1, v2
	v_lshrrev_b32_e32 v9, 2, v2
	v_and_b32_e32 v5, 32, v5
	v_and_or_b32 v8, v2, s6, v8
	v_bfe_i32 v1, v1, 0, 16
	v_and_b32_e32 v7, 24, v7
	v_and_b32_e32 v9, 4, v9
	s_lshl_b32 s6, s9, 17
	s_add_i32 s16, s8, 0
	s_mov_b32 s43, 0x20000
	s_brev_b32 s42, -2
	v_or3_b32 v7, v8, v9, v7
	v_add_lshl_u32 v1, v5, v1, 1
	s_and_b32 s6, s6, 0xffe00000
	s_add_i32 s17, s16, 0x10000
	s_mov_b32 s14, s42
	s_mov_b32 s15, s43
	v_lshl_add_u32 v184, v7, 10, v1
	s_add_i32 s18, s16, 0x12000
	s_add_i32 s49, s6, s10
	s_mov_b32 m0, s17
	s_or_b32 s6, s49, 0x10000
	buffer_load_dwordx4 v184, s[12:15], s49 offen lds
	s_mov_b32 m0, s18
	s_add_i32 s19, s16, 0x2000
	buffer_load_dwordx4 v184, s[12:15], s6 offen lds
	s_mov_b32 m0, s16
	s_add_i32 s20, s16, 0x14000
	s_or_b32 s6, s49, 0x20000
	s_add_i32 s21, s16, 0x16000
	s_add_i32 s22, s16, 0x4000
	s_add_i32 s23, s16, 0x6000
	s_mov_b32 s24, 0
	s_waitcnt vmcnt(5)
	v_lshlrev_b32_e32 v5, 10, v10
	v_and_b32_e32 v5, 0x3fffc00, v5
	s_waitcnt vmcnt(4)
	v_lshl_or_b32 v186, v11, 16, v10
	s_waitcnt vmcnt(2)
	v_lshl_or_b32 v185, v12, 16, v6
	v_lshlrev_b32_e32 v6, 10, v6
	v_and_b32_e32 v7, 0x3fffc00, v6
	v_add_u32_e32 v6, v5, v1
	v_add_u32_e32 v5, v7, v1
	buffer_load_dwordx4 v6, s[40:43], 0 offen lds
	s_mov_b32 m0, s19
	v_bfe_u32 v7, v186, 16, 16
	buffer_load_dwordx4 v5, s[40:43], 0 offen lds
	s_mov_b32 m0, s20
	v_lshl_add_u32 v7, v7, 10, v1
	buffer_load_dwordx4 v184, s[12:15], s6 offen lds
	s_or_b32 s6, s49, 0x30000
	s_mov_b32 m0, s21
	s_cmp_lg_u32 s5, 1
	buffer_load_dwordx4 v184, s[12:15], s6 offen lds
	s_mov_b32 m0, s22
	s_nop 0
	buffer_load_dwordx4 v7, s[40:43], 0 offen lds
	v_bfe_u32 v7, v185, 16, 16
	v_lshl_add_u32 v7, v7, 10, v1
	s_mov_b32 m0, s23
	s_nop 0
	buffer_load_dwordx4 v7, s[40:43], 0 offen lds
	s_cbranch_scc1 .LBB0_2422
	s_barrier

.LBB0_2423:
	v_mov_b32_e32 v218, 0xbd38aa3b
	v_mov_b32_e32 v219, 0xbd38aa3b
	v_mov_b32_e32 v220, 0x44800000
	v_mov_b32_e32 v221, 0x44800000
	v_lshl_add_u32 v222, s47, 8, v187
	v_lshl_or_b32 v224, s46, 7, v188
	s_nop 0
	v_lshl_add_u32 v222, v222, 10, v224
	s_mov_b32 s46, s38
	s_mov_b32 s47, s39
	s_mov_b32 s49, s45
	v_pk_mul_f32 v[226:227], v[174:175], v[218:219]
	v_pk_mul_f32 v[228:229], v[176:177], v[218:219]
	v_pk_mul_f32 v[230:231], v[166:167], v[218:219]
	v_pk_mul_f32 v[232:233], v[168:169], v[218:219]
	v_exp_f32_e32 v226, v226
	v_exp_f32_e32 v227, v227
	v_exp_f32_e32 v228, v228
	v_exp_f32_e32 v229, v229
	v_exp_f32_e32 v230, v230
	v_exp_f32_e32 v231, v231
	v_exp_f32_e32 v232, v232
	v_exp_f32_e32 v233, v233
	v_pk_fma_f32 v[226:227], v[226:227], v[220:221], v[220:221]
	v_pk_fma_f32 v[228:229], v[228:229], v[220:221], v[220:221]
	v_pk_fma_f32 v[230:231], v[230:231], v[220:221], v[220:221]
	v_pk_fma_f32 v[232:233], v[232:233], v[220:221], v[220:221]
	v_rcp_f32_e32 v226, v226
	v_rcp_f32_e32 v227, v227
	v_rcp_f32_e32 v228, v228
	v_rcp_f32_e32 v229, v229
	v_rcp_f32_e32 v230, v230
	v_rcp_f32_e32 v231, v231
	v_rcp_f32_e32 v232, v232
	v_rcp_f32_e32 v233, v233
	v_pk_mul_f32 v[174:175], v[174:175], v[170:171]
	v_pk_mul_f32 v[176:177], v[176:177], v[172:173]
	v_pk_mul_f32 v[166:167], v[166:167], v[162:163]
	v_pk_mul_f32 v[168:169], v[168:169], v[164:165]
	v_pk_mul_f32 v[174:175], v[174:175], v[226:227]
	v_pk_mul_f32 v[176:177], v[176:177], v[228:229]
	v_pk_mul_f32 v[166:167], v[166:167], v[230:231]
	v_pk_mul_f32 v[168:169], v[168:169], v[232:233]
	v_mov_b32_e32 v223, v222
	v_cvt_pk_fp8_f32 v234, v174, v175
	v_cvt_pk_fp8_f32 v235, v166, v167
	v_cvt_pk_fp8_f32 v234, v176, v177 op_sel:[0,0,1]
	v_cvt_pk_fp8_f32 v235, v168, v169 op_sel:[0,0,1]
	s_nop 0
	global_store_dwordx2 v223, v[234:235], s[70:71]
	v_pk_mul_f32 v[226:227], v[158:159], v[218:219]
	v_pk_mul_f32 v[228:229], v[160:161], v[218:219]
	v_pk_mul_f32 v[230:231], v[150:151], v[218:219]
	v_pk_mul_f32 v[232:233], v[152:153], v[218:219]
	v_exp_f32_e32 v226, v226
	v_exp_f32_e32 v227, v227
	v_exp_f32_e32 v228, v228
	v_exp_f32_e32 v229, v229
	v_exp_f32_e32 v230, v230
	v_exp_f32_e32 v231, v231
	v_exp_f32_e32 v232, v232
	v_exp_f32_e32 v233, v233
	v_pk_fma_f32 v[226:227], v[226:227], v[220:221], v[220:221]
	v_pk_fma_f32 v[228:229], v[228:229], v[220:221], v[220:221]
	v_pk_fma_f32 v[230:231], v[230:231], v[220:221], v[220:221]
	v_pk_fma_f32 v[232:233], v[232:233], v[220:221], v[220:221]
	v_rcp_f32_e32 v226, v226
	v_rcp_f32_e32 v227, v227
	v_rcp_f32_e32 v228, v228
	v_rcp_f32_e32 v229, v229
	v_rcp_f32_e32 v230, v230
	v_rcp_f32_e32 v231, v231
	v_rcp_f32_e32 v232, v232
	v_rcp_f32_e32 v233, v233
	v_pk_mul_f32 v[158:159], v[158:159], v[154:155]
	v_pk_mul_f32 v[160:161], v[160:161], v[156:157]
	v_pk_mul_f32 v[150:151], v[150:151], v[146:147]
	v_pk_mul_f32 v[152:153], v[152:153], v[148:149]
	v_pk_mul_f32 v[158:159], v[158:159], v[226:227]
	v_pk_mul_f32 v[160:161], v[160:161], v[228:229]
	v_pk_mul_f32 v[150:151], v[150:151], v[230:231]
	v_pk_mul_f32 v[152:153], v[152:153], v[232:233]
	v_add_u32_e32 v225, 0x4000, v222
	v_cvt_pk_fp8_f32 v236, v158, v159
	v_cvt_pk_fp8_f32 v237, v150, v151
	v_cvt_pk_fp8_f32 v236, v160, v161 op_sel:[0,0,1]
	v_cvt_pk_fp8_f32 v237, v152, v153 op_sel:[0,0,1]
	s_nop 0
	global_store_dwordx2 v225, v[236:237], s[70:71]
	v_pk_mul_f32 v[226:227], v[142:143], v[218:219]
	v_pk_mul_f32 v[228:229], v[144:145], v[218:219]
	v_pk_mul_f32 v[230:231], v[134:135], v[218:219]
	v_pk_mul_f32 v[232:233], v[136:137], v[218:219]
	v_exp_f32_e32 v226, v226
	v_exp_f32_e32 v227, v227
	v_exp_f32_e32 v228, v228
	v_exp_f32_e32 v229, v229
	v_exp_f32_e32 v230, v230
	v_exp_f32_e32 v231, v231
	v_exp_f32_e32 v232, v232
	v_exp_f32_e32 v233, v233
	v_pk_fma_f32 v[226:227], v[226:227], v[220:221], v[220:221]
	v_pk_fma_f32 v[228:229], v[228:229], v[220:221], v[220:221]
	v_pk_fma_f32 v[230:231], v[230:231], v[220:221], v[220:221]
	v_pk_fma_f32 v[232:233], v[232:233], v[220:221], v[220:221]
	v_rcp_f32_e32 v226, v226
	v_rcp_f32_e32 v227, v227
	v_rcp_f32_e32 v228, v228
	v_rcp_f32_e32 v229, v229
	v_rcp_f32_e32 v230, v230
	v_rcp_f32_e32 v231, v231
	v_rcp_f32_e32 v232, v232
	v_rcp_f32_e32 v233, v233
	v_pk_mul_f32 v[142:143], v[142:143], v[138:139]
	v_pk_mul_f32 v[144:145], v[144:145], v[140:141]
	v_pk_mul_f32 v[134:135], v[134:135], v[130:131]
	v_pk_mul_f32 v[136:137], v[136:137], v[132:133]
	v_pk_mul_f32 v[142:143], v[142:143], v[226:227]
	v_pk_mul_f32 v[144:145], v[144:145], v[228:229]
	v_pk_mul_f32 v[134:135], v[134:135], v[230:231]
	v_pk_mul_f32 v[136:137], v[136:137], v[232:233]
	v_add_u32_e32 v223, 0x8000, v222
	v_cvt_pk_fp8_f32 v234, v142, v143
	v_cvt_pk_fp8_f32 v235, v134, v135
	v_cvt_pk_fp8_f32 v234, v144, v145 op_sel:[0,0,1]
	v_cvt_pk_fp8_f32 v235, v136, v137 op_sel:[0,0,1]
	s_nop 0
	global_store_dwordx2 v223, v[234:235], s[70:71]
	v_pk_mul_f32 v[226:227], v[126:127], v[218:219]
	v_pk_mul_f32 v[228:229], v[128:129], v[218:219]
	v_pk_mul_f32 v[230:231], v[118:119], v[218:219]
	v_pk_mul_f32 v[232:233], v[120:121], v[218:219]
	v_exp_f32_e32 v226, v226
	v_exp_f32_e32 v227, v227
	v_exp_f32_e32 v228, v228
	v_exp_f32_e32 v229, v229
	v_exp_f32_e32 v230, v230
	v_exp_f32_e32 v231, v231
	v_exp_f32_e32 v232, v232
	v_exp_f32_e32 v233, v233
	v_pk_fma_f32 v[226:227], v[226:227], v[220:221], v[220:221]
	v_pk_fma_f32 v[228:229], v[228:229], v[220:221], v[220:221]
	v_pk_fma_f32 v[230:231], v[230:231], v[220:221], v[220:221]
	v_pk_fma_f32 v[232:233], v[232:233], v[220:221], v[220:221]
	v_rcp_f32_e32 v226, v226
	v_rcp_f32_e32 v227, v227
	v_rcp_f32_e32 v228, v228
	v_rcp_f32_e32 v229, v229
	v_rcp_f32_e32 v230, v230
	v_rcp_f32_e32 v231, v231
	v_rcp_f32_e32 v232, v232
	v_rcp_f32_e32 v233, v233
	v_pk_mul_f32 v[126:127], v[126:127], v[122:123]
	v_pk_mul_f32 v[128:129], v[128:129], v[124:125]
	v_pk_mul_f32 v[118:119], v[118:119], v[114:115]
	v_pk_mul_f32 v[120:121], v[120:121], v[116:117]
	v_pk_mul_f32 v[126:127], v[126:127], v[226:227]
	v_pk_mul_f32 v[128:129], v[128:129], v[228:229]
	v_pk_mul_f32 v[118:119], v[118:119], v[230:231]
	v_pk_mul_f32 v[120:121], v[120:121], v[232:233]
	v_add_u32_e32 v225, 0xc000, v222
	v_cvt_pk_fp8_f32 v236, v126, v127
	v_cvt_pk_fp8_f32 v237, v118, v119
	v_cvt_pk_fp8_f32 v236, v128, v129 op_sel:[0,0,1]
	v_cvt_pk_fp8_f32 v237, v120, v121 op_sel:[0,0,1]
	s_nop 0
	global_store_dwordx2 v225, v[236:237], s[70:71]
	v_pk_mul_f32 v[226:227], v[110:111], v[218:219]
	v_pk_mul_f32 v[228:229], v[112:113], v[218:219]
	v_pk_mul_f32 v[230:231], v[102:103], v[218:219]
	v_pk_mul_f32 v[232:233], v[104:105], v[218:219]
	v_exp_f32_e32 v226, v226
	v_exp_f32_e32 v227, v227
	v_exp_f32_e32 v228, v228
	v_exp_f32_e32 v229, v229
	v_exp_f32_e32 v230, v230
	v_exp_f32_e32 v231, v231
	v_exp_f32_e32 v232, v232
	v_exp_f32_e32 v233, v233
	v_pk_fma_f32 v[226:227], v[226:227], v[220:221], v[220:221]
	v_pk_fma_f32 v[228:229], v[228:229], v[220:221], v[220:221]
	v_pk_fma_f32 v[230:231], v[230:231], v[220:221], v[220:221]
	v_pk_fma_f32 v[232:233], v[232:233], v[220:221], v[220:221]
	v_rcp_f32_e32 v226, v226
	v_rcp_f32_e32 v227, v227
	v_rcp_f32_e32 v228, v228
	v_rcp_f32_e32 v229, v229
	v_rcp_f32_e32 v230, v230
	v_rcp_f32_e32 v231, v231
	v_rcp_f32_e32 v232, v232
	v_rcp_f32_e32 v233, v233
	v_pk_mul_f32 v[110:111], v[110:111], v[106:107]
	v_pk_mul_f32 v[112:113], v[112:113], v[108:109]
	v_pk_mul_f32 v[102:103], v[102:103], v[98:99]
	v_pk_mul_f32 v[104:105], v[104:105], v[100:101]
	v_pk_mul_f32 v[110:111], v[110:111], v[226:227]
	v_pk_mul_f32 v[112:113], v[112:113], v[228:229]
	v_pk_mul_f32 v[102:103], v[102:103], v[230:231]
	v_pk_mul_f32 v[104:105], v[104:105], v[232:233]
	v_add_u32_e32 v223, 0x20000, v222
	v_cvt_pk_fp8_f32 v234, v110, v111
	v_cvt_pk_fp8_f32 v235, v102, v103
	v_cvt_pk_fp8_f32 v234, v112, v113 op_sel:[0,0,1]
	v_cvt_pk_fp8_f32 v235, v104, v105 op_sel:[0,0,1]
	s_nop 0
	global_store_dwordx2 v223, v[234:235], s[70:71]
	v_pk_mul_f32 v[226:227], v[94:95], v[218:219]
	v_pk_mul_f32 v[228:229], v[96:97], v[218:219]
	v_pk_mul_f32 v[230:231], v[86:87], v[218:219]
	v_pk_mul_f32 v[232:233], v[88:89], v[218:219]
	v_exp_f32_e32 v226, v226
	v_exp_f32_e32 v227, v227
	v_exp_f32_e32 v228, v228
	v_exp_f32_e32 v229, v229
	v_exp_f32_e32 v230, v230
	v_exp_f32_e32 v231, v231
	v_exp_f32_e32 v232, v232
	v_exp_f32_e32 v233, v233
	v_pk_fma_f32 v[226:227], v[226:227], v[220:221], v[220:221]
	v_pk_fma_f32 v[228:229], v[228:229], v[220:221], v[220:221]
	v_pk_fma_f32 v[230:231], v[230:231], v[220:221], v[220:221]
	v_pk_fma_f32 v[232:233], v[232:233], v[220:221], v[220:221]
	v_rcp_f32_e32 v226, v226
	v_rcp_f32_e32 v227, v227
	v_rcp_f32_e32 v228, v228
	v_rcp_f32_e32 v229, v229
	v_rcp_f32_e32 v230, v230
	v_rcp_f32_e32 v231, v231
	v_rcp_f32_e32 v232, v232
	v_rcp_f32_e32 v233, v233
	v_pk_mul_f32 v[94:95], v[94:95], v[90:91]
	v_pk_mul_f32 v[96:97], v[96:97], v[92:93]
	v_pk_mul_f32 v[86:87], v[86:87], v[82:83]
	v_pk_mul_f32 v[88:89], v[88:89], v[84:85]
	v_pk_mul_f32 v[94:95], v[94:95], v[226:227]
	v_pk_mul_f32 v[96:97], v[96:97], v[228:229]
	v_pk_mul_f32 v[86:87], v[86:87], v[230:231]
	v_pk_mul_f32 v[88:89], v[88:89], v[232:233]
	v_add_u32_e32 v225, 0x24000, v222
	v_cvt_pk_fp8_f32 v236, v94, v95
	v_cvt_pk_fp8_f32 v237, v86, v87
	v_cvt_pk_fp8_f32 v236, v96, v97 op_sel:[0,0,1]
	v_cvt_pk_fp8_f32 v237, v88, v89 op_sel:[0,0,1]
	s_nop 0
	global_store_dwordx2 v225, v[236:237], s[70:71]
	v_pk_mul_f32 v[226:227], v[78:79], v[218:219]
	v_pk_mul_f32 v[228:229], v[80:81], v[218:219]
	v_pk_mul_f32 v[230:231], v[70:71], v[218:219]
	v_pk_mul_f32 v[232:233], v[72:73], v[218:219]
	v_exp_f32_e32 v226, v226
	v_exp_f32_e32 v227, v227
	v_exp_f32_e32 v228, v228
	v_exp_f32_e32 v229, v229
	v_exp_f32_e32 v230, v230
	v_exp_f32_e32 v231, v231
	v_exp_f32_e32 v232, v232
	v_exp_f32_e32 v233, v233
	v_pk_fma_f32 v[226:227], v[226:227], v[220:221], v[220:221]
	v_pk_fma_f32 v[228:229], v[228:229], v[220:221], v[220:221]
	v_pk_fma_f32 v[230:231], v[230:231], v[220:221], v[220:221]
	v_pk_fma_f32 v[232:233], v[232:233], v[220:221], v[220:221]
	v_rcp_f32_e32 v226, v226
	v_rcp_f32_e32 v227, v227
	v_rcp_f32_e32 v228, v228
	v_rcp_f32_e32 v229, v229
	v_rcp_f32_e32 v230, v230
	v_rcp_f32_e32 v231, v231
	v_rcp_f32_e32 v232, v232
	v_rcp_f32_e32 v233, v233
	v_pk_mul_f32 v[78:79], v[78:79], v[74:75]
	v_pk_mul_f32 v[80:81], v[80:81], v[76:77]
	v_pk_mul_f32 v[70:71], v[70:71], v[66:67]
	v_pk_mul_f32 v[72:73], v[72:73], v[68:69]
	v_pk_mul_f32 v[78:79], v[78:79], v[226:227]
	v_pk_mul_f32 v[80:81], v[80:81], v[228:229]
	v_pk_mul_f32 v[70:71], v[70:71], v[230:231]
	v_pk_mul_f32 v[72:73], v[72:73], v[232:233]
	v_add_u32_e32 v223, 0x28000, v222
	v_cvt_pk_fp8_f32 v234, v78, v79
	v_cvt_pk_fp8_f32 v235, v70, v71
	v_cvt_pk_fp8_f32 v234, v80, v81 op_sel:[0,0,1]
	v_cvt_pk_fp8_f32 v235, v72, v73 op_sel:[0,0,1]
	s_nop 0
	global_store_dwordx2 v223, v[234:235], s[70:71]
	v_pk_mul_f32 v[226:227], v[62:63], v[218:219]
	v_pk_mul_f32 v[228:229], v[64:65], v[218:219]
	v_pk_mul_f32 v[230:231], v[54:55], v[218:219]
	v_pk_mul_f32 v[232:233], v[56:57], v[218:219]
	v_exp_f32_e32 v226, v226
	v_exp_f32_e32 v227, v227
	v_exp_f32_e32 v228, v228
	v_exp_f32_e32 v229, v229
	v_exp_f32_e32 v230, v230
	v_exp_f32_e32 v231, v231
	v_exp_f32_e32 v232, v232
	v_exp_f32_e32 v233, v233
	v_pk_fma_f32 v[226:227], v[226:227], v[220:221], v[220:221]
	v_pk_fma_f32 v[228:229], v[228:229], v[220:221], v[220:221]
	v_pk_fma_f32 v[230:231], v[230:231], v[220:221], v[220:221]
	v_pk_fma_f32 v[232:233], v[232:233], v[220:221], v[220:221]
	v_rcp_f32_e32 v226, v226
	v_rcp_f32_e32 v227, v227
	v_rcp_f32_e32 v228, v228
	v_rcp_f32_e32 v229, v229
	v_rcp_f32_e32 v230, v230
	v_rcp_f32_e32 v231, v231
	v_rcp_f32_e32 v232, v232
	v_rcp_f32_e32 v233, v233
	v_pk_mul_f32 v[62:63], v[62:63], v[58:59]
	v_pk_mul_f32 v[64:65], v[64:65], v[60:61]
	v_pk_mul_f32 v[54:55], v[54:55], v[50:51]
	v_pk_mul_f32 v[56:57], v[56:57], v[52:53]
	v_pk_mul_f32 v[62:63], v[62:63], v[226:227]
	v_pk_mul_f32 v[64:65], v[64:65], v[228:229]
	v_pk_mul_f32 v[54:55], v[54:55], v[230:231]
	v_pk_mul_f32 v[56:57], v[56:57], v[232:233]
	v_add_u32_e32 v225, 0x2c000, v222
	v_cvt_pk_fp8_f32 v236, v62, v63
	v_cvt_pk_fp8_f32 v237, v54, v55
	v_cvt_pk_fp8_f32 v236, v64, v65 op_sel:[0,0,1]
	v_cvt_pk_fp8_f32 v237, v56, v57 op_sel:[0,0,1]
	s_nop 0
	global_store_dwordx2 v225, v[236:237], s[70:71]
	s_and_b64 vcc, exec, s[4:5]
	s_cbranch_vccnz .LBB0_2438

.LBB0_2435:
	s_and_b64 s[14:15], s[6:7], exec
	s_cselect_b32 s58, 0, s9
	s_add_i32 s14, s49, s9
	s_or_b32 s57, s58, 0x80
	s_waitcnt lgkmcnt(8)
	s_barrier
	s_waitcnt lgkmcnt(0)
	s_and_b64 s[6:7], s[6:7], exec
	s_cselect_b32 s6, s45, s14
	s_add_i32 s7, s6, 0x80
	s_setprio 1
	s_waitcnt lgkmcnt(6)
	v_mfma_f32_16x16x128_f8f6f4 v[174:177], v[2:9], v[42:49], v[174:177]
	v_mfma_f32_16x16x128_f8f6f4 v[166:169], v[10:17], v[42:49], v[166:169]
	s_waitcnt lgkmcnt(4)
	v_mfma_f32_16x16x128_f8f6f4 v[158:161], v[2:9], v[34:41], v[158:161]
	v_mfma_f32_16x16x128_f8f6f4 v[150:153], v[10:17], v[34:41], v[150:153]
	s_waitcnt lgkmcnt(2)
	v_mfma_f32_16x16x128_f8f6f4 v[142:145], v[2:9], v[26:33], v[142:145]
	v_mfma_f32_16x16x128_f8f6f4 v[134:137], v[10:17], v[26:33], v[134:137]
	s_waitcnt lgkmcnt(0)
	v_mfma_f32_16x16x128_f8f6f4 v[126:129], v[2:9], v[18:25], v[126:129]
	v_mfma_f32_16x16x128_f8f6f4 v[118:121], v[10:17], v[18:25], v[118:121]
	s_setprio 0
	s_barrier
	s_mov_b32 m0, s17
	v_add_u32_e32 v210, 0x14000, v189
	s_mov_b32 s14, s42
	s_mov_b32 s15, s43
	ds_read_b128 v[198:201], v210
	ds_read_b128 v[202:205], v210 offset:1024
	ds_read_b128 v[206:209], v210 offset:2048
	ds_read_b128 v[210:213], v210 offset:3072
	buffer_load_dwordx4 v184, s[12:15], s6 offen lds
	s_add_i32 s33, s6, 0x10000
	s_mov_b32 m0, s18
	s_nop 0
	buffer_load_dwordx4 v184, s[12:15], s33 offen lds
	s_barrier
	s_waitcnt lgkmcnt(0)
	s_setprio 1
	s_waitcnt lgkmcnt(2)
	v_mfma_f32_16x16x128_f8f6f4 v[170:173], v[198:205], v[42:49], v[170:173]
	s_waitcnt lgkmcnt(0)
	v_mfma_f32_16x16x128_f8f6f4 v[162:165], v[206:213], v[42:49], v[162:165]
	v_mfma_f32_16x16x128_f8f6f4 v[154:157], v[198:205], v[34:41], v[154:157]
	v_mfma_f32_16x16x128_f8f6f4 v[146:149], v[206:213], v[34:41], v[146:149]
	v_mfma_f32_16x16x128_f8f6f4 v[138:141], v[198:205], v[26:33], v[138:141]
	v_mfma_f32_16x16x128_f8f6f4 v[130:133], v[206:213], v[26:33], v[130:133]
	v_mfma_f32_16x16x128_f8f6f4 v[122:125], v[198:205], v[18:25], v[122:125]
	v_mfma_f32_16x16x128_f8f6f4 v[114:117], v[206:213], v[18:25], v[114:117]
	s_setprio 0
	v_lshlrev_b32_e32 v214, 10, v186
	v_and_b32_e32 v214, 0x3fffc00, v214
	v_lshlrev_b32_e32 v215, 10, v185
	s_mov_b32 m0, s16
	v_add_u32_e32 v214, v214, v1
	v_and_b32_e32 v215, 0x3fffc00, v215
	s_barrier
	ds_read_b128 v[18:21], v191 offset:16384
	ds_read_b128 v[22:25], v191 offset:17408
	ds_read_b128 v[26:29], v191 offset:18432
	ds_read_b128 v[30:33], v191 offset:19456
	ds_read_b128 v[34:37], v191 offset:20480
	ds_read_b128 v[38:41], v191 offset:21504
	ds_read_b128 v[42:45], v191 offset:22528
	ds_read_b128 v[46:49], v191 offset:23552
	buffer_load_dwordx4 v214, s[40:43], s58 offen lds
	v_add_u32_e32 v215, v215, v1
	s_mov_b32 m0, s19
	s_nop 0
	buffer_load_dwordx4 v215, s[40:43], s58 offen lds
	s_barrier
	s_waitcnt lgkmcnt(0)
	s_setprio 1
	s_waitcnt lgkmcnt(6)
	v_mfma_f32_16x16x128_f8f6f4 v[110:113], v[2:9], v[18:25], v[110:113]
	v_mfma_f32_16x16x128_f8f6f4 v[102:105], v[10:17], v[18:25], v[102:105]
	s_waitcnt lgkmcnt(4)
	v_mfma_f32_16x16x128_f8f6f4 v[94:97], v[2:9], v[26:33], v[94:97]
	v_mfma_f32_16x16x128_f8f6f4 v[86:89], v[10:17], v[26:33], v[86:89]
	s_waitcnt lgkmcnt(2)
	v_mfma_f32_16x16x128_f8f6f4 v[78:81], v[2:9], v[34:41], v[78:81]
	v_mfma_f32_16x16x128_f8f6f4 v[70:73], v[10:17], v[34:41], v[70:73]
	s_waitcnt lgkmcnt(0)
	v_mfma_f32_16x16x128_f8f6f4 v[62:65], v[2:9], v[42:49], v[62:65]
	v_mfma_f32_16x16x128_f8f6f4 v[54:57], v[10:17], v[42:49], v[54:57]
	s_setprio 0
	s_barrier
	s_mov_b32 m0, s20
	s_add_i32 s33, s6, 0x20000
	buffer_load_dwordx4 v184, s[12:15], s33 offen lds
	s_add_i32 s33, s6, 0x30000
	s_mov_b32 m0, s21
	s_nop 0
	buffer_load_dwordx4 v184, s[12:15], s33 offen lds
	s_waitcnt vmcnt(6)
	s_barrier
	s_setprio 1
	v_mfma_f32_16x16x128_f8f6f4 v[106:109], v[198:205], v[18:25], v[106:109]
	v_mfma_f32_16x16x128_f8f6f4 v[98:101], v[206:213], v[18:25], v[98:101]
	v_mfma_f32_16x16x128_f8f6f4 v[90:93], v[198:205], v[26:33], v[90:93]
	v_mfma_f32_16x16x128_f8f6f4 v[82:85], v[206:213], v[26:33], v[82:85]
	v_mfma_f32_16x16x128_f8f6f4 v[74:77], v[198:205], v[34:41], v[74:77]
	v_mfma_f32_16x16x128_f8f6f4 v[66:69], v[206:213], v[34:41], v[66:69]
	v_mfma_f32_16x16x128_f8f6f4 v[58:61], v[198:205], v[42:49], v[58:61]
	v_mfma_f32_16x16x128_f8f6f4 v[50:53], v[206:213], v[42:49], v[50:53]
	s_setprio 0
	v_add_u32_e32 v14, 0x18000, v189
	s_barrier
	ds_read_b128 v[2:5], v14
	ds_read_b128 v[6:9], v14 offset:1024
	ds_read_b128 v[10:13], v14 offset:2048
	ds_read_b128 v[14:17], v14 offset:3072
	s_mov_b32 m0, s22
	ds_read_b128 v[18:21], v191 offset:32768
	ds_read_b128 v[22:25], v191 offset:33792
	ds_read_b128 v[26:29], v191 offset:34816
	ds_read_b128 v[30:33], v191 offset:35840
	ds_read_b128 v[34:37], v191 offset:36864
	ds_read_b128 v[38:41], v191 offset:37888
	ds_read_b128 v[42:45], v191 offset:38912
	ds_read_b128 v[46:49], v191 offset:39936
	buffer_load_dwordx4 v196, s[40:43], s58 offen lds
	s_mov_b32 m0, s23
	s_nop 0
	buffer_load_dwordx4 v197, s[40:43], s58 offen lds
	s_waitcnt lgkmcnt(8)
	s_barrier
	s_waitcnt lgkmcnt(0)
	s_setprio 1
	s_waitcnt lgkmcnt(6)
	v_mfma_f32_16x16x128_f8f6f4 v[174:177], v[2:9], v[18:25], v[174:177]
	v_mfma_f32_16x16x128_f8f6f4 v[166:169], v[10:17], v[18:25], v[166:169]
	s_waitcnt lgkmcnt(4)
	v_mfma_f32_16x16x128_f8f6f4 v[158:161], v[2:9], v[26:33], v[158:161]
	v_mfma_f32_16x16x128_f8f6f4 v[150:153], v[10:17], v[26:33], v[150:153]
	s_waitcnt lgkmcnt(2)
	v_mfma_f32_16x16x128_f8f6f4 v[142:145], v[2:9], v[34:41], v[142:145]
	v_mfma_f32_16x16x128_f8f6f4 v[134:137], v[10:17], v[34:41], v[134:137]
	s_waitcnt lgkmcnt(0)
	v_mfma_f32_16x16x128_f8f6f4 v[126:129], v[2:9], v[42:49], v[126:129]
	v_mfma_f32_16x16x128_f8f6f4 v[118:121], v[10:17], v[42:49], v[118:121]
	s_setprio 0
	s_barrier
	s_mov_b32 m0, s25
	v_add_u32_e32 v208, 0x1c000, v189
	ds_read_b128 v[196:199], v208
	ds_read_b128 v[200:203], v208 offset:1024
	ds_read_b128 v[204:207], v208 offset:2048
	ds_read_b128 v[208:211], v208 offset:3072
	buffer_load_dwordx4 v184, s[12:15], s7 offen lds
	s_add_i32 s7, s6, 0x10080
	s_mov_b32 m0, s26
	s_nop 0
	buffer_load_dwordx4 v184, s[12:15], s7 offen lds
	s_barrier
	s_waitcnt lgkmcnt(0)
	s_setprio 1
	s_waitcnt lgkmcnt(2)
	v_mfma_f32_16x16x128_f8f6f4 v[170:173], v[196:203], v[18:25], v[170:173]
	s_waitcnt lgkmcnt(0)
	v_mfma_f32_16x16x128_f8f6f4 v[162:165], v[204:211], v[18:25], v[162:165]
	v_mfma_f32_16x16x128_f8f6f4 v[154:157], v[196:203], v[26:33], v[154:157]
	v_mfma_f32_16x16x128_f8f6f4 v[146:149], v[204:211], v[26:33], v[146:149]
	v_mfma_f32_16x16x128_f8f6f4 v[138:141], v[196:203], v[34:41], v[138:141]
	v_mfma_f32_16x16x128_f8f6f4 v[130:133], v[204:211], v[34:41], v[130:133]
	v_mfma_f32_16x16x128_f8f6f4 v[122:125], v[196:203], v[42:49], v[122:125]
	v_mfma_f32_16x16x128_f8f6f4 v[114:117], v[204:211], v[42:49], v[114:117]
	s_setprio 0
	s_mov_b32 m0, s27
	s_barrier
	ds_read_b128 v[18:21], v191 offset:49152
	ds_read_b128 v[22:25], v191 offset:50176
	ds_read_b128 v[26:29], v191 offset:51200
	ds_read_b128 v[30:33], v191 offset:52224
	ds_read_b128 v[34:37], v191 offset:53248
	ds_read_b128 v[38:41], v191 offset:54272
	ds_read_b128 v[42:45], v191 offset:55296
	ds_read_b128 v[46:49], v191 offset:56320
	buffer_load_dwordx4 v214, s[40:43], s57 offen lds
	s_mov_b32 m0, s28
	s_nop 0
	buffer_load_dwordx4 v215, s[40:43], s57 offen lds
	s_barrier
	s_waitcnt lgkmcnt(0)
	s_setprio 1
	s_waitcnt lgkmcnt(6)
	v_mfma_f32_16x16x128_f8f6f4 v[110:113], v[2:9], v[18:25], v[110:113]
	v_mfma_f32_16x16x128_f8f6f4 v[102:105], v[10:17], v[18:25], v[102:105]
	s_waitcnt lgkmcnt(4)
	v_mfma_f32_16x16x128_f8f6f4 v[94:97], v[2:9], v[26:33], v[94:97]
	v_mfma_f32_16x16x128_f8f6f4 v[86:89], v[10:17], v[26:33], v[86:89]
	s_waitcnt lgkmcnt(2)
	v_mfma_f32_16x16x128_f8f6f4 v[78:81], v[2:9], v[34:41], v[78:81]
	v_mfma_f32_16x16x128_f8f6f4 v[70:73], v[10:17], v[34:41], v[70:73]
	s_waitcnt lgkmcnt(0)
	v_mfma_f32_16x16x128_f8f6f4 v[62:65], v[2:9], v[42:49], v[62:65]
	v_mfma_f32_16x16x128_f8f6f4 v[54:57], v[10:17], v[42:49], v[54:57]
	s_setprio 0
	s_barrier
	s_mov_b32 m0, s29
	s_add_i32 s7, s6, 0x20080
	buffer_load_dwordx4 v184, s[12:15], s7 offen lds
	s_add_i32 s6, s6, 0x30080
	s_mov_b32 m0, s30
	s_nop 0
	buffer_load_dwordx4 v184, s[12:15], s6 offen lds
	s_waitcnt vmcnt(6)
	s_barrier
	s_setprio 1
	v_mfma_f32_16x16x128_f8f6f4 v[106:109], v[196:203], v[18:25], v[106:109]
	v_mfma_f32_16x16x128_f8f6f4 v[98:101], v[204:211], v[18:25], v[98:101]
	v_mfma_f32_16x16x128_f8f6f4 v[90:93], v[196:203], v[26:33], v[90:93]
	v_mfma_f32_16x16x128_f8f6f4 v[82:85], v[204:211], v[26:33], v[82:85]
	v_mfma_f32_16x16x128_f8f6f4 v[74:77], v[196:203], v[34:41], v[74:77]
	v_mfma_f32_16x16x128_f8f6f4 v[66:69], v[204:211], v[34:41], v[66:69]
	v_mfma_f32_16x16x128_f8f6f4 v[58:61], v[196:203], v[42:49], v[58:61]
	v_mfma_f32_16x16x128_f8f6f4 v[50:53], v[204:211], v[42:49], v[50:53]
	s_setprio 0
	s_add_i32 s8, s8, 2
	s_addk_i32 s9, 0x100
	s_cmp_gt_u32 s8, 5
	s_barrier
	s_cbranch_scc1 .LBB0_2423

.LBB0_2497:
	s_ashr_i32 s5, s7, 3
	s_add_u32 s8, s52, 0x3db00000
	s_addc_u32 s7, s53, 0
	s_add_i32 s5, s6, s5
	s_ashr_i32 s6, s5, 31
	s_lshr_b32 s6, s6, 27
	v_bfe_i32 v4, v2, 27, 1
	s_add_i32 s6, s5, s6
	v_lshlrev_b32_e32 v1, 4, v2
	v_lshrrev_b32_e32 v4, 22, v4
	s_ashr_i32 s12, s6, 5
	s_andn2_b32 s6, s6, 31
	v_add_u32_e32 v4, v1, v4
	s_sub_i32 s5, s5, s6
	v_and_b32_e32 v4, 0xfffffc00, v4
	s_bfe_i32 s6, s5, 0x80000
	v_sub_u32_e32 v1, v1, v4
	s_bfe_u32 s6, s6, 0x3000c
	v_ashrrev_i32_e32 v3, 31, v2
	v_lshrrev_b32_e32 v4, 4, v1
	s_add_i32 s6, s5, s6
	v_lshrrev_b32_e32 v3, 26, v3
	v_bitop3_b32 v1, v4, v1, 32 bitop3:0x6c
	s_bfe_i32 s13, s6, 0x80000
	s_and_b32 s6, s6, 0xf8
	v_add_u32_e32 v3, v2, v3
	v_ashrrev_i32_e32 v5, 31, v1
	s_sub_i32 s5, s5, s6
	v_ashrrev_i32_e32 v3, 6, v3
	v_lshrrev_b32_e32 v5, 26, v5
	s_lshl_b32 s12, s12, 3
	s_sext_i32_i8 s5, s5
	v_lshlrev_b32_e32 v4, 3, v3
	v_add_u32_e32 v5, v1, v5
	s_add_i32 s78, s12, s5
	v_and_b32_e32 v4, -16, v4
	v_ashrrev_i32_e32 v6, 6, v5
	v_and_b32_e32 v5, 0xc0, v5
	s_ashr_i32 s5, s78, 31
	s_ashr_i32 s4, s3, 6
	v_add_u32_e32 v4, v6, v4
	v_sub_u32_e32 v1, v1, v5
	v_mov_b32_e32 v5, 1
	v_and_b32_e32 v6, 3, v6
	s_mov_b32 s9, 0x3fffe0
	s_lshr_b32 s5, s5, 28
	v_lshlrev_b32_e32 v3, 5, v3
	v_ashrrev_i16_sdwa v1, v5, sext(v1) dst_sel:DWORD dst_unused:UNUSED_PAD src0_sel:DWORD src1_sel:BYTE_0
	v_lshlrev_b32_e32 v5, 1, v4
	v_lshrrev_b32_e32 v7, 2, v4
	v_and_or_b32 v6, v4, s9, v6
	s_and_b32 s9, s7, 0xffff
	s_lshl_b32 s7, s4, 10
	s_sext_i32_i16 s13, s13
	s_add_i32 s5, s78, s5
	v_and_b32_e32 v3, 32, v3
	v_bfe_i32 v1, v1, 0, 16
	v_and_b32_e32 v5, 24, v5
	v_and_b32_e32 v7, 4, v7
	s_ashr_i32 s73, s13, 3
	s_lshl_b32 s5, s5, 16
	s_add_i32 s21, s7, 0
	s_mov_b32 s47, 0x20000
	s_brev_b32 s46, -2
	v_or3_b32 v5, v6, v7, v5
	v_add_lshl_u32 v3, v3, v1, 1
	s_and_b32 s5, s5, 0xfff00000
	s_lshl_b32 s6, s73, 18
	s_add_i32 s22, s21, 0x10000
	v_lshl_add_u32 v134, v5, 10, v3
	s_mov_b32 s10, s46
	s_mov_b32 s11, s47
	s_add_i32 s79, s5, s6
	s_mov_b32 m0, s22
	s_add_i32 s23, s21, 0x12000
	buffer_load_dwordx4 v134, s[8:11], s79 offen lds
	s_or_b32 s5, s79, 0x10000
	s_mov_b32 m0, s23
	s_and_b32 s45, s71, 0xffff
	v_lshl_add_u32 v1, v4, 10, v3
	buffer_load_dwordx4 v134, s[8:11], s5 offen lds
	s_lshl_b32 s84, s78, 18
	s_mov_b32 m0, s21
	s_add_i32 s24, s21, 0x2000
	buffer_load_dwordx4 v1, s[44:47], s84 offen lds
	s_or_b32 s5, s84, 0x10000
	s_mov_b32 m0, s24
	s_add_i32 s25, s21, 0x14000
	buffer_load_dwordx4 v1, s[44:47], s5 offen lds
	s_or_b32 s5, s79, 0x20000
	s_mov_b32 m0, s25
	s_add_i32 s26, s21, 0x16000
	buffer_load_dwordx4 v134, s[8:11], s5 offen lds
	s_or_b32 s5, s79, 0x30000
	s_mov_b32 m0, s26
	s_add_i32 s27, s21, 0x4000
	buffer_load_dwordx4 v134, s[8:11], s5 offen lds
	s_or_b32 s5, s84, 0x20000
	s_mov_b32 m0, s27
	s_add_i32 s28, s21, 0x6000
	buffer_load_dwordx4 v1, s[44:47], s5 offen lds
	s_or_b32 s5, s84, 0x30000
	s_mov_b32 m0, s28
	s_mov_b32 s29, 0
	buffer_load_dwordx4 v1, s[44:47], s5 offen lds
	s_ashr_i32 s5, s3, 8
	s_cmp_lg_u32 s5, 1
	s_cbranch_scc1 .LBB0_2499
	s_barrier

.LBB0_2509:
	ds_read_b128 v[142:145], v137
	ds_read_b128 v[146:149], v137 offset:1024
	ds_read_b128 v[150:153], v137 offset:2048
	ds_read_b128 v[154:157], v137 offset:3072
	s_add_i32 s10, s7, 0xfffd0080
	s_cmp_eq_u32 s84, 4
	s_cselect_b32 s86, s6, s10
	s_cselect_b32 s85, s59, s79
	s_or_b32 s87, s86, 0x80
	s_add_i32 s10, s7, 0xffff0000
	s_mov_b32 m0, s38
	ds_read_b128 v[158:161], v138
	ds_read_b128 v[162:165], v138 offset:1024
	ds_read_b128 v[166:169], v138 offset:2048
	ds_read_b128 v[170:173], v138 offset:3072
	ds_read_b128 v[174:177], v138 offset:4096
	ds_read_b128 v[178:181], v138 offset:5120
	ds_read_b128 v[182:185], v138 offset:6144
	ds_read_b128 v[186:189], v138 offset:7168
	buffer_load_dwordx4 v1, s[44:47], s10 offen lds
	s_mov_b32 m0, s39
	s_nop 0
	buffer_load_dwordx4 v1, s[44:47], s7 offen lds
	s_waitcnt lgkmcnt(8)
	s_barrier
	s_waitcnt lgkmcnt(0)
	s_setprio 1
	s_waitcnt lgkmcnt(4)
	v_mfma_f32_16x16x128_f8f6f4 v[114:117], v[142:149], v[166:173], v[114:117]
	v_mfma_f32_16x16x128_f8f6f4 v[106:109], v[150:157], v[166:173], v[106:109]
	s_waitcnt lgkmcnt(2)
	v_mfma_f32_16x16x128_f8f6f4 v[98:101], v[142:149], v[174:181], v[98:101]
	v_mfma_f32_16x16x128_f8f6f4 v[198:201], v[142:149], v[158:165], v[126:129]
	v_mfma_f32_16x16x128_f8f6f4 v[202:205], v[150:157], v[158:165], v[122:125]
	v_mfma_f32_16x16x128_f8f6f4 v[206:209], v[150:157], v[174:181], v[90:93]
	s_waitcnt lgkmcnt(0)
	v_mfma_f32_16x16x128_f8f6f4 v[210:213], v[142:149], v[182:189], v[82:85]
	v_mfma_f32_16x16x128_f8f6f4 v[214:217], v[150:157], v[182:189], v[74:77]
	s_setprio 0
	s_barrier
	s_mov_b32 m0, s22
	s_mov_b32 s10, s46
	s_mov_b32 s11, s47
	ds_read_b128 v[122:125], v139
	ds_read_b128 v[126:129], v139 offset:1024
	ds_read_b128 v[190:193], v139 offset:2048
	ds_read_b128 v[194:197], v139 offset:3072
	buffer_load_dwordx4 v134, s[8:11], s85 offen lds
	s_add_i32 s33, s85, 0x10000
	s_mov_b32 m0, s23
	s_nop 0
	buffer_load_dwordx4 v134, s[8:11], s33 offen lds
	s_barrier
	s_waitcnt lgkmcnt(0)
	s_setprio 1
	s_waitcnt lgkmcnt(2)
	v_mfma_f32_16x16x128_f8f6f4 v[118:121], v[122:129], v[158:165], v[118:121]
	s_waitcnt lgkmcnt(0)
	v_mfma_f32_16x16x128_f8f6f4 v[110:113], v[190:197], v[158:165], v[110:113]
	v_mfma_f32_16x16x128_f8f6f4 v[102:105], v[122:129], v[166:173], v[102:105]
	v_mfma_f32_16x16x128_f8f6f4 v[158:161], v[190:197], v[166:173], v[94:97]
	v_mfma_f32_16x16x128_f8f6f4 v[162:165], v[122:129], v[174:181], v[86:89]
	v_mfma_f32_16x16x128_f8f6f4 v[166:169], v[190:197], v[174:181], v[78:81]
	v_mfma_f32_16x16x128_f8f6f4 v[170:173], v[122:129], v[182:189], v[70:73]
	v_mfma_f32_16x16x128_f8f6f4 v[174:177], v[190:197], v[182:189], v[18:21]
	s_setprio 0
	s_mov_b32 m0, s21
	s_barrier
	ds_read_b128 v[66:69], v138 offset:16384
	s_nop 1
	ds_read_b128 v[70:73], v138 offset:17408
	ds_read_b128 v[74:77], v138 offset:18432
	ds_read_b128 v[78:81], v138 offset:19456
	ds_read_b128 v[82:85], v138 offset:20480
	ds_read_b128 v[86:89], v138 offset:21504
	ds_read_b128 v[90:93], v138 offset:22528
	ds_read_b128 v[94:97], v138 offset:23552
	buffer_load_dwordx4 v1, s[44:47], s86 offen lds
	s_add_i32 s33, s86, 0x10000
	s_mov_b32 m0, s24
	s_nop 0
	buffer_load_dwordx4 v1, s[44:47], s33 offen lds
	s_barrier
	s_waitcnt lgkmcnt(0)
	s_setprio 1
	s_waitcnt lgkmcnt(6)
	v_mfma_f32_16x16x128_f8f6f4 v[62:65], v[142:149], v[66:73], v[62:65]
	v_mfma_f32_16x16x128_f8f6f4 v[58:61], v[150:157], v[66:73], v[58:61]
	s_waitcnt lgkmcnt(4)
	v_mfma_f32_16x16x128_f8f6f4 v[50:53], v[142:149], v[74:81], v[50:53]
	s_waitcnt lgkmcnt(0)
	v_mfma_f32_16x16x128_f8f6f4 v[230:233], v[142:149], v[90:97], v[230:233]
	v_mfma_f32_16x16x128_f8f6f4 v[218:221], v[150:157], v[74:81], v[42:45]
	v_mfma_f32_16x16x128_f8f6f4 v[222:225], v[142:149], v[82:89], v[34:37]
	v_mfma_f32_16x16x128_f8f6f4 v[226:229], v[150:157], v[82:89], v[26:29]
	v_mfma_f32_16x16x128_f8f6f4 v[234:237], v[150:157], v[90:97], v[10:13]
	s_setprio 0
	s_barrier
	s_mov_b32 m0, s25
	s_add_i32 s33, s85, 0x20000
	buffer_load_dwordx4 v134, s[8:11], s33 offen lds
	s_add_i32 s33, s85, 0x30000
	s_mov_b32 m0, s26
	s_nop 0
	buffer_load_dwordx4 v134, s[8:11], s33 offen lds
	s_waitcnt vmcnt(6)
	s_barrier
	s_setprio 1
	v_mfma_f32_16x16x128_f8f6f4 v[54:57], v[122:129], v[66:73], v[54:57]
	v_mfma_f32_16x16x128_f8f6f4 v[238:241], v[190:197], v[66:73], v[46:49]
	v_mfma_f32_16x16x128_f8f6f4 v[242:245], v[122:129], v[74:81], v[38:41]
	v_mfma_f32_16x16x128_f8f6f4 v[246:249], v[190:197], v[74:81], v[30:33]
	v_mfma_f32_16x16x128_f8f6f4 v[250:253], v[122:129], v[82:89], v[22:25]
	v_mfma_f32_16x16x128_f8f6f4 v[130:133], v[190:197], v[82:89], v[14:17]
	v_mfma_f32_16x16x128_f8f6f4 v[66:69], v[122:129], v[90:97], v[6:9]
	v_mfma_f32_16x16x128_f8f6f4 v[190:193], v[190:197], v[90:97], v[2:5]
	s_setprio 0
	s_barrier
	s_nop 4
	ds_read_b128 v[2:5], v140
	ds_read_b128 v[6:9], v140 offset:1024
	ds_read_b128 v[10:13], v140 offset:2048
	ds_read_b128 v[14:17], v140 offset:3072
	s_mov_b32 m0, s27
	s_add_i32 s33, s86, 0x20000
	ds_read_b128 v[18:21], v138 offset:32768
	ds_read_b128 v[22:25], v138 offset:33792
	ds_read_b128 v[26:29], v138 offset:34816
	ds_read_b128 v[30:33], v138 offset:35840
	ds_read_b128 v[34:37], v138 offset:36864
	ds_read_b128 v[38:41], v138 offset:37888
	ds_read_b128 v[42:45], v138 offset:38912
	ds_read_b128 v[46:49], v138 offset:39936
	buffer_load_dwordx4 v1, s[44:47], s33 offen lds
	s_add_i32 s33, s86, 0x30000
	s_mov_b32 m0, s28
	s_nop 0
	buffer_load_dwordx4 v1, s[44:47], s33 offen lds
	s_waitcnt lgkmcnt(8)
	s_barrier
	s_waitcnt lgkmcnt(0)
	s_setprio 1
	s_waitcnt lgkmcnt(6)
	v_mfma_f32_16x16x128_f8f6f4 v[126:129], v[2:9], v[18:25], v[198:201]
	v_mfma_f32_16x16x128_f8f6f4 v[122:125], v[10:17], v[18:25], v[202:205]
	s_waitcnt lgkmcnt(4)
	v_mfma_f32_16x16x128_f8f6f4 v[114:117], v[2:9], v[26:33], v[114:117]
	v_mfma_f32_16x16x128_f8f6f4 v[106:109], v[10:17], v[26:33], v[106:109]
	s_waitcnt lgkmcnt(2)
	v_mfma_f32_16x16x128_f8f6f4 v[98:101], v[2:9], v[34:41], v[98:101]
	v_mfma_f32_16x16x128_f8f6f4 v[90:93], v[10:17], v[34:41], v[206:209]
	s_waitcnt lgkmcnt(0)
	v_mfma_f32_16x16x128_f8f6f4 v[82:85], v[2:9], v[42:49], v[210:213]
	v_mfma_f32_16x16x128_f8f6f4 v[74:77], v[10:17], v[42:49], v[214:217]
	s_setprio 0
	s_barrier
	s_mov_b32 m0, s30
	s_add_i32 s33, s85, 0x80
	ds_read_b128 v[142:145], v141
	ds_read_b128 v[146:149], v141 offset:1024
	ds_read_b128 v[150:153], v141 offset:2048
	ds_read_b128 v[154:157], v141 offset:3072
	buffer_load_dwordx4 v134, s[8:11], s33 offen lds
	s_add_i32 s33, s85, 0x10080
	s_mov_b32 m0, s31
	s_nop 0
	buffer_load_dwordx4 v134, s[8:11], s33 offen lds
	s_barrier
	s_waitcnt lgkmcnt(0)
	s_setprio 1
	s_waitcnt lgkmcnt(2)
	v_mfma_f32_16x16x128_f8f6f4 v[118:121], v[142:149], v[18:25], v[118:121]
	s_waitcnt lgkmcnt(0)
	v_mfma_f32_16x16x128_f8f6f4 v[110:113], v[150:157], v[18:25], v[110:113]
	v_mfma_f32_16x16x128_f8f6f4 v[102:105], v[142:149], v[26:33], v[102:105]
	v_mfma_f32_16x16x128_f8f6f4 v[94:97], v[150:157], v[26:33], v[158:161]
	v_mfma_f32_16x16x128_f8f6f4 v[86:89], v[142:149], v[34:41], v[162:165]
	v_mfma_f32_16x16x128_f8f6f4 v[78:81], v[150:157], v[34:41], v[166:169]
	v_mfma_f32_16x16x128_f8f6f4 v[70:73], v[142:149], v[42:49], v[170:173]
	v_mfma_f32_16x16x128_f8f6f4 v[18:21], v[150:157], v[42:49], v[174:177]
	s_setprio 0
	s_mov_b32 m0, s34
	s_barrier
	ds_read_b128 v[158:161], v138 offset:49152
	ds_read_b128 v[162:165], v138 offset:50176
	ds_read_b128 v[166:169], v138 offset:51200
	ds_read_b128 v[170:173], v138 offset:52224
	ds_read_b128 v[174:177], v138 offset:53248
	ds_read_b128 v[178:181], v138 offset:54272
	ds_read_b128 v[182:185], v138 offset:55296
	ds_read_b128 v[186:189], v138 offset:56320
	buffer_load_dwordx4 v1, s[44:47], s87 offen lds
	s_add_i32 s86, s86, 0x10080
	s_mov_b32 m0, s35
	s_nop 0
	buffer_load_dwordx4 v1, s[44:47], s86 offen lds
	s_barrier
	s_waitcnt lgkmcnt(0)
	s_setprio 1
	s_waitcnt lgkmcnt(6)
	v_mfma_f32_16x16x128_f8f6f4 v[62:65], v[2:9], v[158:165], v[62:65]
	v_mfma_f32_16x16x128_f8f6f4 v[58:61], v[10:17], v[158:165], v[58:61]
	s_waitcnt lgkmcnt(4)
	v_mfma_f32_16x16x128_f8f6f4 v[50:53], v[2:9], v[166:173], v[50:53]
	v_mfma_f32_16x16x128_f8f6f4 v[42:45], v[10:17], v[166:173], v[218:221]
	s_waitcnt lgkmcnt(2)
	v_mfma_f32_16x16x128_f8f6f4 v[34:37], v[2:9], v[174:181], v[222:225]
	v_mfma_f32_16x16x128_f8f6f4 v[26:29], v[10:17], v[174:181], v[226:229]
	s_waitcnt lgkmcnt(0)
	v_mfma_f32_16x16x128_f8f6f4 v[230:233], v[2:9], v[182:189], v[230:233]
	v_mfma_f32_16x16x128_f8f6f4 v[10:13], v[10:17], v[182:189], v[234:237]
	s_setprio 0
	s_barrier
	s_mov_b32 m0, s36
	s_add_i32 s33, s85, 0x20080
	buffer_load_dwordx4 v134, s[8:11], s33 offen lds
	s_add_i32 s85, s85, 0x30080
	s_mov_b32 m0, s37
	s_nop 0
	buffer_load_dwordx4 v134, s[8:11], s85 offen lds
	s_waitcnt vmcnt(6)
	s_barrier
	s_setprio 1
	v_mfma_f32_16x16x128_f8f6f4 v[54:57], v[142:149], v[158:165], v[54:57]
	v_mfma_f32_16x16x128_f8f6f4 v[46:49], v[150:157], v[158:165], v[238:241]
	v_mfma_f32_16x16x128_f8f6f4 v[38:41], v[142:149], v[166:173], v[242:245]
	v_mfma_f32_16x16x128_f8f6f4 v[30:33], v[150:157], v[166:173], v[246:249]
	v_mfma_f32_16x16x128_f8f6f4 v[22:25], v[142:149], v[174:181], v[250:253]
	v_mfma_f32_16x16x128_f8f6f4 v[14:17], v[150:157], v[174:181], v[130:133]
	v_mfma_f32_16x16x128_f8f6f4 v[6:9], v[142:149], v[182:189], v[66:69]
	v_mfma_f32_16x16x128_f8f6f4 v[2:5], v[150:157], v[182:189], v[190:193]
	s_setprio 0
	s_add_i32 s84, s84, 2
	s_addk_i32 s7, 0x100
	s_addk_i32 s79, 0x100
	s_cmp_gt_u32 s84, 5
	s_barrier
	s_cbranch_scc0 .LBB0_2509
	v_pk_mul_f32 v[126:127], v[126:127], 0.5 op_sel_hi:[1,0]
	v_mov_b32_e32 v132, 0
	v_cvt_pk_fp8_f32 v132, v126, v127
	v_pk_mul_f32 v[122:123], v[122:123], 0.5 op_sel_hi:[1,0]
	v_mov_b32_e32 v133, 0
	v_cvt_pk_fp8_f32 v133, v122, v123
	v_pk_mul_f32 v[122:123], v[128:129], 0.5 op_sel_hi:[1,0]
	v_pk_mul_f32 v[118:119], v[118:119], 0.5 op_sel_hi:[1,0]
	v_cvt_pk_fp8_f32 v132, v122, v123 op_sel:[0,0,1]
	v_mov_b32_e32 v122, 0
	v_cvt_pk_fp8_f32 v122, v118, v119
	v_pk_mul_f32 v[114:115], v[114:115], 0.5 op_sel_hi:[1,0]
	v_mov_b32_e32 v118, 0
	v_cvt_pk_fp8_f32 v118, v114, v115
	v_pk_mul_f32 v[106:107], v[106:107], 0.5 op_sel_hi:[1,0]
	v_mov_b32_e32 v119, 0
	v_cvt_pk_fp8_f32 v119, v106, v107
	v_pk_mul_f32 v[106:107], v[116:117], 0.5 op_sel_hi:[1,0]
	v_pk_mul_f32 v[94:95], v[94:95], 0.5 op_sel_hi:[1,0]
	v_cvt_pk_fp8_f32 v118, v106, v107 op_sel:[0,0,1]
	v_mov_b32_e32 v107, 0
	v_cvt_pk_fp8_f32 v107, v94, v95
	v_pk_mul_f32 v[110:111], v[110:111], 0.5 op_sel_hi:[1,0]
	v_mov_b32_e32 v123, 0
	v_cvt_pk_fp8_f32 v123, v110, v111
	v_pk_mul_f32 v[96:97], v[96:97], 0.5 op_sel_hi:[1,0]
	v_pk_mul_f32 v[102:103], v[102:103], 0.5 op_sel_hi:[1,0]
	v_mov_b32_e32 v106, 0
	v_cvt_pk_fp8_f32 v107, v96, v97 op_sel:[0,0,1]
	v_pk_mul_f32 v[96:97], v[98:99], 0.5 op_sel_hi:[1,0]
	v_mov_b32_e32 v98, 0
	v_cvt_pk_fp8_f32 v106, v102, v103
	v_cvt_pk_fp8_f32 v98, v96, v97
	v_lshl_add_u32 v66, s78, 8, v135
	v_pk_mul_f32 v[112:113], v[112:113], 0.5 op_sel_hi:[1,0]
	v_pk_mul_f32 v[124:125], v[124:125], 0.5 op_sel_hi:[1,0]
	v_cvt_pk_fp8_f32 v123, v112, v113 op_sel:[0,0,1]
	v_or_b32_e32 v112, 16, v66
	v_pk_mul_f32 v[108:109], v[108:109], 0.5 op_sel_hi:[1,0]
	v_pk_mul_f32 v[90:91], v[90:91], 0.5 op_sel_hi:[1,0]
	v_mov_b32_e32 v99, 0
	v_ashrrev_i32_e32 v67, 31, v66
	v_cvt_pk_fp8_f32 v133, v124, v125 op_sel:[0,0,1]
	v_pk_mul_f32 v[110:111], v[120:121], 0.5 op_sel_hi:[1,0]
	v_ashrrev_i32_e32 v113, 31, v112
	v_cvt_pk_fp8_f32 v119, v108, v109 op_sel:[0,0,1]
	v_pk_mul_f32 v[94:95], v[104:105], 0.5 op_sel_hi:[1,0]
	v_cvt_pk_fp8_f32 v99, v90, v91
	v_pk_mul_f32 v[90:91], v[100:101], 0.5 op_sel_hi:[1,0]
	v_lshl_or_b32 v68, s73, 8, v136
	v_lshlrev_b64 v[130:131], 10, v[66:67]
	v_cvt_pk_fp8_f32 v122, v110, v111 op_sel:[0,0,1]
	v_lshlrev_b64 v[112:113], 10, v[112:113]
	v_cvt_pk_fp8_f32 v106, v94, v95 op_sel:[0,0,1]
	v_cvt_pk_fp8_f32 v98, v90, v91 op_sel:[0,0,1]
	v_pk_mul_f32 v[86:87], v[86:87], 0.5 op_sel_hi:[1,0]
	v_pk_mul_f32 v[78:79], v[78:79], 0.5 op_sel_hi:[1,0]
	v_mov_b32_e32 v90, 0
	v_mov_b32_e32 v91, 0
	v_ashrrev_i32_e32 v69, 31, v68
	v_lshl_add_u64 v[110:111], s[68:69], 0, v[130:131]
	v_lshl_add_u64 v[94:95], s[68:69], 0, v[112:113]
	v_cvt_pk_fp8_f32 v90, v86, v87
	v_cvt_pk_fp8_f32 v91, v78, v79
	v_lshl_add_u64 v[110:111], v[110:111], 0, v[68:69]
	v_lshl_add_u64 v[94:95], v[94:95], 0, v[68:69]
	global_store_dwordx2 v[110:111], v[132:133], off
	global_store_dwordx2 v[110:111], v[122:123], off offset:128
	global_store_dwordx2 v[94:95], v[118:119], off
	global_store_dwordx2 v[94:95], v[106:107], off offset:128
	v_or_b32_e32 v94, 32, v66
	v_pk_mul_f32 v[92:93], v[92:93], 0.5 op_sel_hi:[1,0]
	v_ashrrev_i32_e32 v95, 31, v94
	v_cvt_pk_fp8_f32 v99, v92, v93 op_sel:[0,0,1]
	v_pk_mul_f32 v[78:79], v[88:89], 0.5 op_sel_hi:[1,0]
	v_pk_mul_f32 v[80:81], v[80:81], 0.5 op_sel_hi:[1,0]
	v_lshlrev_b64 v[94:95], 10, v[94:95]
	v_cvt_pk_fp8_f32 v90, v78, v79 op_sel:[0,0,1]
	v_cvt_pk_fp8_f32 v91, v80, v81 op_sel:[0,0,1]
	v_lshl_add_u64 v[78:79], s[68:69], 0, v[94:95]
	v_lshl_add_u64 v[78:79], v[78:79], 0, v[68:69]
	global_store_dwordx2 v[78:79], v[98:99], off
	global_store_dwordx2 v[78:79], v[90:91], off offset:128
	v_pk_mul_f32 v[78:79], v[82:83], 0.5 op_sel_hi:[1,0]
	v_mov_b32_e32 v80, 0
	v_cvt_pk_fp8_f32 v80, v78, v79
	v_pk_mul_f32 v[74:75], v[74:75], 0.5 op_sel_hi:[1,0]
	v_mov_b32_e32 v81, 0
	v_cvt_pk_fp8_f32 v81, v74, v75
	v_pk_mul_f32 v[74:75], v[84:85], 0.5 op_sel_hi:[1,0]
	v_pk_mul_f32 v[18:19], v[18:19], 0.5 op_sel_hi:[1,0]
	v_cvt_pk_fp8_f32 v80, v74, v75 op_sel:[0,0,1]
	v_mov_b32_e32 v75, 0
	v_cvt_pk_fp8_f32 v75, v18, v19
	v_pk_mul_f32 v[20:21], v[20:21], 0.5 op_sel_hi:[1,0]
	v_pk_mul_f32 v[58:59], v[58:59], 0.5 op_sel_hi:[1,0]
	v_pk_mul_f32 v[70:71], v[70:71], 0.5 op_sel_hi:[1,0]
	v_cvt_pk_fp8_f32 v75, v20, v21 op_sel:[0,0,1]
	v_pk_mul_f32 v[20:21], v[62:63], 0.5 op_sel_hi:[1,0]
	v_mov_b32_e32 v62, 0
	v_cvt_pk_fp8_f32 v62, v20, v21
	v_mov_b32_e32 v63, 0
	v_pk_mul_f32 v[20:21], v[64:65], 0.5 op_sel_hi:[1,0]
	v_mov_b32_e32 v74, 0
	v_cvt_pk_fp8_f32 v63, v58, v59
	v_cvt_pk_fp8_f32 v62, v20, v21 op_sel:[0,0,1]
	v_pk_mul_f32 v[20:21], v[54:55], 0.5 op_sel_hi:[1,0]
	v_pk_mul_f32 v[46:47], v[46:47], 0.5 op_sel_hi:[1,0]
	v_mov_b32_e32 v54, 0
	v_mov_b32_e32 v55, 0
	v_cvt_pk_fp8_f32 v74, v70, v71
	v_cvt_pk_fp8_f32 v54, v20, v21
	v_cvt_pk_fp8_f32 v55, v46, v47
	v_or_b32_e32 v66, 48, v66
	v_pk_mul_f32 v[76:77], v[76:77], 0.5 op_sel_hi:[1,0]
	v_pk_mul_f32 v[58:59], v[60:61], 0.5 op_sel_hi:[1,0]
	v_ashrrev_i32_e32 v67, 31, v66
	v_cvt_pk_fp8_f32 v81, v76, v77 op_sel:[0,0,1]
	v_pk_mul_f32 v[18:19], v[72:73], 0.5 op_sel_hi:[1,0]
	v_cvt_pk_fp8_f32 v63, v58, v59 op_sel:[0,0,1]
	v_pk_mul_f32 v[20:21], v[56:57], 0.5 op_sel_hi:[1,0]
	v_pk_mul_f32 v[46:47], v[48:49], 0.5 op_sel_hi:[1,0]
	v_lshlrev_b64 v[66:67], 10, v[66:67]
	v_cvt_pk_fp8_f32 v74, v18, v19 op_sel:[0,0,1]
	v_cvt_pk_fp8_f32 v54, v20, v21 op_sel:[0,0,1]
	v_cvt_pk_fp8_f32 v55, v46, v47 op_sel:[0,0,1]
	v_lshl_add_u64 v[18:19], s[68:69], 0, v[66:67]
	v_add_co_u32_e32 v20, vcc, s47, v110
	v_lshl_add_u64 v[18:19], v[18:19], 0, v[68:69]
	s_nop 0
	v_addc_co_u32_e32 v21, vcc, 0, v111, vcc
	global_store_dwordx2 v[18:19], v[80:81], off
	global_store_dwordx2 v[18:19], v[74:75], off offset:128
	v_lshl_add_u64 v[18:19], v[110:111], 0, s[12:13]
	global_store_dwordx2 v[20:21], v[62:63], off
	global_store_dwordx2 v[18:19], v[54:55], off offset:128
	v_pk_mul_f32 v[20:21], v[50:51], 0.5 op_sel_hi:[1,0]
	v_mov_b32_e32 v46, 0
	v_cvt_pk_fp8_f32 v46, v20, v21
	v_pk_mul_f32 v[42:43], v[42:43], 0.5 op_sel_hi:[1,0]
	v_mov_b32_e32 v47, 0
	v_pk_mul_f32 v[20:21], v[52:53], 0.5 op_sel_hi:[1,0]
	v_cvt_pk_fp8_f32 v47, v42, v43
	v_cvt_pk_fp8_f32 v46, v20, v21 op_sel:[0,0,1]
	v_pk_mul_f32 v[20:21], v[38:39], 0.5 op_sel_hi:[1,0]
	v_pk_mul_f32 v[30:31], v[30:31], 0.5 op_sel_hi:[1,0]
	v_mov_b32_e32 v38, 0
	v_mov_b32_e32 v39, 0
	v_cvt_pk_fp8_f32 v38, v20, v21
	v_cvt_pk_fp8_f32 v39, v30, v31
	v_pk_mul_f32 v[42:43], v[44:45], 0.5 op_sel_hi:[1,0]
	v_pk_mul_f32 v[20:21], v[40:41], 0.5 op_sel_hi:[1,0]
	v_cvt_pk_fp8_f32 v47, v42, v43 op_sel:[0,0,1]
	v_pk_mul_f32 v[30:31], v[32:33], 0.5 op_sel_hi:[1,0]
	v_cvt_pk_fp8_f32 v38, v20, v21 op_sel:[0,0,1]
	v_cvt_pk_fp8_f32 v39, v30, v31 op_sel:[0,0,1]
	v_add_co_u32_e32 v20, vcc, s42, v110
	v_lshl_add_u64 v[18:19], v[110:111], 0, s[14:15]
	s_nop 0
	v_addc_co_u32_e32 v21, vcc, 0, v111, vcc
	global_store_dwordx2 v[20:21], v[46:47], off
	global_store_dwordx2 v[18:19], v[38:39], off offset:128
	v_pk_mul_f32 v[20:21], v[34:35], 0.5 op_sel_hi:[1,0]
	v_mov_b32_e32 v30, 0
	v_cvt_pk_fp8_f32 v30, v20, v21
	v_pk_mul_f32 v[26:27], v[26:27], 0.5 op_sel_hi:[1,0]
	v_mov_b32_e32 v31, 0
	v_pk_mul_f32 v[20:21], v[36:37], 0.5 op_sel_hi:[1,0]
	v_cvt_pk_fp8_f32 v31, v26, v27
	v_cvt_pk_fp8_f32 v30, v20, v21 op_sel:[0,0,1]
	v_pk_mul_f32 v[20:21], v[22:23], 0.5 op_sel_hi:[1,0]
	v_pk_mul_f32 v[14:15], v[14:15], 0.5 op_sel_hi:[1,0]
	v_mov_b32_e32 v22, 0
	v_mov_b32_e32 v23, 0
	v_cvt_pk_fp8_f32 v22, v20, v21
	v_cvt_pk_fp8_f32 v23, v14, v15
	v_pk_mul_f32 v[26:27], v[28:29], 0.5 op_sel_hi:[1,0]
	v_pk_mul_f32 v[14:15], v[24:25], 0.5 op_sel_hi:[1,0]
	v_cvt_pk_fp8_f32 v31, v26, v27 op_sel:[0,0,1]
	v_pk_mul_f32 v[16:17], v[16:17], 0.5 op_sel_hi:[1,0]
	v_cvt_pk_fp8_f32 v22, v14, v15 op_sel:[0,0,1]
	v_cvt_pk_fp8_f32 v23, v16, v17 op_sel:[0,0,1]
	v_add_co_u32_e32 v14, vcc, s43, v110
	v_lshl_add_u64 v[18:19], v[110:111], 0, s[16:17]
	s_nop 0
	v_addc_co_u32_e32 v15, vcc, 0, v111, vcc
	global_store_dwordx2 v[14:15], v[30:31], off
	global_store_dwordx2 v[18:19], v[22:23], off offset:128
	v_pk_mul_f32 v[16:17], v[230:231], 0.5 op_sel_hi:[1,0]
	v_mov_b32_e32 v18, 0
	v_cvt_pk_fp8_f32 v18, v16, v17
	v_pk_mul_f32 v[10:11], v[10:11], 0.5 op_sel_hi:[1,0]
	v_mov_b32_e32 v19, 0
	v_cvt_pk_fp8_f32 v19, v10, v11
	v_pk_mul_f32 v[10:11], v[232:233], 0.5 op_sel_hi:[1,0]
	v_pk_mul_f32 v[6:7], v[6:7], 0.5 op_sel_hi:[1,0]
	v_cvt_pk_fp8_f32 v18, v10, v11 op_sel:[0,0,1]
	v_pk_mul_f32 v[2:3], v[2:3], 0.5 op_sel_hi:[1,0]
	v_mov_b32_e32 v10, 0
	v_mov_b32_e32 v11, 0
	v_cvt_pk_fp8_f32 v10, v6, v7
	v_cvt_pk_fp8_f32 v11, v2, v3
	v_pk_mul_f32 v[12:13], v[12:13], 0.5 op_sel_hi:[1,0]
	v_pk_mul_f32 v[2:3], v[8:9], 0.5 op_sel_hi:[1,0]
	v_cvt_pk_fp8_f32 v19, v12, v13 op_sel:[0,0,1]
	v_pk_mul_f32 v[4:5], v[4:5], 0.5 op_sel_hi:[1,0]
	v_cvt_pk_fp8_f32 v10, v2, v3 op_sel:[0,0,1]
	v_cvt_pk_fp8_f32 v11, v4, v5 op_sel:[0,0,1]
	v_add_co_u32_e32 v2, vcc, s49, v110
	s_mov_b32 s73, s57
	s_nop 0
	v_addc_co_u32_e32 v3, vcc, 0, v111, vcc
	s_and_b64 vcc, exec, s[4:5]
	s_mov_b32 s78, s58
	s_mov_b32 s79, s59
	s_mov_b32 s84, s72
	v_lshl_add_u64 v[14:15], v[110:111], 0, s[18:19]
	global_store_dwordx2 v[2:3], v[18:19], off
	global_store_dwordx2 v[14:15], v[10:11], off offset:128
	s_cbranch_vccz .LBB0_2500
	s_waitcnt vmcnt(0)
	s_cmpk_gt_u32 s3, 0xff
	s_cbranch_scc1 .LBB0_2513
	s_barrier

.LBB0_2670:
	s_cmp_lt_i32 s61, 39
	s_cbranch_scc1 .LBB0_3322
	s_cmp_gt_i32 s60, 38
	s_cbranch_scc1 .LBB0_2740
	s_waitcnt vmcnt(0)
	v_mov_b32_e32 v2, v0
	s_cmpk_gt_i32 s2, 0x5ff
	v_readfirstlane_b32 s3, v2
	s_cbranch_scc1 .LBB0_2690
	v_bfe_i32 v4, v2, 27, 1
	v_lshlrev_b32_e32 v1, 4, v2
	v_lshrrev_b32_e32 v4, 22, v4
	v_add_u32_e32 v4, v1, v4
	v_and_b32_e32 v4, 0xfffffc00, v4
	v_sub_u32_e32 v1, v1, v4
	v_ashrrev_i32_e32 v3, 31, v2
	v_lshrrev_b32_e32 v4, 4, v1
	v_lshrrev_b32_e32 v3, 26, v3
	v_bitop3_b32 v1, v4, v1, 32 bitop3:0x6c
	s_add_u32 s8, s52, 0x1100000
	v_add_u32_e32 v3, v2, v3
	v_ashrrev_i32_e32 v5, 31, v1
	s_addc_u32 s6, s53, 0
	v_ashrrev_i32_e32 v3, 6, v3
	v_lshrrev_b32_e32 v5, 26, v5
	s_ashr_i32 s20, s2, 31
	v_lshlrev_b32_e32 v4, 3, v3
	v_add_u32_e32 v5, v1, v5
	s_lshr_b32 s7, s20, 29
	v_readlane_b32 s10, v255, 8
	v_and_b32_e32 v4, -16, v4
	v_ashrrev_i32_e32 v6, 6, v5
	s_add_i32 s7, s2, s7
	s_ashr_i32 s4, s3, 6
	v_readlane_b32 s11, v255, 9
	v_add_u32_e32 v4, v6, v4
	v_and_b32_e32 v6, 3, v6
	s_mov_b32 s5, 0x1fffe0
	s_ashr_i32 s12, s7, 3
	s_and_b32 s7, s7, -8
	s_and_b32 s41, s11, 0xffff
	v_and_or_b32 v6, v4, s5, v6
	s_ashr_i32 s5, s3, 8
	s_and_b32 s9, s6, 0xffff
	s_lshl_b32 s6, s4, 10
	s_sub_i32 s7, s2, s7
	s_cmp_lt_i32 s7, 0
	s_movk_i32 s21, 0xc1
	s_cselect_b32 s13, s21, 0xc0
	s_mul_i32 s7, s13, s7
	s_add_i32 s7, s7, s12
	s_mul_hi_i32 s12, s7, 0x2aaaaaab
	s_lshr_b32 s13, s12, 31
	s_ashr_i32 s12, s12, 4
	s_add_i32 s12, s12, s13
	s_lshl_b32 s13, s12, 3
	s_mulk_i32 s12, 0x60
	s_sub_i32 s7, s7, s12
	s_bfe_i32 s12, s7, 0x80000
	s_bfe_u32 s12, s12, 0x3000c
	s_add_i32 s12, s7, s12
	s_bfe_i32 s14, s12, 0x80000
	s_and_b32 s12, s12, 0xf8
	s_sub_i32 s7, s7, s12
	s_sext_i32_i8 s7, s7
	s_add_i32 s78, s13, s7
	s_ashr_i32 s7, s78, 31
	v_and_b32_e32 v5, 0xc0, v5
	s_lshr_b32 s7, s7, 12
	v_sub_u32_e32 v1, v1, v5
	v_mov_b32_e32 v5, 1
	s_add_i32 s7, s78, s7
	v_lshlrev_b32_e32 v3, 5, v3
	v_ashrrev_i16_sdwa v1, v5, sext(v1) dst_sel:DWORD dst_unused:UNUSED_PAD src0_sel:DWORD src1_sel:BYTE_0
	v_lshlrev_b32_e32 v5, 1, v4
	v_lshrrev_b32_e32 v7, 2, v4
	s_sext_i32_i16 s14, s14
	s_ashr_i32 s7, s7, 20
	v_and_b32_e32 v3, 32, v3
	v_bfe_i32 v1, v1, 0, 16
	v_and_b32_e32 v5, 24, v5
	v_and_b32_e32 v7, 4, v7
	s_ashr_i32 s73, s14, 3
	s_mul_i32 s7, s7, 12
	s_add_i32 s22, s6, 0
	s_mov_b32 s43, 0x20000
	s_brev_b32 s42, -2
	v_or3_b32 v5, v6, v7, v5
	v_add_lshl_u32 v3, v3, v1, 1
	s_add_i32 s7, s7, s73
	s_add_i32 s23, s22, 0x10000
	v_lshl_add_u32 v144, v5, 11, v3
	s_mov_b32 s10, s42
	s_mov_b32 s11, s43
	s_lshl_b32 s79, s7, 19
	s_mov_b32 m0, s23
	s_add_i32 s24, s22, 0x12000
	buffer_load_dwordx4 v144, s[8:11], s79 offen lds
	s_or_b32 s6, s79, 0x20000
	s_mov_b32 m0, s24
	v_lshl_add_u32 v1, v4, 11, v3
	buffer_load_dwordx4 v144, s[8:11], s6 offen lds
	s_lshl_b32 s84, s78, 19
	s_mov_b32 m0, s22
	s_add_i32 s25, s22, 0x2000
	buffer_load_dwordx4 v1, s[40:43], s84 offen lds
	s_or_b32 s6, s84, 0x20000
	s_mov_b32 m0, s25
	s_add_i32 s26, s22, 0x14000
	buffer_load_dwordx4 v1, s[40:43], s6 offen lds
	s_or_b32 s6, s79, 0x40000
	s_mov_b32 m0, s26
	s_add_i32 s27, s22, 0x16000
	buffer_load_dwordx4 v144, s[8:11], s6 offen lds
	s_or_b32 s6, s79, 0x60000
	s_mov_b32 m0, s27
	s_add_i32 s28, s22, 0x4000
	buffer_load_dwordx4 v144, s[8:11], s6 offen lds
	s_or_b32 s6, s84, 0x40000
	s_mov_b32 m0, s28
	s_add_i32 s29, s22, 0x6000
	buffer_load_dwordx4 v1, s[40:43], s6 offen lds
	s_or_b32 s6, s84, 0x60000
	s_mov_b32 m0, s29
	s_cmp_lg_u32 s5, 1
	buffer_load_dwordx4 v1, s[40:43], s6 offen lds
	s_mov_b32 s30, 0
	s_cbranch_scc1 .LBB0_2675
	s_barrier

.LBB0_2682:
	ds_read_b128 v[136:139], v147
	ds_read_b128 v[140:143], v147 offset:1024
	ds_read_b128 v[152:155], v147 offset:2048
	ds_read_b128 v[156:159], v147 offset:3072
	s_add_i32 s10, s7, 0xfffa0080
	s_cmp_eq_u32 s84, 12
	s_cselect_b32 s86, s6, s10
	s_cselect_b32 s85, s59, s79
	s_or_b32 s87, s86, 0x80
	s_add_i32 s10, s7, 0xfffe0000
	s_mov_b32 m0, s39
	ds_read_b128 v[160:163], v148
	ds_read_b128 v[164:167], v148 offset:1024
	ds_read_b128 v[168:171], v148 offset:2048
	ds_read_b128 v[172:175], v148 offset:3072
	ds_read_b128 v[176:179], v148 offset:4096
	ds_read_b128 v[180:183], v148 offset:5120
	ds_read_b128 v[184:187], v148 offset:6144
	ds_read_b128 v[188:191], v148 offset:7168
	buffer_load_dwordx4 v1, s[40:43], s10 offen lds
	s_mov_b32 m0, s45
	s_nop 0
	buffer_load_dwordx4 v1, s[40:43], s7 offen lds
	s_waitcnt lgkmcnt(8)
	s_barrier
	s_waitcnt lgkmcnt(0)
	s_setprio 1
	s_waitcnt lgkmcnt(7)
	v_mfma_f32_16x16x32_bf16 v[126:129], v[136:139], v[160:163], v[126:129]
	v_mfma_f32_16x16x32_bf16 v[122:125], v[152:155], v[160:163], v[122:125]
	s_waitcnt lgkmcnt(5)
	v_mfma_f32_16x16x32_bf16 v[118:121], v[136:139], v[168:171], v[118:121]
	v_mfma_f32_16x16x32_bf16 v[110:113], v[152:155], v[168:171], v[110:113]
	s_waitcnt lgkmcnt(3)
	v_mfma_f32_16x16x32_bf16 v[102:105], v[136:139], v[176:179], v[102:105]
	v_mfma_f32_16x16x32_bf16 v[94:97], v[152:155], v[176:179], v[94:97]
	s_waitcnt lgkmcnt(1)
	v_mfma_f32_16x16x32_bf16 v[86:89], v[136:139], v[184:187], v[86:89]
	v_mfma_f32_16x16x32_bf16 v[78:81], v[152:155], v[184:187], v[78:81]
	v_mfma_f32_16x16x32_bf16 v[126:129], v[140:143], v[164:167], v[126:129]
	v_mfma_f32_16x16x32_bf16 v[122:125], v[156:159], v[164:167], v[122:125]
	v_mfma_f32_16x16x32_bf16 v[118:121], v[140:143], v[172:175], v[118:121]
	v_mfma_f32_16x16x32_bf16 v[110:113], v[156:159], v[172:175], v[110:113]
	v_mfma_f32_16x16x32_bf16 v[102:105], v[140:143], v[180:183], v[102:105]
	v_mfma_f32_16x16x32_bf16 v[94:97], v[156:159], v[180:183], v[94:97]
	s_waitcnt lgkmcnt(0)
	v_mfma_f32_16x16x32_bf16 v[86:89], v[140:143], v[188:191], v[86:89]
	v_mfma_f32_16x16x32_bf16 v[78:81], v[156:159], v[188:191], v[78:81]
	s_setprio 0
	s_barrier
	s_mov_b32 m0, s23
	s_mov_b32 s10, s42
	s_mov_b32 s11, s43
	ds_read_b128 v[192:195], v149
	ds_read_b128 v[196:199], v149 offset:1024
	ds_read_b128 v[200:203], v149 offset:2048
	ds_read_b128 v[204:207], v149 offset:3072
	buffer_load_dwordx4 v144, s[8:11], s85 offen lds
	s_add_i32 s33, s85, 0x20000
	s_mov_b32 m0, s24
	s_nop 0
	buffer_load_dwordx4 v144, s[8:11], s33 offen lds
	s_barrier
	s_waitcnt lgkmcnt(0)
	s_setprio 1
	s_waitcnt lgkmcnt(3)
	v_mfma_f32_16x16x32_bf16 v[114:117], v[192:195], v[160:163], v[114:117]
	s_waitcnt lgkmcnt(1)
	v_mfma_f32_16x16x32_bf16 v[106:109], v[200:203], v[160:163], v[106:109]
	v_mfma_f32_16x16x32_bf16 v[98:101], v[192:195], v[168:171], v[98:101]
	v_mfma_f32_16x16x32_bf16 v[90:93], v[200:203], v[168:171], v[90:93]
	v_mfma_f32_16x16x32_bf16 v[82:85], v[192:195], v[176:179], v[82:85]
	v_mfma_f32_16x16x32_bf16 v[74:77], v[200:203], v[176:179], v[74:77]
	v_mfma_f32_16x16x32_bf16 v[70:73], v[192:195], v[184:187], v[70:73]
	v_mfma_f32_16x16x32_bf16 v[66:69], v[200:203], v[184:187], v[66:69]
	v_mfma_f32_16x16x32_bf16 v[114:117], v[196:199], v[164:167], v[114:117]
	s_waitcnt lgkmcnt(0)
	v_mfma_f32_16x16x32_bf16 v[106:109], v[204:207], v[164:167], v[106:109]
	v_mfma_f32_16x16x32_bf16 v[98:101], v[196:199], v[172:175], v[98:101]
	v_mfma_f32_16x16x32_bf16 v[90:93], v[204:207], v[172:175], v[90:93]
	v_mfma_f32_16x16x32_bf16 v[82:85], v[196:199], v[180:183], v[82:85]
	v_mfma_f32_16x16x32_bf16 v[74:77], v[204:207], v[180:183], v[74:77]
	v_mfma_f32_16x16x32_bf16 v[70:73], v[196:199], v[188:191], v[70:73]
	v_mfma_f32_16x16x32_bf16 v[66:69], v[204:207], v[188:191], v[66:69]
	s_setprio 0
	s_mov_b32 m0, s22
	s_barrier
	ds_read_b128 v[160:163], v148 offset:16384
	ds_read_b128 v[164:167], v148 offset:17408
	ds_read_b128 v[168:171], v148 offset:18432
	ds_read_b128 v[172:175], v148 offset:19456
	ds_read_b128 v[176:179], v148 offset:20480
	ds_read_b128 v[180:183], v148 offset:21504
	ds_read_b128 v[184:187], v148 offset:22528
	ds_read_b128 v[188:191], v148 offset:23552
	buffer_load_dwordx4 v1, s[40:43], s86 offen lds
	s_add_i32 s33, s86, 0x20000
	s_mov_b32 m0, s25
	s_nop 0
	buffer_load_dwordx4 v1, s[40:43], s33 offen lds
	s_barrier
	s_waitcnt lgkmcnt(0)
	s_setprio 1
	s_waitcnt lgkmcnt(7)
	v_mfma_f32_16x16x32_bf16 v[62:65], v[136:139], v[160:163], v[62:65]
	v_mfma_f32_16x16x32_bf16 v[58:61], v[152:155], v[160:163], v[58:61]
	s_waitcnt lgkmcnt(5)
	v_mfma_f32_16x16x32_bf16 v[54:57], v[136:139], v[168:171], v[54:57]
	v_mfma_f32_16x16x32_bf16 v[46:49], v[152:155], v[168:171], v[46:49]
	s_waitcnt lgkmcnt(3)
	v_mfma_f32_16x16x32_bf16 v[38:41], v[136:139], v[176:179], v[38:41]
	v_mfma_f32_16x16x32_bf16 v[30:33], v[152:155], v[176:179], v[30:33]
	s_waitcnt lgkmcnt(1)
	v_mfma_f32_16x16x32_bf16 v[22:25], v[136:139], v[184:187], v[22:25]
	v_mfma_f32_16x16x32_bf16 v[14:17], v[152:155], v[184:187], v[14:17]
	v_mfma_f32_16x16x32_bf16 v[62:65], v[140:143], v[164:167], v[62:65]
	v_mfma_f32_16x16x32_bf16 v[58:61], v[156:159], v[164:167], v[58:61]
	v_mfma_f32_16x16x32_bf16 v[54:57], v[140:143], v[172:175], v[54:57]
	v_mfma_f32_16x16x32_bf16 v[46:49], v[156:159], v[172:175], v[46:49]
	v_mfma_f32_16x16x32_bf16 v[38:41], v[140:143], v[180:183], v[38:41]
	v_mfma_f32_16x16x32_bf16 v[30:33], v[156:159], v[180:183], v[30:33]
	s_waitcnt lgkmcnt(0)
	v_mfma_f32_16x16x32_bf16 v[22:25], v[140:143], v[188:191], v[22:25]
	v_mfma_f32_16x16x32_bf16 v[14:17], v[156:159], v[188:191], v[14:17]
	s_setprio 0
	s_barrier
	s_mov_b32 m0, s26
	s_add_i32 s33, s85, 0x40000
	buffer_load_dwordx4 v144, s[8:11], s33 offen lds
	s_add_i32 s33, s85, 0x60000
	s_mov_b32 m0, s27
	s_nop 0
	buffer_load_dwordx4 v144, s[8:11], s33 offen lds
	s_waitcnt vmcnt(6)
	s_barrier
	s_setprio 1
	v_mfma_f32_16x16x32_bf16 v[50:53], v[192:195], v[160:163], v[50:53]
	v_mfma_f32_16x16x32_bf16 v[42:45], v[200:203], v[160:163], v[42:45]
	v_mfma_f32_16x16x32_bf16 v[34:37], v[192:195], v[168:171], v[34:37]
	v_mfma_f32_16x16x32_bf16 v[26:29], v[200:203], v[168:171], v[26:29]
	v_mfma_f32_16x16x32_bf16 v[18:21], v[192:195], v[176:179], v[18:21]
	v_mfma_f32_16x16x32_bf16 v[10:13], v[200:203], v[176:179], v[10:13]
	v_mfma_f32_16x16x32_bf16 v[6:9], v[192:195], v[184:187], v[6:9]
	v_mfma_f32_16x16x32_bf16 v[2:5], v[200:203], v[184:187], v[2:5]
	v_mfma_f32_16x16x32_bf16 v[50:53], v[196:199], v[164:167], v[50:53]
	v_mfma_f32_16x16x32_bf16 v[42:45], v[204:207], v[164:167], v[42:45]
	v_mfma_f32_16x16x32_bf16 v[34:37], v[196:199], v[172:175], v[34:37]
	v_mfma_f32_16x16x32_bf16 v[26:29], v[204:207], v[172:175], v[26:29]
	v_mfma_f32_16x16x32_bf16 v[18:21], v[196:199], v[180:183], v[18:21]
	v_mfma_f32_16x16x32_bf16 v[10:13], v[204:207], v[180:183], v[10:13]
	v_mfma_f32_16x16x32_bf16 v[6:9], v[196:199], v[188:191], v[6:9]
	v_mfma_f32_16x16x32_bf16 v[2:5], v[204:207], v[188:191], v[2:5]
	s_setprio 0
	s_barrier
	ds_read_b128 v[136:139], v150
	ds_read_b128 v[140:143], v150 offset:1024
	ds_read_b128 v[152:155], v150 offset:2048
	ds_read_b128 v[156:159], v150 offset:3072
	s_mov_b32 m0, s28
	s_add_i32 s33, s86, 0x40000
	ds_read_b128 v[160:163], v148 offset:32768
	ds_read_b128 v[164:167], v148 offset:33792
	ds_read_b128 v[168:171], v148 offset:34816
	ds_read_b128 v[172:175], v148 offset:35840
	ds_read_b128 v[176:179], v148 offset:36864
	ds_read_b128 v[180:183], v148 offset:37888
	ds_read_b128 v[184:187], v148 offset:38912
	ds_read_b128 v[188:191], v148 offset:39936
	buffer_load_dwordx4 v1, s[40:43], s33 offen lds
	s_add_i32 s33, s86, 0x60000
	s_mov_b32 m0, s29
	s_nop 0
	buffer_load_dwordx4 v1, s[40:43], s33 offen lds
	s_waitcnt lgkmcnt(8)
	s_barrier
	s_waitcnt lgkmcnt(0)
	s_setprio 1
	s_waitcnt lgkmcnt(7)
	v_mfma_f32_16x16x32_bf16 v[126:129], v[136:139], v[160:163], v[126:129]
	v_mfma_f32_16x16x32_bf16 v[122:125], v[152:155], v[160:163], v[122:125]
	s_waitcnt lgkmcnt(5)
	v_mfma_f32_16x16x32_bf16 v[118:121], v[136:139], v[168:171], v[118:121]
	v_mfma_f32_16x16x32_bf16 v[110:113], v[152:155], v[168:171], v[110:113]
	s_waitcnt lgkmcnt(3)
	v_mfma_f32_16x16x32_bf16 v[102:105], v[136:139], v[176:179], v[102:105]
	v_mfma_f32_16x16x32_bf16 v[94:97], v[152:155], v[176:179], v[94:97]
	s_waitcnt lgkmcnt(1)
	v_mfma_f32_16x16x32_bf16 v[86:89], v[136:139], v[184:187], v[86:89]
	v_mfma_f32_16x16x32_bf16 v[78:81], v[152:155], v[184:187], v[78:81]
	v_mfma_f32_16x16x32_bf16 v[126:129], v[140:143], v[164:167], v[126:129]
	v_mfma_f32_16x16x32_bf16 v[122:125], v[156:159], v[164:167], v[122:125]
	v_mfma_f32_16x16x32_bf16 v[118:121], v[140:143], v[172:175], v[118:121]
	v_mfma_f32_16x16x32_bf16 v[110:113], v[156:159], v[172:175], v[110:113]
	v_mfma_f32_16x16x32_bf16 v[102:105], v[140:143], v[180:183], v[102:105]
	v_mfma_f32_16x16x32_bf16 v[94:97], v[156:159], v[180:183], v[94:97]
	s_waitcnt lgkmcnt(0)
	v_mfma_f32_16x16x32_bf16 v[86:89], v[140:143], v[188:191], v[86:89]
	v_mfma_f32_16x16x32_bf16 v[78:81], v[156:159], v[188:191], v[78:81]
	s_setprio 0
	s_barrier
	s_mov_b32 m0, s31
	s_or_b32 s33, s85, 0x80
	ds_read_b128 v[192:195], v151
	ds_read_b128 v[196:199], v151 offset:1024
	ds_read_b128 v[200:203], v151 offset:2048
	ds_read_b128 v[204:207], v151 offset:3072
	buffer_load_dwordx4 v144, s[8:11], s33 offen lds
	s_add_i32 s33, s85, 0x20080
	s_mov_b32 m0, s34
	s_nop 0
	buffer_load_dwordx4 v144, s[8:11], s33 offen lds
	s_barrier
	s_waitcnt lgkmcnt(0)
	s_setprio 1
	s_waitcnt lgkmcnt(3)
	v_mfma_f32_16x16x32_bf16 v[114:117], v[192:195], v[160:163], v[114:117]
	s_waitcnt lgkmcnt(1)
	v_mfma_f32_16x16x32_bf16 v[106:109], v[200:203], v[160:163], v[106:109]
	v_mfma_f32_16x16x32_bf16 v[98:101], v[192:195], v[168:171], v[98:101]
	v_mfma_f32_16x16x32_bf16 v[90:93], v[200:203], v[168:171], v[90:93]
	v_mfma_f32_16x16x32_bf16 v[82:85], v[192:195], v[176:179], v[82:85]
	v_mfma_f32_16x16x32_bf16 v[74:77], v[200:203], v[176:179], v[74:77]
	v_mfma_f32_16x16x32_bf16 v[70:73], v[192:195], v[184:187], v[70:73]
	v_mfma_f32_16x16x32_bf16 v[66:69], v[200:203], v[184:187], v[66:69]
	v_mfma_f32_16x16x32_bf16 v[114:117], v[196:199], v[164:167], v[114:117]
	s_waitcnt lgkmcnt(0)
	v_mfma_f32_16x16x32_bf16 v[106:109], v[204:207], v[164:167], v[106:109]
	v_mfma_f32_16x16x32_bf16 v[98:101], v[196:199], v[172:175], v[98:101]
	v_mfma_f32_16x16x32_bf16 v[90:93], v[204:207], v[172:175], v[90:93]
	v_mfma_f32_16x16x32_bf16 v[82:85], v[196:199], v[180:183], v[82:85]
	v_mfma_f32_16x16x32_bf16 v[74:77], v[204:207], v[180:183], v[74:77]
	v_mfma_f32_16x16x32_bf16 v[70:73], v[196:199], v[188:191], v[70:73]
	v_mfma_f32_16x16x32_bf16 v[66:69], v[204:207], v[188:191], v[66:69]
	s_setprio 0
	s_mov_b32 m0, s35
	s_barrier
	ds_read_b128 v[160:163], v148 offset:49152
	ds_read_b128 v[164:167], v148 offset:50176
	ds_read_b128 v[168:171], v148 offset:51200
	ds_read_b128 v[172:175], v148 offset:52224
	ds_read_b128 v[176:179], v148 offset:53248
	ds_read_b128 v[180:183], v148 offset:54272
	ds_read_b128 v[184:187], v148 offset:55296
	ds_read_b128 v[188:191], v148 offset:56320
	buffer_load_dwordx4 v1, s[40:43], s87 offen lds
	s_add_i32 s86, s86, 0x20080
	s_mov_b32 m0, s36
	s_nop 0
	buffer_load_dwordx4 v1, s[40:43], s86 offen lds
	s_barrier
	s_waitcnt lgkmcnt(0)
	s_setprio 1
	s_waitcnt lgkmcnt(7)
	v_mfma_f32_16x16x32_bf16 v[62:65], v[136:139], v[160:163], v[62:65]
	v_mfma_f32_16x16x32_bf16 v[58:61], v[152:155], v[160:163], v[58:61]
	s_waitcnt lgkmcnt(5)
	v_mfma_f32_16x16x32_bf16 v[54:57], v[136:139], v[168:171], v[54:57]
	v_mfma_f32_16x16x32_bf16 v[46:49], v[152:155], v[168:171], v[46:49]
	s_waitcnt lgkmcnt(3)
	v_mfma_f32_16x16x32_bf16 v[38:41], v[136:139], v[176:179], v[38:41]
	v_mfma_f32_16x16x32_bf16 v[30:33], v[152:155], v[176:179], v[30:33]
	s_waitcnt lgkmcnt(1)
	v_mfma_f32_16x16x32_bf16 v[22:25], v[136:139], v[184:187], v[22:25]
	v_mfma_f32_16x16x32_bf16 v[14:17], v[152:155], v[184:187], v[14:17]
	v_mfma_f32_16x16x32_bf16 v[62:65], v[140:143], v[164:167], v[62:65]
	v_mfma_f32_16x16x32_bf16 v[58:61], v[156:159], v[164:167], v[58:61]
	v_mfma_f32_16x16x32_bf16 v[54:57], v[140:143], v[172:175], v[54:57]
	v_mfma_f32_16x16x32_bf16 v[46:49], v[156:159], v[172:175], v[46:49]
	v_mfma_f32_16x16x32_bf16 v[38:41], v[140:143], v[180:183], v[38:41]
	v_mfma_f32_16x16x32_bf16 v[30:33], v[156:159], v[180:183], v[30:33]
	s_waitcnt lgkmcnt(0)
	v_mfma_f32_16x16x32_bf16 v[22:25], v[140:143], v[188:191], v[22:25]
	v_mfma_f32_16x16x32_bf16 v[14:17], v[156:159], v[188:191], v[14:17]
	s_setprio 0
	s_barrier
	s_mov_b32 m0, s37
	s_add_i32 s33, s85, 0x40080
	buffer_load_dwordx4 v144, s[8:11], s33 offen lds
	s_add_i32 s85, s85, 0x60080
	s_mov_b32 m0, s38
	s_nop 0
	buffer_load_dwordx4 v144, s[8:11], s85 offen lds
	s_waitcnt vmcnt(6)
	s_barrier
	s_setprio 1
	v_mfma_f32_16x16x32_bf16 v[50:53], v[192:195], v[160:163], v[50:53]
	v_mfma_f32_16x16x32_bf16 v[42:45], v[200:203], v[160:163], v[42:45]
	v_mfma_f32_16x16x32_bf16 v[34:37], v[192:195], v[168:171], v[34:37]
	v_mfma_f32_16x16x32_bf16 v[26:29], v[200:203], v[168:171], v[26:29]
	v_mfma_f32_16x16x32_bf16 v[18:21], v[192:195], v[176:179], v[18:21]
	v_mfma_f32_16x16x32_bf16 v[10:13], v[200:203], v[176:179], v[10:13]
	v_mfma_f32_16x16x32_bf16 v[6:9], v[192:195], v[184:187], v[6:9]
	v_mfma_f32_16x16x32_bf16 v[2:5], v[200:203], v[184:187], v[2:5]
	v_mfma_f32_16x16x32_bf16 v[50:53], v[196:199], v[164:167], v[50:53]
	v_mfma_f32_16x16x32_bf16 v[42:45], v[204:207], v[164:167], v[42:45]
	v_mfma_f32_16x16x32_bf16 v[34:37], v[196:199], v[172:175], v[34:37]
	v_mfma_f32_16x16x32_bf16 v[26:29], v[204:207], v[172:175], v[26:29]
	v_mfma_f32_16x16x32_bf16 v[18:21], v[196:199], v[180:183], v[18:21]
	v_mfma_f32_16x16x32_bf16 v[10:13], v[204:207], v[180:183], v[10:13]
	v_mfma_f32_16x16x32_bf16 v[6:9], v[196:199], v[188:191], v[6:9]
	v_mfma_f32_16x16x32_bf16 v[2:5], v[204:207], v[188:191], v[2:5]
	s_setprio 0
	s_add_i32 s84, s84, 2
	s_addk_i32 s7, 0x100
	s_addk_i32 s79, 0x100
	s_cmp_gt_u32 s84, 13
	s_barrier
	s_cbranch_scc0 .LBB0_2682
	v_lshl_add_u32 v142, s78, 8, v145
	v_or_b32_e32 v140, 16, v142
	v_or_b32_e32 v138, 32, v142
	v_or_b32_e32 v136, 48, v142
	s_mov_b64 s[6:7], -1
	s_cmp_gt_i32 s73, 3
	v_ashrrev_i32_e32 v143, 31, v142
	v_ashrrev_i32_e32 v141, 31, v140
	v_ashrrev_i32_e32 v139, 31, v138
	v_ashrrev_i32_e32 v137, 31, v136
	s_cbranch_scc0 .LBB0_2685
	v_pk_mul_f32 v[154:155], v[128:129], v[116:117]
	v_pk_mul_f32 v[152:153], v[126:127], v[114:115]
	v_pk_mul_f32 v[156:157], v[124:125], v[108:109]
	v_pk_mul_f32 v[158:159], v[122:123], v[106:107]
	v_cvt_pk_bf16_f32 v152, v152, v153
	v_cvt_pk_bf16_f32 v153, v154, v155
	v_lshlrev_b32_e32 v134, 1, v146
	v_cvt_pk_bf16_f32 v154, v158, v159
	v_cvt_pk_bf16_f32 v155, v156, v157
	v_lshlrev_b64 v[156:157], 12, v[142:143]
	v_lshl_add_u64 v[156:157], s[82:83], 0, v[156:157]
	v_lshl_or_b32 v134, s73, 8, v134
	v_lshl_add_u64 v[156:157], v[156:157], 0, v[134:135]
	global_store_dwordx4 v[156:157], v[152:155], off offset:1024
	v_pk_mul_f32 v[158:159], v[112:113], v[92:93]
	v_pk_mul_f32 v[160:161], v[110:111], v[90:91]
	v_pk_mul_f32 v[154:155], v[120:121], v[100:101]
	v_pk_mul_f32 v[152:153], v[118:119], v[98:99]
	s_mov_b64 s[6:7], 0
	v_cvt_pk_bf16_f32 v152, v152, v153
	v_cvt_pk_bf16_f32 v153, v154, v155
	v_cvt_pk_bf16_f32 v154, v160, v161
	v_cvt_pk_bf16_f32 v155, v158, v159
	v_lshlrev_b64 v[158:159], 12, v[140:141]
	v_lshl_add_u64 v[158:159], s[82:83], 0, v[158:159]
	v_lshl_add_u64 v[158:159], v[158:159], 0, v[134:135]
	global_store_dwordx4 v[158:159], v[152:155], off offset:1024
	v_pk_mul_f32 v[158:159], v[96:97], v[76:77]
	v_pk_mul_f32 v[160:161], v[94:95], v[74:75]
	v_pk_mul_f32 v[154:155], v[104:105], v[84:85]
	v_pk_mul_f32 v[152:153], v[102:103], v[82:83]
	s_nop 0
	v_cvt_pk_bf16_f32 v152, v152, v153
	v_cvt_pk_bf16_f32 v153, v154, v155
	v_cvt_pk_bf16_f32 v154, v160, v161
	v_cvt_pk_bf16_f32 v155, v158, v159
	v_lshlrev_b64 v[158:159], 12, v[138:139]
	v_lshl_add_u64 v[158:159], s[82:83], 0, v[158:159]
	v_lshl_add_u64 v[158:159], v[158:159], 0, v[134:135]
	global_store_dwordx4 v[158:159], v[152:155], off offset:1024
	v_pk_mul_f32 v[158:159], v[80:81], v[68:69]
	v_pk_mul_f32 v[160:161], v[78:79], v[66:67]
	v_pk_mul_f32 v[154:155], v[88:89], v[72:73]
	v_pk_mul_f32 v[152:153], v[86:87], v[70:71]
	s_nop 0
	v_cvt_pk_bf16_f32 v152, v152, v153
	v_cvt_pk_bf16_f32 v153, v154, v155
	v_cvt_pk_bf16_f32 v154, v160, v161
	v_cvt_pk_bf16_f32 v155, v158, v159
	v_lshlrev_b64 v[158:159], 12, v[136:137]
	v_lshl_add_u64 v[158:159], s[82:83], 0, v[158:159]
	v_lshl_add_u64 v[158:159], v[158:159], 0, v[134:135]
	global_store_dwordx4 v[158:159], v[152:155], off offset:1024
	v_pk_mul_f32 v[158:159], v[60:61], v[44:45]
	v_pk_mul_f32 v[160:161], v[58:59], v[42:43]
	v_pk_mul_f32 v[154:155], v[64:65], v[52:53]
	v_pk_mul_f32 v[152:153], v[62:63], v[50:51]
	s_nop 0
	v_cvt_pk_bf16_f32 v152, v152, v153
	v_cvt_pk_bf16_f32 v153, v154, v155
	v_cvt_pk_bf16_f32 v154, v160, v161
	v_cvt_pk_bf16_f32 v155, v158, v159
	v_add_co_u32_e32 v158, vcc, s47, v156
	v_pk_mul_f32 v[160:161], v[46:47], v[26:27]
	s_nop 0
	v_addc_co_u32_e32 v159, vcc, 0, v157, vcc
	global_store_dwordx4 v[158:159], v[152:155], off offset:1024
	v_pk_mul_f32 v[158:159], v[48:49], v[28:29]
	s_nop 0
	v_pk_mul_f32 v[154:155], v[56:57], v[36:37]
	v_pk_mul_f32 v[152:153], v[54:55], v[34:35]
	s_nop 0
	v_cvt_pk_bf16_f32 v152, v152, v153
	v_cvt_pk_bf16_f32 v153, v154, v155
	v_cvt_pk_bf16_f32 v154, v160, v161
	v_cvt_pk_bf16_f32 v155, v158, v159
	v_add_co_u32_e32 v158, vcc, s49, v156
	v_pk_mul_f32 v[160:161], v[30:31], v[10:11]
	s_nop 0
	v_addc_co_u32_e32 v159, vcc, 0, v157, vcc
	global_store_dwordx4 v[158:159], v[152:155], off offset:1024
	v_pk_mul_f32 v[158:159], v[32:33], v[12:13]
	s_nop 0
	v_pk_mul_f32 v[154:155], v[40:41], v[20:21]
	v_pk_mul_f32 v[152:153], v[38:39], v[18:19]
	s_nop 0
	v_cvt_pk_bf16_f32 v152, v152, v153
	v_cvt_pk_bf16_f32 v153, v154, v155
	v_cvt_pk_bf16_f32 v154, v160, v161
	v_cvt_pk_bf16_f32 v155, v158, v159
	v_add_co_u32_e32 v158, vcc, s50, v156
	v_pk_mul_f32 v[160:161], v[14:15], v[2:3]
	s_nop 0
	v_addc_co_u32_e32 v159, vcc, 0, v157, vcc
	v_add_co_u32_e32 v156, vcc, 0xb0000, v156
	global_store_dwordx4 v[158:159], v[152:155], off offset:1024
	s_nop 0
	v_addc_co_u32_e32 v157, vcc, 0, v157, vcc
	v_pk_mul_f32 v[154:155], v[24:25], v[8:9]
	v_pk_mul_f32 v[152:153], v[22:23], v[6:7]
	v_pk_mul_f32 v[158:159], v[16:17], v[4:5]
	v_cvt_pk_bf16_f32 v152, v152, v153
	v_cvt_pk_bf16_f32 v153, v154, v155
	v_cvt_pk_bf16_f32 v154, v160, v161
	s_nop 0
	v_cvt_pk_bf16_f32 v155, v158, v159
	global_store_dwordx4 v[156:157], v[152:155], off offset:1024

.LBB0_2813:
	s_ashr_i32 s5, s7, 3
	s_add_u32 s8, s52, 0x1900000
	s_addc_u32 s7, s53, 0
	s_add_i32 s5, s6, s5
	s_ashr_i32 s6, s5, 31
	s_lshr_b32 s6, s6, 27
	v_bfe_i32 v5, v2, 27, 1
	s_add_i32 s6, s5, s6
	v_lshlrev_b32_e32 v3, 4, v2
	v_lshrrev_b32_e32 v5, 22, v5
	s_ashr_i32 s12, s6, 5
	s_andn2_b32 s6, s6, 31
	v_add_u32_e32 v5, v3, v5
	s_sub_i32 s5, s5, s6
	v_and_b32_e32 v5, 0xfffffc00, v5
	s_bfe_i32 s6, s5, 0x80000
	v_sub_u32_e32 v3, v3, v5
	s_bfe_u32 s6, s6, 0x3000c
	v_ashrrev_i32_e32 v4, 31, v2
	v_lshrrev_b32_e32 v5, 4, v3
	s_add_i32 s6, s5, s6
	v_lshrrev_b32_e32 v4, 26, v4
	v_bitop3_b32 v3, v5, v3, 32 bitop3:0x6c
	s_bfe_i32 s13, s6, 0x80000
	s_and_b32 s6, s6, 0xf8
	v_add_u32_e32 v4, v2, v4
	v_ashrrev_i32_e32 v6, 31, v3
	s_sub_i32 s5, s5, s6
	v_ashrrev_i32_e32 v4, 6, v4
	v_lshrrev_b32_e32 v6, 26, v6
	s_lshl_b32 s12, s12, 3
	s_sext_i32_i8 s5, s5
	v_lshlrev_b32_e32 v5, 3, v4
	v_add_u32_e32 v6, v3, v6
	s_add_i32 s59, s12, s5
	v_and_b32_e32 v5, -16, v5
	v_ashrrev_i32_e32 v7, 6, v6
	v_and_b32_e32 v6, 0xc0, v6
	s_ashr_i32 s5, s59, 31
	s_ashr_i32 s4, s3, 6
	v_add_u32_e32 v5, v7, v5
	v_sub_u32_e32 v3, v3, v6
	v_mov_b32_e32 v6, 1
	v_and_b32_e32 v7, 3, v7
	s_mov_b32 s9, 0x1fffe0
	s_lshr_b32 s5, s5, 12
	v_lshlrev_b32_e32 v4, 5, v4
	v_ashrrev_i16_sdwa v3, v6, sext(v3) dst_sel:DWORD dst_unused:UNUSED_PAD src0_sel:DWORD src1_sel:BYTE_0
	v_lshlrev_b32_e32 v6, 1, v5
	v_lshrrev_b32_e32 v8, 2, v5
	v_and_or_b32 v7, v5, s9, v7
	s_and_b32 s9, s7, 0xffff
	s_lshl_b32 s7, s4, 10
	s_sext_i32_i16 s13, s13
	s_add_i32 s5, s59, s5
	v_readlane_b32 s10, v255, 11
	v_and_b32_e32 v4, 32, v4
	v_bfe_i32 v3, v3, 0, 16
	v_and_b32_e32 v6, 24, v6
	v_and_b32_e32 v8, 4, v8
	s_ashr_i32 s72, s13, 3
	s_lshl_b32 s5, s5, 1
	s_add_i32 s15, s7, 0
	v_readlane_b32 s11, v255, 12
	s_mov_b32 s51, 0x20000
	s_brev_b32 s50, -2
	v_or3_b32 v6, v7, v8, v6
	v_add_lshl_u32 v3, v4, v3, 1
	s_and_b32 s5, s5, 0xffe00000
	s_lshl_b32 s6, s72, 19
	s_add_i32 s16, s15, 0x10000
	s_and_b32 s49, s11, 0xffff
	v_lshl_add_u32 v193, v6, 11, v3
	s_mov_b32 s10, s50
	s_mov_b32 s11, s51
	s_add_i32 s12, s5, s6
	s_mov_b32 m0, s16
	s_add_i32 s17, s15, 0x12000
	buffer_load_dwordx4 v193, s[8:11], s12 offen lds
	s_or_b32 s5, s12, 0x20000
	s_mov_b32 m0, s17
	v_lshl_add_u32 v192, v5, 11, v3
	buffer_load_dwordx4 v193, s[8:11], s5 offen lds
	s_lshl_b32 s13, s59, 19
	s_mov_b32 m0, s15
	s_add_i32 s18, s15, 0x2000
	buffer_load_dwordx4 v192, s[48:51], s13 offen lds
	s_or_b32 s5, s13, 0x20000
	s_mov_b32 m0, s18
	s_add_i32 s19, s15, 0x14000
	buffer_load_dwordx4 v192, s[48:51], s5 offen lds
	s_or_b32 s5, s12, 0x40000
	s_mov_b32 m0, s19
	s_add_i32 s20, s15, 0x16000
	buffer_load_dwordx4 v193, s[8:11], s5 offen lds
	s_or_b32 s5, s12, 0x60000
	s_mov_b32 m0, s20
	s_add_i32 s21, s15, 0x4000
	buffer_load_dwordx4 v193, s[8:11], s5 offen lds
	s_or_b32 s5, s13, 0x40000
	s_mov_b32 m0, s21
	s_add_i32 s22, s15, 0x6000
	buffer_load_dwordx4 v192, s[48:51], s5 offen lds
	s_or_b32 s5, s13, 0x60000
	s_mov_b32 m0, s22
	s_mov_b32 s23, 0
	buffer_load_dwordx4 v192, s[48:51], s5 offen lds
	s_ashr_i32 s5, s3, 8
	s_mov_b32 s24, 0x10000
	s_cmp_lg_u32 s5, 1
	s_mov_b32 s25, 0x40000
	s_cbranch_scc1 .LBB0_2815
	s_barrier

.LBB0_2817:
	v_lshl_add_u32 v146, s59, 8, v194
	v_add_u32_e32 v132, 0xffff8000, v146
	v_cndmask_b32_e64 v132, v146, v132, s[6:7]
	s_add_u32 s12, s52, s12
	v_lshl_or_b32 v130, s72, 8, v195
	v_ashrrev_i32_e32 v133, 31, v132
	s_addc_u32 s13, s53, s13
	v_ashrrev_i32_e32 v131, 31, v130
	v_lshlrev_b64 v[132:133], 11, v[132:133]
	v_lshl_add_u64 v[132:133], s[12:13], 0, v[132:133]
	v_lshlrev_b64 v[148:149], 1, v[130:131]
	s_lshl_b64 s[6:7], s[10:11], 2
	v_lshl_add_u64 v[150:151], v[132:133], 0, v[148:149]
	s_add_u32 s6, s26, s6
	global_load_dwordx4 v[202:205], v[150:151], off
	global_load_dwordx4 v[206:209], v[150:151], off offset:256
	s_addc_u32 s7, s27, s7
	v_lshl_add_u64 v[130:131], v[130:131], 2, s[6:7]
	v_add_co_u32_e32 v152, vcc, s37, v150
	global_load_dwordx4 v[142:145], v[130:131], off
	global_load_dwordx4 v[138:141], v[130:131], off offset:16
	global_load_dwordx4 v[134:137], v[130:131], off offset:512
	s_nop 0
	global_load_dwordx4 v[130:133], v[130:131], off offset:528
	v_addc_co_u32_e32 v153, vcc, 0, v151, vcc
	global_load_dwordx4 v[210:213], v[152:153], off
	global_load_dwordx4 v[214:217], v[152:153], off offset:256
	v_ashrrev_i32_e32 v147, 31, v146
	v_lshlrev_b64 v[146:147], 11, v[146:147]
	v_lshl_add_u64 v[146:147], s[66:67], 0, v[146:147]
	v_lshl_add_u64 v[190:191], v[146:147], 0, v[148:149]
	v_add_co_u32_e32 v146, vcc, s24, v150
	s_mov_b32 s72, s46
	s_nop 0
	v_addc_co_u32_e32 v147, vcc, 0, v151, vcc
	v_add_co_u32_e32 v148, vcc, s36, v150
	s_mov_b32 s59, s47
	s_nop 0
	v_addc_co_u32_e32 v149, vcc, 0, v151, vcc
	v_add_co_u32_e32 v154, vcc, s25, v150
	s_mov_b32 s12, s57
	s_nop 0
	v_addc_co_u32_e32 v155, vcc, 0, v151, vcc
	v_add_co_u32_e32 v152, vcc, s42, v150
	s_mov_b32 s13, s58
	s_nop 0
	v_addc_co_u32_e32 v153, vcc, 0, v151, vcc
	v_add_co_u32_e32 v156, vcc, s43, v150
	s_waitcnt vmcnt(7)
	v_lshlrev_b32_e32 v228, 16, v204
	v_addc_co_u32_e32 v157, vcc, 0, v151, vcc
	v_add_co_u32_e32 v226, vcc, s45, v150
	v_and_b32_e32 v229, 0xffff0000, v204
	s_nop 0
	v_addc_co_u32_e32 v227, vcc, 0, v151, vcc
	global_load_dwordx4 v[218:221], v[146:147], off
	global_load_dwordx4 v[222:225], v[146:147], off offset:256
	global_load_dwordx4 v[182:185], v[148:149], off
	global_load_dwordx4 v[178:181], v[148:149], off offset:256
	global_load_dwordx4 v[174:177], v[154:155], off
	global_load_dwordx4 v[170:173], v[154:155], off offset:256
	global_load_dwordx4 v[166:169], v[152:153], off
	global_load_dwordx4 v[162:165], v[152:153], off offset:256
	global_load_dwordx4 v[158:161], v[156:157], off
	s_nop 0
	global_load_dwordx4 v[154:157], v[156:157], off offset:256
	s_nop 0
	global_load_dwordx4 v[150:153], v[226:227], off
	global_load_dwordx4 v[146:149], v[226:227], off offset:256
	v_lshlrev_b32_e32 v226, 16, v202
	v_and_b32_e32 v227, 0xffff0000, v202
	v_lshlrev_b32_e32 v202, 16, v203
	v_and_b32_e32 v203, 0xffff0000, v203
	v_lshlrev_b32_e32 v204, 16, v205
	v_and_b32_e32 v205, 0xffff0000, v205
	s_waitcnt vmcnt(17)
	v_pk_fma_f32 v[128:129], v[128:129], v[144:145], v[202:203]
	v_pk_fma_f32 v[126:127], v[126:127], v[142:143], v[226:227]
	s_waitcnt vmcnt(16)
	v_pk_fma_f32 v[202:203], v[124:125], v[140:141], v[204:205]
	v_pk_fma_f32 v[124:125], v[122:123], v[138:139], v[228:229]
	v_cvt_pk_bf16_f32 v122, v126, v127
	v_cvt_pk_bf16_f32 v123, v128, v129
	v_lshlrev_b32_e32 v230, 16, v206
	v_and_b32_e32 v231, 0xffff0000, v206
	v_lshlrev_b32_e32 v206, 16, v207
	v_and_b32_e32 v207, 0xffff0000, v207
	v_lshlrev_b32_e32 v232, 16, v208
	v_and_b32_e32 v233, 0xffff0000, v208
	v_cvt_pk_bf16_f32 v124, v124, v125
	v_cvt_pk_bf16_f32 v125, v202, v203
	global_store_dwordx4 v[190:191], v[122:125], off
	s_waitcnt vmcnt(16)
	v_pk_fma_f32 v[120:121], v[120:121], v[136:137], v[206:207]
	v_pk_fma_f32 v[118:119], v[118:119], v[134:135], v[230:231]
	v_lshlrev_b32_e32 v122, 16, v209
	v_and_b32_e32 v123, 0xffff0000, v209
	s_waitcnt vmcnt(15)
	v_pk_fma_f32 v[122:123], v[116:117], v[132:133], v[122:123]
	v_pk_fma_f32 v[116:117], v[114:115], v[130:131], v[232:233]
	v_cvt_pk_bf16_f32 v114, v118, v119
	v_cvt_pk_bf16_f32 v115, v120, v121
	s_waitcnt vmcnt(14)
	v_lshlrev_b32_e32 v118, 16, v212
	v_cvt_pk_bf16_f32 v116, v116, v117
	v_cvt_pk_bf16_f32 v117, v122, v123
	global_store_dwordx4 v[190:191], v[114:117], off offset:256
	v_and_b32_e32 v119, 0xffff0000, v212
	v_lshlrev_b32_e32 v120, 16, v213
	v_lshlrev_b32_e32 v114, 16, v210
	v_and_b32_e32 v115, 0xffff0000, v210
	v_and_b32_e32 v121, 0xffff0000, v213
	v_pk_fma_f32 v[110:111], v[110:111], v[142:143], v[114:115]
	v_lshlrev_b32_e32 v116, 16, v211
	v_and_b32_e32 v117, 0xffff0000, v211
	v_pk_fma_f32 v[114:115], v[108:109], v[140:141], v[120:121]
	v_pk_fma_f32 v[108:109], v[106:107], v[138:139], v[118:119]
	v_cvt_pk_bf16_f32 v106, v110, v111
	v_add_co_u32_e32 v110, vcc, s37, v190
	v_pk_fma_f32 v[112:113], v[112:113], v[144:145], v[116:117]
	s_nop 0
	v_addc_co_u32_e32 v111, vcc, 0, v191, vcc
	v_cvt_pk_bf16_f32 v107, v112, v113
	v_cvt_pk_bf16_f32 v108, v108, v109
	v_cvt_pk_bf16_f32 v109, v114, v115
	global_store_dwordx4 v[110:111], v[106:109], off
	s_waitcnt vmcnt(15)
	v_lshlrev_b32_e32 v112, 16, v216
	v_and_b32_e32 v113, 0xffff0000, v216
	v_lshlrev_b32_e32 v106, 16, v214
	v_and_b32_e32 v107, 0xffff0000, v214
	v_lshlrev_b32_e32 v108, 16, v215
	v_and_b32_e32 v109, 0xffff0000, v215
	v_lshlrev_b32_e32 v114, 16, v217
	v_and_b32_e32 v115, 0xffff0000, v217
	v_pk_fma_f32 v[104:105], v[104:105], v[136:137], v[108:109]
	v_pk_fma_f32 v[102:103], v[102:103], v[134:135], v[106:107]
	v_pk_fma_f32 v[106:107], v[100:101], v[132:133], v[114:115]
	v_pk_fma_f32 v[100:101], v[98:99], v[130:131], v[112:113]
	v_cvt_pk_bf16_f32 v98, v102, v103
	v_cvt_pk_bf16_f32 v99, v104, v105
	s_waitcnt vmcnt(14)
	v_lshlrev_b32_e32 v102, 16, v220
	v_cvt_pk_bf16_f32 v100, v100, v101
	v_cvt_pk_bf16_f32 v101, v106, v107
	global_store_dwordx4 v[110:111], v[98:101], off offset:256
	v_and_b32_e32 v103, 0xffff0000, v220
	v_lshlrev_b32_e32 v104, 16, v221
	v_lshlrev_b32_e32 v98, 16, v218
	v_and_b32_e32 v99, 0xffff0000, v218
	v_and_b32_e32 v105, 0xffff0000, v221
	v_pk_fma_f32 v[94:95], v[94:95], v[142:143], v[98:99]
	v_lshlrev_b32_e32 v100, 16, v219
	v_and_b32_e32 v101, 0xffff0000, v219
	v_pk_fma_f32 v[98:99], v[92:93], v[140:141], v[104:105]
	v_pk_fma_f32 v[92:93], v[90:91], v[138:139], v[102:103]
	v_cvt_pk_bf16_f32 v90, v94, v95
	v_add_co_u32_e32 v94, vcc, s24, v190
	v_pk_fma_f32 v[96:97], v[96:97], v[144:145], v[100:101]
	s_nop 0
	v_addc_co_u32_e32 v95, vcc, 0, v191, vcc
	v_cvt_pk_bf16_f32 v91, v96, v97
	v_cvt_pk_bf16_f32 v92, v92, v93
	v_cvt_pk_bf16_f32 v93, v98, v99
	global_store_dwordx4 v[94:95], v[90:93], off
	s_waitcnt vmcnt(15)
	v_lshlrev_b32_e32 v96, 16, v224
	v_and_b32_e32 v97, 0xffff0000, v224
	v_lshlrev_b32_e32 v90, 16, v222
	v_and_b32_e32 v91, 0xffff0000, v222
	v_lshlrev_b32_e32 v92, 16, v223
	v_and_b32_e32 v93, 0xffff0000, v223
	v_lshlrev_b32_e32 v98, 16, v225
	v_and_b32_e32 v99, 0xffff0000, v225
	v_pk_fma_f32 v[88:89], v[88:89], v[136:137], v[92:93]
	v_pk_fma_f32 v[86:87], v[86:87], v[134:135], v[90:91]
	v_pk_fma_f32 v[90:91], v[84:85], v[132:133], v[98:99]
	v_pk_fma_f32 v[84:85], v[82:83], v[130:131], v[96:97]
	v_cvt_pk_bf16_f32 v82, v86, v87
	v_cvt_pk_bf16_f32 v83, v88, v89
	s_waitcnt vmcnt(14)
	v_lshlrev_b32_e32 v86, 16, v184
	v_cvt_pk_bf16_f32 v84, v84, v85
	v_cvt_pk_bf16_f32 v85, v90, v91
	global_store_dwordx4 v[94:95], v[82:85], off offset:256
	v_and_b32_e32 v87, 0xffff0000, v184
	v_lshlrev_b32_e32 v88, 16, v185
	v_lshlrev_b32_e32 v82, 16, v182
	v_and_b32_e32 v83, 0xffff0000, v182
	v_and_b32_e32 v89, 0xffff0000, v185
	v_pk_fma_f32 v[78:79], v[78:79], v[142:143], v[82:83]
	v_lshlrev_b32_e32 v84, 16, v183
	v_and_b32_e32 v85, 0xffff0000, v183
	v_pk_fma_f32 v[82:83], v[76:77], v[140:141], v[88:89]
	v_pk_fma_f32 v[76:77], v[74:75], v[138:139], v[86:87]
	v_cvt_pk_bf16_f32 v74, v78, v79
	v_add_co_u32_e32 v78, vcc, s36, v190
	v_pk_fma_f32 v[80:81], v[80:81], v[144:145], v[84:85]
	s_nop 0
	v_addc_co_u32_e32 v79, vcc, 0, v191, vcc
	v_cvt_pk_bf16_f32 v75, v80, v81
	v_cvt_pk_bf16_f32 v76, v76, v77
	v_cvt_pk_bf16_f32 v77, v82, v83
	global_store_dwordx4 v[78:79], v[74:77], off
	s_waitcnt vmcnt(15)
	v_lshlrev_b32_e32 v80, 16, v180
	v_and_b32_e32 v81, 0xffff0000, v180
	v_lshlrev_b32_e32 v74, 16, v178
	v_and_b32_e32 v75, 0xffff0000, v178
	v_lshlrev_b32_e32 v76, 16, v179
	v_and_b32_e32 v77, 0xffff0000, v179
	v_lshlrev_b32_e32 v82, 16, v181
	v_and_b32_e32 v83, 0xffff0000, v181
	v_pk_fma_f32 v[72:73], v[72:73], v[136:137], v[76:77]
	v_pk_fma_f32 v[70:71], v[70:71], v[134:135], v[74:75]
	v_pk_fma_f32 v[74:75], v[68:69], v[132:133], v[82:83]
	v_pk_fma_f32 v[68:69], v[66:67], v[130:131], v[80:81]
	v_cvt_pk_bf16_f32 v66, v70, v71
	v_cvt_pk_bf16_f32 v67, v72, v73
	s_waitcnt vmcnt(14)
	v_lshlrev_b32_e32 v70, 16, v176
	v_cvt_pk_bf16_f32 v68, v68, v69
	v_cvt_pk_bf16_f32 v69, v74, v75
	global_store_dwordx4 v[78:79], v[66:69], off offset:256
	v_and_b32_e32 v71, 0xffff0000, v176
	v_lshlrev_b32_e32 v72, 16, v177
	v_lshlrev_b32_e32 v66, 16, v174
	v_and_b32_e32 v67, 0xffff0000, v174
	v_and_b32_e32 v73, 0xffff0000, v177
	v_pk_fma_f32 v[62:63], v[62:63], v[142:143], v[66:67]
	v_lshlrev_b32_e32 v68, 16, v175
	v_and_b32_e32 v69, 0xffff0000, v175
	v_pk_fma_f32 v[66:67], v[60:61], v[140:141], v[72:73]
	v_pk_fma_f32 v[60:61], v[58:59], v[138:139], v[70:71]
	v_cvt_pk_bf16_f32 v58, v62, v63
	v_add_co_u32_e32 v62, vcc, s25, v190
	v_pk_fma_f32 v[64:65], v[64:65], v[144:145], v[68:69]
	s_nop 0
	v_addc_co_u32_e32 v63, vcc, 0, v191, vcc
	v_cvt_pk_bf16_f32 v59, v64, v65
	v_cvt_pk_bf16_f32 v60, v60, v61
	v_cvt_pk_bf16_f32 v61, v66, v67
	global_store_dwordx4 v[62:63], v[58:61], off
	s_waitcnt vmcnt(15)
	v_lshlrev_b32_e32 v64, 16, v172
	v_and_b32_e32 v65, 0xffff0000, v172
	v_lshlrev_b32_e32 v58, 16, v170
	v_and_b32_e32 v59, 0xffff0000, v170
	v_lshlrev_b32_e32 v60, 16, v171
	v_and_b32_e32 v61, 0xffff0000, v171
	v_lshlrev_b32_e32 v66, 16, v173
	v_and_b32_e32 v67, 0xffff0000, v173
	v_pk_fma_f32 v[56:57], v[56:57], v[136:137], v[60:61]
	v_pk_fma_f32 v[54:55], v[54:55], v[134:135], v[58:59]
	v_pk_fma_f32 v[58:59], v[52:53], v[132:133], v[66:67]
	v_pk_fma_f32 v[52:53], v[50:51], v[130:131], v[64:65]
	v_cvt_pk_bf16_f32 v50, v54, v55
	v_cvt_pk_bf16_f32 v51, v56, v57
	s_waitcnt vmcnt(14)
	v_lshlrev_b32_e32 v54, 16, v168
	v_cvt_pk_bf16_f32 v52, v52, v53
	v_cvt_pk_bf16_f32 v53, v58, v59
	global_store_dwordx4 v[62:63], v[50:53], off offset:256
	v_and_b32_e32 v55, 0xffff0000, v168
	v_lshlrev_b32_e32 v56, 16, v169
	v_lshlrev_b32_e32 v50, 16, v166
	v_and_b32_e32 v51, 0xffff0000, v166
	v_and_b32_e32 v57, 0xffff0000, v169
	v_pk_fma_f32 v[46:47], v[46:47], v[142:143], v[50:51]
	v_lshlrev_b32_e32 v52, 16, v167
	v_and_b32_e32 v53, 0xffff0000, v167
	v_pk_fma_f32 v[50:51], v[44:45], v[140:141], v[56:57]
	v_pk_fma_f32 v[44:45], v[42:43], v[138:139], v[54:55]
	v_cvt_pk_bf16_f32 v42, v46, v47
	v_add_co_u32_e32 v46, vcc, s42, v190
	v_pk_fma_f32 v[48:49], v[48:49], v[144:145], v[52:53]
	s_nop 0
	v_addc_co_u32_e32 v47, vcc, 0, v191, vcc
	v_cvt_pk_bf16_f32 v43, v48, v49
	v_cvt_pk_bf16_f32 v44, v44, v45
	v_cvt_pk_bf16_f32 v45, v50, v51
	global_store_dwordx4 v[46:47], v[42:45], off
	s_waitcnt vmcnt(15)
	v_lshlrev_b32_e32 v48, 16, v164
	v_and_b32_e32 v49, 0xffff0000, v164
	v_lshlrev_b32_e32 v42, 16, v162
	v_and_b32_e32 v43, 0xffff0000, v162
	v_lshlrev_b32_e32 v44, 16, v163
	v_and_b32_e32 v45, 0xffff0000, v163
	v_lshlrev_b32_e32 v50, 16, v165
	v_and_b32_e32 v51, 0xffff0000, v165
	v_pk_fma_f32 v[40:41], v[40:41], v[136:137], v[44:45]
	v_pk_fma_f32 v[38:39], v[38:39], v[134:135], v[42:43]
	v_pk_fma_f32 v[42:43], v[36:37], v[132:133], v[50:51]
	v_pk_fma_f32 v[36:37], v[34:35], v[130:131], v[48:49]
	v_cvt_pk_bf16_f32 v34, v38, v39
	v_cvt_pk_bf16_f32 v35, v40, v41
	s_waitcnt vmcnt(14)
	v_lshlrev_b32_e32 v38, 16, v160
	v_cvt_pk_bf16_f32 v36, v36, v37
	v_cvt_pk_bf16_f32 v37, v42, v43
	global_store_dwordx4 v[46:47], v[34:37], off offset:256
	v_and_b32_e32 v39, 0xffff0000, v160
	v_lshlrev_b32_e32 v40, 16, v161
	v_lshlrev_b32_e32 v34, 16, v158
	v_and_b32_e32 v35, 0xffff0000, v158
	v_and_b32_e32 v41, 0xffff0000, v161
	v_pk_fma_f32 v[30:31], v[30:31], v[142:143], v[34:35]
	v_lshlrev_b32_e32 v36, 16, v159
	v_and_b32_e32 v37, 0xffff0000, v159
	v_pk_fma_f32 v[34:35], v[28:29], v[140:141], v[40:41]
	v_pk_fma_f32 v[28:29], v[26:27], v[138:139], v[38:39]
	v_cvt_pk_bf16_f32 v26, v30, v31
	v_add_co_u32_e32 v30, vcc, s43, v190
	v_pk_fma_f32 v[32:33], v[32:33], v[144:145], v[36:37]
	s_nop 0
	v_addc_co_u32_e32 v31, vcc, 0, v191, vcc
	v_cvt_pk_bf16_f32 v27, v32, v33
	v_cvt_pk_bf16_f32 v28, v28, v29
	v_cvt_pk_bf16_f32 v29, v34, v35
	global_store_dwordx4 v[30:31], v[26:29], off
	s_waitcnt vmcnt(15)
	v_lshlrev_b32_e32 v32, 16, v156
	v_and_b32_e32 v33, 0xffff0000, v156
	v_lshlrev_b32_e32 v26, 16, v154
	v_and_b32_e32 v27, 0xffff0000, v154
	v_lshlrev_b32_e32 v28, 16, v155
	v_and_b32_e32 v29, 0xffff0000, v155
	v_lshlrev_b32_e32 v34, 16, v157
	v_and_b32_e32 v35, 0xffff0000, v157
	v_pk_fma_f32 v[24:25], v[24:25], v[136:137], v[28:29]
	v_pk_fma_f32 v[22:23], v[22:23], v[134:135], v[26:27]
	v_pk_fma_f32 v[26:27], v[20:21], v[132:133], v[34:35]
	v_pk_fma_f32 v[20:21], v[18:19], v[130:131], v[32:33]
	v_cvt_pk_bf16_f32 v18, v22, v23
	v_cvt_pk_bf16_f32 v19, v24, v25
	s_waitcnt vmcnt(14)
	v_lshlrev_b32_e32 v22, 16, v152
	v_cvt_pk_bf16_f32 v20, v20, v21
	v_cvt_pk_bf16_f32 v21, v26, v27
	global_store_dwordx4 v[30:31], v[18:21], off offset:256
	v_and_b32_e32 v23, 0xffff0000, v152
	v_lshlrev_b32_e32 v24, 16, v153
	v_lshlrev_b32_e32 v18, 16, v150
	v_and_b32_e32 v19, 0xffff0000, v150
	v_and_b32_e32 v25, 0xffff0000, v153
	v_pk_fma_f32 v[14:15], v[14:15], v[142:143], v[18:19]
	v_lshlrev_b32_e32 v20, 16, v151
	v_and_b32_e32 v21, 0xffff0000, v151
	v_pk_fma_f32 v[18:19], v[12:13], v[140:141], v[24:25]
	v_pk_fma_f32 v[12:13], v[10:11], v[138:139], v[22:23]
	v_cvt_pk_bf16_f32 v10, v14, v15
	v_add_co_u32_e32 v14, vcc, s45, v190
	v_pk_fma_f32 v[16:17], v[16:17], v[144:145], v[20:21]
	s_nop 0
	v_addc_co_u32_e32 v15, vcc, 0, v191, vcc
	v_cvt_pk_bf16_f32 v11, v16, v17
	v_cvt_pk_bf16_f32 v12, v12, v13
	v_cvt_pk_bf16_f32 v13, v18, v19
	global_store_dwordx4 v[14:15], v[10:13], off
	s_waitcnt vmcnt(15)
	v_lshlrev_b32_e32 v16, 16, v148
	v_and_b32_e32 v17, 0xffff0000, v148
	v_lshlrev_b32_e32 v10, 16, v146
	v_and_b32_e32 v11, 0xffff0000, v146
	v_lshlrev_b32_e32 v18, 16, v149
	v_and_b32_e32 v19, 0xffff0000, v149
	v_lshlrev_b32_e32 v12, 16, v147
	v_and_b32_e32 v13, 0xffff0000, v147
	v_pk_fma_f32 v[6:7], v[6:7], v[134:135], v[10:11]
	v_pk_fma_f32 v[10:11], v[4:5], v[132:133], v[18:19]
	v_pk_fma_f32 v[4:5], v[2:3], v[130:131], v[16:17]
	s_and_b64 vcc, exec, s[4:5]
	v_pk_fma_f32 v[8:9], v[8:9], v[136:137], v[12:13]
	v_cvt_pk_bf16_f32 v2, v6, v7
	s_nop 0
	v_cvt_pk_bf16_f32 v3, v8, v9
	v_cvt_pk_bf16_f32 v4, v4, v5
	v_cvt_pk_bf16_f32 v5, v10, v11
	global_store_dwordx4 v[14:15], v[2:5], off offset:256
	s_cbranch_vccnz .LBB0_2830

.LBB0_2827:
	ds_read_b128 v[130:133], v196
	ds_read_b128 v[134:137], v196 offset:1024
	ds_read_b128 v[138:141], v196 offset:2048
	ds_read_b128 v[142:145], v196 offset:3072
	s_add_i32 s10, s7, 0xfffa0080
	s_cmp_eq_u32 s13, 12
	s_cselect_b32 s78, s6, s10
	s_cselect_b32 s73, s57, s12
	s_or_b32 s79, s78, 0x80
	s_add_i32 s10, s7, 0xfffe0000
	s_mov_b32 m0, s38
	ds_read_b128 v[146:149], v197
	ds_read_b128 v[150:153], v197 offset:1024
	ds_read_b128 v[154:157], v197 offset:2048
	ds_read_b128 v[158:161], v197 offset:3072
	ds_read_b128 v[162:165], v197 offset:4096
	ds_read_b128 v[166:169], v197 offset:5120
	ds_read_b128 v[170:173], v197 offset:6144
	ds_read_b128 v[174:177], v197 offset:7168
	buffer_load_dwordx4 v192, s[48:51], s10 offen lds
	s_mov_b32 m0, s39
	s_nop 0
	buffer_load_dwordx4 v192, s[48:51], s7 offen lds
	s_waitcnt lgkmcnt(8)
	s_barrier
	s_waitcnt lgkmcnt(0)
	s_setprio 1
	s_waitcnt lgkmcnt(7)
	v_mfma_f32_16x16x32_bf16 v[126:129], v[130:133], v[146:149], v[126:129]
	v_mfma_f32_16x16x32_bf16 v[122:125], v[138:141], v[146:149], v[122:125]
	s_waitcnt lgkmcnt(5)
	v_mfma_f32_16x16x32_bf16 v[110:113], v[130:133], v[154:157], v[110:113]
	v_mfma_f32_16x16x32_bf16 v[106:109], v[138:141], v[154:157], v[106:109]
	s_waitcnt lgkmcnt(3)
	v_mfma_f32_16x16x32_bf16 v[94:97], v[130:133], v[162:165], v[94:97]
	v_mfma_f32_16x16x32_bf16 v[90:93], v[138:141], v[162:165], v[90:93]
	s_waitcnt lgkmcnt(1)
	v_mfma_f32_16x16x32_bf16 v[78:81], v[130:133], v[170:173], v[78:81]
	v_mfma_f32_16x16x32_bf16 v[74:77], v[138:141], v[170:173], v[74:77]
	v_mfma_f32_16x16x32_bf16 v[126:129], v[134:137], v[150:153], v[126:129]
	v_mfma_f32_16x16x32_bf16 v[122:125], v[142:145], v[150:153], v[122:125]
	v_mfma_f32_16x16x32_bf16 v[110:113], v[134:137], v[158:161], v[110:113]
	v_mfma_f32_16x16x32_bf16 v[106:109], v[142:145], v[158:161], v[106:109]
	v_mfma_f32_16x16x32_bf16 v[94:97], v[134:137], v[166:169], v[94:97]
	v_mfma_f32_16x16x32_bf16 v[90:93], v[142:145], v[166:169], v[90:93]
	s_waitcnt lgkmcnt(0)
	v_mfma_f32_16x16x32_bf16 v[78:81], v[134:137], v[174:177], v[78:81]
	v_mfma_f32_16x16x32_bf16 v[74:77], v[142:145], v[174:177], v[74:77]
	s_setprio 0
	s_barrier
	s_mov_b32 m0, s16
	s_mov_b32 s10, s50
	s_mov_b32 s11, s51
	ds_read_b128 v[178:181], v198
	ds_read_b128 v[182:185], v198 offset:1024
	ds_read_b128 v[202:205], v198 offset:2048
	ds_read_b128 v[206:209], v198 offset:3072
	buffer_load_dwordx4 v193, s[8:11], s73 offen lds
	s_add_i32 s33, s73, 0x20000
	s_mov_b32 m0, s17
	s_nop 0
	buffer_load_dwordx4 v193, s[8:11], s33 offen lds
	s_barrier
	s_waitcnt lgkmcnt(0)
	s_setprio 1
	s_waitcnt lgkmcnt(3)
	v_mfma_f32_16x16x32_bf16 v[118:121], v[178:181], v[146:149], v[118:121]
	s_waitcnt lgkmcnt(1)
	v_mfma_f32_16x16x32_bf16 v[114:117], v[202:205], v[146:149], v[114:117]
	v_mfma_f32_16x16x32_bf16 v[102:105], v[178:181], v[154:157], v[102:105]
	v_mfma_f32_16x16x32_bf16 v[98:101], v[202:205], v[154:157], v[98:101]
	v_mfma_f32_16x16x32_bf16 v[86:89], v[178:181], v[162:165], v[86:89]
	v_mfma_f32_16x16x32_bf16 v[82:85], v[202:205], v[162:165], v[82:85]
	v_mfma_f32_16x16x32_bf16 v[70:73], v[178:181], v[170:173], v[70:73]
	v_mfma_f32_16x16x32_bf16 v[66:69], v[202:205], v[170:173], v[66:69]
	v_mfma_f32_16x16x32_bf16 v[118:121], v[182:185], v[150:153], v[118:121]
	s_waitcnt lgkmcnt(0)
	v_mfma_f32_16x16x32_bf16 v[114:117], v[206:209], v[150:153], v[114:117]
	v_mfma_f32_16x16x32_bf16 v[102:105], v[182:185], v[158:161], v[102:105]
	v_mfma_f32_16x16x32_bf16 v[98:101], v[206:209], v[158:161], v[98:101]
	v_mfma_f32_16x16x32_bf16 v[86:89], v[182:185], v[166:169], v[86:89]
	v_mfma_f32_16x16x32_bf16 v[82:85], v[206:209], v[166:169], v[82:85]
	v_mfma_f32_16x16x32_bf16 v[70:73], v[182:185], v[174:177], v[70:73]
	v_mfma_f32_16x16x32_bf16 v[66:69], v[206:209], v[174:177], v[66:69]
	s_setprio 0
	s_mov_b32 m0, s15
	s_barrier
	ds_read_b128 v[146:149], v197 offset:16384
	ds_read_b128 v[150:153], v197 offset:17408
	ds_read_b128 v[154:157], v197 offset:18432
	ds_read_b128 v[158:161], v197 offset:19456
	ds_read_b128 v[162:165], v197 offset:20480
	ds_read_b128 v[166:169], v197 offset:21504
	ds_read_b128 v[170:173], v197 offset:22528
	ds_read_b128 v[174:177], v197 offset:23552
	buffer_load_dwordx4 v192, s[48:51], s78 offen lds
	s_add_i32 s33, s78, 0x20000
	s_mov_b32 m0, s18
	s_nop 0
	buffer_load_dwordx4 v192, s[48:51], s33 offen lds
	s_barrier
	s_waitcnt lgkmcnt(0)
	s_setprio 1
	s_waitcnt lgkmcnt(7)
	v_mfma_f32_16x16x32_bf16 v[62:65], v[130:133], v[146:149], v[62:65]
	v_mfma_f32_16x16x32_bf16 v[58:61], v[138:141], v[146:149], v[58:61]
	s_waitcnt lgkmcnt(5)
	v_mfma_f32_16x16x32_bf16 v[46:49], v[130:133], v[154:157], v[46:49]
	v_mfma_f32_16x16x32_bf16 v[42:45], v[138:141], v[154:157], v[42:45]
	s_waitcnt lgkmcnt(3)
	v_mfma_f32_16x16x32_bf16 v[30:33], v[130:133], v[162:165], v[30:33]
	v_mfma_f32_16x16x32_bf16 v[26:29], v[138:141], v[162:165], v[26:29]
	s_waitcnt lgkmcnt(1)
	v_mfma_f32_16x16x32_bf16 v[14:17], v[130:133], v[170:173], v[14:17]
	v_mfma_f32_16x16x32_bf16 v[10:13], v[138:141], v[170:173], v[10:13]
	v_mfma_f32_16x16x32_bf16 v[62:65], v[134:137], v[150:153], v[62:65]
	v_mfma_f32_16x16x32_bf16 v[58:61], v[142:145], v[150:153], v[58:61]
	v_mfma_f32_16x16x32_bf16 v[46:49], v[134:137], v[158:161], v[46:49]
	v_mfma_f32_16x16x32_bf16 v[42:45], v[142:145], v[158:161], v[42:45]
	v_mfma_f32_16x16x32_bf16 v[30:33], v[134:137], v[166:169], v[30:33]
	v_mfma_f32_16x16x32_bf16 v[26:29], v[142:145], v[166:169], v[26:29]
	s_waitcnt lgkmcnt(0)
	v_mfma_f32_16x16x32_bf16 v[14:17], v[134:137], v[174:177], v[14:17]
	v_mfma_f32_16x16x32_bf16 v[10:13], v[142:145], v[174:177], v[10:13]
	s_setprio 0
	s_barrier
	s_mov_b32 m0, s19
	s_add_i32 s33, s73, 0x40000
	buffer_load_dwordx4 v193, s[8:11], s33 offen lds
	s_add_i32 s33, s73, 0x60000
	s_mov_b32 m0, s20
	s_nop 0
	buffer_load_dwordx4 v193, s[8:11], s33 offen lds
	s_waitcnt vmcnt(6)
	s_barrier
	s_setprio 1
	v_mfma_f32_16x16x32_bf16 v[54:57], v[178:181], v[146:149], v[54:57]
	v_mfma_f32_16x16x32_bf16 v[50:53], v[202:205], v[146:149], v[50:53]
	v_mfma_f32_16x16x32_bf16 v[38:41], v[178:181], v[154:157], v[38:41]
	v_mfma_f32_16x16x32_bf16 v[34:37], v[202:205], v[154:157], v[34:37]
	v_mfma_f32_16x16x32_bf16 v[22:25], v[178:181], v[162:165], v[22:25]
	v_mfma_f32_16x16x32_bf16 v[18:21], v[202:205], v[162:165], v[18:21]
	v_mfma_f32_16x16x32_bf16 v[6:9], v[178:181], v[170:173], v[6:9]
	v_mfma_f32_16x16x32_bf16 v[2:5], v[202:205], v[170:173], v[2:5]
	v_mfma_f32_16x16x32_bf16 v[54:57], v[182:185], v[150:153], v[54:57]
	v_mfma_f32_16x16x32_bf16 v[50:53], v[206:209], v[150:153], v[50:53]
	v_mfma_f32_16x16x32_bf16 v[38:41], v[182:185], v[158:161], v[38:41]
	v_mfma_f32_16x16x32_bf16 v[34:37], v[206:209], v[158:161], v[34:37]
	v_mfma_f32_16x16x32_bf16 v[22:25], v[182:185], v[166:169], v[22:25]
	v_mfma_f32_16x16x32_bf16 v[18:21], v[206:209], v[166:169], v[18:21]
	v_mfma_f32_16x16x32_bf16 v[6:9], v[182:185], v[174:177], v[6:9]
	v_mfma_f32_16x16x32_bf16 v[2:5], v[206:209], v[174:177], v[2:5]
	s_setprio 0
	s_barrier
	ds_read_b128 v[130:133], v199
	ds_read_b128 v[134:137], v199 offset:1024
	ds_read_b128 v[138:141], v199 offset:2048
	ds_read_b128 v[142:145], v199 offset:3072
	s_mov_b32 m0, s21
	s_add_i32 s33, s78, 0x40000
	ds_read_b128 v[146:149], v197 offset:32768
	ds_read_b128 v[150:153], v197 offset:33792
	ds_read_b128 v[154:157], v197 offset:34816
	ds_read_b128 v[158:161], v197 offset:35840
	ds_read_b128 v[162:165], v197 offset:36864
	ds_read_b128 v[166:169], v197 offset:37888
	ds_read_b128 v[170:173], v197 offset:38912
	ds_read_b128 v[174:177], v197 offset:39936
	buffer_load_dwordx4 v192, s[48:51], s33 offen lds
	s_add_i32 s33, s78, 0x60000
	s_mov_b32 m0, s22
	s_nop 0
	buffer_load_dwordx4 v192, s[48:51], s33 offen lds
	s_waitcnt lgkmcnt(8)
	s_barrier
	s_waitcnt lgkmcnt(0)
	s_setprio 1
	s_waitcnt lgkmcnt(7)
	v_mfma_f32_16x16x32_bf16 v[126:129], v[130:133], v[146:149], v[126:129]
	v_mfma_f32_16x16x32_bf16 v[122:125], v[138:141], v[146:149], v[122:125]
	s_waitcnt lgkmcnt(5)
	v_mfma_f32_16x16x32_bf16 v[110:113], v[130:133], v[154:157], v[110:113]
	v_mfma_f32_16x16x32_bf16 v[106:109], v[138:141], v[154:157], v[106:109]
	s_waitcnt lgkmcnt(3)
	v_mfma_f32_16x16x32_bf16 v[94:97], v[130:133], v[162:165], v[94:97]
	v_mfma_f32_16x16x32_bf16 v[90:93], v[138:141], v[162:165], v[90:93]
	s_waitcnt lgkmcnt(1)
	v_mfma_f32_16x16x32_bf16 v[78:81], v[130:133], v[170:173], v[78:81]
	v_mfma_f32_16x16x32_bf16 v[74:77], v[138:141], v[170:173], v[74:77]
	v_mfma_f32_16x16x32_bf16 v[126:129], v[134:137], v[150:153], v[126:129]
	v_mfma_f32_16x16x32_bf16 v[122:125], v[142:145], v[150:153], v[122:125]
	v_mfma_f32_16x16x32_bf16 v[110:113], v[134:137], v[158:161], v[110:113]
	v_mfma_f32_16x16x32_bf16 v[106:109], v[142:145], v[158:161], v[106:109]
	v_mfma_f32_16x16x32_bf16 v[94:97], v[134:137], v[166:169], v[94:97]
	v_mfma_f32_16x16x32_bf16 v[90:93], v[142:145], v[166:169], v[90:93]
	s_waitcnt lgkmcnt(0)
	v_mfma_f32_16x16x32_bf16 v[78:81], v[134:137], v[174:177], v[78:81]
	v_mfma_f32_16x16x32_bf16 v[74:77], v[142:145], v[174:177], v[74:77]
	s_setprio 0
	s_barrier
	s_mov_b32 m0, s28
	s_add_i32 s33, s73, 0x80
	ds_read_b128 v[178:181], v200
	ds_read_b128 v[182:185], v200 offset:1024
	ds_read_b128 v[202:205], v200 offset:2048
	ds_read_b128 v[206:209], v200 offset:3072
	buffer_load_dwordx4 v193, s[8:11], s33 offen lds
	s_add_i32 s33, s73, 0x20080
	s_mov_b32 m0, s29
	s_nop 0
	buffer_load_dwordx4 v193, s[8:11], s33 offen lds
	s_barrier
	s_waitcnt lgkmcnt(0)
	s_setprio 1
	s_waitcnt lgkmcnt(3)
	v_mfma_f32_16x16x32_bf16 v[118:121], v[178:181], v[146:149], v[118:121]
	s_waitcnt lgkmcnt(1)
	v_mfma_f32_16x16x32_bf16 v[114:117], v[202:205], v[146:149], v[114:117]
	v_mfma_f32_16x16x32_bf16 v[102:105], v[178:181], v[154:157], v[102:105]
	v_mfma_f32_16x16x32_bf16 v[98:101], v[202:205], v[154:157], v[98:101]
	v_mfma_f32_16x16x32_bf16 v[86:89], v[178:181], v[162:165], v[86:89]
	v_mfma_f32_16x16x32_bf16 v[82:85], v[202:205], v[162:165], v[82:85]
	v_mfma_f32_16x16x32_bf16 v[70:73], v[178:181], v[170:173], v[70:73]
	v_mfma_f32_16x16x32_bf16 v[66:69], v[202:205], v[170:173], v[66:69]
	v_mfma_f32_16x16x32_bf16 v[118:121], v[182:185], v[150:153], v[118:121]
	s_waitcnt lgkmcnt(0)
	v_mfma_f32_16x16x32_bf16 v[114:117], v[206:209], v[150:153], v[114:117]
	v_mfma_f32_16x16x32_bf16 v[102:105], v[182:185], v[158:161], v[102:105]
	v_mfma_f32_16x16x32_bf16 v[98:101], v[206:209], v[158:161], v[98:101]
	v_mfma_f32_16x16x32_bf16 v[86:89], v[182:185], v[166:169], v[86:89]
	v_mfma_f32_16x16x32_bf16 v[82:85], v[206:209], v[166:169], v[82:85]
	v_mfma_f32_16x16x32_bf16 v[70:73], v[182:185], v[174:177], v[70:73]
	v_mfma_f32_16x16x32_bf16 v[66:69], v[206:209], v[174:177], v[66:69]
	s_setprio 0
	s_mov_b32 m0, s30
	s_barrier
	ds_read_b128 v[146:149], v197 offset:49152
	ds_read_b128 v[150:153], v197 offset:50176
	ds_read_b128 v[154:157], v197 offset:51200
	ds_read_b128 v[158:161], v197 offset:52224
	ds_read_b128 v[162:165], v197 offset:53248
	ds_read_b128 v[166:169], v197 offset:54272
	ds_read_b128 v[170:173], v197 offset:55296
	ds_read_b128 v[174:177], v197 offset:56320
	buffer_load_dwordx4 v192, s[48:51], s79 offen lds
	s_add_i32 s78, s78, 0x20080
	s_mov_b32 m0, s31
	s_nop 0
	buffer_load_dwordx4 v192, s[48:51], s78 offen lds
	s_barrier
	s_waitcnt lgkmcnt(0)
	s_setprio 1
	s_waitcnt lgkmcnt(7)
	v_mfma_f32_16x16x32_bf16 v[62:65], v[130:133], v[146:149], v[62:65]
	v_mfma_f32_16x16x32_bf16 v[58:61], v[138:141], v[146:149], v[58:61]
	s_waitcnt lgkmcnt(5)
	v_mfma_f32_16x16x32_bf16 v[46:49], v[130:133], v[154:157], v[46:49]
	v_mfma_f32_16x16x32_bf16 v[42:45], v[138:141], v[154:157], v[42:45]
	s_waitcnt lgkmcnt(3)
	v_mfma_f32_16x16x32_bf16 v[30:33], v[130:133], v[162:165], v[30:33]
	v_mfma_f32_16x16x32_bf16 v[26:29], v[138:141], v[162:165], v[26:29]
	s_waitcnt lgkmcnt(1)
	v_mfma_f32_16x16x32_bf16 v[14:17], v[130:133], v[170:173], v[14:17]
	v_mfma_f32_16x16x32_bf16 v[10:13], v[138:141], v[170:173], v[10:13]
	v_mfma_f32_16x16x32_bf16 v[62:65], v[134:137], v[150:153], v[62:65]
	v_mfma_f32_16x16x32_bf16 v[58:61], v[142:145], v[150:153], v[58:61]
	v_mfma_f32_16x16x32_bf16 v[46:49], v[134:137], v[158:161], v[46:49]
	v_mfma_f32_16x16x32_bf16 v[42:45], v[142:145], v[158:161], v[42:45]
	v_mfma_f32_16x16x32_bf16 v[30:33], v[134:137], v[166:169], v[30:33]
	v_mfma_f32_16x16x32_bf16 v[26:29], v[142:145], v[166:169], v[26:29]
	s_waitcnt lgkmcnt(0)
	v_mfma_f32_16x16x32_bf16 v[14:17], v[134:137], v[174:177], v[14:17]
	v_mfma_f32_16x16x32_bf16 v[10:13], v[142:145], v[174:177], v[10:13]
	s_setprio 0
	s_barrier
	s_mov_b32 m0, s34
	s_add_i32 s33, s73, 0x40080
	buffer_load_dwordx4 v193, s[8:11], s33 offen lds
	s_add_i32 s73, s73, 0x60080
	s_mov_b32 m0, s35
	s_nop 0
	buffer_load_dwordx4 v193, s[8:11], s73 offen lds
	s_waitcnt vmcnt(6)
	s_barrier
	s_setprio 1
	v_mfma_f32_16x16x32_bf16 v[54:57], v[178:181], v[146:149], v[54:57]
	v_mfma_f32_16x16x32_bf16 v[50:53], v[202:205], v[146:149], v[50:53]
	v_mfma_f32_16x16x32_bf16 v[38:41], v[178:181], v[154:157], v[38:41]
	v_mfma_f32_16x16x32_bf16 v[34:37], v[202:205], v[154:157], v[34:37]
	v_mfma_f32_16x16x32_bf16 v[22:25], v[178:181], v[162:165], v[22:25]
	v_mfma_f32_16x16x32_bf16 v[18:21], v[202:205], v[162:165], v[18:21]
	v_mfma_f32_16x16x32_bf16 v[6:9], v[178:181], v[170:173], v[6:9]
	v_mfma_f32_16x16x32_bf16 v[2:5], v[202:205], v[170:173], v[2:5]
	v_mfma_f32_16x16x32_bf16 v[54:57], v[182:185], v[150:153], v[54:57]
	v_mfma_f32_16x16x32_bf16 v[50:53], v[206:209], v[150:153], v[50:53]
	v_mfma_f32_16x16x32_bf16 v[38:41], v[182:185], v[158:161], v[38:41]
	v_mfma_f32_16x16x32_bf16 v[34:37], v[206:209], v[158:161], v[34:37]
	v_mfma_f32_16x16x32_bf16 v[22:25], v[182:185], v[166:169], v[22:25]
	v_mfma_f32_16x16x32_bf16 v[18:21], v[206:209], v[166:169], v[18:21]
	v_mfma_f32_16x16x32_bf16 v[6:9], v[182:185], v[174:177], v[6:9]
	v_mfma_f32_16x16x32_bf16 v[2:5], v[206:209], v[174:177], v[2:5]
	s_setprio 0
	s_add_i32 s13, s13, 2
	s_addk_i32 s7, 0x100
	s_addk_i32 s12, 0x100
	s_cmp_gt_u32 s13, 13
	s_barrier
	s_cbranch_scc0 .LBB0_2827
	s_cmpk_gt_i32 s59, 0x7f
	s_cselect_b64 s[6:7], -1, 0
	s_and_b64 vcc, exec, s[6:7]
	s_cbranch_vccz .LBB0_2816
	s_mov_b64 s[10:11], 0xc000
	s_mov_b64 s[12:13], 0xcb00000
	s_branch .LBB0_2817

.LBB0_3096:
	s_ashr_i32 s7, s7, 3
	s_add_u32 s12, s52, 0x2b00000
	s_addc_u32 s8, s53, 0
	s_add_i32 s6, s6, s7
	s_ashr_i32 s7, s6, 31
	s_lshr_b32 s7, s7, 26
	s_add_i32 s7, s6, s7
	v_ashrrev_i32_e32 v3, 31, v4
	s_ashr_i32 s9, s7, 6
	s_andn2_b32 s7, s7, 63
	v_lshrrev_b32_e32 v3, 26, v3
	s_sub_i32 s6, s6, s7
	v_add_u32_e32 v3, v4, v3
	s_bfe_i32 s7, s6, 0x80000
	v_ashrrev_i32_e32 v5, 6, v3
	v_bfe_i32 v3, v4, 27, 1
	s_bfe_u32 s7, s7, 0x3000c
	v_lshlrev_b32_e32 v2, 4, v4
	v_lshrrev_b32_e32 v3, 22, v3
	s_add_i32 s7, s6, s7
	v_add_u32_e32 v3, v2, v3
	s_bfe_i32 s10, s7, 0x80000
	s_and_b32 s7, s7, 0xf8
	v_and_b32_e32 v3, 0xfffffc00, v3
	s_sub_i32 s6, s6, s7
	v_sub_u32_e32 v2, v2, v3
	s_lshl_b32 s9, s9, 3
	s_sext_i32_i8 s6, s6
	v_lshrrev_b32_e32 v3, 4, v2
	s_add_i32 s47, s9, s6
	v_bitop3_b32 v8, v3, v2, 32 bitop3:0x6c
	s_ashr_i32 s6, s47, 31
	v_ashrrev_i32_e32 v3, 31, v8
	s_lshr_b32 s6, s6, 28
	v_readlane_b32 s14, v255, 8
	v_lshrrev_b32_e32 v3, 26, v3
	s_sext_i32_i16 s10, s10
	s_add_i32 s9, s47, s6
	s_lshl_b32 s6, s47, 8
	s_ashr_i32 s4, s3, 6
	v_readlane_b32 s15, v255, 9
	v_lshlrev_b32_e32 v2, 3, v5
	v_add_u32_e32 v9, v8, v3
	s_ashr_i32 s46, s10, 3
	s_ashr_i32 s7, s6, 31
	s_and_b32 s41, s15, 0xffff
	v_and_b32_e32 v2, -16, v2
	v_ashrrev_i32_e32 v10, 6, v9
	s_ashr_i32 s5, s3, 8
	s_and_b32 s13, s8, 0xffff
	s_lshl_b32 s8, s4, 10
	s_lshl_b32 s10, s46, 18
	s_lshl_b64 s[6:7], s[6:7], 2
	v_add_u32_e32 v2, v10, v2
	s_add_u32 s6, s74, s6
	s_addc_u32 s7, s75, s7
	v_ashrrev_i32_e32 v3, 31, v2
	v_lshl_add_u64 v[6:7], v[2:3], 2, s[6:7]
	global_load_dword v11, v[6:7], off
	global_load_dword v12, v[6:7], off offset:512
	global_load_dword v13, v[6:7], off offset:768
	global_load_dword v14, v[6:7], off offset:256
	v_and_b32_e32 v7, 0xc0, v9
	v_mov_b32_e32 v6, 1
	v_sub_u32_e32 v7, v8, v7
	s_mov_b32 s6, 0x3fffe0
	v_lshlrev_b32_e32 v5, 5, v5
	v_and_b32_e32 v8, 3, v10
	v_ashrrev_i16_sdwa v6, v6, sext(v7) dst_sel:DWORD dst_unused:UNUSED_PAD src0_sel:DWORD src1_sel:BYTE_0
	v_lshlrev_b32_e32 v7, 1, v2
	v_lshrrev_b32_e32 v9, 2, v2
	v_and_b32_e32 v5, 32, v5
	v_and_or_b32 v8, v2, s6, v8
	v_bfe_i32 v6, v6, 0, 16
	v_and_b32_e32 v7, 24, v7
	v_and_b32_e32 v9, 4, v9
	s_lshl_b32 s6, s9, 17
	s_add_i32 s16, s8, 0
	s_mov_b32 s43, 0x20000
	s_brev_b32 s42, -2
	v_or3_b32 v7, v8, v9, v7
	v_add_lshl_u32 v184, v5, v6, 1
	s_and_b32 s6, s6, 0xffe00000
	s_add_i32 s17, s16, 0x10000
	s_mov_b32 s14, s42
	s_mov_b32 s15, s43
	v_lshl_add_u32 v185, v7, 10, v184
	s_add_i32 s18, s16, 0x12000
	s_add_i32 s50, s6, s10
	s_mov_b32 m0, s17
	s_or_b32 s6, s50, 0x10000
	buffer_load_dwordx4 v185, s[12:15], s50 offen lds
	s_mov_b32 m0, s18
	s_add_i32 s19, s16, 0x2000
	buffer_load_dwordx4 v185, s[12:15], s6 offen lds
	s_mov_b32 m0, s16
	s_add_i32 s20, s16, 0x14000
	s_or_b32 s6, s50, 0x20000
	s_add_i32 s21, s16, 0x16000
	s_add_i32 s22, s16, 0x4000
	s_add_i32 s23, s16, 0x6000
	s_mov_b32 s24, 0
	s_waitcnt vmcnt(5)
	v_lshlrev_b32_e32 v5, 10, v11
	v_and_b32_e32 v5, 0x3fffc00, v5
	s_waitcnt vmcnt(4)
	v_lshl_or_b32 v187, v12, 16, v11
	s_waitcnt vmcnt(2)
	v_lshlrev_b32_e32 v6, 10, v14
	v_and_b32_e32 v7, 0x3fffc00, v6
	v_add_u32_e32 v6, v5, v184
	v_add_u32_e32 v5, v7, v184
	buffer_load_dwordx4 v6, s[40:43], 0 offen lds
	s_mov_b32 m0, s19
	v_bfe_u32 v7, v187, 16, 16
	buffer_load_dwordx4 v5, s[40:43], 0 offen lds
	s_mov_b32 m0, s20
	v_lshl_or_b32 v186, v13, 16, v14
	buffer_load_dwordx4 v185, s[12:15], s6 offen lds
	s_or_b32 s6, s50, 0x30000
	s_mov_b32 m0, s21
	v_lshl_add_u32 v7, v7, 10, v184
	buffer_load_dwordx4 v185, s[12:15], s6 offen lds
	s_mov_b32 m0, s22
	s_cmp_lg_u32 s5, 1
	buffer_load_dwordx4 v7, s[40:43], 0 offen lds
	v_bfe_u32 v7, v186, 16, 16
	v_lshl_add_u32 v7, v7, 10, v184
	s_mov_b32 m0, s23
	s_nop 0
	buffer_load_dwordx4 v7, s[40:43], 0 offen lds
	s_cbranch_scc1 .LBB0_3098
	s_barrier

.LBB0_3099:
	v_mov_b32_e32 v218, 0xbd38aa3b
	v_mov_b32_e32 v219, 0xbd38aa3b
	v_mov_b32_e32 v220, 0x44800000
	v_mov_b32_e32 v221, 0x44800000
	v_lshl_add_u32 v222, s47, 8, v188
	v_lshl_or_b32 v224, s46, 7, v189
	s_nop 0
	v_lshl_add_u32 v222, v222, 10, v224
	s_mov_b32 s46, s38
	s_mov_b32 s47, s39
	s_mov_b32 s50, s45
	v_pk_mul_f32 v[226:227], v[174:175], v[218:219]
	v_pk_mul_f32 v[228:229], v[176:177], v[218:219]
	v_pk_mul_f32 v[230:231], v[166:167], v[218:219]
	v_pk_mul_f32 v[232:233], v[168:169], v[218:219]
	v_exp_f32_e32 v226, v226
	v_exp_f32_e32 v227, v227
	v_exp_f32_e32 v228, v228
	v_exp_f32_e32 v229, v229
	v_exp_f32_e32 v230, v230
	v_exp_f32_e32 v231, v231
	v_exp_f32_e32 v232, v232
	v_exp_f32_e32 v233, v233
	v_pk_fma_f32 v[226:227], v[226:227], v[220:221], v[220:221]
	v_pk_fma_f32 v[228:229], v[228:229], v[220:221], v[220:221]
	v_pk_fma_f32 v[230:231], v[230:231], v[220:221], v[220:221]
	v_pk_fma_f32 v[232:233], v[232:233], v[220:221], v[220:221]
	v_rcp_f32_e32 v226, v226
	v_rcp_f32_e32 v227, v227
	v_rcp_f32_e32 v228, v228
	v_rcp_f32_e32 v229, v229
	v_rcp_f32_e32 v230, v230
	v_rcp_f32_e32 v231, v231
	v_rcp_f32_e32 v232, v232
	v_rcp_f32_e32 v233, v233
	v_pk_mul_f32 v[174:175], v[174:175], v[170:171]
	v_pk_mul_f32 v[176:177], v[176:177], v[172:173]
	v_pk_mul_f32 v[166:167], v[166:167], v[162:163]
	v_pk_mul_f32 v[168:169], v[168:169], v[164:165]
	v_pk_mul_f32 v[174:175], v[174:175], v[226:227]
	v_pk_mul_f32 v[176:177], v[176:177], v[228:229]
	v_pk_mul_f32 v[166:167], v[166:167], v[230:231]
	v_pk_mul_f32 v[168:169], v[168:169], v[232:233]
	v_mov_b32_e32 v223, v222
	v_cvt_pk_fp8_f32 v234, v174, v175
	v_cvt_pk_fp8_f32 v235, v166, v167
	v_cvt_pk_fp8_f32 v234, v176, v177 op_sel:[0,0,1]
	v_cvt_pk_fp8_f32 v235, v168, v169 op_sel:[0,0,1]
	s_nop 0
	global_store_dwordx2 v223, v[234:235], s[70:71]
	v_pk_mul_f32 v[226:227], v[158:159], v[218:219]
	v_pk_mul_f32 v[228:229], v[160:161], v[218:219]
	v_pk_mul_f32 v[230:231], v[150:151], v[218:219]
	v_pk_mul_f32 v[232:233], v[152:153], v[218:219]
	v_exp_f32_e32 v226, v226
	v_exp_f32_e32 v227, v227
	v_exp_f32_e32 v228, v228
	v_exp_f32_e32 v229, v229
	v_exp_f32_e32 v230, v230
	v_exp_f32_e32 v231, v231
	v_exp_f32_e32 v232, v232
	v_exp_f32_e32 v233, v233
	v_pk_fma_f32 v[226:227], v[226:227], v[220:221], v[220:221]
	v_pk_fma_f32 v[228:229], v[228:229], v[220:221], v[220:221]
	v_pk_fma_f32 v[230:231], v[230:231], v[220:221], v[220:221]
	v_pk_fma_f32 v[232:233], v[232:233], v[220:221], v[220:221]
	v_rcp_f32_e32 v226, v226
	v_rcp_f32_e32 v227, v227
	v_rcp_f32_e32 v228, v228
	v_rcp_f32_e32 v229, v229
	v_rcp_f32_e32 v230, v230
	v_rcp_f32_e32 v231, v231
	v_rcp_f32_e32 v232, v232
	v_rcp_f32_e32 v233, v233
	v_pk_mul_f32 v[158:159], v[158:159], v[154:155]
	v_pk_mul_f32 v[160:161], v[160:161], v[156:157]
	v_pk_mul_f32 v[150:151], v[150:151], v[146:147]
	v_pk_mul_f32 v[152:153], v[152:153], v[148:149]
	v_pk_mul_f32 v[158:159], v[158:159], v[226:227]
	v_pk_mul_f32 v[160:161], v[160:161], v[228:229]
	v_pk_mul_f32 v[150:151], v[150:151], v[230:231]
	v_pk_mul_f32 v[152:153], v[152:153], v[232:233]
	v_add_u32_e32 v225, 0x4000, v222
	v_cvt_pk_fp8_f32 v236, v158, v159
	v_cvt_pk_fp8_f32 v237, v150, v151
	v_cvt_pk_fp8_f32 v236, v160, v161 op_sel:[0,0,1]
	v_cvt_pk_fp8_f32 v237, v152, v153 op_sel:[0,0,1]
	s_nop 0
	global_store_dwordx2 v225, v[236:237], s[70:71]
	v_pk_mul_f32 v[226:227], v[142:143], v[218:219]
	v_pk_mul_f32 v[228:229], v[144:145], v[218:219]
	v_pk_mul_f32 v[230:231], v[134:135], v[218:219]
	v_pk_mul_f32 v[232:233], v[136:137], v[218:219]
	v_exp_f32_e32 v226, v226
	v_exp_f32_e32 v227, v227
	v_exp_f32_e32 v228, v228
	v_exp_f32_e32 v229, v229
	v_exp_f32_e32 v230, v230
	v_exp_f32_e32 v231, v231
	v_exp_f32_e32 v232, v232
	v_exp_f32_e32 v233, v233
	v_pk_fma_f32 v[226:227], v[226:227], v[220:221], v[220:221]
	v_pk_fma_f32 v[228:229], v[228:229], v[220:221], v[220:221]
	v_pk_fma_f32 v[230:231], v[230:231], v[220:221], v[220:221]
	v_pk_fma_f32 v[232:233], v[232:233], v[220:221], v[220:221]
	v_rcp_f32_e32 v226, v226
	v_rcp_f32_e32 v227, v227
	v_rcp_f32_e32 v228, v228
	v_rcp_f32_e32 v229, v229
	v_rcp_f32_e32 v230, v230
	v_rcp_f32_e32 v231, v231
	v_rcp_f32_e32 v232, v232
	v_rcp_f32_e32 v233, v233
	v_pk_mul_f32 v[142:143], v[142:143], v[138:139]
	v_pk_mul_f32 v[144:145], v[144:145], v[140:141]
	v_pk_mul_f32 v[134:135], v[134:135], v[130:131]
	v_pk_mul_f32 v[136:137], v[136:137], v[132:133]
	v_pk_mul_f32 v[142:143], v[142:143], v[226:227]
	v_pk_mul_f32 v[144:145], v[144:145], v[228:229]
	v_pk_mul_f32 v[134:135], v[134:135], v[230:231]
	v_pk_mul_f32 v[136:137], v[136:137], v[232:233]
	v_add_u32_e32 v223, 0x8000, v222
	v_cvt_pk_fp8_f32 v234, v142, v143
	v_cvt_pk_fp8_f32 v235, v134, v135
	v_cvt_pk_fp8_f32 v234, v144, v145 op_sel:[0,0,1]
	v_cvt_pk_fp8_f32 v235, v136, v137 op_sel:[0,0,1]
	s_nop 0
	global_store_dwordx2 v223, v[234:235], s[70:71]
	v_pk_mul_f32 v[226:227], v[126:127], v[218:219]
	v_pk_mul_f32 v[228:229], v[128:129], v[218:219]
	v_pk_mul_f32 v[230:231], v[118:119], v[218:219]
	v_pk_mul_f32 v[232:233], v[120:121], v[218:219]
	v_exp_f32_e32 v226, v226
	v_exp_f32_e32 v227, v227
	v_exp_f32_e32 v228, v228
	v_exp_f32_e32 v229, v229
	v_exp_f32_e32 v230, v230
	v_exp_f32_e32 v231, v231
	v_exp_f32_e32 v232, v232
	v_exp_f32_e32 v233, v233
	v_pk_fma_f32 v[226:227], v[226:227], v[220:221], v[220:221]
	v_pk_fma_f32 v[228:229], v[228:229], v[220:221], v[220:221]
	v_pk_fma_f32 v[230:231], v[230:231], v[220:221], v[220:221]
	v_pk_fma_f32 v[232:233], v[232:233], v[220:221], v[220:221]
	v_rcp_f32_e32 v226, v226
	v_rcp_f32_e32 v227, v227
	v_rcp_f32_e32 v228, v228
	v_rcp_f32_e32 v229, v229
	v_rcp_f32_e32 v230, v230
	v_rcp_f32_e32 v231, v231
	v_rcp_f32_e32 v232, v232
	v_rcp_f32_e32 v233, v233
	v_pk_mul_f32 v[126:127], v[126:127], v[122:123]
	v_pk_mul_f32 v[128:129], v[128:129], v[124:125]
	v_pk_mul_f32 v[118:119], v[118:119], v[114:115]
	v_pk_mul_f32 v[120:121], v[120:121], v[116:117]
	v_pk_mul_f32 v[126:127], v[126:127], v[226:227]
	v_pk_mul_f32 v[128:129], v[128:129], v[228:229]
	v_pk_mul_f32 v[118:119], v[118:119], v[230:231]
	v_pk_mul_f32 v[120:121], v[120:121], v[232:233]
	v_add_u32_e32 v225, 0xc000, v222
	v_cvt_pk_fp8_f32 v236, v126, v127
	v_cvt_pk_fp8_f32 v237, v118, v119
	v_cvt_pk_fp8_f32 v236, v128, v129 op_sel:[0,0,1]
	v_cvt_pk_fp8_f32 v237, v120, v121 op_sel:[0,0,1]
	s_nop 0
	global_store_dwordx2 v225, v[236:237], s[70:71]
	v_pk_mul_f32 v[226:227], v[110:111], v[218:219]
	v_pk_mul_f32 v[228:229], v[112:113], v[218:219]
	v_pk_mul_f32 v[230:231], v[102:103], v[218:219]
	v_pk_mul_f32 v[232:233], v[104:105], v[218:219]
	v_exp_f32_e32 v226, v226
	v_exp_f32_e32 v227, v227
	v_exp_f32_e32 v228, v228
	v_exp_f32_e32 v229, v229
	v_exp_f32_e32 v230, v230
	v_exp_f32_e32 v231, v231
	v_exp_f32_e32 v232, v232
	v_exp_f32_e32 v233, v233
	v_pk_fma_f32 v[226:227], v[226:227], v[220:221], v[220:221]
	v_pk_fma_f32 v[228:229], v[228:229], v[220:221], v[220:221]
	v_pk_fma_f32 v[230:231], v[230:231], v[220:221], v[220:221]
	v_pk_fma_f32 v[232:233], v[232:233], v[220:221], v[220:221]
	v_rcp_f32_e32 v226, v226
	v_rcp_f32_e32 v227, v227
	v_rcp_f32_e32 v228, v228
	v_rcp_f32_e32 v229, v229
	v_rcp_f32_e32 v230, v230
	v_rcp_f32_e32 v231, v231
	v_rcp_f32_e32 v232, v232
	v_rcp_f32_e32 v233, v233
	v_pk_mul_f32 v[110:111], v[110:111], v[106:107]
	v_pk_mul_f32 v[112:113], v[112:113], v[108:109]
	v_pk_mul_f32 v[102:103], v[102:103], v[98:99]
	v_pk_mul_f32 v[104:105], v[104:105], v[100:101]
	v_pk_mul_f32 v[110:111], v[110:111], v[226:227]
	v_pk_mul_f32 v[112:113], v[112:113], v[228:229]
	v_pk_mul_f32 v[102:103], v[102:103], v[230:231]
	v_pk_mul_f32 v[104:105], v[104:105], v[232:233]
	v_add_u32_e32 v223, 0x20000, v222
	v_cvt_pk_fp8_f32 v234, v110, v111
	v_cvt_pk_fp8_f32 v235, v102, v103
	v_cvt_pk_fp8_f32 v234, v112, v113 op_sel:[0,0,1]
	v_cvt_pk_fp8_f32 v235, v104, v105 op_sel:[0,0,1]
	s_nop 0
	global_store_dwordx2 v223, v[234:235], s[70:71]
	v_pk_mul_f32 v[226:227], v[94:95], v[218:219]
	v_pk_mul_f32 v[228:229], v[96:97], v[218:219]
	v_pk_mul_f32 v[230:231], v[86:87], v[218:219]
	v_pk_mul_f32 v[232:233], v[88:89], v[218:219]
	v_exp_f32_e32 v226, v226
	v_exp_f32_e32 v227, v227
	v_exp_f32_e32 v228, v228
	v_exp_f32_e32 v229, v229
	v_exp_f32_e32 v230, v230
	v_exp_f32_e32 v231, v231
	v_exp_f32_e32 v232, v232
	v_exp_f32_e32 v233, v233
	v_pk_fma_f32 v[226:227], v[226:227], v[220:221], v[220:221]
	v_pk_fma_f32 v[228:229], v[228:229], v[220:221], v[220:221]
	v_pk_fma_f32 v[230:231], v[230:231], v[220:221], v[220:221]
	v_pk_fma_f32 v[232:233], v[232:233], v[220:221], v[220:221]
	v_rcp_f32_e32 v226, v226
	v_rcp_f32_e32 v227, v227
	v_rcp_f32_e32 v228, v228
	v_rcp_f32_e32 v229, v229
	v_rcp_f32_e32 v230, v230
	v_rcp_f32_e32 v231, v231
	v_rcp_f32_e32 v232, v232
	v_rcp_f32_e32 v233, v233
	v_pk_mul_f32 v[94:95], v[94:95], v[90:91]
	v_pk_mul_f32 v[96:97], v[96:97], v[92:93]
	v_pk_mul_f32 v[86:87], v[86:87], v[82:83]
	v_pk_mul_f32 v[88:89], v[88:89], v[84:85]
	v_pk_mul_f32 v[94:95], v[94:95], v[226:227]
	v_pk_mul_f32 v[96:97], v[96:97], v[228:229]
	v_pk_mul_f32 v[86:87], v[86:87], v[230:231]
	v_pk_mul_f32 v[88:89], v[88:89], v[232:233]
	v_add_u32_e32 v225, 0x24000, v222
	v_cvt_pk_fp8_f32 v236, v94, v95
	v_cvt_pk_fp8_f32 v237, v86, v87
	v_cvt_pk_fp8_f32 v236, v96, v97 op_sel:[0,0,1]
	v_cvt_pk_fp8_f32 v237, v88, v89 op_sel:[0,0,1]
	s_nop 0
	global_store_dwordx2 v225, v[236:237], s[70:71]
	v_pk_mul_f32 v[226:227], v[78:79], v[218:219]
	v_pk_mul_f32 v[228:229], v[80:81], v[218:219]
	v_pk_mul_f32 v[230:231], v[70:71], v[218:219]
	v_pk_mul_f32 v[232:233], v[72:73], v[218:219]
	v_exp_f32_e32 v226, v226
	v_exp_f32_e32 v227, v227
	v_exp_f32_e32 v228, v228
	v_exp_f32_e32 v229, v229
	v_exp_f32_e32 v230, v230
	v_exp_f32_e32 v231, v231
	v_exp_f32_e32 v232, v232
	v_exp_f32_e32 v233, v233
	v_pk_fma_f32 v[226:227], v[226:227], v[220:221], v[220:221]
	v_pk_fma_f32 v[228:229], v[228:229], v[220:221], v[220:221]
	v_pk_fma_f32 v[230:231], v[230:231], v[220:221], v[220:221]
	v_pk_fma_f32 v[232:233], v[232:233], v[220:221], v[220:221]
	v_rcp_f32_e32 v226, v226
	v_rcp_f32_e32 v227, v227
	v_rcp_f32_e32 v228, v228
	v_rcp_f32_e32 v229, v229
	v_rcp_f32_e32 v230, v230
	v_rcp_f32_e32 v231, v231
	v_rcp_f32_e32 v232, v232
	v_rcp_f32_e32 v233, v233
	v_pk_mul_f32 v[78:79], v[78:79], v[74:75]
	v_pk_mul_f32 v[80:81], v[80:81], v[76:77]
	v_pk_mul_f32 v[70:71], v[70:71], v[66:67]
	v_pk_mul_f32 v[72:73], v[72:73], v[68:69]
	v_pk_mul_f32 v[78:79], v[78:79], v[226:227]
	v_pk_mul_f32 v[80:81], v[80:81], v[228:229]
	v_pk_mul_f32 v[70:71], v[70:71], v[230:231]
	v_pk_mul_f32 v[72:73], v[72:73], v[232:233]
	v_add_u32_e32 v223, 0x28000, v222
	v_cvt_pk_fp8_f32 v234, v78, v79
	v_cvt_pk_fp8_f32 v235, v70, v71
	v_cvt_pk_fp8_f32 v234, v80, v81 op_sel:[0,0,1]
	v_cvt_pk_fp8_f32 v235, v72, v73 op_sel:[0,0,1]
	s_nop 0
	global_store_dwordx2 v223, v[234:235], s[70:71]
	v_pk_mul_f32 v[226:227], v[62:63], v[218:219]
	v_pk_mul_f32 v[228:229], v[64:65], v[218:219]
	v_pk_mul_f32 v[230:231], v[54:55], v[218:219]
	v_pk_mul_f32 v[232:233], v[56:57], v[218:219]
	v_exp_f32_e32 v226, v226
	v_exp_f32_e32 v227, v227
	v_exp_f32_e32 v228, v228
	v_exp_f32_e32 v229, v229
	v_exp_f32_e32 v230, v230
	v_exp_f32_e32 v231, v231
	v_exp_f32_e32 v232, v232
	v_exp_f32_e32 v233, v233
	v_pk_fma_f32 v[226:227], v[226:227], v[220:221], v[220:221]
	v_pk_fma_f32 v[228:229], v[228:229], v[220:221], v[220:221]
	v_pk_fma_f32 v[230:231], v[230:231], v[220:221], v[220:221]
	v_pk_fma_f32 v[232:233], v[232:233], v[220:221], v[220:221]
	v_rcp_f32_e32 v226, v226
	v_rcp_f32_e32 v227, v227
	v_rcp_f32_e32 v228, v228
	v_rcp_f32_e32 v229, v229
	v_rcp_f32_e32 v230, v230
	v_rcp_f32_e32 v231, v231
	v_rcp_f32_e32 v232, v232
	v_rcp_f32_e32 v233, v233
	v_pk_mul_f32 v[62:63], v[62:63], v[58:59]
	v_pk_mul_f32 v[64:65], v[64:65], v[60:61]
	v_pk_mul_f32 v[54:55], v[54:55], v[50:51]
	v_pk_mul_f32 v[56:57], v[56:57], v[52:53]
	v_pk_mul_f32 v[62:63], v[62:63], v[226:227]
	v_pk_mul_f32 v[64:65], v[64:65], v[228:229]
	v_pk_mul_f32 v[54:55], v[54:55], v[230:231]
	v_pk_mul_f32 v[56:57], v[56:57], v[232:233]
	v_add_u32_e32 v225, 0x2c000, v222
	v_cvt_pk_fp8_f32 v236, v62, v63
	v_cvt_pk_fp8_f32 v237, v54, v55
	v_cvt_pk_fp8_f32 v236, v64, v65 op_sel:[0,0,1]
	v_cvt_pk_fp8_f32 v237, v56, v57 op_sel:[0,0,1]
	s_nop 0
	global_store_dwordx2 v225, v[236:237], s[70:71]
	s_and_b64 vcc, exec, s[4:5]
	s_cbranch_vccnz .LBB0_3114

.LBB0_3111:
	s_and_b64 s[14:15], s[6:7], exec
	s_cselect_b32 s57, 0, s9
	s_add_i32 s14, s50, s9
	s_or_b32 s51, s57, 0x80
	s_waitcnt lgkmcnt(8)
	s_barrier
	s_waitcnt lgkmcnt(0)
	s_and_b64 s[6:7], s[6:7], exec
	s_cselect_b32 s6, s45, s14
	s_add_i32 s7, s6, 0x80
	s_setprio 1
	s_waitcnt lgkmcnt(6)
	v_mfma_f32_16x16x128_f8f6f4 v[174:177], v[2:9], v[42:49], v[174:177]
	v_mfma_f32_16x16x128_f8f6f4 v[166:169], v[10:17], v[42:49], v[166:169]
	s_waitcnt lgkmcnt(4)
	v_mfma_f32_16x16x128_f8f6f4 v[158:161], v[2:9], v[34:41], v[158:161]
	v_mfma_f32_16x16x128_f8f6f4 v[150:153], v[10:17], v[34:41], v[150:153]
	s_waitcnt lgkmcnt(2)
	v_mfma_f32_16x16x128_f8f6f4 v[142:145], v[2:9], v[26:33], v[142:145]
	v_mfma_f32_16x16x128_f8f6f4 v[134:137], v[10:17], v[26:33], v[134:137]
	s_waitcnt lgkmcnt(0)
	v_mfma_f32_16x16x128_f8f6f4 v[126:129], v[2:9], v[18:25], v[126:129]
	v_mfma_f32_16x16x128_f8f6f4 v[118:121], v[10:17], v[18:25], v[118:121]
	s_setprio 0
	s_barrier
	s_mov_b32 m0, s17
	v_add_u32_e32 v199, 0x14000, v190
	s_mov_b32 s14, s42
	s_mov_b32 s15, s43
	ds_read_b128 v[200:203], v199
	ds_read_b128 v[204:207], v199 offset:1024
	ds_read_b128 v[208:211], v199 offset:2048
	ds_read_b128 v[212:215], v199 offset:3072
	buffer_load_dwordx4 v185, s[12:15], s6 offen lds
	s_add_i32 s33, s6, 0x10000
	s_mov_b32 m0, s18
	s_nop 0
	buffer_load_dwordx4 v185, s[12:15], s33 offen lds
	s_barrier
	s_waitcnt lgkmcnt(0)
	s_setprio 1
	s_waitcnt lgkmcnt(2)
	v_mfma_f32_16x16x128_f8f6f4 v[170:173], v[200:207], v[42:49], v[170:173]
	s_waitcnt lgkmcnt(0)
	v_mfma_f32_16x16x128_f8f6f4 v[162:165], v[208:215], v[42:49], v[162:165]
	v_mfma_f32_16x16x128_f8f6f4 v[154:157], v[200:207], v[34:41], v[154:157]
	v_mfma_f32_16x16x128_f8f6f4 v[146:149], v[208:215], v[34:41], v[146:149]
	v_mfma_f32_16x16x128_f8f6f4 v[138:141], v[200:207], v[26:33], v[138:141]
	v_mfma_f32_16x16x128_f8f6f4 v[130:133], v[208:215], v[26:33], v[130:133]
	v_mfma_f32_16x16x128_f8f6f4 v[122:125], v[200:207], v[18:25], v[122:125]
	v_mfma_f32_16x16x128_f8f6f4 v[114:117], v[208:215], v[18:25], v[114:117]
	s_setprio 0
	v_lshlrev_b32_e32 v199, 10, v187
	v_and_b32_e32 v199, 0x3fffc00, v199
	v_add_u32_e32 v216, v199, v184
	v_lshlrev_b32_e32 v199, 10, v186
	s_mov_b32 m0, s16
	v_and_b32_e32 v199, 0x3fffc00, v199
	s_barrier
	ds_read_b128 v[18:21], v192 offset:16384
	ds_read_b128 v[22:25], v192 offset:17408
	ds_read_b128 v[26:29], v192 offset:18432
	ds_read_b128 v[30:33], v192 offset:19456
	ds_read_b128 v[34:37], v192 offset:20480
	ds_read_b128 v[38:41], v192 offset:21504
	ds_read_b128 v[42:45], v192 offset:22528
	ds_read_b128 v[46:49], v192 offset:23552
	buffer_load_dwordx4 v216, s[40:43], s57 offen lds
	v_add_u32_e32 v217, v199, v184
	s_mov_b32 m0, s19
	s_nop 0
	buffer_load_dwordx4 v217, s[40:43], s57 offen lds
	s_barrier
	s_waitcnt lgkmcnt(0)
	s_setprio 1
	s_waitcnt lgkmcnt(6)
	v_mfma_f32_16x16x128_f8f6f4 v[110:113], v[2:9], v[18:25], v[110:113]
	v_mfma_f32_16x16x128_f8f6f4 v[102:105], v[10:17], v[18:25], v[102:105]
	s_waitcnt lgkmcnt(4)
	v_mfma_f32_16x16x128_f8f6f4 v[94:97], v[2:9], v[26:33], v[94:97]
	v_mfma_f32_16x16x128_f8f6f4 v[86:89], v[10:17], v[26:33], v[86:89]
	s_waitcnt lgkmcnt(2)
	v_mfma_f32_16x16x128_f8f6f4 v[78:81], v[2:9], v[34:41], v[78:81]
	v_mfma_f32_16x16x128_f8f6f4 v[70:73], v[10:17], v[34:41], v[70:73]
	s_waitcnt lgkmcnt(0)
	v_mfma_f32_16x16x128_f8f6f4 v[62:65], v[2:9], v[42:49], v[62:65]
	v_mfma_f32_16x16x128_f8f6f4 v[54:57], v[10:17], v[42:49], v[54:57]
	s_setprio 0
	s_barrier
	s_mov_b32 m0, s20
	s_add_i32 s33, s6, 0x20000
	buffer_load_dwordx4 v185, s[12:15], s33 offen lds
	s_add_i32 s33, s6, 0x30000
	s_mov_b32 m0, s21
	s_nop 0
	buffer_load_dwordx4 v185, s[12:15], s33 offen lds
	s_waitcnt vmcnt(6)
	s_barrier
	s_setprio 1
	v_mfma_f32_16x16x128_f8f6f4 v[106:109], v[200:207], v[18:25], v[106:109]
	v_mfma_f32_16x16x128_f8f6f4 v[98:101], v[208:215], v[18:25], v[98:101]
	v_mfma_f32_16x16x128_f8f6f4 v[90:93], v[200:207], v[26:33], v[90:93]
	v_mfma_f32_16x16x128_f8f6f4 v[82:85], v[208:215], v[26:33], v[82:85]
	v_mfma_f32_16x16x128_f8f6f4 v[74:77], v[200:207], v[34:41], v[74:77]
	v_mfma_f32_16x16x128_f8f6f4 v[66:69], v[208:215], v[34:41], v[66:69]
	v_mfma_f32_16x16x128_f8f6f4 v[58:61], v[200:207], v[42:49], v[58:61]
	v_mfma_f32_16x16x128_f8f6f4 v[50:53], v[208:215], v[42:49], v[50:53]
	s_setprio 0
	v_add_u32_e32 v14, 0x18000, v190
	s_barrier
	ds_read_b128 v[2:5], v14
	ds_read_b128 v[6:9], v14 offset:1024
	ds_read_b128 v[10:13], v14 offset:2048
	ds_read_b128 v[14:17], v14 offset:3072
	s_mov_b32 m0, s22
	ds_read_b128 v[18:21], v192 offset:32768
	ds_read_b128 v[22:25], v192 offset:33792
	ds_read_b128 v[26:29], v192 offset:34816
	ds_read_b128 v[30:33], v192 offset:35840
	ds_read_b128 v[34:37], v192 offset:36864
	ds_read_b128 v[38:41], v192 offset:37888
	ds_read_b128 v[42:45], v192 offset:38912
	ds_read_b128 v[46:49], v192 offset:39936
	buffer_load_dwordx4 v197, s[40:43], s57 offen lds
	s_mov_b32 m0, s23
	s_nop 0
	buffer_load_dwordx4 v198, s[40:43], s57 offen lds
	s_waitcnt lgkmcnt(8)
	s_barrier
	s_waitcnt lgkmcnt(0)
	s_setprio 1
	s_waitcnt lgkmcnt(6)
	v_mfma_f32_16x16x128_f8f6f4 v[174:177], v[2:9], v[18:25], v[174:177]
	v_mfma_f32_16x16x128_f8f6f4 v[166:169], v[10:17], v[18:25], v[166:169]
	s_waitcnt lgkmcnt(4)
	v_mfma_f32_16x16x128_f8f6f4 v[158:161], v[2:9], v[26:33], v[158:161]
	v_mfma_f32_16x16x128_f8f6f4 v[150:153], v[10:17], v[26:33], v[150:153]
	s_waitcnt lgkmcnt(2)
	v_mfma_f32_16x16x128_f8f6f4 v[142:145], v[2:9], v[34:41], v[142:145]
	v_mfma_f32_16x16x128_f8f6f4 v[134:137], v[10:17], v[34:41], v[134:137]
	s_waitcnt lgkmcnt(0)
	v_mfma_f32_16x16x128_f8f6f4 v[126:129], v[2:9], v[42:49], v[126:129]
	v_mfma_f32_16x16x128_f8f6f4 v[118:121], v[10:17], v[42:49], v[118:121]
	s_setprio 0
	s_barrier
	s_mov_b32 m0, s25
	v_add_u32_e32 v197, 0x1c000, v190
	ds_read_b128 v[198:201], v197
	ds_read_b128 v[202:205], v197 offset:1024
	ds_read_b128 v[206:209], v197 offset:2048
	ds_read_b128 v[210:213], v197 offset:3072
	buffer_load_dwordx4 v185, s[12:15], s7 offen lds
	s_add_i32 s7, s6, 0x10080
	s_mov_b32 m0, s26
	s_nop 0
	buffer_load_dwordx4 v185, s[12:15], s7 offen lds
	s_barrier
	s_waitcnt lgkmcnt(0)
	s_setprio 1
	s_waitcnt lgkmcnt(2)
	v_mfma_f32_16x16x128_f8f6f4 v[170:173], v[198:205], v[18:25], v[170:173]
	s_waitcnt lgkmcnt(0)
	v_mfma_f32_16x16x128_f8f6f4 v[162:165], v[206:213], v[18:25], v[162:165]
	v_mfma_f32_16x16x128_f8f6f4 v[154:157], v[198:205], v[26:33], v[154:157]
	v_mfma_f32_16x16x128_f8f6f4 v[146:149], v[206:213], v[26:33], v[146:149]
	v_mfma_f32_16x16x128_f8f6f4 v[138:141], v[198:205], v[34:41], v[138:141]
	v_mfma_f32_16x16x128_f8f6f4 v[130:133], v[206:213], v[34:41], v[130:133]
	v_mfma_f32_16x16x128_f8f6f4 v[122:125], v[198:205], v[42:49], v[122:125]
	v_mfma_f32_16x16x128_f8f6f4 v[114:117], v[206:213], v[42:49], v[114:117]
	s_setprio 0
	s_mov_b32 m0, s27
	s_barrier
	ds_read_b128 v[18:21], v192 offset:49152
	ds_read_b128 v[22:25], v192 offset:50176
	ds_read_b128 v[26:29], v192 offset:51200
	ds_read_b128 v[30:33], v192 offset:52224
	ds_read_b128 v[34:37], v192 offset:53248
	ds_read_b128 v[38:41], v192 offset:54272
	ds_read_b128 v[42:45], v192 offset:55296
	ds_read_b128 v[46:49], v192 offset:56320
	buffer_load_dwordx4 v216, s[40:43], s51 offen lds
	s_mov_b32 m0, s28
	s_nop 0
	buffer_load_dwordx4 v217, s[40:43], s51 offen lds
	s_barrier
	s_waitcnt lgkmcnt(0)
	s_setprio 1
	s_waitcnt lgkmcnt(6)
	v_mfma_f32_16x16x128_f8f6f4 v[110:113], v[2:9], v[18:25], v[110:113]
	v_mfma_f32_16x16x128_f8f6f4 v[102:105], v[10:17], v[18:25], v[102:105]
	s_waitcnt lgkmcnt(4)
	v_mfma_f32_16x16x128_f8f6f4 v[94:97], v[2:9], v[26:33], v[94:97]
	v_mfma_f32_16x16x128_f8f6f4 v[86:89], v[10:17], v[26:33], v[86:89]
	s_waitcnt lgkmcnt(2)
	v_mfma_f32_16x16x128_f8f6f4 v[78:81], v[2:9], v[34:41], v[78:81]
	v_mfma_f32_16x16x128_f8f6f4 v[70:73], v[10:17], v[34:41], v[70:73]
	s_waitcnt lgkmcnt(0)
	v_mfma_f32_16x16x128_f8f6f4 v[62:65], v[2:9], v[42:49], v[62:65]
	v_mfma_f32_16x16x128_f8f6f4 v[54:57], v[10:17], v[42:49], v[54:57]
	s_setprio 0
	s_barrier
	s_mov_b32 m0, s29
	s_add_i32 s7, s6, 0x20080
	buffer_load_dwordx4 v185, s[12:15], s7 offen lds
	s_add_i32 s6, s6, 0x30080
	s_mov_b32 m0, s30
	s_nop 0
	buffer_load_dwordx4 v185, s[12:15], s6 offen lds
	s_waitcnt vmcnt(6)
	s_barrier
	s_setprio 1
	v_mfma_f32_16x16x128_f8f6f4 v[106:109], v[198:205], v[18:25], v[106:109]
	v_mfma_f32_16x16x128_f8f6f4 v[98:101], v[206:213], v[18:25], v[98:101]
	v_mfma_f32_16x16x128_f8f6f4 v[90:93], v[198:205], v[26:33], v[90:93]
	v_mfma_f32_16x16x128_f8f6f4 v[82:85], v[206:213], v[26:33], v[82:85]
	v_mfma_f32_16x16x128_f8f6f4 v[74:77], v[198:205], v[34:41], v[74:77]
	v_mfma_f32_16x16x128_f8f6f4 v[66:69], v[206:213], v[34:41], v[66:69]
	v_mfma_f32_16x16x128_f8f6f4 v[58:61], v[198:205], v[42:49], v[58:61]
	v_mfma_f32_16x16x128_f8f6f4 v[50:53], v[206:213], v[42:49], v[50:53]
	s_setprio 0
	s_add_i32 s8, s8, 2
	s_addk_i32 s9, 0x100
	s_cmp_gt_u32 s8, 5
	s_barrier
	s_cbranch_scc1 .LBB0_3099

.LBB0_3173:
	s_add_u32 s8, s52, 0x6b00000
	s_addc_u32 s7, s53, 0
	s_add_i32 s5, s6, s5
	s_ashr_i32 s6, s5, 31
	s_lshr_b32 s6, s6, 27
	v_bfe_i32 v5, v2, 27, 1
	s_add_i32 s6, s5, s6
	v_lshlrev_b32_e32 v3, 4, v2
	v_lshrrev_b32_e32 v5, 22, v5
	s_ashr_i32 s12, s6, 5
	s_and_b32 s6, s6, 0xffe0
	v_add_u32_e32 v5, v3, v5
	s_sub_i32 s5, s5, s6
	v_and_b32_e32 v5, 0xfffffc00, v5
	s_bfe_i32 s6, s5, 0x80000
	v_sub_u32_e32 v3, v3, v5
	s_bfe_u32 s6, s6, 0x3000c
	v_ashrrev_i32_e32 v4, 31, v2
	v_lshrrev_b32_e32 v5, 4, v3
	s_add_i32 s6, s5, s6
	v_lshrrev_b32_e32 v4, 26, v4
	v_bitop3_b32 v3, v5, v3, 32 bitop3:0x6c
	s_bfe_i32 s13, s6, 0x80000
	s_and_b32 s6, s6, 0xf8
	v_add_u32_e32 v4, v2, v4
	v_ashrrev_i32_e32 v6, 31, v3
	s_sub_i32 s5, s5, s6
	v_ashrrev_i32_e32 v4, 6, v4
	v_lshrrev_b32_e32 v6, 26, v6
	s_lshl_b32 s12, s12, 3
	s_sext_i32_i8 s5, s5
	v_lshlrev_b32_e32 v5, 3, v4
	v_add_u32_e32 v6, v3, v6
	s_add_i32 s70, s12, s5
	v_and_b32_e32 v5, -16, v5
	v_ashrrev_i32_e32 v7, 6, v6
	v_and_b32_e32 v6, 0xc0, v6
	s_ashr_i32 s5, s70, 31
	s_ashr_i32 s4, s3, 6
	v_add_u32_e32 v5, v7, v5
	v_sub_u32_e32 v3, v3, v6
	v_mov_b32_e32 v6, 1
	v_and_b32_e32 v7, 3, v7
	s_mov_b32 s9, 0x3fffe0
	s_lshr_b32 s5, s5, 28
	v_lshlrev_b32_e32 v4, 5, v4
	v_ashrrev_i16_sdwa v3, v6, sext(v3) dst_sel:DWORD dst_unused:UNUSED_PAD src0_sel:DWORD src1_sel:BYTE_0
	v_lshlrev_b32_e32 v6, 1, v5
	v_lshrrev_b32_e32 v8, 2, v5
	v_and_or_b32 v7, v5, s9, v7
	s_and_b32 s9, s7, 0xffff
	s_lshl_b32 s7, s4, 10
	s_sext_i32_i16 s13, s13
	s_add_i32 s5, s70, s5
	v_and_b32_e32 v4, 32, v4
	v_bfe_i32 v3, v3, 0, 16
	v_and_b32_e32 v6, 24, v6
	v_and_b32_e32 v8, 4, v8
	s_ashr_i32 s59, s13, 3
	s_lshl_b32 s5, s5, 16
	s_add_i32 s21, s7, 0
	s_mov_b32 s47, 0x20000
	s_brev_b32 s46, -2
	v_or3_b32 v6, v7, v8, v6
	v_add_lshl_u32 v3, v4, v3, 1
	s_and_b32 s5, s5, 0xfff00000
	s_lshl_b32 s6, s59, 18
	s_add_i32 s22, s21, 0x10000
	s_and_b32 s45, s71, 0xffff
	v_lshl_add_u32 v135, v6, 10, v3
	s_mov_b32 s10, s46
	s_mov_b32 s11, s47
	s_add_i32 s71, s5, s6
	s_mov_b32 m0, s22
	s_add_i32 s23, s21, 0x12000
	buffer_load_dwordx4 v135, s[8:11], s71 offen lds
	s_or_b32 s5, s71, 0x10000
	s_mov_b32 m0, s23
	v_lshl_add_u32 v134, v5, 10, v3
	buffer_load_dwordx4 v135, s[8:11], s5 offen lds
	s_lshl_b32 s72, s70, 18
	s_mov_b32 m0, s21
	s_add_i32 s24, s21, 0x2000
	buffer_load_dwordx4 v134, s[44:47], s72 offen lds
	s_or_b32 s5, s72, 0x10000
	s_mov_b32 m0, s24
	s_add_i32 s25, s21, 0x14000
	buffer_load_dwordx4 v134, s[44:47], s5 offen lds
	s_or_b32 s5, s71, 0x20000
	s_mov_b32 m0, s25
	s_add_i32 s26, s21, 0x16000
	buffer_load_dwordx4 v135, s[8:11], s5 offen lds
	s_or_b32 s5, s71, 0x30000
	s_mov_b32 m0, s26
	s_add_i32 s27, s21, 0x4000
	buffer_load_dwordx4 v135, s[8:11], s5 offen lds
	s_or_b32 s5, s72, 0x20000
	s_mov_b32 m0, s27
	s_add_i32 s28, s21, 0x6000
	buffer_load_dwordx4 v134, s[44:47], s5 offen lds
	s_or_b32 s5, s72, 0x30000
	s_mov_b32 m0, s28
	s_mov_b32 s29, 0
	buffer_load_dwordx4 v134, s[44:47], s5 offen lds
	s_ashr_i32 s5, s3, 8
	s_cmp_lg_u32 s5, 1
	s_cbranch_scc1 .LBB0_3175
	s_barrier

.LBB0_3185:
	ds_read_b128 v[144:147], v138
	ds_read_b128 v[148:151], v138 offset:1024
	ds_read_b128 v[152:155], v138 offset:2048
	ds_read_b128 v[156:159], v138 offset:3072
	s_add_i32 s10, s7, 0xfffd0080
	s_cmp_eq_u32 s72, 4
	s_cselect_b32 s74, s6, s10
	s_cselect_b32 s73, s57, s71
	s_or_b32 s75, s74, 0x80
	s_add_i32 s10, s7, 0xffff0000
	s_mov_b32 m0, s38
	ds_read_b128 v[160:163], v139
	ds_read_b128 v[164:167], v139 offset:1024
	ds_read_b128 v[168:171], v139 offset:2048
	ds_read_b128 v[172:175], v139 offset:3072
	ds_read_b128 v[176:179], v139 offset:4096
	ds_read_b128 v[180:183], v139 offset:5120
	ds_read_b128 v[184:187], v139 offset:6144
	ds_read_b128 v[188:191], v139 offset:7168
	buffer_load_dwordx4 v134, s[44:47], s10 offen lds
	s_mov_b32 m0, s39
	s_nop 0
	buffer_load_dwordx4 v134, s[44:47], s7 offen lds
	s_waitcnt lgkmcnt(8)
	s_barrier
	s_waitcnt lgkmcnt(0)
	s_setprio 1
	s_waitcnt lgkmcnt(4)
	v_mfma_f32_16x16x128_f8f6f4 v[114:117], v[144:151], v[168:175], v[114:117]
	v_mfma_f32_16x16x128_f8f6f4 v[106:109], v[152:159], v[168:175], v[106:109]
	s_waitcnt lgkmcnt(2)
	v_mfma_f32_16x16x128_f8f6f4 v[98:101], v[144:151], v[176:183], v[98:101]
	v_mfma_f32_16x16x128_f8f6f4 v[200:203], v[144:151], v[160:167], v[126:129]
	v_mfma_f32_16x16x128_f8f6f4 v[204:207], v[152:159], v[160:167], v[122:125]
	v_mfma_f32_16x16x128_f8f6f4 v[208:211], v[152:159], v[176:183], v[90:93]
	s_waitcnt lgkmcnt(0)
	v_mfma_f32_16x16x128_f8f6f4 v[212:215], v[144:151], v[184:191], v[82:85]
	v_mfma_f32_16x16x128_f8f6f4 v[216:219], v[152:159], v[184:191], v[74:77]
	s_setprio 0
	s_barrier
	s_mov_b32 m0, s22
	s_mov_b32 s10, s46
	s_mov_b32 s11, s47
	ds_read_b128 v[122:125], v254
	ds_read_b128 v[126:129], v254 offset:1024
	ds_read_b128 v[192:195], v254 offset:2048
	ds_read_b128 v[196:199], v254 offset:3072
	buffer_load_dwordx4 v135, s[8:11], s73 offen lds
	s_add_i32 s33, s73, 0x10000
	s_mov_b32 m0, s23
	s_nop 0
	buffer_load_dwordx4 v135, s[8:11], s33 offen lds
	s_barrier
	s_waitcnt lgkmcnt(0)
	s_setprio 1
	s_waitcnt lgkmcnt(2)
	v_mfma_f32_16x16x128_f8f6f4 v[118:121], v[122:129], v[160:167], v[118:121]
	s_waitcnt lgkmcnt(0)
	v_mfma_f32_16x16x128_f8f6f4 v[110:113], v[192:199], v[160:167], v[110:113]
	v_mfma_f32_16x16x128_f8f6f4 v[102:105], v[122:129], v[168:175], v[102:105]
	v_mfma_f32_16x16x128_f8f6f4 v[160:163], v[192:199], v[168:175], v[94:97]
	v_mfma_f32_16x16x128_f8f6f4 v[164:167], v[122:129], v[176:183], v[86:89]
	v_mfma_f32_16x16x128_f8f6f4 v[168:171], v[192:199], v[176:183], v[78:81]
	v_mfma_f32_16x16x128_f8f6f4 v[172:175], v[122:129], v[184:191], v[70:73]
	v_mfma_f32_16x16x128_f8f6f4 v[176:179], v[192:199], v[184:191], v[18:21]
	s_setprio 0
	s_mov_b32 m0, s21
	s_barrier
	ds_read_b128 v[66:69], v139 offset:16384
	s_nop 1
	ds_read_b128 v[70:73], v139 offset:17408
	ds_read_b128 v[74:77], v139 offset:18432
	ds_read_b128 v[78:81], v139 offset:19456
	ds_read_b128 v[82:85], v139 offset:20480
	ds_read_b128 v[86:89], v139 offset:21504
	ds_read_b128 v[90:93], v139 offset:22528
	ds_read_b128 v[94:97], v139 offset:23552
	buffer_load_dwordx4 v134, s[44:47], s74 offen lds
	s_add_i32 s33, s74, 0x10000
	s_mov_b32 m0, s24
	s_nop 0
	buffer_load_dwordx4 v134, s[44:47], s33 offen lds
	s_barrier
	s_waitcnt lgkmcnt(0)
	s_setprio 1
	s_waitcnt lgkmcnt(6)
	v_mfma_f32_16x16x128_f8f6f4 v[62:65], v[144:151], v[66:73], v[62:65]
	v_mfma_f32_16x16x128_f8f6f4 v[58:61], v[152:159], v[66:73], v[58:61]
	s_waitcnt lgkmcnt(4)
	v_mfma_f32_16x16x128_f8f6f4 v[50:53], v[144:151], v[74:81], v[50:53]
	s_waitcnt lgkmcnt(0)
	v_mfma_f32_16x16x128_f8f6f4 v[232:235], v[144:151], v[90:97], v[232:235]
	v_mfma_f32_16x16x128_f8f6f4 v[220:223], v[152:159], v[74:81], v[42:45]
	v_mfma_f32_16x16x128_f8f6f4 v[224:227], v[144:151], v[82:89], v[34:37]
	v_mfma_f32_16x16x128_f8f6f4 v[228:231], v[152:159], v[82:89], v[26:29]
	v_mfma_f32_16x16x128_f8f6f4 v[236:239], v[152:159], v[90:97], v[10:13]
	s_setprio 0
	s_barrier
	s_mov_b32 m0, s25
	s_add_i32 s33, s73, 0x20000
	buffer_load_dwordx4 v135, s[8:11], s33 offen lds
	s_add_i32 s33, s73, 0x30000
	s_mov_b32 m0, s26
	s_nop 0
	buffer_load_dwordx4 v135, s[8:11], s33 offen lds
	s_waitcnt vmcnt(6)
	s_barrier
	s_setprio 1
	v_mfma_f32_16x16x128_f8f6f4 v[54:57], v[122:129], v[66:73], v[54:57]
	v_mfma_f32_16x16x128_f8f6f4 v[240:243], v[192:199], v[66:73], v[46:49]
	v_mfma_f32_16x16x128_f8f6f4 v[244:247], v[122:129], v[74:81], v[38:41]
	v_mfma_f32_16x16x128_f8f6f4 v[248:251], v[192:199], v[74:81], v[30:33]
	v_mfma_f32_16x16x128_f8f6f4 v[130:133], v[122:129], v[82:89], v[22:25]
	v_mfma_f32_16x16x128_f8f6f4 v[140:143], v[192:199], v[82:89], v[14:17]
	v_mfma_f32_16x16x128_f8f6f4 v[66:69], v[122:129], v[90:97], v[6:9]
	v_mfma_f32_16x16x128_f8f6f4 v[192:195], v[192:199], v[90:97], v[2:5]
	s_setprio 0
	s_barrier
	s_nop 4
	ds_read_b128 v[2:5], v252
	ds_read_b128 v[6:9], v252 offset:1024
	ds_read_b128 v[10:13], v252 offset:2048
	ds_read_b128 v[14:17], v252 offset:3072
	s_mov_b32 m0, s27
	s_add_i32 s33, s74, 0x20000
	ds_read_b128 v[18:21], v139 offset:32768
	ds_read_b128 v[22:25], v139 offset:33792
	ds_read_b128 v[26:29], v139 offset:34816
	ds_read_b128 v[30:33], v139 offset:35840
	ds_read_b128 v[34:37], v139 offset:36864
	ds_read_b128 v[38:41], v139 offset:37888
	ds_read_b128 v[42:45], v139 offset:38912
	ds_read_b128 v[46:49], v139 offset:39936
	buffer_load_dwordx4 v134, s[44:47], s33 offen lds
	s_add_i32 s33, s74, 0x30000
	s_mov_b32 m0, s28
	s_nop 0
	buffer_load_dwordx4 v134, s[44:47], s33 offen lds
	s_waitcnt lgkmcnt(8)
	s_barrier
	s_waitcnt lgkmcnt(0)
	s_setprio 1
	s_waitcnt lgkmcnt(6)
	v_mfma_f32_16x16x128_f8f6f4 v[126:129], v[2:9], v[18:25], v[200:203]
	v_mfma_f32_16x16x128_f8f6f4 v[122:125], v[10:17], v[18:25], v[204:207]
	s_waitcnt lgkmcnt(4)
	v_mfma_f32_16x16x128_f8f6f4 v[114:117], v[2:9], v[26:33], v[114:117]
	v_mfma_f32_16x16x128_f8f6f4 v[106:109], v[10:17], v[26:33], v[106:109]
	s_waitcnt lgkmcnt(2)
	v_mfma_f32_16x16x128_f8f6f4 v[98:101], v[2:9], v[34:41], v[98:101]
	v_mfma_f32_16x16x128_f8f6f4 v[90:93], v[10:17], v[34:41], v[208:211]
	s_waitcnt lgkmcnt(0)
	v_mfma_f32_16x16x128_f8f6f4 v[82:85], v[2:9], v[42:49], v[212:215]
	v_mfma_f32_16x16x128_f8f6f4 v[74:77], v[10:17], v[42:49], v[216:219]
	s_setprio 0
	s_barrier
	s_mov_b32 m0, s30
	s_add_i32 s33, s73, 0x80
	ds_read_b128 v[144:147], v253
	ds_read_b128 v[148:151], v253 offset:1024
	ds_read_b128 v[152:155], v253 offset:2048
	ds_read_b128 v[156:159], v253 offset:3072
	buffer_load_dwordx4 v135, s[8:11], s33 offen lds
	s_add_i32 s33, s73, 0x10080
	s_mov_b32 m0, s31
	s_nop 0
	buffer_load_dwordx4 v135, s[8:11], s33 offen lds
	s_barrier
	s_waitcnt lgkmcnt(0)
	s_setprio 1
	s_waitcnt lgkmcnt(2)
	v_mfma_f32_16x16x128_f8f6f4 v[118:121], v[144:151], v[18:25], v[118:121]
	s_waitcnt lgkmcnt(0)
	v_mfma_f32_16x16x128_f8f6f4 v[110:113], v[152:159], v[18:25], v[110:113]
	v_mfma_f32_16x16x128_f8f6f4 v[102:105], v[144:151], v[26:33], v[102:105]
	v_mfma_f32_16x16x128_f8f6f4 v[94:97], v[152:159], v[26:33], v[160:163]
	v_mfma_f32_16x16x128_f8f6f4 v[86:89], v[144:151], v[34:41], v[164:167]
	v_mfma_f32_16x16x128_f8f6f4 v[78:81], v[152:159], v[34:41], v[168:171]
	v_mfma_f32_16x16x128_f8f6f4 v[70:73], v[144:151], v[42:49], v[172:175]
	v_mfma_f32_16x16x128_f8f6f4 v[18:21], v[152:159], v[42:49], v[176:179]
	s_setprio 0
	s_mov_b32 m0, s34
	s_barrier
	ds_read_b128 v[160:163], v139 offset:49152
	ds_read_b128 v[164:167], v139 offset:50176
	ds_read_b128 v[168:171], v139 offset:51200
	ds_read_b128 v[172:175], v139 offset:52224
	ds_read_b128 v[176:179], v139 offset:53248
	ds_read_b128 v[180:183], v139 offset:54272
	ds_read_b128 v[184:187], v139 offset:55296
	ds_read_b128 v[188:191], v139 offset:56320
	buffer_load_dwordx4 v134, s[44:47], s75 offen lds
	s_add_i32 s74, s74, 0x10080
	s_mov_b32 m0, s35
	s_nop 0
	buffer_load_dwordx4 v134, s[44:47], s74 offen lds
	s_barrier
	s_waitcnt lgkmcnt(0)
	s_setprio 1
	s_waitcnt lgkmcnt(6)
	v_mfma_f32_16x16x128_f8f6f4 v[62:65], v[2:9], v[160:167], v[62:65]
	v_mfma_f32_16x16x128_f8f6f4 v[58:61], v[10:17], v[160:167], v[58:61]
	s_waitcnt lgkmcnt(4)
	v_mfma_f32_16x16x128_f8f6f4 v[50:53], v[2:9], v[168:175], v[50:53]
	v_mfma_f32_16x16x128_f8f6f4 v[42:45], v[10:17], v[168:175], v[220:223]
	s_waitcnt lgkmcnt(2)
	v_mfma_f32_16x16x128_f8f6f4 v[34:37], v[2:9], v[176:183], v[224:227]
	v_mfma_f32_16x16x128_f8f6f4 v[26:29], v[10:17], v[176:183], v[228:231]
	s_waitcnt lgkmcnt(0)
	v_mfma_f32_16x16x128_f8f6f4 v[232:235], v[2:9], v[184:191], v[232:235]
	v_mfma_f32_16x16x128_f8f6f4 v[10:13], v[10:17], v[184:191], v[236:239]
	s_setprio 0
	s_barrier
	s_mov_b32 m0, s36
	s_add_i32 s33, s73, 0x20080
	buffer_load_dwordx4 v135, s[8:11], s33 offen lds
	s_add_i32 s73, s73, 0x30080
	s_mov_b32 m0, s37
	s_nop 0
	buffer_load_dwordx4 v135, s[8:11], s73 offen lds
	s_waitcnt vmcnt(6)
	s_barrier
	s_setprio 1
	v_mfma_f32_16x16x128_f8f6f4 v[54:57], v[144:151], v[160:167], v[54:57]
	v_mfma_f32_16x16x128_f8f6f4 v[46:49], v[152:159], v[160:167], v[240:243]
	v_mfma_f32_16x16x128_f8f6f4 v[38:41], v[144:151], v[168:175], v[244:247]
	v_mfma_f32_16x16x128_f8f6f4 v[30:33], v[152:159], v[168:175], v[248:251]
	v_mfma_f32_16x16x128_f8f6f4 v[22:25], v[144:151], v[176:183], v[130:133]
	v_mfma_f32_16x16x128_f8f6f4 v[14:17], v[152:159], v[176:183], v[140:143]
	v_mfma_f32_16x16x128_f8f6f4 v[6:9], v[144:151], v[184:191], v[66:69]
	v_mfma_f32_16x16x128_f8f6f4 v[2:5], v[152:159], v[184:191], v[192:195]
	s_setprio 0
	s_add_i32 s72, s72, 2
	s_addk_i32 s7, 0x100
	s_addk_i32 s71, 0x100
	s_cmp_gt_u32 s72, 5
	s_barrier
	s_cbranch_scc0 .LBB0_3185
	v_pk_mul_f32 v[126:127], v[126:127], 0.5 op_sel_hi:[1,0]
	v_mov_b32_e32 v132, 0
	v_cvt_pk_fp8_f32 v132, v126, v127
	v_pk_mul_f32 v[122:123], v[122:123], 0.5 op_sel_hi:[1,0]
	v_mov_b32_e32 v133, 0
	v_cvt_pk_fp8_f32 v133, v122, v123
	v_pk_mul_f32 v[122:123], v[128:129], 0.5 op_sel_hi:[1,0]
	v_pk_mul_f32 v[118:119], v[118:119], 0.5 op_sel_hi:[1,0]
	v_cvt_pk_fp8_f32 v132, v122, v123 op_sel:[0,0,1]
	v_mov_b32_e32 v122, 0
	v_cvt_pk_fp8_f32 v122, v118, v119
	v_pk_mul_f32 v[114:115], v[114:115], 0.5 op_sel_hi:[1,0]
	v_mov_b32_e32 v118, 0
	v_cvt_pk_fp8_f32 v118, v114, v115
	v_pk_mul_f32 v[106:107], v[106:107], 0.5 op_sel_hi:[1,0]
	v_mov_b32_e32 v119, 0
	v_cvt_pk_fp8_f32 v119, v106, v107
	v_pk_mul_f32 v[106:107], v[116:117], 0.5 op_sel_hi:[1,0]
	v_pk_mul_f32 v[94:95], v[94:95], 0.5 op_sel_hi:[1,0]
	v_cvt_pk_fp8_f32 v118, v106, v107 op_sel:[0,0,1]
	v_mov_b32_e32 v107, 0
	v_cvt_pk_fp8_f32 v107, v94, v95
	v_pk_mul_f32 v[110:111], v[110:111], 0.5 op_sel_hi:[1,0]
	v_mov_b32_e32 v123, 0
	v_cvt_pk_fp8_f32 v123, v110, v111
	v_pk_mul_f32 v[96:97], v[96:97], 0.5 op_sel_hi:[1,0]
	v_pk_mul_f32 v[102:103], v[102:103], 0.5 op_sel_hi:[1,0]
	v_mov_b32_e32 v106, 0
	v_cvt_pk_fp8_f32 v107, v96, v97 op_sel:[0,0,1]
	v_pk_mul_f32 v[96:97], v[98:99], 0.5 op_sel_hi:[1,0]
	v_mov_b32_e32 v98, 0
	v_cvt_pk_fp8_f32 v106, v102, v103
	v_cvt_pk_fp8_f32 v98, v96, v97
	v_lshl_add_u32 v66, s70, 8, v136
	v_pk_mul_f32 v[112:113], v[112:113], 0.5 op_sel_hi:[1,0]
	v_pk_mul_f32 v[124:125], v[124:125], 0.5 op_sel_hi:[1,0]
	v_cvt_pk_fp8_f32 v123, v112, v113 op_sel:[0,0,1]
	v_or_b32_e32 v112, 16, v66
	v_pk_mul_f32 v[108:109], v[108:109], 0.5 op_sel_hi:[1,0]
	v_pk_mul_f32 v[90:91], v[90:91], 0.5 op_sel_hi:[1,0]
	v_mov_b32_e32 v99, 0
	v_ashrrev_i32_e32 v67, 31, v66
	v_cvt_pk_fp8_f32 v133, v124, v125 op_sel:[0,0,1]
	v_pk_mul_f32 v[110:111], v[120:121], 0.5 op_sel_hi:[1,0]
	v_ashrrev_i32_e32 v113, 31, v112
	v_cvt_pk_fp8_f32 v119, v108, v109 op_sel:[0,0,1]
	v_pk_mul_f32 v[94:95], v[104:105], 0.5 op_sel_hi:[1,0]
	v_cvt_pk_fp8_f32 v99, v90, v91
	v_pk_mul_f32 v[90:91], v[100:101], 0.5 op_sel_hi:[1,0]
	v_lshl_or_b32 v68, s59, 8, v137
	v_lshlrev_b64 v[130:131], 10, v[66:67]
	v_cvt_pk_fp8_f32 v122, v110, v111 op_sel:[0,0,1]
	v_lshlrev_b64 v[112:113], 10, v[112:113]
	v_cvt_pk_fp8_f32 v106, v94, v95 op_sel:[0,0,1]
	v_cvt_pk_fp8_f32 v98, v90, v91 op_sel:[0,0,1]
	v_pk_mul_f32 v[86:87], v[86:87], 0.5 op_sel_hi:[1,0]
	v_pk_mul_f32 v[78:79], v[78:79], 0.5 op_sel_hi:[1,0]
	v_mov_b32_e32 v90, 0
	v_mov_b32_e32 v91, 0
	v_ashrrev_i32_e32 v69, 31, v68
	v_lshl_add_u64 v[110:111], s[68:69], 0, v[130:131]
	v_lshl_add_u64 v[94:95], s[68:69], 0, v[112:113]
	v_cvt_pk_fp8_f32 v90, v86, v87
	v_cvt_pk_fp8_f32 v91, v78, v79
	v_lshl_add_u64 v[110:111], v[110:111], 0, v[68:69]
	v_lshl_add_u64 v[94:95], v[94:95], 0, v[68:69]
	global_store_dwordx2 v[110:111], v[132:133], off
	global_store_dwordx2 v[110:111], v[122:123], off offset:128
	global_store_dwordx2 v[94:95], v[118:119], off
	global_store_dwordx2 v[94:95], v[106:107], off offset:128
	v_or_b32_e32 v94, 32, v66
	v_pk_mul_f32 v[92:93], v[92:93], 0.5 op_sel_hi:[1,0]
	v_ashrrev_i32_e32 v95, 31, v94
	v_cvt_pk_fp8_f32 v99, v92, v93 op_sel:[0,0,1]
	v_pk_mul_f32 v[78:79], v[88:89], 0.5 op_sel_hi:[1,0]
	v_pk_mul_f32 v[80:81], v[80:81], 0.5 op_sel_hi:[1,0]
	v_lshlrev_b64 v[94:95], 10, v[94:95]
	v_cvt_pk_fp8_f32 v90, v78, v79 op_sel:[0,0,1]
	v_cvt_pk_fp8_f32 v91, v80, v81 op_sel:[0,0,1]
	v_lshl_add_u64 v[78:79], s[68:69], 0, v[94:95]
	v_lshl_add_u64 v[78:79], v[78:79], 0, v[68:69]
	global_store_dwordx2 v[78:79], v[98:99], off
	global_store_dwordx2 v[78:79], v[90:91], off offset:128
	v_pk_mul_f32 v[78:79], v[82:83], 0.5 op_sel_hi:[1,0]
	v_mov_b32_e32 v80, 0
	v_cvt_pk_fp8_f32 v80, v78, v79
	v_pk_mul_f32 v[74:75], v[74:75], 0.5 op_sel_hi:[1,0]
	v_mov_b32_e32 v81, 0
	v_cvt_pk_fp8_f32 v81, v74, v75
	v_pk_mul_f32 v[74:75], v[84:85], 0.5 op_sel_hi:[1,0]
	v_pk_mul_f32 v[18:19], v[18:19], 0.5 op_sel_hi:[1,0]
	v_cvt_pk_fp8_f32 v80, v74, v75 op_sel:[0,0,1]
	v_mov_b32_e32 v75, 0
	v_cvt_pk_fp8_f32 v75, v18, v19
	v_pk_mul_f32 v[20:21], v[20:21], 0.5 op_sel_hi:[1,0]
	v_pk_mul_f32 v[58:59], v[58:59], 0.5 op_sel_hi:[1,0]
	v_pk_mul_f32 v[70:71], v[70:71], 0.5 op_sel_hi:[1,0]
	v_cvt_pk_fp8_f32 v75, v20, v21 op_sel:[0,0,1]
	v_pk_mul_f32 v[20:21], v[62:63], 0.5 op_sel_hi:[1,0]
	v_mov_b32_e32 v62, 0
	v_cvt_pk_fp8_f32 v62, v20, v21
	v_mov_b32_e32 v63, 0
	v_pk_mul_f32 v[20:21], v[64:65], 0.5 op_sel_hi:[1,0]
	v_mov_b32_e32 v74, 0
	v_cvt_pk_fp8_f32 v63, v58, v59
	v_cvt_pk_fp8_f32 v62, v20, v21 op_sel:[0,0,1]
	v_pk_mul_f32 v[20:21], v[54:55], 0.5 op_sel_hi:[1,0]
	v_pk_mul_f32 v[46:47], v[46:47], 0.5 op_sel_hi:[1,0]
	v_mov_b32_e32 v54, 0
	v_mov_b32_e32 v55, 0
	v_cvt_pk_fp8_f32 v74, v70, v71
	v_cvt_pk_fp8_f32 v54, v20, v21
	v_cvt_pk_fp8_f32 v55, v46, v47
	v_or_b32_e32 v66, 48, v66
	v_pk_mul_f32 v[76:77], v[76:77], 0.5 op_sel_hi:[1,0]
	v_pk_mul_f32 v[58:59], v[60:61], 0.5 op_sel_hi:[1,0]
	v_ashrrev_i32_e32 v67, 31, v66
	v_cvt_pk_fp8_f32 v81, v76, v77 op_sel:[0,0,1]
	v_pk_mul_f32 v[18:19], v[72:73], 0.5 op_sel_hi:[1,0]
	v_cvt_pk_fp8_f32 v63, v58, v59 op_sel:[0,0,1]
	v_pk_mul_f32 v[20:21], v[56:57], 0.5 op_sel_hi:[1,0]
	v_pk_mul_f32 v[46:47], v[48:49], 0.5 op_sel_hi:[1,0]
	v_lshlrev_b64 v[66:67], 10, v[66:67]
	v_cvt_pk_fp8_f32 v74, v18, v19 op_sel:[0,0,1]
	v_cvt_pk_fp8_f32 v54, v20, v21 op_sel:[0,0,1]
	v_cvt_pk_fp8_f32 v55, v46, v47 op_sel:[0,0,1]
	v_lshl_add_u64 v[18:19], s[68:69], 0, v[66:67]
	v_add_co_u32_e32 v20, vcc, s47, v110
	v_lshl_add_u64 v[18:19], v[18:19], 0, v[68:69]
	s_nop 0
	v_addc_co_u32_e32 v21, vcc, 0, v111, vcc
	global_store_dwordx2 v[18:19], v[80:81], off
	global_store_dwordx2 v[18:19], v[74:75], off offset:128
	v_lshl_add_u64 v[18:19], v[110:111], 0, s[12:13]
	global_store_dwordx2 v[20:21], v[62:63], off
	global_store_dwordx2 v[18:19], v[54:55], off offset:128
	v_pk_mul_f32 v[20:21], v[50:51], 0.5 op_sel_hi:[1,0]
	v_mov_b32_e32 v46, 0
	v_cvt_pk_fp8_f32 v46, v20, v21
	v_pk_mul_f32 v[42:43], v[42:43], 0.5 op_sel_hi:[1,0]
	v_mov_b32_e32 v47, 0
	v_pk_mul_f32 v[20:21], v[52:53], 0.5 op_sel_hi:[1,0]
	v_cvt_pk_fp8_f32 v47, v42, v43
	v_cvt_pk_fp8_f32 v46, v20, v21 op_sel:[0,0,1]
	v_pk_mul_f32 v[20:21], v[38:39], 0.5 op_sel_hi:[1,0]
	v_pk_mul_f32 v[30:31], v[30:31], 0.5 op_sel_hi:[1,0]
	v_mov_b32_e32 v38, 0
	v_mov_b32_e32 v39, 0
	v_cvt_pk_fp8_f32 v38, v20, v21
	v_cvt_pk_fp8_f32 v39, v30, v31
	v_pk_mul_f32 v[42:43], v[44:45], 0.5 op_sel_hi:[1,0]
	v_pk_mul_f32 v[20:21], v[40:41], 0.5 op_sel_hi:[1,0]
	v_cvt_pk_fp8_f32 v47, v42, v43 op_sel:[0,0,1]
	v_pk_mul_f32 v[30:31], v[32:33], 0.5 op_sel_hi:[1,0]
	v_cvt_pk_fp8_f32 v38, v20, v21 op_sel:[0,0,1]
	v_cvt_pk_fp8_f32 v39, v30, v31 op_sel:[0,0,1]
	v_add_co_u32_e32 v20, vcc, s41, v110
	v_lshl_add_u64 v[18:19], v[110:111], 0, s[14:15]
	s_nop 0
	v_addc_co_u32_e32 v21, vcc, 0, v111, vcc
	global_store_dwordx2 v[20:21], v[46:47], off
	global_store_dwordx2 v[18:19], v[38:39], off offset:128
	v_pk_mul_f32 v[20:21], v[34:35], 0.5 op_sel_hi:[1,0]
	v_mov_b32_e32 v30, 0
	v_cvt_pk_fp8_f32 v30, v20, v21
	v_pk_mul_f32 v[26:27], v[26:27], 0.5 op_sel_hi:[1,0]
	v_mov_b32_e32 v31, 0
	v_pk_mul_f32 v[20:21], v[36:37], 0.5 op_sel_hi:[1,0]
	v_cvt_pk_fp8_f32 v31, v26, v27
	v_cvt_pk_fp8_f32 v30, v20, v21 op_sel:[0,0,1]
	v_pk_mul_f32 v[20:21], v[22:23], 0.5 op_sel_hi:[1,0]
	v_pk_mul_f32 v[14:15], v[14:15], 0.5 op_sel_hi:[1,0]
	v_mov_b32_e32 v22, 0
	v_mov_b32_e32 v23, 0
	v_cvt_pk_fp8_f32 v22, v20, v21
	v_cvt_pk_fp8_f32 v23, v14, v15
	v_pk_mul_f32 v[26:27], v[28:29], 0.5 op_sel_hi:[1,0]
	v_pk_mul_f32 v[14:15], v[24:25], 0.5 op_sel_hi:[1,0]
	v_cvt_pk_fp8_f32 v31, v26, v27 op_sel:[0,0,1]
	v_pk_mul_f32 v[16:17], v[16:17], 0.5 op_sel_hi:[1,0]
	v_cvt_pk_fp8_f32 v22, v14, v15 op_sel:[0,0,1]
	v_cvt_pk_fp8_f32 v23, v16, v17 op_sel:[0,0,1]
	v_add_co_u32_e32 v14, vcc, s42, v110
	v_lshl_add_u64 v[18:19], v[110:111], 0, s[16:17]
	s_nop 0
	v_addc_co_u32_e32 v15, vcc, 0, v111, vcc
	global_store_dwordx2 v[14:15], v[30:31], off
	global_store_dwordx2 v[18:19], v[22:23], off offset:128
	v_pk_mul_f32 v[16:17], v[232:233], 0.5 op_sel_hi:[1,0]
	v_mov_b32_e32 v18, 0
	v_cvt_pk_fp8_f32 v18, v16, v17
	v_pk_mul_f32 v[10:11], v[10:11], 0.5 op_sel_hi:[1,0]
	v_mov_b32_e32 v19, 0
	v_cvt_pk_fp8_f32 v19, v10, v11
	v_pk_mul_f32 v[10:11], v[234:235], 0.5 op_sel_hi:[1,0]
	v_pk_mul_f32 v[6:7], v[6:7], 0.5 op_sel_hi:[1,0]
	v_cvt_pk_fp8_f32 v18, v10, v11 op_sel:[0,0,1]
	v_pk_mul_f32 v[2:3], v[2:3], 0.5 op_sel_hi:[1,0]
	v_mov_b32_e32 v10, 0
	v_mov_b32_e32 v11, 0
	v_cvt_pk_fp8_f32 v10, v6, v7
	v_cvt_pk_fp8_f32 v11, v2, v3
	v_pk_mul_f32 v[12:13], v[12:13], 0.5 op_sel_hi:[1,0]
	v_pk_mul_f32 v[2:3], v[8:9], 0.5 op_sel_hi:[1,0]
	v_cvt_pk_fp8_f32 v19, v12, v13 op_sel:[0,0,1]
	v_pk_mul_f32 v[4:5], v[4:5], 0.5 op_sel_hi:[1,0]
	v_cvt_pk_fp8_f32 v10, v2, v3 op_sel:[0,0,1]
	v_cvt_pk_fp8_f32 v11, v4, v5 op_sel:[0,0,1]
	v_add_co_u32_e32 v2, vcc, s43, v110
	s_mov_b32 s59, s50
	s_nop 0
	v_addc_co_u32_e32 v3, vcc, 0, v111, vcc
	s_and_b64 vcc, exec, s[4:5]
	s_mov_b32 s70, s51
	s_mov_b32 s71, s57
	s_mov_b32 s72, s58
	v_lshl_add_u64 v[14:15], v[110:111], 0, s[18:19]
	global_store_dwordx2 v[2:3], v[18:19], off
	global_store_dwordx2 v[14:15], v[10:11], off offset:128
	s_cbranch_vccz .LBB0_3176
	s_waitcnt vmcnt(0)
	s_cmpk_gt_u32 s3, 0xff
	s_cbranch_scc1 .LBB0_3189
	s_barrier

	.amdhsa_kernel _Z10fwd_kernel4Args
		.amdhsa_group_segment_fixed_size 0
		.amdhsa_private_segment_fixed_size 0
		.amdhsa_kernarg_size 504
		.amdhsa_user_sgpr_count 2
		.amdhsa_user_sgpr_dispatch_ptr 0
		.amdhsa_user_sgpr_queue_ptr 0
		.amdhsa_user_sgpr_kernarg_segment_ptr 1
		.amdhsa_user_sgpr_dispatch_id 0
		.amdhsa_user_sgpr_kernarg_preload_length 0
		.amdhsa_user_sgpr_kernarg_preload_offset 0
		.amdhsa_user_sgpr_private_segment_size 0
		.amdhsa_uses_dynamic_stack 0
		.amdhsa_enable_private_segment 0
		.amdhsa_system_sgpr_workgroup_id_x 1
		.amdhsa_system_sgpr_workgroup_id_y 0
		.amdhsa_system_sgpr_workgroup_id_z 0
		.amdhsa_system_sgpr_workgroup_info 0
		.amdhsa_system_vgpr_workitem_id 0
		.amdhsa_next_free_vgpr 256
		.amdhsa_next_free_sgpr 100
		.amdhsa_accum_offset 256
		.amdhsa_reserve_vcc 1
		.amdhsa_float_round_mode_32 0
		.amdhsa_float_round_mode_16_64 0
		.amdhsa_float_denorm_mode_32 3
		.amdhsa_float_denorm_mode_16_64 3
		.amdhsa_dx10_clamp 1
		.amdhsa_ieee_mode 1
		.amdhsa_fp16_overflow 0
		.amdhsa_tg_split 0
		.amdhsa_exception_fp_ieee_invalid_op 0
		.amdhsa_exception_fp_denorm_src 0
		.amdhsa_exception_fp_ieee_div_zero 0
		.amdhsa_exception_fp_ieee_overflow 0
		.amdhsa_exception_fp_ieee_underflow 0
		.amdhsa_exception_fp_ieee_inexact 0
		.amdhsa_exception_int_div_zero 0
	.end_amdhsa_kernel

amdhsa.kernels:
  - .agpr_count:     0
    .args:
      - .offset:         0
        .size:           248
        .value_kind:     by_value
      - .offset:         248
        .size:           4
        .value_kind:     hidden_block_count_x
      - .offset:         252
        .size:           4
        .value_kind:     hidden_block_count_y
      - .offset:         256
        .size:           4
        .value_kind:     hidden_block_count_z
      - .offset:         260
        .size:           2
        .value_kind:     hidden_group_size_x
      - .offset:         262
        .size:           2
        .value_kind:     hidden_group_size_y
      - .offset:         264
        .size:           2
        .value_kind:     hidden_group_size_z
      - .offset:         266
        .size:           2
        .value_kind:     hidden_remainder_x
      - .offset:         268
        .size:           2
        .value_kind:     hidden_remainder_y
      - .offset:         270
        .size:           2
        .value_kind:     hidden_remainder_z
      - .offset:         288
        .size:           8
        .value_kind:     hidden_global_offset_x
      - .offset:         296
        .size:           8
        .value_kind:     hidden_global_offset_y
      - .offset:         304
        .size:           8
        .value_kind:     hidden_global_offset_z
      - .offset:         312
        .size:           2
        .value_kind:     hidden_grid_dims
      - .offset:         368
        .size:           4
        .value_kind:     hidden_dynamic_lds_size
    .group_segment_fixed_size: 0
    .kernarg_segment_align: 8
    .kernarg_segment_size: 504
    .language:       OpenCL C
    .language_version:
      - 2
      - 0
    .max_flat_workgroup_size: 512
    .name:           _Z10fwd_kernel4Args
    .private_segment_fixed_size: 0
    .sgpr_count:     106
    .sgpr_spill_count: 18
    .symbol:         _Z10fwd_kernel4Args.kd
    .uniform_work_group_size: 1
    .uses_dynamic_stack: false
    .vgpr_count:     256
    .vgpr_spill_count: 0
    .wavefront_size: 64
